# k21 minus the mid-phase s_setprio 0/1 flip pairs inside the MFMA blocks (MFMA stream kept free of SALU)
# speedup vs baseline: 1.0054x; 1.0054x over previous
;     __device__ bool next(int i, Unit& u) const { if (i >= 2) return false; const int x = c & 7, j = c >> 3; u.pm = 32 * i + 4 * x + (j & 3); u.pn = j >> 2; return true; }
; #define PG8_STAGE(bufoff, gbase, voff) do { _Pragma("unroll") for (int _i = 0; _i < 2; ++_i) \
;         __builtin_amdgcn_global_load_lds((const unsigned*)((const char*)(gbase) + (voff)[_i]), (LAS unsigned*)(lds + (bufoff) + ldsw + _i * 8192), 16, 0, 0); } while (0)
; #define PG8_WAIT_V(n) asm volatile("s_waitcnt vmcnt(" #n ")" ::: "memory")
; #define PG8_BAR __builtin_amdgcn_s_barrier()
; template <class Epi, class Sched, bool ALIGN_EPI = true>
; __device__ __forceinline__ void gemm_phase(LAS unsigned char* lds, const Gemm g, const Sched& S, const Epi& E) {
;     ...
;         const bool has_next = S.next(ui + 1, nxt);
;         const char* nA = has_next ? (const char*)g.A + ((size_t)nxt.pm * BM * g.lda + (size_t)nxt.pn * g.a_pn_off) * 2 : cA; const char* nB = has_next ? (const char*)g.Bt + (size_t)nxt.pn * BM * g.ldb * 2 : cB;
;         for (int t = 0; t < nt; t += 2) {
;             const bool last = (t == nt - 2);
;             const char* a1 = cA + (size_t)(t + 1) * kstep;
;             const char* a2 = last ? nA : cA + (size_t)(t + 2) * kstep; const char* b2 = last ? nB : cB + (size_t)(t + 2) * kstep;
;             const char* a3 = a2 + kstep; const char* b3 = b2 + kstep;
;             PG8_LDB(B0, 0, 0); PG8_LDB(B1, 0, 1); PG8_SCHED; PG8_LDA(At, 0, 0); PG8_STAGE(PG8_SA(1, 1), a1 + hA, voffA);
;             PG8_WAIT_V(8); PG8_WAIT_L(0); PG8_BAR; PG8_MMA(0, 0, At, B0); PG8_MMA(0, 1, At, B1); PG8_BAR; PG8_SCHED;
;             PG8_LDA(At, 0, 1); PG8_STAGE(PG8_SB(0, 0), b2, voffB); PG8_STAGE(PG8_SB(0, 1), b2 + hB, voffB); PG8_STAGE(PG8_SA(0, 0), a2, voffA);
;             PG8_WAIT_V(8); PG8_WAIT_L(0); PG8_BAR; PG8_MMA(1, 0, At, B0); PG8_MMA(1, 1, At, B1); PG8_BAR; PG8_SCHED;
;             PG8_LDB(B0, 1, 0); PG8_LDB(B1, 1, 1); PG8_SCHED; PG8_LDA(At, 1, 0); PG8_STAGE(PG8_SA(0, 1), a2 + hA, voffA);
;             PG8_WAIT_V(8); PG8_WAIT_L(0); PG8_BAR; PG8_MMA(0, 0, At, B0); PG8_MMA(0, 1, At, B1); PG8_BAR; PG8_SCHED;
;             PG8_LDA(At, 1, 1); PG8_STAGE(PG8_SB(1, 0), b3, voffB); PG8_STAGE(PG8_SB(1, 1), b3 + hB, voffB); PG8_STAGE(PG8_SA(1, 0), a3, voffA);
;             PG8_WAIT_V(8); PG8_WAIT_L(0); PG8_BAR; PG8_MMA(1, 0, At, B0); PG8_MMA(1, 1, At, B1); PG8_BAR; PG8_SCHED;
.LBB0_76:
	s_ashr_i32 s15, s14, 31
	s_lshl_b64 s[18:19], s[14:15], 20
	s_add_u32 s38, s46, s18
	s_addc_u32 s39, s47, s19
	s_and_b64 s[18:19], s[4:5], exec
	s_cselect_b32 s15, s39, s7
	s_cselect_b32 s17, s38, s6
	s_ashr_i32 s13, s12, 31
	s_lshl_b64 s[18:19], s[12:13], 20
	s_add_u32 s40, s53, s18
	s_addc_u32 s41, s58, s19
	s_and_b64 s[18:19], s[4:5], exec
	s_cselect_b32 s13, s41, s43
	s_cselect_b32 s18, s40, s42
	s_add_u32 s6, s6, 0x80080
	s_addc_u32 s7, s7, 0
	s_add_u32 s19, s42, 0x100
	s_addc_u32 s24, s43, 0
	s_mov_b32 s25, -2
	s_add_u32 s26, s6, 0xfff80080
	s_addc_u32 s27, s7, -1
	s_add_i32 s30, 0, 0x10000
	s_cmp_eq_u32 s25, 28
	s_cselect_b32 s45, s15, s27
	s_cselect_b32 s44, s17, s26
	s_cselect_b32 s43, s13, s24
	s_cselect_b32 s42, s18, s19
	s_add_i32 s31, 0, 0x14000
	v_add_u32_e32 v144, s30, v166
	v_add_u32_e32 v156, s31, v166
	ds_read_b128 v[132:135], v144
	ds_read_b128 v[136:139], v144 offset:1024
	ds_read_b128 v[140:143], v144 offset:2048
	ds_read_b128 v[144:147], v144 offset:3072
	ds_read_b128 v[170:173], v156
	ds_read_b128 v[174:177], v156 offset:1024
	ds_read_b128 v[178:181], v156 offset:2048
	ds_read_b128 v[182:185], v156 offset:3072
	v_lshl_add_u64 v[156:157], s[6:7], 0, v[152:153]
	s_add_i32 m0, s60, 0xc000
	ds_read_b128 v[186:189], v168
	ds_read_b128 v[190:193], v168 offset:1024
	ds_read_b128 v[194:197], v168 offset:2048
	ds_read_b128 v[204:207], v168 offset:3072
	ds_read_b128 v[208:211], v168 offset:4096
	ds_read_b128 v[212:215], v168 offset:5120
	ds_read_b128 v[216:219], v168 offset:6144
	ds_read_b128 v[220:223], v168 offset:7168
	global_load_lds_dwordx4 v[156:157], off
	v_lshl_add_u64 v[156:157], s[6:7], 0, v[154:155]
	s_add_i32 m0, s60, 0xe000
	s_nop 0
	global_load_lds_dwordx4 v[156:157], off
	s_waitcnt vmcnt(8)
	s_waitcnt lgkmcnt(0)
	s_barrier
	s_setprio 1
	s_waitcnt lgkmcnt(0)
	v_mfma_f32_16x16x32_bf16 v[128:131], v[132:135], v[186:189], 0
	v_mfma_f32_16x16x32_bf16 v[128:131], v[136:139], v[190:193], v[128:131]
	v_mfma_f32_16x16x32_bf16 v[124:127], v[140:143], v[186:189], 0
	v_mfma_f32_16x16x32_bf16 v[124:127], v[144:147], v[190:193], v[124:127]
	v_mfma_f32_16x16x32_bf16 v[116:119], v[132:135], v[194:197], 0
	v_mfma_f32_16x16x32_bf16 v[116:119], v[136:139], v[204:207], v[116:119]
	v_mfma_f32_16x16x32_bf16 v[112:115], v[140:143], v[194:197], 0
	v_mfma_f32_16x16x32_bf16 v[112:115], v[144:147], v[204:207], v[112:115]
	v_mfma_f32_16x16x32_bf16 v[104:107], v[132:135], v[208:211], 0
	v_mfma_f32_16x16x32_bf16 v[104:107], v[136:139], v[212:215], v[104:107]
	v_mfma_f32_16x16x32_bf16 v[96:99], v[140:143], v[208:211], 0
	v_mfma_f32_16x16x32_bf16 v[96:99], v[144:147], v[212:215], v[96:99]
	v_mfma_f32_16x16x32_bf16 v[88:91], v[132:135], v[216:219], 0
	v_mfma_f32_16x16x32_bf16 v[88:91], v[136:139], v[220:223], v[88:91]
	v_mfma_f32_16x16x32_bf16 v[80:83], v[140:143], v[216:219], 0
	v_mfma_f32_16x16x32_bf16 v[80:83], v[144:147], v[220:223], v[80:83]
	v_mfma_f32_16x16x32_bf16 v[120:123], v[170:173], v[186:189], 0
	v_mfma_f32_16x16x32_bf16 v[120:123], v[174:177], v[190:193], v[120:123]
	v_mfma_f32_16x16x32_bf16 v[108:111], v[178:181], v[186:189], 0
	v_mfma_f32_16x16x32_bf16 v[108:111], v[182:185], v[190:193], v[108:111]
	v_mfma_f32_16x16x32_bf16 v[100:103], v[170:173], v[194:197], 0
	v_mfma_f32_16x16x32_bf16 v[100:103], v[174:177], v[204:207], v[100:103]
	v_mfma_f32_16x16x32_bf16 v[92:95], v[178:181], v[194:197], 0
	v_mfma_f32_16x16x32_bf16 v[92:95], v[182:185], v[204:207], v[92:95]
	v_mfma_f32_16x16x32_bf16 v[84:87], v[170:173], v[208:211], 0
	v_mfma_f32_16x16x32_bf16 v[84:87], v[174:177], v[212:215], v[84:87]
	v_mfma_f32_16x16x32_bf16 v[76:79], v[178:181], v[208:211], 0
	v_mfma_f32_16x16x32_bf16 v[76:79], v[182:185], v[212:215], v[76:79]
	v_mfma_f32_16x16x32_bf16 v[72:75], v[170:173], v[216:219], 0
	v_mfma_f32_16x16x32_bf16 v[72:75], v[174:177], v[220:223], v[72:75]
	s_setprio 2
	s_barrier
	v_mfma_f32_16x16x32_bf16 v[68:71], v[178:181], v[216:219], 0
	v_mfma_f32_16x16x32_bf16 v[68:71], v[182:185], v[220:223], v[68:71]
	s_setprio 0
	s_add_i32 s26, s30, s59
	v_lshl_add_u64 v[156:157], s[42:43], 0, v[2:3]
	s_mov_b32 m0, s26
	ds_read_b128 v[186:189], v168 offset:16384
	ds_read_b128 v[190:193], v168 offset:17408
	ds_read_b128 v[194:197], v168 offset:18432
	ds_read_b128 v[204:207], v168 offset:19456
	ds_read_b128 v[208:211], v168 offset:20480
	ds_read_b128 v[212:215], v168 offset:21504
	ds_read_b128 v[216:219], v168 offset:22528
	ds_read_b128 v[220:223], v168 offset:23552
	global_load_lds_dwordx4 v[156:157], off
	s_add_i32 m0, s26, 0x2000
	s_add_u32 s26, s42, 0x80000
	v_lshl_add_u64 v[164:165], s[42:43], 0, v[0:1]
	s_addc_u32 s27, s43, 0
	s_add_i32 s30, s31, s59
	global_load_lds_dwordx4 v[164:165], off
	v_lshl_add_u64 v[224:225], s[26:27], 0, v[2:3]
	s_mov_b32 m0, s30
	v_lshl_add_u64 v[226:227], s[44:45], 0, v[148:149]
	global_load_lds_dwordx4 v[224:225], off
	v_lshl_add_u64 v[224:225], s[26:27], 0, v[0:1]
	s_add_i32 m0, s30, 0x2000
	s_nop 0
	global_load_lds_dwordx4 v[224:225], off
	v_lshl_add_u64 v[224:225], s[44:45], 0, v[150:151]
	s_mov_b32 m0, s60
	s_nop 0
	global_load_lds_dwordx4 v[224:225], off
	s_mov_b32 m0, s61
	s_nop 0
	global_load_lds_dwordx4 v[226:227], off
	s_waitcnt vmcnt(8)
	s_waitcnt lgkmcnt(0)
	s_barrier
; #define PG8_STAGE(bufoff, gbase, voff) do { _Pragma("unroll") for (int _i = 0; _i < 2; ++_i) \
;         __builtin_amdgcn_global_load_lds((const unsigned*)((const char*)(gbase) + (voff)[_i]), (LAS unsigned*)(lds + (bufoff) + ldsw + _i * 8192), 16, 0, 0); } while (0)
; #define PG8_LDA(dst, b, h) do { _Pragma("unroll") for (int m = 0; m < 4; ++m) _Pragma("unroll") for (int k = 0; k < 2; ++k) dst[m][k] = *(const LAS bf16x8*)(lds + PG8_SA(b, h) + aoff + m * 2048 + k * 1024); } while (0)
; #define PG8_LDB(dst, b, h) do { _Pragma("unroll") for (int n = 0; n < 2; ++n) _Pragma("unroll") for (int k = 0; k < 2; ++k) dst[n][k] = *(const LAS bf16x8*)(lds + PG8_SB(b, h) + boff + n * 2048 + k * 1024); } while (0)
; #define PG8_MMA(ai, bj, At, Bt) do { __builtin_amdgcn_s_setprio(1); _Pragma("unroll") for (int m = 0; m < 4; ++m) _Pragma("unroll") for (int n = 0; n < 2; ++n) _Pragma("unroll") for (int k = 0; k < 2; ++k) \
;         acc[ai][bj][m][n] = __builtin_amdgcn_mfma_f32_16x16x32_bf16(Bt[n][k], At[m][k], acc[ai][bj][m][n], 0, 0, 0); __builtin_amdgcn_s_setprio(0); } while (0)
; #define PG8_WAIT_V(n) asm volatile("s_waitcnt vmcnt(" #n ")" ::: "memory")
; #define PG8_WAIT_L(n) asm volatile("s_waitcnt lgkmcnt(" #n ")" ::: "memory")
; #define PG8_BAR __builtin_amdgcn_s_barrier()
; #define PG8_SCHED __builtin_amdgcn_sched_barrier(0)
; template <class Epi, class Sched, bool ALIGN_EPI = true>
; __device__ __forceinline__ void gemm_phase(LAS unsigned char* lds, const Gemm g, const Sched& S, const Epi& E) {
;     ...
;             PG8_LDA(At, 0, 1); PG8_STAGE(PG8_SB(0, 0), b2, voffB); PG8_STAGE(PG8_SB(0, 1), b2 + hB, voffB); PG8_STAGE(PG8_SA(0, 0), a2, voffA);
;             PG8_WAIT_V(8); PG8_WAIT_L(0); PG8_BAR; PG8_MMA(1, 0, At, B0); PG8_MMA(1, 1, At, B1); PG8_BAR; PG8_SCHED;
;             PG8_LDB(B0, 1, 0); PG8_LDB(B1, 1, 1); PG8_SCHED; PG8_LDA(At, 1, 0); PG8_STAGE(PG8_SA(0, 1), a2 + hA, voffA);
;             PG8_WAIT_V(8); PG8_WAIT_L(0); PG8_BAR; PG8_MMA(0, 0, At, B0); PG8_MMA(0, 1, At, B1); PG8_BAR; PG8_SCHED;
	s_setprio 1
	s_waitcnt lgkmcnt(0)
	v_mfma_f32_16x16x32_bf16 v[64:67], v[132:135], v[186:189], 0
	v_mfma_f32_16x16x32_bf16 v[64:67], v[136:139], v[190:193], v[64:67]
	v_mfma_f32_16x16x32_bf16 v[60:63], v[140:143], v[186:189], 0
	v_mfma_f32_16x16x32_bf16 v[60:63], v[144:147], v[190:193], v[60:63]
	v_mfma_f32_16x16x32_bf16 v[56:59], v[132:135], v[194:197], 0
	v_mfma_f32_16x16x32_bf16 v[56:59], v[136:139], v[204:207], v[56:59]
	v_mfma_f32_16x16x32_bf16 v[48:51], v[140:143], v[194:197], 0
	v_mfma_f32_16x16x32_bf16 v[48:51], v[144:147], v[204:207], v[48:51]
	v_mfma_f32_16x16x32_bf16 v[40:43], v[132:135], v[208:211], 0
	v_mfma_f32_16x16x32_bf16 v[40:43], v[136:139], v[212:215], v[40:43]
	v_mfma_f32_16x16x32_bf16 v[32:35], v[140:143], v[208:211], 0
	v_mfma_f32_16x16x32_bf16 v[32:35], v[144:147], v[212:215], v[32:35]
	v_mfma_f32_16x16x32_bf16 v[24:27], v[132:135], v[216:219], 0
	v_mfma_f32_16x16x32_bf16 v[24:27], v[136:139], v[220:223], v[24:27]
	v_mfma_f32_16x16x32_bf16 v[16:19], v[140:143], v[216:219], 0
	v_mfma_f32_16x16x32_bf16 v[16:19], v[144:147], v[220:223], v[16:19]
	v_mfma_f32_16x16x32_bf16 v[52:55], v[170:173], v[186:189], 0
	v_mfma_f32_16x16x32_bf16 v[52:55], v[174:177], v[190:193], v[52:55]
	v_mfma_f32_16x16x32_bf16 v[44:47], v[178:181], v[186:189], 0
	v_mfma_f32_16x16x32_bf16 v[44:47], v[182:185], v[190:193], v[44:47]
	v_mfma_f32_16x16x32_bf16 v[36:39], v[170:173], v[194:197], 0
	v_mfma_f32_16x16x32_bf16 v[36:39], v[174:177], v[204:207], v[36:39]
	v_mfma_f32_16x16x32_bf16 v[28:31], v[178:181], v[194:197], 0
	v_mfma_f32_16x16x32_bf16 v[28:31], v[182:185], v[204:207], v[28:31]
	v_mfma_f32_16x16x32_bf16 v[20:23], v[170:173], v[208:211], 0
	v_mfma_f32_16x16x32_bf16 v[20:23], v[174:177], v[212:215], v[20:23]
	v_mfma_f32_16x16x32_bf16 v[12:15], v[178:181], v[208:211], 0
	v_mfma_f32_16x16x32_bf16 v[12:15], v[182:185], v[212:215], v[12:15]
	v_mfma_f32_16x16x32_bf16 v[8:11], v[170:173], v[216:219], 0
	v_mfma_f32_16x16x32_bf16 v[8:11], v[174:177], v[220:223], v[8:11]
	s_setprio 2
	s_barrier
	v_mfma_f32_16x16x32_bf16 v[4:7], v[178:181], v[216:219], 0
	v_mfma_f32_16x16x32_bf16 v[4:7], v[182:185], v[220:223], v[4:7]
	s_setprio 0
	s_add_i32 s30, 0, 0x18000
	s_add_i32 s31, 0, 0x1c000
	v_add_u32_e32 v144, s30, v166
	v_add_u32_e32 v160, s31, v166
	ds_read_b128 v[132:135], v144
	ds_read_b128 v[136:139], v144 offset:1024
	ds_read_b128 v[140:143], v144 offset:2048
	ds_read_b128 v[144:147], v144 offset:3072
	ds_read_b128 v[170:173], v160
	ds_read_b128 v[174:177], v160 offset:1024
	ds_read_b128 v[178:181], v160 offset:2048
	ds_read_b128 v[182:185], v160 offset:3072
	s_add_u32 s26, s44, 0x80000
	s_addc_u32 s27, s45, 0
	s_mov_b32 m0, s62
	v_lshl_add_u64 v[228:229], s[26:27], 0, v[150:151]
	ds_read_b128 v[186:189], v168 offset:32768
	ds_read_b128 v[190:193], v168 offset:33792
	ds_read_b128 v[194:197], v168 offset:34816
	ds_read_b128 v[204:207], v168 offset:35840
	ds_read_b128 v[208:211], v168 offset:36864
	ds_read_b128 v[212:215], v168 offset:37888
	ds_read_b128 v[216:219], v168 offset:38912
	ds_read_b128 v[220:223], v168 offset:39936
	global_load_lds_dwordx4 v[228:229], off
	v_lshl_add_u64 v[228:229], s[26:27], 0, v[148:149]
	s_mov_b32 m0, s63
	s_nop 0
	global_load_lds_dwordx4 v[228:229], off
	s_waitcnt vmcnt(8)
	s_waitcnt lgkmcnt(0)
	s_barrier
	s_setprio 1
	s_waitcnt lgkmcnt(0)
	v_mfma_f32_16x16x32_bf16 v[128:131], v[132:135], v[186:189], v[128:131]
	v_mfma_f32_16x16x32_bf16 v[128:131], v[136:139], v[190:193], v[128:131]
	v_mfma_f32_16x16x32_bf16 v[124:127], v[140:143], v[186:189], v[124:127]
	v_mfma_f32_16x16x32_bf16 v[124:127], v[144:147], v[190:193], v[124:127]
	v_mfma_f32_16x16x32_bf16 v[116:119], v[132:135], v[194:197], v[116:119]
	v_mfma_f32_16x16x32_bf16 v[116:119], v[136:139], v[204:207], v[116:119]
	v_mfma_f32_16x16x32_bf16 v[112:115], v[140:143], v[194:197], v[112:115]
	v_mfma_f32_16x16x32_bf16 v[112:115], v[144:147], v[204:207], v[112:115]
	v_mfma_f32_16x16x32_bf16 v[104:107], v[132:135], v[208:211], v[104:107]
	v_mfma_f32_16x16x32_bf16 v[104:107], v[136:139], v[212:215], v[104:107]
	v_mfma_f32_16x16x32_bf16 v[96:99], v[140:143], v[208:211], v[96:99]
	v_mfma_f32_16x16x32_bf16 v[96:99], v[144:147], v[212:215], v[96:99]
	v_mfma_f32_16x16x32_bf16 v[88:91], v[132:135], v[216:219], v[88:91]
	v_mfma_f32_16x16x32_bf16 v[88:91], v[136:139], v[220:223], v[88:91]
	v_mfma_f32_16x16x32_bf16 v[80:83], v[140:143], v[216:219], v[80:83]
	v_mfma_f32_16x16x32_bf16 v[80:83], v[144:147], v[220:223], v[80:83]
	v_mfma_f32_16x16x32_bf16 v[120:123], v[170:173], v[186:189], v[120:123]
	v_mfma_f32_16x16x32_bf16 v[120:123], v[174:177], v[190:193], v[120:123]
	v_mfma_f32_16x16x32_bf16 v[108:111], v[178:181], v[186:189], v[108:111]
	v_mfma_f32_16x16x32_bf16 v[108:111], v[182:185], v[190:193], v[108:111]
	v_mfma_f32_16x16x32_bf16 v[100:103], v[170:173], v[194:197], v[100:103]
	v_mfma_f32_16x16x32_bf16 v[100:103], v[174:177], v[204:207], v[100:103]
	v_mfma_f32_16x16x32_bf16 v[92:95], v[178:181], v[194:197], v[92:95]
	v_mfma_f32_16x16x32_bf16 v[92:95], v[182:185], v[204:207], v[92:95]
	v_mfma_f32_16x16x32_bf16 v[84:87], v[170:173], v[208:211], v[84:87]
	v_mfma_f32_16x16x32_bf16 v[84:87], v[174:177], v[212:215], v[84:87]
	v_mfma_f32_16x16x32_bf16 v[76:79], v[178:181], v[208:211], v[76:79]
	v_mfma_f32_16x16x32_bf16 v[76:79], v[182:185], v[212:215], v[76:79]
	v_mfma_f32_16x16x32_bf16 v[72:75], v[170:173], v[216:219], v[72:75]
	v_mfma_f32_16x16x32_bf16 v[72:75], v[174:177], v[220:223], v[72:75]
	s_setprio 2
	s_barrier
; #define PG8_STAGE(bufoff, gbase, voff) do { _Pragma("unroll") for (int _i = 0; _i < 2; ++_i) \
;         __builtin_amdgcn_global_load_lds((const unsigned*)((const char*)(gbase) + (voff)[_i]), (LAS unsigned*)(lds + (bufoff) + ldsw + _i * 8192), 16, 0, 0); } while (0)
; #define PG8_LDA(dst, b, h) do { _Pragma("unroll") for (int m = 0; m < 4; ++m) _Pragma("unroll") for (int k = 0; k < 2; ++k) dst[m][k] = *(const LAS bf16x8*)(lds + PG8_SA(b, h) + aoff + m * 2048 + k * 1024); } while (0)
; #define PG8_MMA(ai, bj, At, Bt) do { __builtin_amdgcn_s_setprio(1); _Pragma("unroll") for (int m = 0; m < 4; ++m) _Pragma("unroll") for (int n = 0; n < 2; ++n) _Pragma("unroll") for (int k = 0; k < 2; ++k) \
;         acc[ai][bj][m][n] = __builtin_amdgcn_mfma_f32_16x16x32_bf16(Bt[n][k], At[m][k], acc[ai][bj][m][n], 0, 0, 0); __builtin_amdgcn_s_setprio(0); } while (0)
; #define PG8_WAIT_V(n) asm volatile("s_waitcnt vmcnt(" #n ")" ::: "memory")
; #define PG8_WAIT_L(n) asm volatile("s_waitcnt lgkmcnt(" #n ")" ::: "memory")
; #define PG8_BAR __builtin_amdgcn_s_barrier()
; #define PG8_SCHED __builtin_amdgcn_sched_barrier(0)
; template <class Epi, class Sched, bool ALIGN_EPI = true>
; __device__ __forceinline__ void gemm_phase(LAS unsigned char* lds, const Gemm g, const Sched& S, const Epi& E) {
;     ...
;             const bool last = (t == nt - 2);
;             const char* a1 = cA + (size_t)(t + 1) * kstep;
;             const char* a2 = last ? nA : cA + (size_t)(t + 2) * kstep; const char* b2 = last ? nB : cB + (size_t)(t + 2) * kstep;
;             const char* a3 = a2 + kstep; const char* b3 = b2 + kstep;
;     ...
;             PG8_LDA(At, 1, 1); PG8_STAGE(PG8_SB(1, 0), b3, voffB); PG8_STAGE(PG8_SB(1, 1), b3 + hB, voffB); PG8_STAGE(PG8_SA(1, 0), a3, voffA);
;             PG8_WAIT_V(8); PG8_WAIT_L(0); PG8_BAR; PG8_MMA(1, 0, At, B0); PG8_MMA(1, 1, At, B1); PG8_BAR; PG8_SCHED;
	v_mfma_f32_16x16x32_bf16 v[68:71], v[178:181], v[216:219], v[68:71]
	v_mfma_f32_16x16x32_bf16 v[68:71], v[182:185], v[220:223], v[68:71]
	s_setprio 0
	s_add_i32 s26, s30, s59
	v_lshl_add_u64 v[156:157], v[156:157], 0, s[86:87]
	s_mov_b32 m0, s26
	ds_read_b128 v[186:189], v168 offset:49152
	ds_read_b128 v[190:193], v168 offset:50176
	ds_read_b128 v[194:197], v168 offset:51200
	ds_read_b128 v[204:207], v168 offset:52224
	ds_read_b128 v[208:211], v168 offset:53248
	ds_read_b128 v[212:215], v168 offset:54272
	ds_read_b128 v[216:219], v168 offset:55296
	ds_read_b128 v[220:223], v168 offset:56320
	global_load_lds_dwordx4 v[156:157], off
	s_add_i32 m0, s26, 0x2000
	s_add_u32 s26, s42, 0x80080
	v_lshl_add_u64 v[156:157], v[164:165], 0, s[86:87]
	s_addc_u32 s27, s43, 0
	s_add_i32 s30, s31, s59
	global_load_lds_dwordx4 v[156:157], off
	v_lshl_add_u64 v[156:157], s[26:27], 0, v[2:3]
	s_mov_b32 m0, s30
	s_nop 0
	global_load_lds_dwordx4 v[156:157], off
	v_lshl_add_u64 v[156:157], s[26:27], 0, v[0:1]
	s_add_i32 m0, s30, 0x2000
	s_nop 0
	global_load_lds_dwordx4 v[156:157], off
	v_lshl_add_u64 v[156:157], v[224:225], 0, s[86:87]
	s_mov_b32 m0, s64
	s_nop 0
	global_load_lds_dwordx4 v[156:157], off
	v_lshl_add_u64 v[156:157], v[226:227], 0, s[86:87]
	s_mov_b32 m0, s65
	s_nop 0
	global_load_lds_dwordx4 v[156:157], off
	s_waitcnt vmcnt(8)
	s_waitcnt lgkmcnt(0)
	s_barrier
	s_setprio 1
	s_waitcnt lgkmcnt(0)
	v_mfma_f32_16x16x32_bf16 v[64:67], v[132:135], v[186:189], v[64:67]
	v_mfma_f32_16x16x32_bf16 v[64:67], v[136:139], v[190:193], v[64:67]
	s_add_i32 s25, s25, 2
	s_add_u32 s6, s6, 0x100
	v_mfma_f32_16x16x32_bf16 v[60:63], v[140:143], v[186:189], v[60:63]
	v_mfma_f32_16x16x32_bf16 v[60:63], v[144:147], v[190:193], v[60:63]
	s_addc_u32 s7, s7, 0
	s_add_u32 s19, s19, 0x100
	v_mfma_f32_16x16x32_bf16 v[56:59], v[132:135], v[194:197], v[56:59]
	v_mfma_f32_16x16x32_bf16 v[56:59], v[136:139], v[204:207], v[56:59]
	s_addc_u32 s24, s24, 0
	s_add_u32 s26, s6, 0xfff80080
	v_mfma_f32_16x16x32_bf16 v[48:51], v[140:143], v[194:197], v[48:51]
	v_mfma_f32_16x16x32_bf16 v[48:51], v[144:147], v[204:207], v[48:51]
	s_addc_u32 s27, s7, -1
	s_add_i32 s30, 0, 0x10000
	v_mfma_f32_16x16x32_bf16 v[40:43], v[132:135], v[208:211], v[40:43]
	v_mfma_f32_16x16x32_bf16 v[40:43], v[136:139], v[212:215], v[40:43]
	s_cmp_eq_u32 s25, 28
	s_cselect_b32 s45, s15, s27
	v_mfma_f32_16x16x32_bf16 v[32:35], v[140:143], v[208:211], v[32:35]
	v_mfma_f32_16x16x32_bf16 v[32:35], v[144:147], v[212:215], v[32:35]
	s_cselect_b32 s44, s17, s26
	s_cselect_b32 s43, s13, s24
	v_mfma_f32_16x16x32_bf16 v[24:27], v[132:135], v[216:219], v[24:27]
	v_mfma_f32_16x16x32_bf16 v[24:27], v[136:139], v[220:223], v[24:27]
	s_cselect_b32 s42, s18, s19
	s_add_i32 s31, 0, 0x14000
	v_mfma_f32_16x16x32_bf16 v[16:19], v[140:143], v[216:219], v[16:19]
	v_mfma_f32_16x16x32_bf16 v[16:19], v[144:147], v[220:223], v[16:19]
	v_mfma_f32_16x16x32_bf16 v[52:55], v[170:173], v[186:189], v[52:55]
	v_mfma_f32_16x16x32_bf16 v[52:55], v[174:177], v[190:193], v[52:55]
	v_mfma_f32_16x16x32_bf16 v[44:47], v[178:181], v[186:189], v[44:47]
	v_mfma_f32_16x16x32_bf16 v[44:47], v[182:185], v[190:193], v[44:47]
	v_mfma_f32_16x16x32_bf16 v[36:39], v[170:173], v[194:197], v[36:39]
	v_mfma_f32_16x16x32_bf16 v[36:39], v[174:177], v[204:207], v[36:39]
	v_mfma_f32_16x16x32_bf16 v[28:31], v[178:181], v[194:197], v[28:31]
	v_mfma_f32_16x16x32_bf16 v[28:31], v[182:185], v[204:207], v[28:31]
	v_mfma_f32_16x16x32_bf16 v[20:23], v[170:173], v[208:211], v[20:23]
	v_mfma_f32_16x16x32_bf16 v[20:23], v[174:177], v[212:215], v[20:23]
	v_mfma_f32_16x16x32_bf16 v[12:15], v[178:181], v[208:211], v[12:15]
	v_mfma_f32_16x16x32_bf16 v[12:15], v[182:185], v[212:215], v[12:15]
	v_mfma_f32_16x16x32_bf16 v[8:11], v[170:173], v[216:219], v[8:11]
	v_mfma_f32_16x16x32_bf16 v[8:11], v[174:177], v[220:223], v[8:11]
	s_setprio 2
	s_barrier
	v_mfma_f32_16x16x32_bf16 v[4:7], v[178:181], v[216:219], v[4:7]
	v_mfma_f32_16x16x32_bf16 v[4:7], v[182:185], v[220:223], v[4:7]
	s_setprio 0
	s_cmp_gt_u32 s25, 29
	s_cbranch_scc1 .Lpeel_exit_77
.LBB0_77:
	v_add_u32_e32 v144, s30, v166
	v_add_u32_e32 v156, s31, v166
	ds_read_b128 v[132:135], v144
	ds_read_b128 v[136:139], v144 offset:1024
	ds_read_b128 v[140:143], v144 offset:2048
	ds_read_b128 v[144:147], v144 offset:3072
	ds_read_b128 v[170:173], v156
	ds_read_b128 v[174:177], v156 offset:1024
	ds_read_b128 v[178:181], v156 offset:2048
	ds_read_b128 v[182:185], v156 offset:3072
	v_lshl_add_u64 v[156:157], s[6:7], 0, v[152:153]
	s_add_i32 m0, s60, 0xc000
	ds_read_b128 v[186:189], v168
	ds_read_b128 v[190:193], v168 offset:1024
	ds_read_b128 v[194:197], v168 offset:2048
	ds_read_b128 v[204:207], v168 offset:3072
	ds_read_b128 v[208:211], v168 offset:4096
	ds_read_b128 v[212:215], v168 offset:5120
	ds_read_b128 v[216:219], v168 offset:6144
	ds_read_b128 v[220:223], v168 offset:7168
	global_load_lds_dwordx4 v[156:157], off
	v_lshl_add_u64 v[156:157], s[6:7], 0, v[154:155]
	s_add_i32 m0, s60, 0xe000
	s_nop 0
	global_load_lds_dwordx4 v[156:157], off
	s_waitcnt vmcnt(8)
	s_waitcnt lgkmcnt(0)
	s_barrier
; #define PG8_STAGE(bufoff, gbase, voff) do { _Pragma("unroll") for (int _i = 0; _i < 2; ++_i) \
;         __builtin_amdgcn_global_load_lds((const unsigned*)((const char*)(gbase) + (voff)[_i]), (LAS unsigned*)(lds + (bufoff) + ldsw + _i * 8192), 16, 0, 0); } while (0)
; #define PG8_LDA(dst, b, h) do { _Pragma("unroll") for (int m = 0; m < 4; ++m) _Pragma("unroll") for (int k = 0; k < 2; ++k) dst[m][k] = *(const LAS bf16x8*)(lds + PG8_SA(b, h) + aoff + m * 2048 + k * 1024); } while (0)
; #define PG8_LDB(dst, b, h) do { _Pragma("unroll") for (int n = 0; n < 2; ++n) _Pragma("unroll") for (int k = 0; k < 2; ++k) dst[n][k] = *(const LAS bf16x8*)(lds + PG8_SB(b, h) + boff + n * 2048 + k * 1024); } while (0)
; #define PG8_MMA(ai, bj, At, Bt) do { __builtin_amdgcn_s_setprio(1); _Pragma("unroll") for (int m = 0; m < 4; ++m) _Pragma("unroll") for (int n = 0; n < 2; ++n) _Pragma("unroll") for (int k = 0; k < 2; ++k) \
;         acc[ai][bj][m][n] = __builtin_amdgcn_mfma_f32_16x16x32_bf16(Bt[n][k], At[m][k], acc[ai][bj][m][n], 0, 0, 0); __builtin_amdgcn_s_setprio(0); } while (0)
; #define PG8_WAIT_V(n) asm volatile("s_waitcnt vmcnt(" #n ")" ::: "memory")
; #define PG8_WAIT_L(n) asm volatile("s_waitcnt lgkmcnt(" #n ")" ::: "memory")
; #define PG8_BAR __builtin_amdgcn_s_barrier()
; #define PG8_SCHED __builtin_amdgcn_sched_barrier(0)
; template <class Epi, class Sched, bool ALIGN_EPI = true>
; __device__ __forceinline__ void gemm_phase(LAS unsigned char* lds, const Gemm g, const Sched& S, const Epi& E) {
;     ...
;             PG8_LDB(B0, 0, 0); PG8_LDB(B1, 0, 1); PG8_SCHED; PG8_LDA(At, 0, 0); PG8_STAGE(PG8_SA(1, 1), a1 + hA, voffA);
;             PG8_WAIT_V(8); PG8_WAIT_L(0); PG8_BAR; PG8_MMA(0, 0, At, B0); PG8_MMA(0, 1, At, B1); PG8_BAR; PG8_SCHED;
;             PG8_LDA(At, 0, 1); PG8_STAGE(PG8_SB(0, 0), b2, voffB); PG8_STAGE(PG8_SB(0, 1), b2 + hB, voffB); PG8_STAGE(PG8_SA(0, 0), a2, voffA);
;             PG8_WAIT_V(8); PG8_WAIT_L(0); PG8_BAR; PG8_MMA(1, 0, At, B0); PG8_MMA(1, 1, At, B1); PG8_BAR; PG8_SCHED;
;             PG8_LDB(B0, 1, 0); PG8_LDB(B1, 1, 1); PG8_SCHED; PG8_LDA(At, 1, 0); PG8_STAGE(PG8_SA(0, 1), a2 + hA, voffA);
;             PG8_WAIT_V(8); PG8_WAIT_L(0); PG8_BAR; PG8_MMA(0, 0, At, B0); PG8_MMA(0, 1, At, B1); PG8_BAR; PG8_SCHED;
	s_setprio 1
	s_waitcnt lgkmcnt(0)
	v_mfma_f32_16x16x32_bf16 v[128:131], v[132:135], v[186:189], v[128:131]
	v_mfma_f32_16x16x32_bf16 v[128:131], v[136:139], v[190:193], v[128:131]
	v_mfma_f32_16x16x32_bf16 v[124:127], v[140:143], v[186:189], v[124:127]
	v_mfma_f32_16x16x32_bf16 v[124:127], v[144:147], v[190:193], v[124:127]
	v_mfma_f32_16x16x32_bf16 v[116:119], v[132:135], v[194:197], v[116:119]
	v_mfma_f32_16x16x32_bf16 v[116:119], v[136:139], v[204:207], v[116:119]
	v_mfma_f32_16x16x32_bf16 v[112:115], v[140:143], v[194:197], v[112:115]
	v_mfma_f32_16x16x32_bf16 v[112:115], v[144:147], v[204:207], v[112:115]
	v_mfma_f32_16x16x32_bf16 v[104:107], v[132:135], v[208:211], v[104:107]
	v_mfma_f32_16x16x32_bf16 v[104:107], v[136:139], v[212:215], v[104:107]
	v_mfma_f32_16x16x32_bf16 v[96:99], v[140:143], v[208:211], v[96:99]
	v_mfma_f32_16x16x32_bf16 v[96:99], v[144:147], v[212:215], v[96:99]
	v_mfma_f32_16x16x32_bf16 v[88:91], v[132:135], v[216:219], v[88:91]
	v_mfma_f32_16x16x32_bf16 v[88:91], v[136:139], v[220:223], v[88:91]
	v_mfma_f32_16x16x32_bf16 v[80:83], v[140:143], v[216:219], v[80:83]
	v_mfma_f32_16x16x32_bf16 v[80:83], v[144:147], v[220:223], v[80:83]
	v_mfma_f32_16x16x32_bf16 v[120:123], v[170:173], v[186:189], v[120:123]
	v_mfma_f32_16x16x32_bf16 v[120:123], v[174:177], v[190:193], v[120:123]
	v_mfma_f32_16x16x32_bf16 v[108:111], v[178:181], v[186:189], v[108:111]
	v_mfma_f32_16x16x32_bf16 v[108:111], v[182:185], v[190:193], v[108:111]
	v_mfma_f32_16x16x32_bf16 v[100:103], v[170:173], v[194:197], v[100:103]
	v_mfma_f32_16x16x32_bf16 v[100:103], v[174:177], v[204:207], v[100:103]
	v_mfma_f32_16x16x32_bf16 v[92:95], v[178:181], v[194:197], v[92:95]
	v_mfma_f32_16x16x32_bf16 v[92:95], v[182:185], v[204:207], v[92:95]
	v_mfma_f32_16x16x32_bf16 v[84:87], v[170:173], v[208:211], v[84:87]
	v_mfma_f32_16x16x32_bf16 v[84:87], v[174:177], v[212:215], v[84:87]
	v_mfma_f32_16x16x32_bf16 v[76:79], v[178:181], v[208:211], v[76:79]
	v_mfma_f32_16x16x32_bf16 v[76:79], v[182:185], v[212:215], v[76:79]
	v_mfma_f32_16x16x32_bf16 v[72:75], v[170:173], v[216:219], v[72:75]
	v_mfma_f32_16x16x32_bf16 v[72:75], v[174:177], v[220:223], v[72:75]
	s_setprio 2
	s_barrier
	v_mfma_f32_16x16x32_bf16 v[68:71], v[178:181], v[216:219], v[68:71]
	v_mfma_f32_16x16x32_bf16 v[68:71], v[182:185], v[220:223], v[68:71]
	s_setprio 0
	s_add_i32 s26, s30, s59
	v_lshl_add_u64 v[156:157], s[42:43], 0, v[2:3]
	s_mov_b32 m0, s26
	ds_read_b128 v[186:189], v168 offset:16384
	ds_read_b128 v[190:193], v168 offset:17408
	ds_read_b128 v[194:197], v168 offset:18432
	ds_read_b128 v[204:207], v168 offset:19456
	ds_read_b128 v[208:211], v168 offset:20480
	ds_read_b128 v[212:215], v168 offset:21504
	ds_read_b128 v[216:219], v168 offset:22528
	ds_read_b128 v[220:223], v168 offset:23552
	global_load_lds_dwordx4 v[156:157], off
	s_add_i32 m0, s26, 0x2000
	s_add_u32 s26, s42, 0x80000
	v_lshl_add_u64 v[164:165], s[42:43], 0, v[0:1]
	s_addc_u32 s27, s43, 0
	s_add_i32 s30, s31, s59
	global_load_lds_dwordx4 v[164:165], off
	v_lshl_add_u64 v[224:225], s[26:27], 0, v[2:3]
	s_mov_b32 m0, s30
	v_lshl_add_u64 v[226:227], s[44:45], 0, v[148:149]
	global_load_lds_dwordx4 v[224:225], off
	v_lshl_add_u64 v[224:225], s[26:27], 0, v[0:1]
	s_add_i32 m0, s30, 0x2000
	s_nop 0
	global_load_lds_dwordx4 v[224:225], off
	v_lshl_add_u64 v[224:225], s[44:45], 0, v[150:151]
	s_mov_b32 m0, s60
	s_nop 0
	global_load_lds_dwordx4 v[224:225], off
	s_mov_b32 m0, s61
	s_nop 0
	global_load_lds_dwordx4 v[226:227], off
	s_waitcnt vmcnt(8)
	s_waitcnt lgkmcnt(0)
	s_barrier
	s_setprio 1
	s_waitcnt lgkmcnt(0)
	v_mfma_f32_16x16x32_bf16 v[64:67], v[132:135], v[186:189], v[64:67]
	v_mfma_f32_16x16x32_bf16 v[64:67], v[136:139], v[190:193], v[64:67]
	v_mfma_f32_16x16x32_bf16 v[60:63], v[140:143], v[186:189], v[60:63]
	v_mfma_f32_16x16x32_bf16 v[60:63], v[144:147], v[190:193], v[60:63]
	v_mfma_f32_16x16x32_bf16 v[56:59], v[132:135], v[194:197], v[56:59]
	v_mfma_f32_16x16x32_bf16 v[56:59], v[136:139], v[204:207], v[56:59]
	v_mfma_f32_16x16x32_bf16 v[48:51], v[140:143], v[194:197], v[48:51]
	v_mfma_f32_16x16x32_bf16 v[48:51], v[144:147], v[204:207], v[48:51]
	v_mfma_f32_16x16x32_bf16 v[40:43], v[132:135], v[208:211], v[40:43]
	v_mfma_f32_16x16x32_bf16 v[40:43], v[136:139], v[212:215], v[40:43]
	v_mfma_f32_16x16x32_bf16 v[32:35], v[140:143], v[208:211], v[32:35]
	v_mfma_f32_16x16x32_bf16 v[32:35], v[144:147], v[212:215], v[32:35]
	v_mfma_f32_16x16x32_bf16 v[24:27], v[132:135], v[216:219], v[24:27]
	v_mfma_f32_16x16x32_bf16 v[24:27], v[136:139], v[220:223], v[24:27]
	v_mfma_f32_16x16x32_bf16 v[16:19], v[140:143], v[216:219], v[16:19]
	v_mfma_f32_16x16x32_bf16 v[16:19], v[144:147], v[220:223], v[16:19]
	v_mfma_f32_16x16x32_bf16 v[52:55], v[170:173], v[186:189], v[52:55]
	v_mfma_f32_16x16x32_bf16 v[52:55], v[174:177], v[190:193], v[52:55]
	v_mfma_f32_16x16x32_bf16 v[44:47], v[178:181], v[186:189], v[44:47]
	v_mfma_f32_16x16x32_bf16 v[44:47], v[182:185], v[190:193], v[44:47]
	v_mfma_f32_16x16x32_bf16 v[36:39], v[170:173], v[194:197], v[36:39]
	v_mfma_f32_16x16x32_bf16 v[36:39], v[174:177], v[204:207], v[36:39]
	v_mfma_f32_16x16x32_bf16 v[28:31], v[178:181], v[194:197], v[28:31]
	v_mfma_f32_16x16x32_bf16 v[28:31], v[182:185], v[204:207], v[28:31]
	v_mfma_f32_16x16x32_bf16 v[20:23], v[170:173], v[208:211], v[20:23]
	v_mfma_f32_16x16x32_bf16 v[20:23], v[174:177], v[212:215], v[20:23]
	v_mfma_f32_16x16x32_bf16 v[12:15], v[178:181], v[208:211], v[12:15]
	v_mfma_f32_16x16x32_bf16 v[12:15], v[182:185], v[212:215], v[12:15]
	v_mfma_f32_16x16x32_bf16 v[8:11], v[170:173], v[216:219], v[8:11]
	v_mfma_f32_16x16x32_bf16 v[8:11], v[174:177], v[220:223], v[8:11]
	s_setprio 2
	s_barrier
; #define PG8_STAGE(bufoff, gbase, voff) do { _Pragma("unroll") for (int _i = 0; _i < 2; ++_i) \
;         __builtin_amdgcn_global_load_lds((const unsigned*)((const char*)(gbase) + (voff)[_i]), (LAS unsigned*)(lds + (bufoff) + ldsw + _i * 8192), 16, 0, 0); } while (0)
; #define PG8_LDA(dst, b, h) do { _Pragma("unroll") for (int m = 0; m < 4; ++m) _Pragma("unroll") for (int k = 0; k < 2; ++k) dst[m][k] = *(const LAS bf16x8*)(lds + PG8_SA(b, h) + aoff + m * 2048 + k * 1024); } while (0)
; #define PG8_LDB(dst, b, h) do { _Pragma("unroll") for (int n = 0; n < 2; ++n) _Pragma("unroll") for (int k = 0; k < 2; ++k) dst[n][k] = *(const LAS bf16x8*)(lds + PG8_SB(b, h) + boff + n * 2048 + k * 1024); } while (0)
; #define PG8_MMA(ai, bj, At, Bt) do { __builtin_amdgcn_s_setprio(1); _Pragma("unroll") for (int m = 0; m < 4; ++m) _Pragma("unroll") for (int n = 0; n < 2; ++n) _Pragma("unroll") for (int k = 0; k < 2; ++k) \
;         acc[ai][bj][m][n] = __builtin_amdgcn_mfma_f32_16x16x32_bf16(Bt[n][k], At[m][k], acc[ai][bj][m][n], 0, 0, 0); __builtin_amdgcn_s_setprio(0); } while (0)
; #define PG8_WAIT_V(n) asm volatile("s_waitcnt vmcnt(" #n ")" ::: "memory")
; #define PG8_WAIT_L(n) asm volatile("s_waitcnt lgkmcnt(" #n ")" ::: "memory")
; #define PG8_BAR __builtin_amdgcn_s_barrier()
; #define PG8_SCHED __builtin_amdgcn_sched_barrier(0)
; template <class Epi, class Sched, bool ALIGN_EPI = true>
; __device__ __forceinline__ void gemm_phase(LAS unsigned char* lds, const Gemm g, const Sched& S, const Epi& E) {
;     ...
;             PG8_LDB(B0, 1, 0); PG8_LDB(B1, 1, 1); PG8_SCHED; PG8_LDA(At, 1, 0); PG8_STAGE(PG8_SA(0, 1), a2 + hA, voffA);
;             PG8_WAIT_V(8); PG8_WAIT_L(0); PG8_BAR; PG8_MMA(0, 0, At, B0); PG8_MMA(0, 1, At, B1); PG8_BAR; PG8_SCHED;
	v_mfma_f32_16x16x32_bf16 v[4:7], v[178:181], v[216:219], v[4:7]
	v_mfma_f32_16x16x32_bf16 v[4:7], v[182:185], v[220:223], v[4:7]
	s_setprio 0
	s_add_i32 s30, 0, 0x18000
	s_add_i32 s31, 0, 0x1c000
	v_add_u32_e32 v144, s30, v166
	v_add_u32_e32 v160, s31, v166
	ds_read_b128 v[132:135], v144
	ds_read_b128 v[136:139], v144 offset:1024
	ds_read_b128 v[140:143], v144 offset:2048
	ds_read_b128 v[144:147], v144 offset:3072
	ds_read_b128 v[170:173], v160
	ds_read_b128 v[174:177], v160 offset:1024
	ds_read_b128 v[178:181], v160 offset:2048
	ds_read_b128 v[182:185], v160 offset:3072
	s_add_u32 s26, s44, 0x80000
	s_addc_u32 s27, s45, 0
	s_mov_b32 m0, s62
	v_lshl_add_u64 v[228:229], s[26:27], 0, v[150:151]
	ds_read_b128 v[186:189], v168 offset:32768
	ds_read_b128 v[190:193], v168 offset:33792
	ds_read_b128 v[194:197], v168 offset:34816
	ds_read_b128 v[204:207], v168 offset:35840
	ds_read_b128 v[208:211], v168 offset:36864
	ds_read_b128 v[212:215], v168 offset:37888
	ds_read_b128 v[216:219], v168 offset:38912
	ds_read_b128 v[220:223], v168 offset:39936
	global_load_lds_dwordx4 v[228:229], off
	v_lshl_add_u64 v[228:229], s[26:27], 0, v[148:149]
	s_mov_b32 m0, s63
	s_nop 0
	global_load_lds_dwordx4 v[228:229], off
	s_waitcnt vmcnt(8)
	s_waitcnt lgkmcnt(0)
	s_barrier
	s_setprio 1
	s_waitcnt lgkmcnt(0)
	v_mfma_f32_16x16x32_bf16 v[128:131], v[132:135], v[186:189], v[128:131]
	v_mfma_f32_16x16x32_bf16 v[128:131], v[136:139], v[190:193], v[128:131]
	v_mfma_f32_16x16x32_bf16 v[124:127], v[140:143], v[186:189], v[124:127]
	v_mfma_f32_16x16x32_bf16 v[124:127], v[144:147], v[190:193], v[124:127]
	v_mfma_f32_16x16x32_bf16 v[116:119], v[132:135], v[194:197], v[116:119]
	v_mfma_f32_16x16x32_bf16 v[116:119], v[136:139], v[204:207], v[116:119]
	v_mfma_f32_16x16x32_bf16 v[112:115], v[140:143], v[194:197], v[112:115]
	v_mfma_f32_16x16x32_bf16 v[112:115], v[144:147], v[204:207], v[112:115]
	v_mfma_f32_16x16x32_bf16 v[104:107], v[132:135], v[208:211], v[104:107]
	v_mfma_f32_16x16x32_bf16 v[104:107], v[136:139], v[212:215], v[104:107]
	v_mfma_f32_16x16x32_bf16 v[96:99], v[140:143], v[208:211], v[96:99]
	v_mfma_f32_16x16x32_bf16 v[96:99], v[144:147], v[212:215], v[96:99]
	v_mfma_f32_16x16x32_bf16 v[88:91], v[132:135], v[216:219], v[88:91]
	v_mfma_f32_16x16x32_bf16 v[88:91], v[136:139], v[220:223], v[88:91]
	v_mfma_f32_16x16x32_bf16 v[80:83], v[140:143], v[216:219], v[80:83]
	v_mfma_f32_16x16x32_bf16 v[80:83], v[144:147], v[220:223], v[80:83]
	v_mfma_f32_16x16x32_bf16 v[120:123], v[170:173], v[186:189], v[120:123]
	v_mfma_f32_16x16x32_bf16 v[120:123], v[174:177], v[190:193], v[120:123]
	v_mfma_f32_16x16x32_bf16 v[108:111], v[178:181], v[186:189], v[108:111]
	v_mfma_f32_16x16x32_bf16 v[108:111], v[182:185], v[190:193], v[108:111]
	v_mfma_f32_16x16x32_bf16 v[100:103], v[170:173], v[194:197], v[100:103]
	v_mfma_f32_16x16x32_bf16 v[100:103], v[174:177], v[204:207], v[100:103]
	v_mfma_f32_16x16x32_bf16 v[92:95], v[178:181], v[194:197], v[92:95]
	v_mfma_f32_16x16x32_bf16 v[92:95], v[182:185], v[204:207], v[92:95]
	v_mfma_f32_16x16x32_bf16 v[84:87], v[170:173], v[208:211], v[84:87]
	v_mfma_f32_16x16x32_bf16 v[84:87], v[174:177], v[212:215], v[84:87]
	v_mfma_f32_16x16x32_bf16 v[76:79], v[178:181], v[208:211], v[76:79]
	v_mfma_f32_16x16x32_bf16 v[76:79], v[182:185], v[212:215], v[76:79]
	v_mfma_f32_16x16x32_bf16 v[72:75], v[170:173], v[216:219], v[72:75]
	v_mfma_f32_16x16x32_bf16 v[72:75], v[174:177], v[220:223], v[72:75]
	s_setprio 2
	s_barrier
; #define PG8_STAGE(bufoff, gbase, voff) do { _Pragma("unroll") for (int _i = 0; _i < 2; ++_i) \
;         __builtin_amdgcn_global_load_lds((const unsigned*)((const char*)(gbase) + (voff)[_i]), (LAS unsigned*)(lds + (bufoff) + ldsw + _i * 8192), 16, 0, 0); } while (0)
; #define PG8_LDA(dst, b, h) do { _Pragma("unroll") for (int m = 0; m < 4; ++m) _Pragma("unroll") for (int k = 0; k < 2; ++k) dst[m][k] = *(const LAS bf16x8*)(lds + PG8_SA(b, h) + aoff + m * 2048 + k * 1024); } while (0)
; #define PG8_MMA(ai, bj, At, Bt) do { __builtin_amdgcn_s_setprio(1); _Pragma("unroll") for (int m = 0; m < 4; ++m) _Pragma("unroll") for (int n = 0; n < 2; ++n) _Pragma("unroll") for (int k = 0; k < 2; ++k) \
;         acc[ai][bj][m][n] = __builtin_amdgcn_mfma_f32_16x16x32_bf16(Bt[n][k], At[m][k], acc[ai][bj][m][n], 0, 0, 0); __builtin_amdgcn_s_setprio(0); } while (0)
; #define PG8_WAIT_V(n) asm volatile("s_waitcnt vmcnt(" #n ")" ::: "memory")
; #define PG8_WAIT_L(n) asm volatile("s_waitcnt lgkmcnt(" #n ")" ::: "memory")
; #define PG8_BAR __builtin_amdgcn_s_barrier()
; #define PG8_SCHED __builtin_amdgcn_sched_barrier(0)
; template <class Epi, class Sched, bool ALIGN_EPI = true>
; __device__ __forceinline__ void gemm_phase(LAS unsigned char* lds, const Gemm g, const Sched& S, const Epi& E) {
;     ...
;             const bool last = (t == nt - 2);
;             const char* a1 = cA + (size_t)(t + 1) * kstep;
;             const char* a2 = last ? nA : cA + (size_t)(t + 2) * kstep; const char* b2 = last ? nB : cB + (size_t)(t + 2) * kstep;
;             const char* a3 = a2 + kstep; const char* b3 = b2 + kstep;
;     ...
;             PG8_LDA(At, 1, 1); PG8_STAGE(PG8_SB(1, 0), b3, voffB); PG8_STAGE(PG8_SB(1, 1), b3 + hB, voffB); PG8_STAGE(PG8_SA(1, 0), a3, voffA);
;             PG8_WAIT_V(8); PG8_WAIT_L(0); PG8_BAR; PG8_MMA(1, 0, At, B0); PG8_MMA(1, 1, At, B1); PG8_BAR; PG8_SCHED;
;         }
	v_mfma_f32_16x16x32_bf16 v[68:71], v[178:181], v[216:219], v[68:71]
	v_mfma_f32_16x16x32_bf16 v[68:71], v[182:185], v[220:223], v[68:71]
	s_setprio 0
	s_add_i32 s26, s30, s59
	v_lshl_add_u64 v[156:157], v[156:157], 0, s[86:87]
	s_mov_b32 m0, s26
	ds_read_b128 v[186:189], v168 offset:49152
	ds_read_b128 v[190:193], v168 offset:50176
	ds_read_b128 v[194:197], v168 offset:51200
	ds_read_b128 v[204:207], v168 offset:52224
	ds_read_b128 v[208:211], v168 offset:53248
	ds_read_b128 v[212:215], v168 offset:54272
	ds_read_b128 v[216:219], v168 offset:55296
	ds_read_b128 v[220:223], v168 offset:56320
	global_load_lds_dwordx4 v[156:157], off
	s_add_i32 m0, s26, 0x2000
	s_add_u32 s26, s42, 0x80080
	v_lshl_add_u64 v[156:157], v[164:165], 0, s[86:87]
	s_addc_u32 s27, s43, 0
	s_add_i32 s30, s31, s59
	global_load_lds_dwordx4 v[156:157], off
	v_lshl_add_u64 v[156:157], s[26:27], 0, v[2:3]
	s_mov_b32 m0, s30
	s_nop 0
	global_load_lds_dwordx4 v[156:157], off
	v_lshl_add_u64 v[156:157], s[26:27], 0, v[0:1]
	s_add_i32 m0, s30, 0x2000
	s_nop 0
	global_load_lds_dwordx4 v[156:157], off
	v_lshl_add_u64 v[156:157], v[224:225], 0, s[86:87]
	s_mov_b32 m0, s64
	s_nop 0
	global_load_lds_dwordx4 v[156:157], off
	v_lshl_add_u64 v[156:157], v[226:227], 0, s[86:87]
	s_mov_b32 m0, s65
	s_nop 0
	global_load_lds_dwordx4 v[156:157], off
	s_waitcnt vmcnt(8)
	s_waitcnt lgkmcnt(0)
	s_barrier
	s_setprio 1
	s_waitcnt lgkmcnt(0)
	v_mfma_f32_16x16x32_bf16 v[64:67], v[132:135], v[186:189], v[64:67]
	v_mfma_f32_16x16x32_bf16 v[64:67], v[136:139], v[190:193], v[64:67]
	s_add_i32 s25, s25, 2
	s_add_u32 s6, s6, 0x100
	v_mfma_f32_16x16x32_bf16 v[60:63], v[140:143], v[186:189], v[60:63]
	v_mfma_f32_16x16x32_bf16 v[60:63], v[144:147], v[190:193], v[60:63]
	s_addc_u32 s7, s7, 0
	s_add_u32 s19, s19, 0x100
	v_mfma_f32_16x16x32_bf16 v[56:59], v[132:135], v[194:197], v[56:59]
	v_mfma_f32_16x16x32_bf16 v[56:59], v[136:139], v[204:207], v[56:59]
	s_addc_u32 s24, s24, 0
	s_add_u32 s26, s6, 0xfff80080
	v_mfma_f32_16x16x32_bf16 v[48:51], v[140:143], v[194:197], v[48:51]
	v_mfma_f32_16x16x32_bf16 v[48:51], v[144:147], v[204:207], v[48:51]
	s_addc_u32 s27, s7, -1
	s_add_i32 s30, 0, 0x10000
	v_mfma_f32_16x16x32_bf16 v[40:43], v[132:135], v[208:211], v[40:43]
	v_mfma_f32_16x16x32_bf16 v[40:43], v[136:139], v[212:215], v[40:43]
	s_cmp_eq_u32 s25, 28
	s_cselect_b32 s45, s15, s27
	v_mfma_f32_16x16x32_bf16 v[32:35], v[140:143], v[208:211], v[32:35]
	v_mfma_f32_16x16x32_bf16 v[32:35], v[144:147], v[212:215], v[32:35]
	s_cselect_b32 s44, s17, s26
	s_cselect_b32 s43, s13, s24
	v_mfma_f32_16x16x32_bf16 v[24:27], v[132:135], v[216:219], v[24:27]
	v_mfma_f32_16x16x32_bf16 v[24:27], v[136:139], v[220:223], v[24:27]
	s_cselect_b32 s42, s18, s19
	s_add_i32 s31, 0, 0x14000
	v_mfma_f32_16x16x32_bf16 v[16:19], v[140:143], v[216:219], v[16:19]
	v_mfma_f32_16x16x32_bf16 v[16:19], v[144:147], v[220:223], v[16:19]
	v_mfma_f32_16x16x32_bf16 v[52:55], v[170:173], v[186:189], v[52:55]
	v_mfma_f32_16x16x32_bf16 v[52:55], v[174:177], v[190:193], v[52:55]
	v_mfma_f32_16x16x32_bf16 v[44:47], v[178:181], v[186:189], v[44:47]
	v_mfma_f32_16x16x32_bf16 v[44:47], v[182:185], v[190:193], v[44:47]
	v_mfma_f32_16x16x32_bf16 v[36:39], v[170:173], v[194:197], v[36:39]
	v_mfma_f32_16x16x32_bf16 v[36:39], v[174:177], v[204:207], v[36:39]
	v_mfma_f32_16x16x32_bf16 v[28:31], v[178:181], v[194:197], v[28:31]
	v_mfma_f32_16x16x32_bf16 v[28:31], v[182:185], v[204:207], v[28:31]
	v_mfma_f32_16x16x32_bf16 v[20:23], v[170:173], v[208:211], v[20:23]
	v_mfma_f32_16x16x32_bf16 v[20:23], v[174:177], v[212:215], v[20:23]
	v_mfma_f32_16x16x32_bf16 v[12:15], v[178:181], v[208:211], v[12:15]
	v_mfma_f32_16x16x32_bf16 v[12:15], v[182:185], v[212:215], v[12:15]
	v_mfma_f32_16x16x32_bf16 v[8:11], v[170:173], v[216:219], v[8:11]
	v_mfma_f32_16x16x32_bf16 v[8:11], v[174:177], v[220:223], v[8:11]
	s_setprio 2
	s_barrier
	v_mfma_f32_16x16x32_bf16 v[4:7], v[178:181], v[216:219], v[4:7]
	v_mfma_f32_16x16x32_bf16 v[4:7], v[182:185], v[220:223], v[4:7]
	s_setprio 0
	s_cmp_gt_u32 s25, 29
	s_cbranch_scc0 .LBB0_77

;     __device__ bool next(int i, Unit& u) const { if (i >= 2) return false; const int x = c & 7, j = c >> 3; u.pm = 32 * i + 4 * x + (j & 3); u.pn = j >> 2; return true; }
; #define PG8_STAGE(bufoff, gbase, voff) do { _Pragma("unroll") for (int _i = 0; _i < 2; ++_i) \
;         __builtin_amdgcn_global_load_lds((const unsigned*)((const char*)(gbase) + (voff)[_i]), (LAS unsigned*)(lds + (bufoff) + ldsw + _i * 8192), 16, 0, 0); } while (0)
; #define PG8_WAIT_V(n) asm volatile("s_waitcnt vmcnt(" #n ")" ::: "memory")
; #define PG8_BAR __builtin_amdgcn_s_barrier()
; template <class Epi, class Sched, bool ALIGN_EPI = true>
; __device__ __forceinline__ void gemm_phase(LAS unsigned char* lds, const Gemm g, const Sched& S, const Epi& E) {
;     ...
;         const bool has_next = S.next(ui + 1, nxt);
;         const char* nA = has_next ? (const char*)g.A + ((size_t)nxt.pm * BM * g.lda + (size_t)nxt.pn * g.a_pn_off) * 2 : cA; const char* nB = has_next ? (const char*)g.Bt + (size_t)nxt.pn * BM * g.ldb * 2 : cB;
;         for (int t = 0; t < nt; t += 2) {
;             const bool last = (t == nt - 2);
;             const char* a1 = cA + (size_t)(t + 1) * kstep;
;             const char* a2 = last ? nA : cA + (size_t)(t + 2) * kstep; const char* b2 = last ? nB : cB + (size_t)(t + 2) * kstep;
;             const char* a3 = a2 + kstep; const char* b3 = b2 + kstep;
;             PG8_LDB(B0, 0, 0); PG8_LDB(B1, 0, 1); PG8_SCHED; PG8_LDA(At, 0, 0); PG8_STAGE(PG8_SA(1, 1), a1 + hA, voffA);
;             PG8_WAIT_V(8); PG8_WAIT_L(0); PG8_BAR; PG8_MMA(0, 0, At, B0); PG8_MMA(0, 1, At, B1); PG8_BAR; PG8_SCHED;
;             PG8_LDA(At, 0, 1); PG8_STAGE(PG8_SB(0, 0), b2, voffB); PG8_STAGE(PG8_SB(0, 1), b2 + hB, voffB); PG8_STAGE(PG8_SA(0, 0), a2, voffA);
;             PG8_WAIT_V(8); PG8_WAIT_L(0); PG8_BAR; PG8_MMA(1, 0, At, B0); PG8_MMA(1, 1, At, B1); PG8_BAR; PG8_SCHED;
;             PG8_LDB(B0, 1, 0); PG8_LDB(B1, 1, 1); PG8_SCHED; PG8_LDA(At, 1, 0); PG8_STAGE(PG8_SA(0, 1), a2 + hA, voffA);
;             PG8_WAIT_V(8); PG8_WAIT_L(0); PG8_BAR; PG8_MMA(0, 0, At, B0); PG8_MMA(0, 1, At, B1); PG8_BAR; PG8_SCHED;
;             PG8_LDA(At, 1, 1); PG8_STAGE(PG8_SB(1, 0), b3, voffB); PG8_STAGE(PG8_SB(1, 1), b3 + hB, voffB); PG8_STAGE(PG8_SA(1, 0), a3, voffA);
;             PG8_WAIT_V(8); PG8_WAIT_L(0); PG8_BAR; PG8_MMA(1, 0, At, B0); PG8_MMA(1, 1, At, B1); PG8_BAR; PG8_SCHED;
.LBB0_217:
	s_ashr_i32 s11, s10, 31
	s_lshl_b64 s[12:13], s[10:11], 20
	s_add_u32 s12, s46, s12
	s_addc_u32 s13, s47, s13
	s_and_b64 s[14:15], s[4:5], exec
	s_cselect_b32 s11, s13, s39
	s_cselect_b32 s18, s12, s38
	s_ashr_i32 s9, s8, 31
	s_lshl_b64 s[14:15], s[8:9], 20
	s_add_u32 s14, s44, s14
	s_addc_u32 s15, s45, s15
	s_and_b64 s[24:25], s[4:5], exec
	s_cselect_b32 s9, s15, s41
	s_cselect_b32 s19, s14, s40
	s_add_u32 s38, s38, 0x80080
	s_addc_u32 s39, s39, 0
	s_add_u32 s24, s40, 0x100
	s_addc_u32 s25, s41, 0
	s_mov_b32 s26, -2
	s_add_u32 s27, s38, 0xfff80080
	s_addc_u32 s30, s39, -1
	s_add_i32 s31, 0, 0x10000
	s_cmp_eq_u32 s26, 28
	s_cselect_b32 s43, s11, s30
	s_cselect_b32 s42, s18, s27
	v_add_u32_e32 v156, s31, v145
	s_cselect_b32 s41, s9, s25
	s_cselect_b32 s40, s19, s24
	s_add_i32 s27, 0, 0x14000
	ds_read_b128 v[140:143], v156
	ds_read_b128 v[148:151], v156 offset:1024
	ds_read_b128 v[152:155], v156 offset:2048
	ds_read_b128 v[164:167], v156 offset:3072
	v_add_u32_e32 v156, s27, v145
	ds_read_b128 v[168:171], v156
	ds_read_b128 v[172:175], v156 offset:1024
	ds_read_b128 v[176:179], v156 offset:2048
	ds_read_b128 v[180:183], v156 offset:3072
	v_lshl_add_u64 v[156:157], s[38:39], 0, v[136:137]
	s_add_i32 m0, s58, 0xc000
	ds_read_b128 v[184:187], v147
	ds_read_b128 v[188:191], v147 offset:1024
	ds_read_b128 v[192:195], v147 offset:2048
	ds_read_b128 v[204:207], v147 offset:3072
	ds_read_b128 v[208:211], v147 offset:4096
	ds_read_b128 v[212:215], v147 offset:5120
	ds_read_b128 v[216:219], v147 offset:6144
	ds_read_b128 v[220:223], v147 offset:7168
	global_load_lds_dwordx4 v[156:157], off
	v_lshl_add_u64 v[156:157], s[38:39], 0, v[138:139]
	s_add_i32 m0, s58, 0xe000
	s_nop 0
	global_load_lds_dwordx4 v[156:157], off
	s_waitcnt vmcnt(8)
	s_waitcnt lgkmcnt(0)
	s_barrier
	s_setprio 1
	s_waitcnt lgkmcnt(0)
	v_mfma_f32_16x16x32_bf16 v[128:131], v[140:143], v[184:187], 0
	v_mfma_f32_16x16x32_bf16 v[128:131], v[148:151], v[188:191], v[128:131]
	v_mfma_f32_16x16x32_bf16 v[124:127], v[152:155], v[184:187], 0
	v_mfma_f32_16x16x32_bf16 v[124:127], v[164:167], v[188:191], v[124:127]
	v_mfma_f32_16x16x32_bf16 v[120:123], v[140:143], v[192:195], 0
	v_mfma_f32_16x16x32_bf16 v[120:123], v[148:151], v[204:207], v[120:123]
	v_mfma_f32_16x16x32_bf16 v[112:115], v[152:155], v[192:195], 0
	v_mfma_f32_16x16x32_bf16 v[112:115], v[164:167], v[204:207], v[112:115]
	v_mfma_f32_16x16x32_bf16 v[104:107], v[140:143], v[208:211], 0
	v_mfma_f32_16x16x32_bf16 v[104:107], v[148:151], v[212:215], v[104:107]
	v_mfma_f32_16x16x32_bf16 v[96:99], v[152:155], v[208:211], 0
	v_mfma_f32_16x16x32_bf16 v[96:99], v[164:167], v[212:215], v[96:99]
	v_mfma_f32_16x16x32_bf16 v[88:91], v[140:143], v[216:219], 0
	v_mfma_f32_16x16x32_bf16 v[88:91], v[148:151], v[220:223], v[88:91]
	v_mfma_f32_16x16x32_bf16 v[80:83], v[152:155], v[216:219], 0
	v_mfma_f32_16x16x32_bf16 v[80:83], v[164:167], v[220:223], v[80:83]
	v_mfma_f32_16x16x32_bf16 v[116:119], v[168:171], v[184:187], 0
	v_mfma_f32_16x16x32_bf16 v[116:119], v[172:175], v[188:191], v[116:119]
	v_mfma_f32_16x16x32_bf16 v[108:111], v[176:179], v[184:187], 0
	v_mfma_f32_16x16x32_bf16 v[108:111], v[180:183], v[188:191], v[108:111]
	v_mfma_f32_16x16x32_bf16 v[100:103], v[168:171], v[192:195], 0
	v_mfma_f32_16x16x32_bf16 v[100:103], v[172:175], v[204:207], v[100:103]
	v_mfma_f32_16x16x32_bf16 v[92:95], v[176:179], v[192:195], 0
	v_mfma_f32_16x16x32_bf16 v[92:95], v[180:183], v[204:207], v[92:95]
	v_mfma_f32_16x16x32_bf16 v[84:87], v[168:171], v[208:211], 0
	v_mfma_f32_16x16x32_bf16 v[84:87], v[172:175], v[212:215], v[84:87]
	v_mfma_f32_16x16x32_bf16 v[76:79], v[176:179], v[208:211], 0
	v_mfma_f32_16x16x32_bf16 v[76:79], v[180:183], v[212:215], v[76:79]
	v_mfma_f32_16x16x32_bf16 v[72:75], v[168:171], v[216:219], 0
	v_mfma_f32_16x16x32_bf16 v[72:75], v[172:175], v[220:223], v[72:75]
	s_setprio 2
	s_barrier
	v_mfma_f32_16x16x32_bf16 v[68:71], v[176:179], v[216:219], 0
	v_mfma_f32_16x16x32_bf16 v[68:71], v[180:183], v[220:223], v[68:71]
	s_setprio 0
	s_add_i32 s30, s31, s53
	v_lshl_add_u64 v[156:157], s[40:41], 0, v[2:3]
	s_mov_b32 m0, s30
	ds_read_b128 v[184:187], v147 offset:16384
	ds_read_b128 v[188:191], v147 offset:17408
	ds_read_b128 v[192:195], v147 offset:18432
	ds_read_b128 v[204:207], v147 offset:19456
	ds_read_b128 v[208:211], v147 offset:20480
	ds_read_b128 v[212:215], v147 offset:21504
	ds_read_b128 v[216:219], v147 offset:22528
	ds_read_b128 v[220:223], v147 offset:23552
	global_load_lds_dwordx4 v[156:157], off
	s_add_i32 m0, s30, 0x2000
	s_add_u32 s30, s40, 0x80000
	v_lshl_add_u64 v[196:197], s[40:41], 0, v[0:1]
	s_addc_u32 s31, s41, 0
	s_add_i32 s27, s27, s53
	global_load_lds_dwordx4 v[196:197], off
	v_lshl_add_u64 v[224:225], s[30:31], 0, v[2:3]
	s_mov_b32 m0, s27
	v_lshl_add_u64 v[226:227], s[42:43], 0, v[132:133]
	global_load_lds_dwordx4 v[224:225], off
	v_lshl_add_u64 v[224:225], s[30:31], 0, v[0:1]
	s_add_i32 m0, s27, 0x2000
	s_nop 0
	global_load_lds_dwordx4 v[224:225], off
	v_lshl_add_u64 v[224:225], s[42:43], 0, v[134:135]
	s_mov_b32 m0, s58
	s_nop 0
	global_load_lds_dwordx4 v[224:225], off
	s_mov_b32 m0, s59
	s_nop 0
	global_load_lds_dwordx4 v[226:227], off
	s_waitcnt vmcnt(8)
	s_waitcnt lgkmcnt(0)
	s_barrier
; #define PG8_STAGE(bufoff, gbase, voff) do { _Pragma("unroll") for (int _i = 0; _i < 2; ++_i) \
;         __builtin_amdgcn_global_load_lds((const unsigned*)((const char*)(gbase) + (voff)[_i]), (LAS unsigned*)(lds + (bufoff) + ldsw + _i * 8192), 16, 0, 0); } while (0)
; #define PG8_LDA(dst, b, h) do { _Pragma("unroll") for (int m = 0; m < 4; ++m) _Pragma("unroll") for (int k = 0; k < 2; ++k) dst[m][k] = *(const LAS bf16x8*)(lds + PG8_SA(b, h) + aoff + m * 2048 + k * 1024); } while (0)
; #define PG8_LDB(dst, b, h) do { _Pragma("unroll") for (int n = 0; n < 2; ++n) _Pragma("unroll") for (int k = 0; k < 2; ++k) dst[n][k] = *(const LAS bf16x8*)(lds + PG8_SB(b, h) + boff + n * 2048 + k * 1024); } while (0)
; #define PG8_MMA(ai, bj, At, Bt) do { __builtin_amdgcn_s_setprio(1); _Pragma("unroll") for (int m = 0; m < 4; ++m) _Pragma("unroll") for (int n = 0; n < 2; ++n) _Pragma("unroll") for (int k = 0; k < 2; ++k) \
;         acc[ai][bj][m][n] = __builtin_amdgcn_mfma_f32_16x16x32_bf16(Bt[n][k], At[m][k], acc[ai][bj][m][n], 0, 0, 0); __builtin_amdgcn_s_setprio(0); } while (0)
; #define PG8_WAIT_V(n) asm volatile("s_waitcnt vmcnt(" #n ")" ::: "memory")
; #define PG8_WAIT_L(n) asm volatile("s_waitcnt lgkmcnt(" #n ")" ::: "memory")
; #define PG8_BAR __builtin_amdgcn_s_barrier()
; #define PG8_SCHED __builtin_amdgcn_sched_barrier(0)
; template <class Epi, class Sched, bool ALIGN_EPI = true>
; __device__ __forceinline__ void gemm_phase(LAS unsigned char* lds, const Gemm g, const Sched& S, const Epi& E) {
;     ...
;             PG8_LDA(At, 0, 1); PG8_STAGE(PG8_SB(0, 0), b2, voffB); PG8_STAGE(PG8_SB(0, 1), b2 + hB, voffB); PG8_STAGE(PG8_SA(0, 0), a2, voffA);
;             PG8_WAIT_V(8); PG8_WAIT_L(0); PG8_BAR; PG8_MMA(1, 0, At, B0); PG8_MMA(1, 1, At, B1); PG8_BAR; PG8_SCHED;
;             PG8_LDB(B0, 1, 0); PG8_LDB(B1, 1, 1); PG8_SCHED; PG8_LDA(At, 1, 0); PG8_STAGE(PG8_SA(0, 1), a2 + hA, voffA);
;             PG8_WAIT_V(8); PG8_WAIT_L(0); PG8_BAR; PG8_MMA(0, 0, At, B0); PG8_MMA(0, 1, At, B1); PG8_BAR; PG8_SCHED;
	s_setprio 1
	s_waitcnt lgkmcnt(0)
	v_mfma_f32_16x16x32_bf16 v[64:67], v[140:143], v[184:187], 0
	v_mfma_f32_16x16x32_bf16 v[64:67], v[148:151], v[188:191], v[64:67]
	v_mfma_f32_16x16x32_bf16 v[60:63], v[152:155], v[184:187], 0
	v_mfma_f32_16x16x32_bf16 v[60:63], v[164:167], v[188:191], v[60:63]
	v_mfma_f32_16x16x32_bf16 v[56:59], v[140:143], v[192:195], 0
	v_mfma_f32_16x16x32_bf16 v[56:59], v[148:151], v[204:207], v[56:59]
	v_mfma_f32_16x16x32_bf16 v[48:51], v[152:155], v[192:195], 0
	v_mfma_f32_16x16x32_bf16 v[48:51], v[164:167], v[204:207], v[48:51]
	v_mfma_f32_16x16x32_bf16 v[40:43], v[140:143], v[208:211], 0
	v_mfma_f32_16x16x32_bf16 v[40:43], v[148:151], v[212:215], v[40:43]
	v_mfma_f32_16x16x32_bf16 v[32:35], v[152:155], v[208:211], 0
	v_mfma_f32_16x16x32_bf16 v[32:35], v[164:167], v[212:215], v[32:35]
	v_mfma_f32_16x16x32_bf16 v[24:27], v[140:143], v[216:219], 0
	v_mfma_f32_16x16x32_bf16 v[24:27], v[148:151], v[220:223], v[24:27]
	v_mfma_f32_16x16x32_bf16 v[16:19], v[152:155], v[216:219], 0
	v_mfma_f32_16x16x32_bf16 v[16:19], v[164:167], v[220:223], v[16:19]
	v_mfma_f32_16x16x32_bf16 v[52:55], v[168:171], v[184:187], 0
	v_mfma_f32_16x16x32_bf16 v[52:55], v[172:175], v[188:191], v[52:55]
	v_mfma_f32_16x16x32_bf16 v[44:47], v[176:179], v[184:187], 0
	v_mfma_f32_16x16x32_bf16 v[44:47], v[180:183], v[188:191], v[44:47]
	v_mfma_f32_16x16x32_bf16 v[36:39], v[168:171], v[192:195], 0
	v_mfma_f32_16x16x32_bf16 v[36:39], v[172:175], v[204:207], v[36:39]
	v_mfma_f32_16x16x32_bf16 v[28:31], v[176:179], v[192:195], 0
	v_mfma_f32_16x16x32_bf16 v[28:31], v[180:183], v[204:207], v[28:31]
	v_mfma_f32_16x16x32_bf16 v[20:23], v[168:171], v[208:211], 0
	v_mfma_f32_16x16x32_bf16 v[20:23], v[172:175], v[212:215], v[20:23]
	v_mfma_f32_16x16x32_bf16 v[12:15], v[176:179], v[208:211], 0
	v_mfma_f32_16x16x32_bf16 v[12:15], v[180:183], v[212:215], v[12:15]
	v_mfma_f32_16x16x32_bf16 v[8:11], v[168:171], v[216:219], 0
	v_mfma_f32_16x16x32_bf16 v[8:11], v[172:175], v[220:223], v[8:11]
	s_setprio 2
	s_barrier
	v_mfma_f32_16x16x32_bf16 v[4:7], v[176:179], v[216:219], 0
	v_mfma_f32_16x16x32_bf16 v[4:7], v[180:183], v[220:223], v[4:7]
	s_setprio 0
	s_add_i32 s27, 0, 0x18000
	v_add_u32_e32 v158, s27, v145
	s_add_i32 s65, 0, 0x1c000
	ds_read_b128 v[140:143], v158
	ds_read_b128 v[148:151], v158 offset:1024
	ds_read_b128 v[152:155], v158 offset:2048
	ds_read_b128 v[164:167], v158 offset:3072
	v_add_u32_e32 v158, s65, v145
	ds_read_b128 v[168:171], v158
	ds_read_b128 v[172:175], v158 offset:1024
	ds_read_b128 v[176:179], v158 offset:2048
	ds_read_b128 v[180:183], v158 offset:3072
	s_add_u32 s30, s42, 0x80000
	s_addc_u32 s31, s43, 0
	s_mov_b32 m0, s60
	v_lshl_add_u64 v[228:229], s[30:31], 0, v[134:135]
	ds_read_b128 v[184:187], v147 offset:32768
	ds_read_b128 v[188:191], v147 offset:33792
	ds_read_b128 v[192:195], v147 offset:34816
	ds_read_b128 v[204:207], v147 offset:35840
	ds_read_b128 v[208:211], v147 offset:36864
	ds_read_b128 v[212:215], v147 offset:37888
	ds_read_b128 v[216:219], v147 offset:38912
	ds_read_b128 v[220:223], v147 offset:39936
	global_load_lds_dwordx4 v[228:229], off
	v_lshl_add_u64 v[228:229], s[30:31], 0, v[132:133]
	s_mov_b32 m0, s61
	s_nop 0
	global_load_lds_dwordx4 v[228:229], off
	s_waitcnt vmcnt(8)
	s_waitcnt lgkmcnt(0)
	s_barrier
	s_setprio 1
	s_waitcnt lgkmcnt(0)
	v_mfma_f32_16x16x32_bf16 v[128:131], v[140:143], v[184:187], v[128:131]
	v_mfma_f32_16x16x32_bf16 v[128:131], v[148:151], v[188:191], v[128:131]
	v_mfma_f32_16x16x32_bf16 v[124:127], v[152:155], v[184:187], v[124:127]
	v_mfma_f32_16x16x32_bf16 v[124:127], v[164:167], v[188:191], v[124:127]
	v_mfma_f32_16x16x32_bf16 v[120:123], v[140:143], v[192:195], v[120:123]
	v_mfma_f32_16x16x32_bf16 v[120:123], v[148:151], v[204:207], v[120:123]
	v_mfma_f32_16x16x32_bf16 v[112:115], v[152:155], v[192:195], v[112:115]
	v_mfma_f32_16x16x32_bf16 v[112:115], v[164:167], v[204:207], v[112:115]
	v_mfma_f32_16x16x32_bf16 v[104:107], v[140:143], v[208:211], v[104:107]
	v_mfma_f32_16x16x32_bf16 v[104:107], v[148:151], v[212:215], v[104:107]
	v_mfma_f32_16x16x32_bf16 v[96:99], v[152:155], v[208:211], v[96:99]
	v_mfma_f32_16x16x32_bf16 v[96:99], v[164:167], v[212:215], v[96:99]
	v_mfma_f32_16x16x32_bf16 v[88:91], v[140:143], v[216:219], v[88:91]
	v_mfma_f32_16x16x32_bf16 v[88:91], v[148:151], v[220:223], v[88:91]
	v_mfma_f32_16x16x32_bf16 v[80:83], v[152:155], v[216:219], v[80:83]
	v_mfma_f32_16x16x32_bf16 v[80:83], v[164:167], v[220:223], v[80:83]
	v_mfma_f32_16x16x32_bf16 v[116:119], v[168:171], v[184:187], v[116:119]
	v_mfma_f32_16x16x32_bf16 v[116:119], v[172:175], v[188:191], v[116:119]
	v_mfma_f32_16x16x32_bf16 v[108:111], v[176:179], v[184:187], v[108:111]
	v_mfma_f32_16x16x32_bf16 v[108:111], v[180:183], v[188:191], v[108:111]
	v_mfma_f32_16x16x32_bf16 v[100:103], v[168:171], v[192:195], v[100:103]
	v_mfma_f32_16x16x32_bf16 v[100:103], v[172:175], v[204:207], v[100:103]
	v_mfma_f32_16x16x32_bf16 v[92:95], v[176:179], v[192:195], v[92:95]
	v_mfma_f32_16x16x32_bf16 v[92:95], v[180:183], v[204:207], v[92:95]
	v_mfma_f32_16x16x32_bf16 v[84:87], v[168:171], v[208:211], v[84:87]
	v_mfma_f32_16x16x32_bf16 v[84:87], v[172:175], v[212:215], v[84:87]
	v_mfma_f32_16x16x32_bf16 v[76:79], v[176:179], v[208:211], v[76:79]
	v_mfma_f32_16x16x32_bf16 v[76:79], v[180:183], v[212:215], v[76:79]
	v_mfma_f32_16x16x32_bf16 v[72:75], v[168:171], v[216:219], v[72:75]
	v_mfma_f32_16x16x32_bf16 v[72:75], v[172:175], v[220:223], v[72:75]
	s_setprio 2
	s_barrier
; #define PG8_STAGE(bufoff, gbase, voff) do { _Pragma("unroll") for (int _i = 0; _i < 2; ++_i) \
;         __builtin_amdgcn_global_load_lds((const unsigned*)((const char*)(gbase) + (voff)[_i]), (LAS unsigned*)(lds + (bufoff) + ldsw + _i * 8192), 16, 0, 0); } while (0)
; #define PG8_LDA(dst, b, h) do { _Pragma("unroll") for (int m = 0; m < 4; ++m) _Pragma("unroll") for (int k = 0; k < 2; ++k) dst[m][k] = *(const LAS bf16x8*)(lds + PG8_SA(b, h) + aoff + m * 2048 + k * 1024); } while (0)
; #define PG8_MMA(ai, bj, At, Bt) do { __builtin_amdgcn_s_setprio(1); _Pragma("unroll") for (int m = 0; m < 4; ++m) _Pragma("unroll") for (int n = 0; n < 2; ++n) _Pragma("unroll") for (int k = 0; k < 2; ++k) \
;         acc[ai][bj][m][n] = __builtin_amdgcn_mfma_f32_16x16x32_bf16(Bt[n][k], At[m][k], acc[ai][bj][m][n], 0, 0, 0); __builtin_amdgcn_s_setprio(0); } while (0)
; #define PG8_WAIT_V(n) asm volatile("s_waitcnt vmcnt(" #n ")" ::: "memory")
; #define PG8_WAIT_L(n) asm volatile("s_waitcnt lgkmcnt(" #n ")" ::: "memory")
; #define PG8_BAR __builtin_amdgcn_s_barrier()
; #define PG8_SCHED __builtin_amdgcn_sched_barrier(0)
; template <class Epi, class Sched, bool ALIGN_EPI = true>
; __device__ __forceinline__ void gemm_phase(LAS unsigned char* lds, const Gemm g, const Sched& S, const Epi& E) {
;     ...
;             const bool last = (t == nt - 2);
;             const char* a1 = cA + (size_t)(t + 1) * kstep;
;             const char* a2 = last ? nA : cA + (size_t)(t + 2) * kstep; const char* b2 = last ? nB : cB + (size_t)(t + 2) * kstep;
;             const char* a3 = a2 + kstep; const char* b3 = b2 + kstep;
;     ...
;             PG8_LDA(At, 1, 1); PG8_STAGE(PG8_SB(1, 0), b3, voffB); PG8_STAGE(PG8_SB(1, 1), b3 + hB, voffB); PG8_STAGE(PG8_SA(1, 0), a3, voffA);
;             PG8_WAIT_V(8); PG8_WAIT_L(0); PG8_BAR; PG8_MMA(1, 0, At, B0); PG8_MMA(1, 1, At, B1); PG8_BAR; PG8_SCHED;
	v_mfma_f32_16x16x32_bf16 v[68:71], v[176:179], v[216:219], v[68:71]
	v_mfma_f32_16x16x32_bf16 v[68:71], v[180:183], v[220:223], v[68:71]
	s_setprio 0
	s_add_i32 s27, s27, s53
	v_lshl_add_u64 v[156:157], v[156:157], 0, s[86:87]
	s_mov_b32 m0, s27
	ds_read_b128 v[184:187], v147 offset:49152
	ds_read_b128 v[188:191], v147 offset:50176
	ds_read_b128 v[192:195], v147 offset:51200
	ds_read_b128 v[204:207], v147 offset:52224
	ds_read_b128 v[208:211], v147 offset:53248
	ds_read_b128 v[212:215], v147 offset:54272
	ds_read_b128 v[216:219], v147 offset:55296
	ds_read_b128 v[220:223], v147 offset:56320
	global_load_lds_dwordx4 v[156:157], off
	s_add_i32 m0, s27, 0x2000
	s_add_u32 s30, s40, 0x80080
	v_lshl_add_u64 v[156:157], v[196:197], 0, s[86:87]
	s_addc_u32 s31, s41, 0
	s_add_i32 s27, s65, s53
	global_load_lds_dwordx4 v[156:157], off
	v_lshl_add_u64 v[156:157], s[30:31], 0, v[2:3]
	s_mov_b32 m0, s27
	s_nop 0
	global_load_lds_dwordx4 v[156:157], off
	v_lshl_add_u64 v[156:157], s[30:31], 0, v[0:1]
	s_add_i32 m0, s27, 0x2000
	s_nop 0
	global_load_lds_dwordx4 v[156:157], off
	v_lshl_add_u64 v[156:157], v[224:225], 0, s[86:87]
	s_mov_b32 m0, s62
	s_nop 0
	global_load_lds_dwordx4 v[156:157], off
	v_lshl_add_u64 v[156:157], v[226:227], 0, s[86:87]
	s_mov_b32 m0, s63
	s_nop 0
	global_load_lds_dwordx4 v[156:157], off
	s_waitcnt vmcnt(8)
	s_waitcnt lgkmcnt(0)
	s_barrier
	s_setprio 1
	s_waitcnt lgkmcnt(0)
	v_mfma_f32_16x16x32_bf16 v[64:67], v[140:143], v[184:187], v[64:67]
	v_mfma_f32_16x16x32_bf16 v[64:67], v[148:151], v[188:191], v[64:67]
	s_add_i32 s26, s26, 2
	s_add_u32 s38, s38, 0x100
	v_mfma_f32_16x16x32_bf16 v[60:63], v[152:155], v[184:187], v[60:63]
	v_mfma_f32_16x16x32_bf16 v[60:63], v[164:167], v[188:191], v[60:63]
	s_addc_u32 s39, s39, 0
	s_add_u32 s24, s24, 0x100
	v_mfma_f32_16x16x32_bf16 v[56:59], v[140:143], v[192:195], v[56:59]
	v_mfma_f32_16x16x32_bf16 v[56:59], v[148:151], v[204:207], v[56:59]
	s_addc_u32 s25, s25, 0
	s_add_u32 s27, s38, 0xfff80080
	v_mfma_f32_16x16x32_bf16 v[48:51], v[152:155], v[192:195], v[48:51]
	v_mfma_f32_16x16x32_bf16 v[48:51], v[164:167], v[204:207], v[48:51]
	s_addc_u32 s30, s39, -1
	s_add_i32 s31, 0, 0x10000
	v_mfma_f32_16x16x32_bf16 v[40:43], v[140:143], v[208:211], v[40:43]
	v_mfma_f32_16x16x32_bf16 v[40:43], v[148:151], v[212:215], v[40:43]
	s_cmp_eq_u32 s26, 28
	s_cselect_b32 s43, s11, s30
	v_mfma_f32_16x16x32_bf16 v[32:35], v[152:155], v[208:211], v[32:35]
	v_mfma_f32_16x16x32_bf16 v[32:35], v[164:167], v[212:215], v[32:35]
	s_cselect_b32 s42, s18, s27
	s_cselect_b32 s41, s9, s25
	v_mfma_f32_16x16x32_bf16 v[24:27], v[140:143], v[216:219], v[24:27]
	v_mfma_f32_16x16x32_bf16 v[24:27], v[148:151], v[220:223], v[24:27]
	s_cselect_b32 s40, s19, s24
	s_add_i32 s27, 0, 0x14000
	v_mfma_f32_16x16x32_bf16 v[16:19], v[152:155], v[216:219], v[16:19]
	v_mfma_f32_16x16x32_bf16 v[16:19], v[164:167], v[220:223], v[16:19]
	v_mfma_f32_16x16x32_bf16 v[52:55], v[168:171], v[184:187], v[52:55]
	v_mfma_f32_16x16x32_bf16 v[52:55], v[172:175], v[188:191], v[52:55]
	v_mfma_f32_16x16x32_bf16 v[44:47], v[176:179], v[184:187], v[44:47]
	v_mfma_f32_16x16x32_bf16 v[44:47], v[180:183], v[188:191], v[44:47]
	v_mfma_f32_16x16x32_bf16 v[36:39], v[168:171], v[192:195], v[36:39]
	v_mfma_f32_16x16x32_bf16 v[36:39], v[172:175], v[204:207], v[36:39]
	v_mfma_f32_16x16x32_bf16 v[28:31], v[176:179], v[192:195], v[28:31]
	v_mfma_f32_16x16x32_bf16 v[28:31], v[180:183], v[204:207], v[28:31]
	v_mfma_f32_16x16x32_bf16 v[20:23], v[168:171], v[208:211], v[20:23]
	v_mfma_f32_16x16x32_bf16 v[20:23], v[172:175], v[212:215], v[20:23]
	v_mfma_f32_16x16x32_bf16 v[12:15], v[176:179], v[208:211], v[12:15]
	v_mfma_f32_16x16x32_bf16 v[12:15], v[180:183], v[212:215], v[12:15]
	v_mfma_f32_16x16x32_bf16 v[8:11], v[168:171], v[216:219], v[8:11]
	v_mfma_f32_16x16x32_bf16 v[8:11], v[172:175], v[220:223], v[8:11]
	s_setprio 2
	s_barrier
	v_mfma_f32_16x16x32_bf16 v[4:7], v[176:179], v[216:219], v[4:7]
	v_mfma_f32_16x16x32_bf16 v[4:7], v[180:183], v[220:223], v[4:7]
	s_setprio 0
	s_cmp_gt_u32 s26, 29
	s_cbranch_scc1 .Lpeel_exit_218
.LBB0_218:
	v_add_u32_e32 v156, s31, v145
	ds_read_b128 v[140:143], v156
	ds_read_b128 v[148:151], v156 offset:1024
	ds_read_b128 v[152:155], v156 offset:2048
	ds_read_b128 v[164:167], v156 offset:3072
	v_add_u32_e32 v156, s27, v145
	ds_read_b128 v[168:171], v156
	ds_read_b128 v[172:175], v156 offset:1024
	ds_read_b128 v[176:179], v156 offset:2048
	ds_read_b128 v[180:183], v156 offset:3072
	v_lshl_add_u64 v[156:157], s[38:39], 0, v[136:137]
	s_add_i32 m0, s58, 0xc000
	ds_read_b128 v[184:187], v147
	ds_read_b128 v[188:191], v147 offset:1024
	ds_read_b128 v[192:195], v147 offset:2048
	ds_read_b128 v[204:207], v147 offset:3072
	ds_read_b128 v[208:211], v147 offset:4096
	ds_read_b128 v[212:215], v147 offset:5120
	ds_read_b128 v[216:219], v147 offset:6144
	ds_read_b128 v[220:223], v147 offset:7168
	global_load_lds_dwordx4 v[156:157], off
	v_lshl_add_u64 v[156:157], s[38:39], 0, v[138:139]
	s_add_i32 m0, s58, 0xe000
	s_nop 0
	global_load_lds_dwordx4 v[156:157], off
	s_waitcnt vmcnt(8)
	s_waitcnt lgkmcnt(0)
	s_barrier
; #define PG8_STAGE(bufoff, gbase, voff) do { _Pragma("unroll") for (int _i = 0; _i < 2; ++_i) \
;         __builtin_amdgcn_global_load_lds((const unsigned*)((const char*)(gbase) + (voff)[_i]), (LAS unsigned*)(lds + (bufoff) + ldsw + _i * 8192), 16, 0, 0); } while (0)
; #define PG8_LDA(dst, b, h) do { _Pragma("unroll") for (int m = 0; m < 4; ++m) _Pragma("unroll") for (int k = 0; k < 2; ++k) dst[m][k] = *(const LAS bf16x8*)(lds + PG8_SA(b, h) + aoff + m * 2048 + k * 1024); } while (0)
; #define PG8_LDB(dst, b, h) do { _Pragma("unroll") for (int n = 0; n < 2; ++n) _Pragma("unroll") for (int k = 0; k < 2; ++k) dst[n][k] = *(const LAS bf16x8*)(lds + PG8_SB(b, h) + boff + n * 2048 + k * 1024); } while (0)
; #define PG8_MMA(ai, bj, At, Bt) do { __builtin_amdgcn_s_setprio(1); _Pragma("unroll") for (int m = 0; m < 4; ++m) _Pragma("unroll") for (int n = 0; n < 2; ++n) _Pragma("unroll") for (int k = 0; k < 2; ++k) \
;         acc[ai][bj][m][n] = __builtin_amdgcn_mfma_f32_16x16x32_bf16(Bt[n][k], At[m][k], acc[ai][bj][m][n], 0, 0, 0); __builtin_amdgcn_s_setprio(0); } while (0)
; #define PG8_WAIT_V(n) asm volatile("s_waitcnt vmcnt(" #n ")" ::: "memory")
; #define PG8_WAIT_L(n) asm volatile("s_waitcnt lgkmcnt(" #n ")" ::: "memory")
; #define PG8_BAR __builtin_amdgcn_s_barrier()
; #define PG8_SCHED __builtin_amdgcn_sched_barrier(0)
; template <class Epi, class Sched, bool ALIGN_EPI = true>
; __device__ __forceinline__ void gemm_phase(LAS unsigned char* lds, const Gemm g, const Sched& S, const Epi& E) {
;     ...
;             PG8_WAIT_V(8); PG8_WAIT_L(0); PG8_BAR; PG8_MMA(0, 0, At, B0); PG8_MMA(0, 1, At, B1); PG8_BAR; PG8_SCHED;
;             PG8_LDA(At, 0, 1); PG8_STAGE(PG8_SB(0, 0), b2, voffB); PG8_STAGE(PG8_SB(0, 1), b2 + hB, voffB); PG8_STAGE(PG8_SA(0, 0), a2, voffA);
;             PG8_WAIT_V(8); PG8_WAIT_L(0); PG8_BAR; PG8_MMA(1, 0, At, B0); PG8_MMA(1, 1, At, B1); PG8_BAR; PG8_SCHED;
;             PG8_LDB(B0, 1, 0); PG8_LDB(B1, 1, 1); PG8_SCHED; PG8_LDA(At, 1, 0); PG8_STAGE(PG8_SA(0, 1), a2 + hA, voffA);
;             PG8_WAIT_V(8); PG8_WAIT_L(0); PG8_BAR; PG8_MMA(0, 0, At, B0); PG8_MMA(0, 1, At, B1); PG8_BAR; PG8_SCHED;
	s_setprio 1
	s_waitcnt lgkmcnt(0)
	v_mfma_f32_16x16x32_bf16 v[128:131], v[140:143], v[184:187], v[128:131]
	v_mfma_f32_16x16x32_bf16 v[128:131], v[148:151], v[188:191], v[128:131]
	v_mfma_f32_16x16x32_bf16 v[124:127], v[152:155], v[184:187], v[124:127]
	v_mfma_f32_16x16x32_bf16 v[124:127], v[164:167], v[188:191], v[124:127]
	v_mfma_f32_16x16x32_bf16 v[120:123], v[140:143], v[192:195], v[120:123]
	v_mfma_f32_16x16x32_bf16 v[120:123], v[148:151], v[204:207], v[120:123]
	v_mfma_f32_16x16x32_bf16 v[112:115], v[152:155], v[192:195], v[112:115]
	v_mfma_f32_16x16x32_bf16 v[112:115], v[164:167], v[204:207], v[112:115]
	v_mfma_f32_16x16x32_bf16 v[104:107], v[140:143], v[208:211], v[104:107]
	v_mfma_f32_16x16x32_bf16 v[104:107], v[148:151], v[212:215], v[104:107]
	v_mfma_f32_16x16x32_bf16 v[96:99], v[152:155], v[208:211], v[96:99]
	v_mfma_f32_16x16x32_bf16 v[96:99], v[164:167], v[212:215], v[96:99]
	v_mfma_f32_16x16x32_bf16 v[88:91], v[140:143], v[216:219], v[88:91]
	v_mfma_f32_16x16x32_bf16 v[88:91], v[148:151], v[220:223], v[88:91]
	v_mfma_f32_16x16x32_bf16 v[80:83], v[152:155], v[216:219], v[80:83]
	v_mfma_f32_16x16x32_bf16 v[80:83], v[164:167], v[220:223], v[80:83]
	v_mfma_f32_16x16x32_bf16 v[116:119], v[168:171], v[184:187], v[116:119]
	v_mfma_f32_16x16x32_bf16 v[116:119], v[172:175], v[188:191], v[116:119]
	v_mfma_f32_16x16x32_bf16 v[108:111], v[176:179], v[184:187], v[108:111]
	v_mfma_f32_16x16x32_bf16 v[108:111], v[180:183], v[188:191], v[108:111]
	v_mfma_f32_16x16x32_bf16 v[100:103], v[168:171], v[192:195], v[100:103]
	v_mfma_f32_16x16x32_bf16 v[100:103], v[172:175], v[204:207], v[100:103]
	v_mfma_f32_16x16x32_bf16 v[92:95], v[176:179], v[192:195], v[92:95]
	v_mfma_f32_16x16x32_bf16 v[92:95], v[180:183], v[204:207], v[92:95]
	v_mfma_f32_16x16x32_bf16 v[84:87], v[168:171], v[208:211], v[84:87]
	v_mfma_f32_16x16x32_bf16 v[84:87], v[172:175], v[212:215], v[84:87]
	v_mfma_f32_16x16x32_bf16 v[76:79], v[176:179], v[208:211], v[76:79]
	v_mfma_f32_16x16x32_bf16 v[76:79], v[180:183], v[212:215], v[76:79]
	v_mfma_f32_16x16x32_bf16 v[72:75], v[168:171], v[216:219], v[72:75]
	v_mfma_f32_16x16x32_bf16 v[72:75], v[172:175], v[220:223], v[72:75]
	s_setprio 2
	s_barrier
	v_mfma_f32_16x16x32_bf16 v[68:71], v[176:179], v[216:219], v[68:71]
	v_mfma_f32_16x16x32_bf16 v[68:71], v[180:183], v[220:223], v[68:71]
	s_setprio 0
	s_add_i32 s30, s31, s53
	v_lshl_add_u64 v[156:157], s[40:41], 0, v[2:3]
	s_mov_b32 m0, s30
	ds_read_b128 v[184:187], v147 offset:16384
	ds_read_b128 v[188:191], v147 offset:17408
	ds_read_b128 v[192:195], v147 offset:18432
	ds_read_b128 v[204:207], v147 offset:19456
	ds_read_b128 v[208:211], v147 offset:20480
	ds_read_b128 v[212:215], v147 offset:21504
	ds_read_b128 v[216:219], v147 offset:22528
	ds_read_b128 v[220:223], v147 offset:23552
	global_load_lds_dwordx4 v[156:157], off
	s_add_i32 m0, s30, 0x2000
	s_add_u32 s30, s40, 0x80000
	v_lshl_add_u64 v[196:197], s[40:41], 0, v[0:1]
	s_addc_u32 s31, s41, 0
	s_add_i32 s27, s27, s53
	global_load_lds_dwordx4 v[196:197], off
	v_lshl_add_u64 v[224:225], s[30:31], 0, v[2:3]
	s_mov_b32 m0, s27
	v_lshl_add_u64 v[226:227], s[42:43], 0, v[132:133]
	global_load_lds_dwordx4 v[224:225], off
	v_lshl_add_u64 v[224:225], s[30:31], 0, v[0:1]
	s_add_i32 m0, s27, 0x2000
	s_nop 0
	global_load_lds_dwordx4 v[224:225], off
	v_lshl_add_u64 v[224:225], s[42:43], 0, v[134:135]
	s_mov_b32 m0, s58
	s_nop 0
	global_load_lds_dwordx4 v[224:225], off
	s_mov_b32 m0, s59
	s_nop 0
	global_load_lds_dwordx4 v[226:227], off
	s_waitcnt vmcnt(8)
	s_waitcnt lgkmcnt(0)
	s_barrier
	s_setprio 1
	s_waitcnt lgkmcnt(0)
	v_mfma_f32_16x16x32_bf16 v[64:67], v[140:143], v[184:187], v[64:67]
	v_mfma_f32_16x16x32_bf16 v[64:67], v[148:151], v[188:191], v[64:67]
	v_mfma_f32_16x16x32_bf16 v[60:63], v[152:155], v[184:187], v[60:63]
	v_mfma_f32_16x16x32_bf16 v[60:63], v[164:167], v[188:191], v[60:63]
	v_mfma_f32_16x16x32_bf16 v[56:59], v[140:143], v[192:195], v[56:59]
	v_mfma_f32_16x16x32_bf16 v[56:59], v[148:151], v[204:207], v[56:59]
	v_mfma_f32_16x16x32_bf16 v[48:51], v[152:155], v[192:195], v[48:51]
	v_mfma_f32_16x16x32_bf16 v[48:51], v[164:167], v[204:207], v[48:51]
	v_mfma_f32_16x16x32_bf16 v[40:43], v[140:143], v[208:211], v[40:43]
	v_mfma_f32_16x16x32_bf16 v[40:43], v[148:151], v[212:215], v[40:43]
	v_mfma_f32_16x16x32_bf16 v[32:35], v[152:155], v[208:211], v[32:35]
	v_mfma_f32_16x16x32_bf16 v[32:35], v[164:167], v[212:215], v[32:35]
	v_mfma_f32_16x16x32_bf16 v[24:27], v[140:143], v[216:219], v[24:27]
	v_mfma_f32_16x16x32_bf16 v[24:27], v[148:151], v[220:223], v[24:27]
	v_mfma_f32_16x16x32_bf16 v[16:19], v[152:155], v[216:219], v[16:19]
	v_mfma_f32_16x16x32_bf16 v[16:19], v[164:167], v[220:223], v[16:19]
	v_mfma_f32_16x16x32_bf16 v[52:55], v[168:171], v[184:187], v[52:55]
	v_mfma_f32_16x16x32_bf16 v[52:55], v[172:175], v[188:191], v[52:55]
	v_mfma_f32_16x16x32_bf16 v[44:47], v[176:179], v[184:187], v[44:47]
	v_mfma_f32_16x16x32_bf16 v[44:47], v[180:183], v[188:191], v[44:47]
	v_mfma_f32_16x16x32_bf16 v[36:39], v[168:171], v[192:195], v[36:39]
	v_mfma_f32_16x16x32_bf16 v[36:39], v[172:175], v[204:207], v[36:39]
	v_mfma_f32_16x16x32_bf16 v[28:31], v[176:179], v[192:195], v[28:31]
	v_mfma_f32_16x16x32_bf16 v[28:31], v[180:183], v[204:207], v[28:31]
	v_mfma_f32_16x16x32_bf16 v[20:23], v[168:171], v[208:211], v[20:23]
	v_mfma_f32_16x16x32_bf16 v[20:23], v[172:175], v[212:215], v[20:23]
	v_mfma_f32_16x16x32_bf16 v[12:15], v[176:179], v[208:211], v[12:15]
	v_mfma_f32_16x16x32_bf16 v[12:15], v[180:183], v[212:215], v[12:15]
	v_mfma_f32_16x16x32_bf16 v[8:11], v[168:171], v[216:219], v[8:11]
	v_mfma_f32_16x16x32_bf16 v[8:11], v[172:175], v[220:223], v[8:11]
	s_setprio 2
	s_barrier
; #define PG8_STAGE(bufoff, gbase, voff) do { _Pragma("unroll") for (int _i = 0; _i < 2; ++_i) \
;         __builtin_amdgcn_global_load_lds((const unsigned*)((const char*)(gbase) + (voff)[_i]), (LAS unsigned*)(lds + (bufoff) + ldsw + _i * 8192), 16, 0, 0); } while (0)
; #define PG8_LDA(dst, b, h) do { _Pragma("unroll") for (int m = 0; m < 4; ++m) _Pragma("unroll") for (int k = 0; k < 2; ++k) dst[m][k] = *(const LAS bf16x8*)(lds + PG8_SA(b, h) + aoff + m * 2048 + k * 1024); } while (0)
; #define PG8_LDB(dst, b, h) do { _Pragma("unroll") for (int n = 0; n < 2; ++n) _Pragma("unroll") for (int k = 0; k < 2; ++k) dst[n][k] = *(const LAS bf16x8*)(lds + PG8_SB(b, h) + boff + n * 2048 + k * 1024); } while (0)
; #define PG8_MMA(ai, bj, At, Bt) do { __builtin_amdgcn_s_setprio(1); _Pragma("unroll") for (int m = 0; m < 4; ++m) _Pragma("unroll") for (int n = 0; n < 2; ++n) _Pragma("unroll") for (int k = 0; k < 2; ++k) \
;         acc[ai][bj][m][n] = __builtin_amdgcn_mfma_f32_16x16x32_bf16(Bt[n][k], At[m][k], acc[ai][bj][m][n], 0, 0, 0); __builtin_amdgcn_s_setprio(0); } while (0)
; #define PG8_WAIT_V(n) asm volatile("s_waitcnt vmcnt(" #n ")" ::: "memory")
; #define PG8_WAIT_L(n) asm volatile("s_waitcnt lgkmcnt(" #n ")" ::: "memory")
; #define PG8_BAR __builtin_amdgcn_s_barrier()
; #define PG8_SCHED __builtin_amdgcn_sched_barrier(0)
; template <class Epi, class Sched, bool ALIGN_EPI = true>
; __device__ __forceinline__ void gemm_phase(LAS unsigned char* lds, const Gemm g, const Sched& S, const Epi& E) {
;     ...
;             PG8_LDB(B0, 1, 0); PG8_LDB(B1, 1, 1); PG8_SCHED; PG8_LDA(At, 1, 0); PG8_STAGE(PG8_SA(0, 1), a2 + hA, voffA);
;             PG8_WAIT_V(8); PG8_WAIT_L(0); PG8_BAR; PG8_MMA(0, 0, At, B0); PG8_MMA(0, 1, At, B1); PG8_BAR; PG8_SCHED;
	v_mfma_f32_16x16x32_bf16 v[4:7], v[176:179], v[216:219], v[4:7]
	v_mfma_f32_16x16x32_bf16 v[4:7], v[180:183], v[220:223], v[4:7]
	s_setprio 0
	s_add_i32 s27, 0, 0x18000
	v_add_u32_e32 v158, s27, v145
	s_add_i32 s65, 0, 0x1c000
	ds_read_b128 v[140:143], v158
	ds_read_b128 v[148:151], v158 offset:1024
	ds_read_b128 v[152:155], v158 offset:2048
	ds_read_b128 v[164:167], v158 offset:3072
	v_add_u32_e32 v158, s65, v145
	ds_read_b128 v[168:171], v158
	ds_read_b128 v[172:175], v158 offset:1024
	ds_read_b128 v[176:179], v158 offset:2048
	ds_read_b128 v[180:183], v158 offset:3072
	s_add_u32 s30, s42, 0x80000
	s_addc_u32 s31, s43, 0
	s_mov_b32 m0, s60
	v_lshl_add_u64 v[228:229], s[30:31], 0, v[134:135]
	ds_read_b128 v[184:187], v147 offset:32768
	ds_read_b128 v[188:191], v147 offset:33792
	ds_read_b128 v[192:195], v147 offset:34816
	ds_read_b128 v[204:207], v147 offset:35840
	ds_read_b128 v[208:211], v147 offset:36864
	ds_read_b128 v[212:215], v147 offset:37888
	ds_read_b128 v[216:219], v147 offset:38912
	ds_read_b128 v[220:223], v147 offset:39936
	global_load_lds_dwordx4 v[228:229], off
	v_lshl_add_u64 v[228:229], s[30:31], 0, v[132:133]
	s_mov_b32 m0, s61
	s_nop 0
	global_load_lds_dwordx4 v[228:229], off
	s_waitcnt vmcnt(8)
	s_waitcnt lgkmcnt(0)
	s_barrier
	s_setprio 1
	s_waitcnt lgkmcnt(0)
	v_mfma_f32_16x16x32_bf16 v[128:131], v[140:143], v[184:187], v[128:131]
	v_mfma_f32_16x16x32_bf16 v[128:131], v[148:151], v[188:191], v[128:131]
	v_mfma_f32_16x16x32_bf16 v[124:127], v[152:155], v[184:187], v[124:127]
	v_mfma_f32_16x16x32_bf16 v[124:127], v[164:167], v[188:191], v[124:127]
	v_mfma_f32_16x16x32_bf16 v[120:123], v[140:143], v[192:195], v[120:123]
	v_mfma_f32_16x16x32_bf16 v[120:123], v[148:151], v[204:207], v[120:123]
	v_mfma_f32_16x16x32_bf16 v[112:115], v[152:155], v[192:195], v[112:115]
	v_mfma_f32_16x16x32_bf16 v[112:115], v[164:167], v[204:207], v[112:115]
	v_mfma_f32_16x16x32_bf16 v[104:107], v[140:143], v[208:211], v[104:107]
	v_mfma_f32_16x16x32_bf16 v[104:107], v[148:151], v[212:215], v[104:107]
	v_mfma_f32_16x16x32_bf16 v[96:99], v[152:155], v[208:211], v[96:99]
	v_mfma_f32_16x16x32_bf16 v[96:99], v[164:167], v[212:215], v[96:99]
	v_mfma_f32_16x16x32_bf16 v[88:91], v[140:143], v[216:219], v[88:91]
	v_mfma_f32_16x16x32_bf16 v[88:91], v[148:151], v[220:223], v[88:91]
	v_mfma_f32_16x16x32_bf16 v[80:83], v[152:155], v[216:219], v[80:83]
	v_mfma_f32_16x16x32_bf16 v[80:83], v[164:167], v[220:223], v[80:83]
	v_mfma_f32_16x16x32_bf16 v[116:119], v[168:171], v[184:187], v[116:119]
	v_mfma_f32_16x16x32_bf16 v[116:119], v[172:175], v[188:191], v[116:119]
	v_mfma_f32_16x16x32_bf16 v[108:111], v[176:179], v[184:187], v[108:111]
	v_mfma_f32_16x16x32_bf16 v[108:111], v[180:183], v[188:191], v[108:111]
	v_mfma_f32_16x16x32_bf16 v[100:103], v[168:171], v[192:195], v[100:103]
	v_mfma_f32_16x16x32_bf16 v[100:103], v[172:175], v[204:207], v[100:103]
	v_mfma_f32_16x16x32_bf16 v[92:95], v[176:179], v[192:195], v[92:95]
	v_mfma_f32_16x16x32_bf16 v[92:95], v[180:183], v[204:207], v[92:95]
	v_mfma_f32_16x16x32_bf16 v[84:87], v[168:171], v[208:211], v[84:87]
	v_mfma_f32_16x16x32_bf16 v[84:87], v[172:175], v[212:215], v[84:87]
	v_mfma_f32_16x16x32_bf16 v[76:79], v[176:179], v[208:211], v[76:79]
	v_mfma_f32_16x16x32_bf16 v[76:79], v[180:183], v[212:215], v[76:79]
	v_mfma_f32_16x16x32_bf16 v[72:75], v[168:171], v[216:219], v[72:75]
	v_mfma_f32_16x16x32_bf16 v[72:75], v[172:175], v[220:223], v[72:75]
	s_setprio 2
	s_barrier
; #define PG8_STAGE(bufoff, gbase, voff) do { _Pragma("unroll") for (int _i = 0; _i < 2; ++_i) \
;         __builtin_amdgcn_global_load_lds((const unsigned*)((const char*)(gbase) + (voff)[_i]), (LAS unsigned*)(lds + (bufoff) + ldsw + _i * 8192), 16, 0, 0); } while (0)
; #define PG8_LDA(dst, b, h) do { _Pragma("unroll") for (int m = 0; m < 4; ++m) _Pragma("unroll") for (int k = 0; k < 2; ++k) dst[m][k] = *(const LAS bf16x8*)(lds + PG8_SA(b, h) + aoff + m * 2048 + k * 1024); } while (0)
; #define PG8_MMA(ai, bj, At, Bt) do { __builtin_amdgcn_s_setprio(1); _Pragma("unroll") for (int m = 0; m < 4; ++m) _Pragma("unroll") for (int n = 0; n < 2; ++n) _Pragma("unroll") for (int k = 0; k < 2; ++k) \
;         acc[ai][bj][m][n] = __builtin_amdgcn_mfma_f32_16x16x32_bf16(Bt[n][k], At[m][k], acc[ai][bj][m][n], 0, 0, 0); __builtin_amdgcn_s_setprio(0); } while (0)
; #define PG8_WAIT_V(n) asm volatile("s_waitcnt vmcnt(" #n ")" ::: "memory")
; #define PG8_WAIT_L(n) asm volatile("s_waitcnt lgkmcnt(" #n ")" ::: "memory")
; #define PG8_BAR __builtin_amdgcn_s_barrier()
; #define PG8_SCHED __builtin_amdgcn_sched_barrier(0)
; template <class Epi, class Sched, bool ALIGN_EPI = true>
; __device__ __forceinline__ void gemm_phase(LAS unsigned char* lds, const Gemm g, const Sched& S, const Epi& E) {
;     ...
;             const bool last = (t == nt - 2);
;             const char* a1 = cA + (size_t)(t + 1) * kstep;
;             const char* a2 = last ? nA : cA + (size_t)(t + 2) * kstep; const char* b2 = last ? nB : cB + (size_t)(t + 2) * kstep;
;             const char* a3 = a2 + kstep; const char* b3 = b2 + kstep;
;     ...
;             PG8_LDA(At, 1, 1); PG8_STAGE(PG8_SB(1, 0), b3, voffB); PG8_STAGE(PG8_SB(1, 1), b3 + hB, voffB); PG8_STAGE(PG8_SA(1, 0), a3, voffA);
;             PG8_WAIT_V(8); PG8_WAIT_L(0); PG8_BAR; PG8_MMA(1, 0, At, B0); PG8_MMA(1, 1, At, B1); PG8_BAR; PG8_SCHED;
;         }
	v_mfma_f32_16x16x32_bf16 v[68:71], v[176:179], v[216:219], v[68:71]
	v_mfma_f32_16x16x32_bf16 v[68:71], v[180:183], v[220:223], v[68:71]
	s_setprio 0
	s_add_i32 s27, s27, s53
	v_lshl_add_u64 v[156:157], v[156:157], 0, s[86:87]
	s_mov_b32 m0, s27
	ds_read_b128 v[184:187], v147 offset:49152
	ds_read_b128 v[188:191], v147 offset:50176
	ds_read_b128 v[192:195], v147 offset:51200
	ds_read_b128 v[204:207], v147 offset:52224
	ds_read_b128 v[208:211], v147 offset:53248
	ds_read_b128 v[212:215], v147 offset:54272
	ds_read_b128 v[216:219], v147 offset:55296
	ds_read_b128 v[220:223], v147 offset:56320
	global_load_lds_dwordx4 v[156:157], off
	s_add_i32 m0, s27, 0x2000
	s_add_u32 s30, s40, 0x80080
	v_lshl_add_u64 v[156:157], v[196:197], 0, s[86:87]
	s_addc_u32 s31, s41, 0
	s_add_i32 s27, s65, s53
	global_load_lds_dwordx4 v[156:157], off
	v_lshl_add_u64 v[156:157], s[30:31], 0, v[2:3]
	s_mov_b32 m0, s27
	s_nop 0
	global_load_lds_dwordx4 v[156:157], off
	v_lshl_add_u64 v[156:157], s[30:31], 0, v[0:1]
	s_add_i32 m0, s27, 0x2000
	s_nop 0
	global_load_lds_dwordx4 v[156:157], off
	v_lshl_add_u64 v[156:157], v[224:225], 0, s[86:87]
	s_mov_b32 m0, s62
	s_nop 0
	global_load_lds_dwordx4 v[156:157], off
	v_lshl_add_u64 v[156:157], v[226:227], 0, s[86:87]
	s_mov_b32 m0, s63
	s_nop 0
	global_load_lds_dwordx4 v[156:157], off
	s_waitcnt vmcnt(8)
	s_waitcnt lgkmcnt(0)
	s_barrier
	s_setprio 1
	s_waitcnt lgkmcnt(0)
	v_mfma_f32_16x16x32_bf16 v[64:67], v[140:143], v[184:187], v[64:67]
	v_mfma_f32_16x16x32_bf16 v[64:67], v[148:151], v[188:191], v[64:67]
	s_add_i32 s26, s26, 2
	s_add_u32 s38, s38, 0x100
	v_mfma_f32_16x16x32_bf16 v[60:63], v[152:155], v[184:187], v[60:63]
	v_mfma_f32_16x16x32_bf16 v[60:63], v[164:167], v[188:191], v[60:63]
	s_addc_u32 s39, s39, 0
	s_add_u32 s24, s24, 0x100
	v_mfma_f32_16x16x32_bf16 v[56:59], v[140:143], v[192:195], v[56:59]
	v_mfma_f32_16x16x32_bf16 v[56:59], v[148:151], v[204:207], v[56:59]
	s_addc_u32 s25, s25, 0
	s_add_u32 s27, s38, 0xfff80080
	v_mfma_f32_16x16x32_bf16 v[48:51], v[152:155], v[192:195], v[48:51]
	v_mfma_f32_16x16x32_bf16 v[48:51], v[164:167], v[204:207], v[48:51]
	s_addc_u32 s30, s39, -1
	s_add_i32 s31, 0, 0x10000
	v_mfma_f32_16x16x32_bf16 v[40:43], v[140:143], v[208:211], v[40:43]
	v_mfma_f32_16x16x32_bf16 v[40:43], v[148:151], v[212:215], v[40:43]
	s_cmp_eq_u32 s26, 28
	s_cselect_b32 s43, s11, s30
	v_mfma_f32_16x16x32_bf16 v[32:35], v[152:155], v[208:211], v[32:35]
	v_mfma_f32_16x16x32_bf16 v[32:35], v[164:167], v[212:215], v[32:35]
	s_cselect_b32 s42, s18, s27
	s_cselect_b32 s41, s9, s25
	v_mfma_f32_16x16x32_bf16 v[24:27], v[140:143], v[216:219], v[24:27]
	v_mfma_f32_16x16x32_bf16 v[24:27], v[148:151], v[220:223], v[24:27]
	s_cselect_b32 s40, s19, s24
	s_add_i32 s27, 0, 0x14000
	v_mfma_f32_16x16x32_bf16 v[16:19], v[152:155], v[216:219], v[16:19]
	v_mfma_f32_16x16x32_bf16 v[16:19], v[164:167], v[220:223], v[16:19]
	v_mfma_f32_16x16x32_bf16 v[52:55], v[168:171], v[184:187], v[52:55]
	v_mfma_f32_16x16x32_bf16 v[52:55], v[172:175], v[188:191], v[52:55]
	v_mfma_f32_16x16x32_bf16 v[44:47], v[176:179], v[184:187], v[44:47]
	v_mfma_f32_16x16x32_bf16 v[44:47], v[180:183], v[188:191], v[44:47]
	v_mfma_f32_16x16x32_bf16 v[36:39], v[168:171], v[192:195], v[36:39]
	v_mfma_f32_16x16x32_bf16 v[36:39], v[172:175], v[204:207], v[36:39]
	v_mfma_f32_16x16x32_bf16 v[28:31], v[176:179], v[192:195], v[28:31]
	v_mfma_f32_16x16x32_bf16 v[28:31], v[180:183], v[204:207], v[28:31]
	v_mfma_f32_16x16x32_bf16 v[20:23], v[168:171], v[208:211], v[20:23]
	v_mfma_f32_16x16x32_bf16 v[20:23], v[172:175], v[212:215], v[20:23]
	v_mfma_f32_16x16x32_bf16 v[12:15], v[176:179], v[208:211], v[12:15]
	v_mfma_f32_16x16x32_bf16 v[12:15], v[180:183], v[212:215], v[12:15]
	v_mfma_f32_16x16x32_bf16 v[8:11], v[168:171], v[216:219], v[8:11]
	v_mfma_f32_16x16x32_bf16 v[8:11], v[172:175], v[220:223], v[8:11]
	s_setprio 2
	s_barrier
	v_mfma_f32_16x16x32_bf16 v[4:7], v[176:179], v[216:219], v[4:7]
	v_mfma_f32_16x16x32_bf16 v[4:7], v[180:183], v[220:223], v[4:7]
	s_setprio 0
	s_cmp_gt_u32 s26, 29
	s_cbranch_scc0 .LBB0_218

; #define PG8_STAGE(bufoff, gbase, voff) do { _Pragma("unroll") for (int _i = 0; _i < 2; ++_i) \
;         __builtin_amdgcn_global_load_lds((const unsigned*)((const char*)(gbase) + (voff)[_i]), (LAS unsigned*)(lds + (bufoff) + ldsw + _i * 8192), 16, 0, 0); } while (0)
; #define PG8_LDA(dst, b, h) do { _Pragma("unroll") for (int m = 0; m < 4; ++m) _Pragma("unroll") for (int k = 0; k < 2; ++k) dst[m][k] = *(const LAS bf16x8*)(lds + PG8_SA(b, h) + aoff + m * 2048 + k * 1024); } while (0)
; #define PG8_LDB(dst, b, h) do { _Pragma("unroll") for (int n = 0; n < 2; ++n) _Pragma("unroll") for (int k = 0; k < 2; ++k) dst[n][k] = *(const LAS bf16x8*)(lds + PG8_SB(b, h) + boff + n * 2048 + k * 1024); } while (0)
; #define PG8_WAIT_V(n) asm volatile("s_waitcnt vmcnt(" #n ")" ::: "memory")
; #define PG8_WAIT_L(n) asm volatile("s_waitcnt lgkmcnt(" #n ")" ::: "memory")
; template <class Epi, class Sched, bool ALIGN_EPI = true>
; __device__ __forceinline__ void gemm_phase(LAS unsigned char* lds, const Gemm g, const Sched& S, const Epi& E) {
;     ...
;             const bool last = (t == nt - 2);
;             const char* a1 = cA + (size_t)(t + 1) * kstep;
;             const char* a2 = last ? nA : cA + (size_t)(t + 2) * kstep; const char* b2 = last ? nB : cB + (size_t)(t + 2) * kstep;
;             const char* a3 = a2 + kstep; const char* b3 = b2 + kstep;
;             PG8_LDB(B0, 0, 0); PG8_LDB(B1, 0, 1); PG8_SCHED; PG8_LDA(At, 0, 0); PG8_STAGE(PG8_SA(1, 1), a1 + hA, voffA);
;             PG8_WAIT_V(8); PG8_WAIT_L(0); PG8_BAR; PG8_MMA(0, 0, At, B0); PG8_MMA(0, 1, At, B1); PG8_BAR; PG8_SCHED;
;             PG8_LDA(At, 0, 1); PG8_STAGE(PG8_SB(0, 0), b2, voffB); PG8_STAGE(PG8_SB(0, 1), b2 + hB, voffB); PG8_STAGE(PG8_SA(0, 0), a2, voffA);
;             PG8_WAIT_V(8); PG8_WAIT_L(0); PG8_BAR; PG8_MMA(1, 0, At, B0); PG8_MMA(1, 1, At, B1); PG8_BAR; PG8_SCHED;
;             PG8_LDB(B0, 1, 0); PG8_LDB(B1, 1, 1); PG8_SCHED; PG8_LDA(At, 1, 0); PG8_STAGE(PG8_SA(0, 1), a2 + hA, voffA);
;             PG8_WAIT_V(8); PG8_WAIT_L(0); PG8_BAR; PG8_MMA(0, 0, At, B0); PG8_MMA(0, 1, At, B1); PG8_BAR; PG8_SCHED;
;             PG8_LDA(At, 1, 1); PG8_STAGE(PG8_SB(1, 0), b3, voffB); PG8_STAGE(PG8_SB(1, 1), b3 + hB, voffB); PG8_STAGE(PG8_SA(1, 0), a3, voffA);
;             PG8_WAIT_V(8); PG8_WAIT_L(0); PG8_BAR; PG8_MMA(1, 0, At, B0); PG8_MMA(1, 1, At, B1); PG8_BAR; PG8_SCHED;
.LBB0_369:
	s_add_u32 s24, s44, s17
	s_addc_u32 s25, s45, 0
	s_add_u32 s26, s24, 0x100
	s_addc_u32 s27, s25, 0
	s_and_b64 s[18:19], s[58:59], exec
	s_cselect_b32 s63, s39, s27
	s_cselect_b32 s62, s38, s26
	s_add_u32 s17, s42, s17
	s_addc_u32 s18, s43, 0
	s_add_u32 s17, s17, 0x100
	s_addc_u32 s26, s18, 0
	s_add_i32 s31, 0, 0x10000
	s_and_b64 s[18:19], s[58:59], exec
	s_cselect_b32 vcc_hi, s13, s26
	s_cselect_b32 vcc_lo, s15, s17
	s_add_i32 s59, 0, 0x14000
	s_add_u32 s66, s24, 0x40080
	s_addc_u32 s67, s25, 0
	s_add_i32 s30, s31, s53
	s_add_i32 m0, s36, 0xc000
	s_add_i32 s77, s36, 0xe000
	s_add_i32 s25, s30, 0x2000
	s_add_u32 s64, vcc_lo, 0x10000
	v_add_u32_e32 v144, s31, v157
	v_add_u32_e32 v160, s59, v157
	s_addc_u32 s65, vcc_hi, 0
	s_add_i32 s27, s59, s53
	ds_read_b128 v[132:135], v144
	ds_read_b128 v[136:139], v144 offset:1024
	ds_read_b128 v[140:143], v144 offset:2048
	ds_read_b128 v[144:147], v144 offset:3072
	ds_read_b128 v[152:155], v160
	ds_read_b128 v[166:169], v160 offset:1024
	ds_read_b128 v[170:173], v160 offset:2048
	ds_read_b128 v[174:177], v160 offset:3072
	s_add_i32 s26, s27, 0x2000
	s_add_i32 s24, 0, 0x18000
	s_add_i32 s19, 0, 0x1c000
	s_add_u32 s60, s62, 0x40000
	s_addc_u32 s61, s63, 0
	s_add_i32 s18, s24, s53
	s_add_i32 s17, s18, 0x2000
	s_add_u32 s58, vcc_lo, 0x10080
	s_addc_u32 s59, vcc_hi, 0
	s_add_i32 s31, s19, s53
	s_add_i32 s68, s31, 0x2000
	v_lshl_add_u64 v[216:217], s[66:67], 0, v[150:151]
	ds_read_b128 v[178:181], v164
	ds_read_b128 v[182:185], v164 offset:1024
	ds_read_b128 v[186:189], v164 offset:2048
	ds_read_b128 v[190:193], v164 offset:3072
	ds_read_b128 v[194:197], v164 offset:4096
	ds_read_b128 v[204:207], v164 offset:5120
	ds_read_b128 v[208:211], v164 offset:6144
	ds_read_b128 v[212:215], v164 offset:7168
	global_load_lds_dwordx4 v[216:217], off
	v_lshl_add_u64 v[216:217], s[66:67], 0, v[148:149]
	s_mov_b32 m0, s77
	s_nop 0
	global_load_lds_dwordx4 v[216:217], off
	s_waitcnt vmcnt(8)
	s_waitcnt lgkmcnt(0)
	s_barrier
	s_setprio 1
	s_waitcnt lgkmcnt(0)
	v_mfma_f32_16x16x32_bf16 v[128:131], v[132:135], v[178:181], v[128:131]
	v_mfma_f32_16x16x32_bf16 v[124:127], v[140:143], v[178:181], v[124:127]
	v_mfma_f32_16x16x32_bf16 v[116:119], v[132:135], v[186:189], v[116:119]
	v_mfma_f32_16x16x32_bf16 v[108:111], v[140:143], v[186:189], v[108:111]
	v_mfma_f32_16x16x32_bf16 v[100:103], v[132:135], v[194:197], v[100:103]
	v_mfma_f32_16x16x32_bf16 v[92:95], v[140:143], v[194:197], v[92:95]
	v_mfma_f32_16x16x32_bf16 v[84:87], v[132:135], v[208:211], v[84:87]
	v_mfma_f32_16x16x32_bf16 v[76:79], v[140:143], v[208:211], v[76:79]
	v_mfma_f32_16x16x32_bf16 v[128:131], v[136:139], v[182:185], v[128:131]
	v_mfma_f32_16x16x32_bf16 v[124:127], v[144:147], v[182:185], v[124:127]
	v_mfma_f32_16x16x32_bf16 v[116:119], v[136:139], v[190:193], v[116:119]
	v_mfma_f32_16x16x32_bf16 v[108:111], v[144:147], v[190:193], v[108:111]
	v_mfma_f32_16x16x32_bf16 v[100:103], v[136:139], v[204:207], v[100:103]
	v_mfma_f32_16x16x32_bf16 v[92:95], v[144:147], v[204:207], v[92:95]
	v_mfma_f32_16x16x32_bf16 v[84:87], v[136:139], v[212:215], v[84:87]
	v_mfma_f32_16x16x32_bf16 v[76:79], v[144:147], v[212:215], v[76:79]
	v_mfma_f32_16x16x32_bf16 v[120:123], v[152:155], v[178:181], v[120:123]
	v_mfma_f32_16x16x32_bf16 v[112:115], v[170:173], v[178:181], v[112:115]
	v_mfma_f32_16x16x32_bf16 v[104:107], v[152:155], v[186:189], v[104:107]
	v_mfma_f32_16x16x32_bf16 v[96:99], v[170:173], v[186:189], v[96:99]
	v_mfma_f32_16x16x32_bf16 v[88:91], v[152:155], v[194:197], v[88:91]
	v_mfma_f32_16x16x32_bf16 v[80:83], v[170:173], v[194:197], v[80:83]
	v_mfma_f32_16x16x32_bf16 v[72:75], v[152:155], v[208:211], v[72:75]
	v_mfma_f32_16x16x32_bf16 v[68:71], v[170:173], v[208:211], v[68:71]
	v_mfma_f32_16x16x32_bf16 v[120:123], v[166:169], v[182:185], v[120:123]
	v_mfma_f32_16x16x32_bf16 v[112:115], v[174:177], v[182:185], v[112:115]
	v_mfma_f32_16x16x32_bf16 v[104:107], v[166:169], v[190:193], v[104:107]
	v_mfma_f32_16x16x32_bf16 v[96:99], v[174:177], v[190:193], v[96:99]
	v_mfma_f32_16x16x32_bf16 v[88:91], v[166:169], v[204:207], v[88:91]
	v_mfma_f32_16x16x32_bf16 v[80:83], v[174:177], v[204:207], v[80:83]
	v_mfma_f32_16x16x32_bf16 v[72:75], v[166:169], v[212:215], v[72:75]
	v_mfma_f32_16x16x32_bf16 v[68:71], v[174:177], v[212:215], v[68:71]
	s_setprio 0
	s_barrier
	s_mov_b32 m0, s30
	v_lshl_add_u64 v[216:217], vcc, 0, v[2:3]
	ds_read_b128 v[178:181], v164 offset:16384
	ds_read_b128 v[182:185], v164 offset:17408
	ds_read_b128 v[186:189], v164 offset:18432
	ds_read_b128 v[190:193], v164 offset:19456
	ds_read_b128 v[194:197], v164 offset:20480
	ds_read_b128 v[204:207], v164 offset:21504
	ds_read_b128 v[208:211], v164 offset:22528
	ds_read_b128 v[212:215], v164 offset:23552
	global_load_lds_dwordx4 v[216:217], off
	v_lshl_add_u64 v[218:219], vcc, 0, v[0:1]
	s_mov_b32 m0, s25
	v_lshl_add_u64 v[220:221], s[64:65], 0, v[2:3]
	global_load_lds_dwordx4 v[218:219], off
	s_mov_b32 m0, s27
	v_lshl_add_u64 v[222:223], s[62:63], 0, v[148:149]
	global_load_lds_dwordx4 v[220:221], off
	v_lshl_add_u64 v[220:221], s[64:65], 0, v[0:1]
	s_mov_b32 m0, s26
	s_nop 0
	global_load_lds_dwordx4 v[220:221], off
	v_lshl_add_u64 v[220:221], s[62:63], 0, v[150:151]
	s_mov_b32 m0, s36
	s_nop 0
	global_load_lds_dwordx4 v[220:221], off
	s_mov_b32 m0, s78
	s_nop 0
	global_load_lds_dwordx4 v[222:223], off
	s_waitcnt vmcnt(8)
	s_waitcnt lgkmcnt(0)
	s_barrier
; #define PG8_STAGE(bufoff, gbase, voff) do { _Pragma("unroll") for (int _i = 0; _i < 2; ++_i) \
;         __builtin_amdgcn_global_load_lds((const unsigned*)((const char*)(gbase) + (voff)[_i]), (LAS unsigned*)(lds + (bufoff) + ldsw + _i * 8192), 16, 0, 0); } while (0)
; #define PG8_LDA(dst, b, h) do { _Pragma("unroll") for (int m = 0; m < 4; ++m) _Pragma("unroll") for (int k = 0; k < 2; ++k) dst[m][k] = *(const LAS bf16x8*)(lds + PG8_SA(b, h) + aoff + m * 2048 + k * 1024); } while (0)
; #define PG8_LDB(dst, b, h) do { _Pragma("unroll") for (int n = 0; n < 2; ++n) _Pragma("unroll") for (int k = 0; k < 2; ++k) dst[n][k] = *(const LAS bf16x8*)(lds + PG8_SB(b, h) + boff + n * 2048 + k * 1024); } while (0)
; #define PG8_MMA(ai, bj, At, Bt) do { __builtin_amdgcn_s_setprio(1); _Pragma("unroll") for (int m = 0; m < 4; ++m) _Pragma("unroll") for (int n = 0; n < 2; ++n) _Pragma("unroll") for (int k = 0; k < 2; ++k) \
;         acc[ai][bj][m][n] = __builtin_amdgcn_mfma_f32_16x16x32_bf16(Bt[n][k], At[m][k], acc[ai][bj][m][n], 0, 0, 0); __builtin_amdgcn_s_setprio(0); } while (0)
; #define PG8_WAIT_V(n) asm volatile("s_waitcnt vmcnt(" #n ")" ::: "memory")
; #define PG8_WAIT_L(n) asm volatile("s_waitcnt lgkmcnt(" #n ")" ::: "memory")
; #define PG8_BAR __builtin_amdgcn_s_barrier()
; #define PG8_SCHED __builtin_amdgcn_sched_barrier(0)
; template <class Epi, class Sched, bool ALIGN_EPI = true>
; __device__ __forceinline__ void gemm_phase(LAS unsigned char* lds, const Gemm g, const Sched& S, const Epi& E) {
;     ...
;             PG8_LDA(At, 0, 1); PG8_STAGE(PG8_SB(0, 0), b2, voffB); PG8_STAGE(PG8_SB(0, 1), b2 + hB, voffB); PG8_STAGE(PG8_SA(0, 0), a2, voffA);
;             PG8_WAIT_V(8); PG8_WAIT_L(0); PG8_BAR; PG8_MMA(1, 0, At, B0); PG8_MMA(1, 1, At, B1); PG8_BAR; PG8_SCHED;
;             PG8_LDB(B0, 1, 0); PG8_LDB(B1, 1, 1); PG8_SCHED; PG8_LDA(At, 1, 0); PG8_STAGE(PG8_SA(0, 1), a2 + hA, voffA);
;             PG8_WAIT_V(8); PG8_WAIT_L(0); PG8_BAR; PG8_MMA(0, 0, At, B0); PG8_MMA(0, 1, At, B1); PG8_BAR; PG8_SCHED;
	s_setprio 1
	s_waitcnt lgkmcnt(0)
	v_mfma_f32_16x16x32_bf16 v[64:67], v[132:135], v[178:181], v[64:67]
	v_mfma_f32_16x16x32_bf16 v[60:63], v[140:143], v[178:181], v[60:63]
	v_mfma_f32_16x16x32_bf16 v[56:59], v[132:135], v[186:189], v[56:59]
	v_mfma_f32_16x16x32_bf16 v[48:51], v[140:143], v[186:189], v[48:51]
	v_mfma_f32_16x16x32_bf16 v[40:43], v[132:135], v[194:197], v[40:43]
	v_mfma_f32_16x16x32_bf16 v[32:35], v[140:143], v[194:197], v[32:35]
	v_mfma_f32_16x16x32_bf16 v[24:27], v[132:135], v[208:211], v[24:27]
	v_mfma_f32_16x16x32_bf16 v[16:19], v[140:143], v[208:211], v[16:19]
	v_mfma_f32_16x16x32_bf16 v[64:67], v[136:139], v[182:185], v[64:67]
	v_mfma_f32_16x16x32_bf16 v[60:63], v[144:147], v[182:185], v[60:63]
	v_mfma_f32_16x16x32_bf16 v[56:59], v[136:139], v[190:193], v[56:59]
	v_mfma_f32_16x16x32_bf16 v[48:51], v[144:147], v[190:193], v[48:51]
	v_mfma_f32_16x16x32_bf16 v[40:43], v[136:139], v[204:207], v[40:43]
	v_mfma_f32_16x16x32_bf16 v[32:35], v[144:147], v[204:207], v[32:35]
	v_mfma_f32_16x16x32_bf16 v[24:27], v[136:139], v[212:215], v[24:27]
	v_mfma_f32_16x16x32_bf16 v[16:19], v[144:147], v[212:215], v[16:19]
	v_mfma_f32_16x16x32_bf16 v[52:55], v[152:155], v[178:181], v[52:55]
	v_mfma_f32_16x16x32_bf16 v[44:47], v[170:173], v[178:181], v[44:47]
	v_mfma_f32_16x16x32_bf16 v[36:39], v[152:155], v[186:189], v[36:39]
	v_mfma_f32_16x16x32_bf16 v[28:31], v[170:173], v[186:189], v[28:31]
	v_mfma_f32_16x16x32_bf16 v[20:23], v[152:155], v[194:197], v[20:23]
	v_mfma_f32_16x16x32_bf16 v[12:15], v[170:173], v[194:197], v[12:15]
	v_mfma_f32_16x16x32_bf16 v[8:11], v[152:155], v[208:211], v[8:11]
	v_mfma_f32_16x16x32_bf16 v[4:7], v[170:173], v[208:211], v[4:7]
	v_mfma_f32_16x16x32_bf16 v[52:55], v[166:169], v[182:185], v[52:55]
	v_mfma_f32_16x16x32_bf16 v[44:47], v[174:177], v[182:185], v[44:47]
	v_mfma_f32_16x16x32_bf16 v[36:39], v[166:169], v[190:193], v[36:39]
	v_mfma_f32_16x16x32_bf16 v[28:31], v[174:177], v[190:193], v[28:31]
	v_mfma_f32_16x16x32_bf16 v[20:23], v[166:169], v[204:207], v[20:23]
	v_mfma_f32_16x16x32_bf16 v[12:15], v[174:177], v[204:207], v[12:15]
	v_mfma_f32_16x16x32_bf16 v[8:11], v[166:169], v[212:215], v[8:11]
	v_mfma_f32_16x16x32_bf16 v[4:7], v[174:177], v[212:215], v[4:7]
	s_setprio 0
	s_barrier
	v_add_u32_e32 v144, s24, v157
	v_add_u32_e32 v160, s19, v157
	ds_read_b128 v[132:135], v144
	ds_read_b128 v[136:139], v144 offset:1024
	ds_read_b128 v[140:143], v144 offset:2048
	ds_read_b128 v[144:147], v144 offset:3072
	ds_read_b128 v[152:155], v160
	ds_read_b128 v[166:169], v160 offset:1024
	ds_read_b128 v[170:173], v160 offset:2048
	ds_read_b128 v[174:177], v160 offset:3072
	s_mov_b32 m0, s79
	v_lshl_add_u64 v[224:225], s[60:61], 0, v[150:151]
	ds_read_b128 v[178:181], v164 offset:32768
	ds_read_b128 v[182:185], v164 offset:33792
	ds_read_b128 v[186:189], v164 offset:34816
	ds_read_b128 v[190:193], v164 offset:35840
	ds_read_b128 v[194:197], v164 offset:36864
	ds_read_b128 v[204:207], v164 offset:37888
	ds_read_b128 v[208:211], v164 offset:38912
	ds_read_b128 v[212:215], v164 offset:39936
	global_load_lds_dwordx4 v[224:225], off
	v_lshl_add_u64 v[224:225], s[60:61], 0, v[148:149]
	s_mov_b32 m0, s80
	s_nop 0
	global_load_lds_dwordx4 v[224:225], off
	s_waitcnt vmcnt(8)
	s_waitcnt lgkmcnt(0)
	s_barrier
	s_setprio 1
	s_waitcnt lgkmcnt(0)
	v_mfma_f32_16x16x32_bf16 v[128:131], v[132:135], v[178:181], v[128:131]
	v_mfma_f32_16x16x32_bf16 v[124:127], v[140:143], v[178:181], v[124:127]
	v_mfma_f32_16x16x32_bf16 v[116:119], v[132:135], v[186:189], v[116:119]
	v_mfma_f32_16x16x32_bf16 v[108:111], v[140:143], v[186:189], v[108:111]
	v_mfma_f32_16x16x32_bf16 v[100:103], v[132:135], v[194:197], v[100:103]
	v_mfma_f32_16x16x32_bf16 v[92:95], v[140:143], v[194:197], v[92:95]
	v_mfma_f32_16x16x32_bf16 v[84:87], v[132:135], v[208:211], v[84:87]
	v_mfma_f32_16x16x32_bf16 v[76:79], v[140:143], v[208:211], v[76:79]
	v_mfma_f32_16x16x32_bf16 v[128:131], v[136:139], v[182:185], v[128:131]
	v_mfma_f32_16x16x32_bf16 v[124:127], v[144:147], v[182:185], v[124:127]
	v_mfma_f32_16x16x32_bf16 v[116:119], v[136:139], v[190:193], v[116:119]
	v_mfma_f32_16x16x32_bf16 v[108:111], v[144:147], v[190:193], v[108:111]
	v_mfma_f32_16x16x32_bf16 v[100:103], v[136:139], v[204:207], v[100:103]
	v_mfma_f32_16x16x32_bf16 v[92:95], v[144:147], v[204:207], v[92:95]
	v_mfma_f32_16x16x32_bf16 v[84:87], v[136:139], v[212:215], v[84:87]
	v_mfma_f32_16x16x32_bf16 v[76:79], v[144:147], v[212:215], v[76:79]
	v_mfma_f32_16x16x32_bf16 v[120:123], v[152:155], v[178:181], v[120:123]
	v_mfma_f32_16x16x32_bf16 v[112:115], v[170:173], v[178:181], v[112:115]
	v_mfma_f32_16x16x32_bf16 v[104:107], v[152:155], v[186:189], v[104:107]
	v_mfma_f32_16x16x32_bf16 v[96:99], v[170:173], v[186:189], v[96:99]
	v_mfma_f32_16x16x32_bf16 v[88:91], v[152:155], v[194:197], v[88:91]
	v_mfma_f32_16x16x32_bf16 v[80:83], v[170:173], v[194:197], v[80:83]
	v_mfma_f32_16x16x32_bf16 v[72:75], v[152:155], v[208:211], v[72:75]
	v_mfma_f32_16x16x32_bf16 v[68:71], v[170:173], v[208:211], v[68:71]
	v_mfma_f32_16x16x32_bf16 v[120:123], v[166:169], v[182:185], v[120:123]
	v_mfma_f32_16x16x32_bf16 v[112:115], v[174:177], v[182:185], v[112:115]
	v_mfma_f32_16x16x32_bf16 v[104:107], v[166:169], v[190:193], v[104:107]
	v_mfma_f32_16x16x32_bf16 v[96:99], v[174:177], v[190:193], v[96:99]
	v_mfma_f32_16x16x32_bf16 v[88:91], v[166:169], v[204:207], v[88:91]
	v_mfma_f32_16x16x32_bf16 v[80:83], v[174:177], v[204:207], v[80:83]
	v_mfma_f32_16x16x32_bf16 v[72:75], v[166:169], v[212:215], v[72:75]
	v_mfma_f32_16x16x32_bf16 v[68:71], v[174:177], v[212:215], v[68:71]
	s_setprio 0
	s_barrier
; #define PG8_STAGE(bufoff, gbase, voff) do { _Pragma("unroll") for (int _i = 0; _i < 2; ++_i) \
;         __builtin_amdgcn_global_load_lds((const unsigned*)((const char*)(gbase) + (voff)[_i]), (LAS unsigned*)(lds + (bufoff) + ldsw + _i * 8192), 16, 0, 0); } while (0)
; #define PG8_LDA(dst, b, h) do { _Pragma("unroll") for (int m = 0; m < 4; ++m) _Pragma("unroll") for (int k = 0; k < 2; ++k) dst[m][k] = *(const LAS bf16x8*)(lds + PG8_SA(b, h) + aoff + m * 2048 + k * 1024); } while (0)
; #define PG8_MMA(ai, bj, At, Bt) do { __builtin_amdgcn_s_setprio(1); _Pragma("unroll") for (int m = 0; m < 4; ++m) _Pragma("unroll") for (int n = 0; n < 2; ++n) _Pragma("unroll") for (int k = 0; k < 2; ++k) \
;         acc[ai][bj][m][n] = __builtin_amdgcn_mfma_f32_16x16x32_bf16(Bt[n][k], At[m][k], acc[ai][bj][m][n], 0, 0, 0); __builtin_amdgcn_s_setprio(0); } while (0)
; #define PG8_WAIT_V(n) asm volatile("s_waitcnt vmcnt(" #n ")" ::: "memory")
; #define PG8_WAIT_L(n) asm volatile("s_waitcnt lgkmcnt(" #n ")" ::: "memory")
; #define PG8_BAR __builtin_amdgcn_s_barrier()
; #define PG8_SCHED __builtin_amdgcn_sched_barrier(0)
; template <class Epi, class Sched, bool ALIGN_EPI = true>
; __device__ __forceinline__ void gemm_phase(LAS unsigned char* lds, const Gemm g, const Sched& S, const Epi& E) {
;     ...
;             PG8_LDA(At, 1, 1); PG8_STAGE(PG8_SB(1, 0), b3, voffB); PG8_STAGE(PG8_SB(1, 1), b3 + hB, voffB); PG8_STAGE(PG8_SA(1, 0), a3, voffA);
;             PG8_WAIT_V(8); PG8_WAIT_L(0); PG8_BAR; PG8_MMA(1, 0, At, B0); PG8_MMA(1, 1, At, B1); PG8_BAR; PG8_SCHED;
;         }
	s_mov_b32 m0, s18
	v_lshl_add_u64 v[216:217], v[216:217], 0, s[86:87]
	ds_read_b128 v[178:181], v164 offset:49152
	ds_read_b128 v[182:185], v164 offset:50176
	ds_read_b128 v[186:189], v164 offset:51200
	ds_read_b128 v[190:193], v164 offset:52224
	ds_read_b128 v[194:197], v164 offset:53248
	ds_read_b128 v[204:207], v164 offset:54272
	ds_read_b128 v[208:211], v164 offset:55296
	ds_read_b128 v[212:215], v164 offset:56320
	global_load_lds_dwordx4 v[216:217], off
	v_lshl_add_u64 v[216:217], v[218:219], 0, s[86:87]
	s_mov_b32 m0, s17
	s_nop 0
	global_load_lds_dwordx4 v[216:217], off
	v_lshl_add_u64 v[216:217], s[58:59], 0, v[2:3]
	s_mov_b32 m0, s31
	s_nop 0
	global_load_lds_dwordx4 v[216:217], off
	v_lshl_add_u64 v[216:217], s[58:59], 0, v[0:1]
	s_mov_b32 m0, s68
	s_nop 0
	global_load_lds_dwordx4 v[216:217], off
	v_lshl_add_u64 v[216:217], v[220:221], 0, s[86:87]
	s_mov_b32 m0, s81
	s_nop 0
	global_load_lds_dwordx4 v[216:217], off
	v_lshl_add_u64 v[216:217], v[222:223], 0, s[86:87]
	s_mov_b32 m0, s82
	s_nop 0
	global_load_lds_dwordx4 v[216:217], off
	s_waitcnt vmcnt(8)
	s_waitcnt lgkmcnt(0)
	s_barrier
	s_setprio 1
	s_waitcnt lgkmcnt(0)
	v_mfma_f32_16x16x32_bf16 v[64:67], v[132:135], v[178:181], v[64:67]
	v_mfma_f32_16x16x32_bf16 v[60:63], v[140:143], v[178:181], v[60:63]
	v_mfma_f32_16x16x32_bf16 v[56:59], v[132:135], v[186:189], v[56:59]
	v_mfma_f32_16x16x32_bf16 v[48:51], v[140:143], v[186:189], v[48:51]
	v_mfma_f32_16x16x32_bf16 v[40:43], v[132:135], v[194:197], v[40:43]
	v_mfma_f32_16x16x32_bf16 v[32:35], v[140:143], v[194:197], v[32:35]
	v_mfma_f32_16x16x32_bf16 v[24:27], v[132:135], v[208:211], v[24:27]
	v_mfma_f32_16x16x32_bf16 v[16:19], v[140:143], v[208:211], v[16:19]
	v_mfma_f32_16x16x32_bf16 v[64:67], v[136:139], v[182:185], v[64:67]
	v_mfma_f32_16x16x32_bf16 v[60:63], v[144:147], v[182:185], v[60:63]
	v_mfma_f32_16x16x32_bf16 v[56:59], v[136:139], v[190:193], v[56:59]
	v_mfma_f32_16x16x32_bf16 v[48:51], v[144:147], v[190:193], v[48:51]
	v_mfma_f32_16x16x32_bf16 v[40:43], v[136:139], v[204:207], v[40:43]
	v_mfma_f32_16x16x32_bf16 v[32:35], v[144:147], v[204:207], v[32:35]
	v_mfma_f32_16x16x32_bf16 v[24:27], v[136:139], v[212:215], v[24:27]
	v_mfma_f32_16x16x32_bf16 v[16:19], v[144:147], v[212:215], v[16:19]
	v_mfma_f32_16x16x32_bf16 v[52:55], v[152:155], v[178:181], v[52:55]
	v_mfma_f32_16x16x32_bf16 v[44:47], v[170:173], v[178:181], v[44:47]
	v_mfma_f32_16x16x32_bf16 v[36:39], v[152:155], v[186:189], v[36:39]
	v_mfma_f32_16x16x32_bf16 v[28:31], v[170:173], v[186:189], v[28:31]
	v_mfma_f32_16x16x32_bf16 v[20:23], v[152:155], v[194:197], v[20:23]
	v_mfma_f32_16x16x32_bf16 v[12:15], v[170:173], v[194:197], v[12:15]
	v_mfma_f32_16x16x32_bf16 v[8:11], v[152:155], v[208:211], v[8:11]
	v_mfma_f32_16x16x32_bf16 v[4:7], v[170:173], v[208:211], v[4:7]
	v_mfma_f32_16x16x32_bf16 v[52:55], v[166:169], v[182:185], v[52:55]
	v_mfma_f32_16x16x32_bf16 v[44:47], v[174:177], v[182:185], v[44:47]
	v_mfma_f32_16x16x32_bf16 v[36:39], v[166:169], v[190:193], v[36:39]
	v_mfma_f32_16x16x32_bf16 v[28:31], v[174:177], v[190:193], v[28:31]
	v_mfma_f32_16x16x32_bf16 v[20:23], v[166:169], v[204:207], v[20:23]
	v_mfma_f32_16x16x32_bf16 v[12:15], v[174:177], v[204:207], v[12:15]
	v_mfma_f32_16x16x32_bf16 v[8:11], v[166:169], v[212:215], v[8:11]
	v_mfma_f32_16x16x32_bf16 v[4:7], v[174:177], v[212:215], v[4:7]
	s_setprio 0
	s_barrier
	s_movk_i32 s17, 0x100
	s_andn2_b64 vcc, exec, s[6:7]
	s_mov_b64 s[58:59], -1
	s_mov_b64 s[6:7], 0
	s_cbranch_vccz .LBB0_369
	s_and_b64 vcc, exec, s[10:11]
	s_cbranch_vccz .LBB0_372
	s_barrier

; #define PG8_STAGE(bufoff, gbase, voff) do { _Pragma("unroll") for (int _i = 0; _i < 2; ++_i) \
;         __builtin_amdgcn_global_load_lds((const unsigned*)((const char*)(gbase) + (voff)[_i]), (LAS unsigned*)(lds + (bufoff) + ldsw + _i * 8192), 16, 0, 0); } while (0)
; #define PG8_LDA(dst, b, h) do { _Pragma("unroll") for (int m = 0; m < 4; ++m) _Pragma("unroll") for (int k = 0; k < 2; ++k) dst[m][k] = *(const LAS bf16x8*)(lds + PG8_SA(b, h) + aoff + m * 2048 + k * 1024); } while (0)
; #define PG8_LDB(dst, b, h) do { _Pragma("unroll") for (int n = 0; n < 2; ++n) _Pragma("unroll") for (int k = 0; k < 2; ++k) dst[n][k] = *(const LAS bf16x8*)(lds + PG8_SB(b, h) + boff + n * 2048 + k * 1024); } while (0)
; #define PG8_MMA(ai, bj, At, Bt) do { __builtin_amdgcn_s_setprio(1); _Pragma("unroll") for (int m = 0; m < 4; ++m) _Pragma("unroll") for (int n = 0; n < 2; ++n) _Pragma("unroll") for (int k = 0; k < 2; ++k) \
;         acc[ai][bj][m][n] = __builtin_amdgcn_mfma_f32_16x16x32_bf16(Bt[n][k], At[m][k], acc[ai][bj][m][n], 0, 0, 0); __builtin_amdgcn_s_setprio(0); } while (0)
; #define PG8_WAIT_V(n) asm volatile("s_waitcnt vmcnt(" #n ")" ::: "memory")
; template <class Epi, class Sched, bool ALIGN_EPI = true>
; __device__ __forceinline__ void gemm_phase(LAS unsigned char* lds, const Gemm g, const Sched& S, const Epi& E) {
;     ...
;             const bool last = (t == nt - 2);
;             const char* a1 = cA + (size_t)(t + 1) * kstep;
;             const char* a2 = last ? nA : cA + (size_t)(t + 2) * kstep; const char* b2 = last ? nB : cB + (size_t)(t + 2) * kstep;
;             const char* a3 = a2 + kstep; const char* b3 = b2 + kstep;
;             PG8_LDB(B0, 0, 0); PG8_LDB(B1, 0, 1); PG8_SCHED; PG8_LDA(At, 0, 0); PG8_STAGE(PG8_SA(1, 1), a1 + hA, voffA);
;             PG8_WAIT_V(8); PG8_WAIT_L(0); PG8_BAR; PG8_MMA(0, 0, At, B0); PG8_MMA(0, 1, At, B1); PG8_BAR; PG8_SCHED;
;             PG8_LDA(At, 0, 1); PG8_STAGE(PG8_SB(0, 0), b2, voffB); PG8_STAGE(PG8_SB(0, 1), b2 + hB, voffB); PG8_STAGE(PG8_SA(0, 0), a2, voffA);
;             PG8_WAIT_V(8); PG8_WAIT_L(0); PG8_BAR; PG8_MMA(1, 0, At, B0); PG8_MMA(1, 1, At, B1); PG8_BAR; PG8_SCHED;
;             PG8_LDB(B0, 1, 0); PG8_LDB(B1, 1, 1); PG8_SCHED; PG8_LDA(At, 1, 0); PG8_STAGE(PG8_SA(0, 1), a2 + hA, voffA);
;             PG8_WAIT_V(8); PG8_WAIT_L(0); PG8_BAR; PG8_MMA(0, 0, At, B0); PG8_MMA(0, 1, At, B1); PG8_BAR; PG8_SCHED;
.LBB0_544:
	s_add_u32 s60, s58, 0x100
	s_addc_u32 s61, s59, 0
	s_add_i32 s31, 0, 0x10000
	s_cmp_eq_u32 s30, 28
	s_cselect_b32 s65, s18, s61
	s_cselect_b32 s64, s19, s60
	v_add_u32_e32 v140, s31, v143
	s_cselect_b32 s63, s24, s27
	s_cselect_b32 s62, s25, s26
	s_add_i32 s36, 0, 0x14000
	ds_read_b128 v[136:139], v140
	ds_read_b128 v[146:149], v140 offset:1024
	ds_read_b128 v[150:153], v140 offset:2048
	ds_read_b128 v[154:157], v140 offset:3072
	v_add_u32_e32 v140, s36, v143
	ds_read_b128 v[164:167], v140
	ds_read_b128 v[168:171], v140 offset:1024
	ds_read_b128 v[172:175], v140 offset:2048
	ds_read_b128 v[176:179], v140 offset:3072
	v_lshl_add_u64 v[140:141], s[58:59], 0, v[132:133]
	s_add_i32 m0, s75, 0xc000
	ds_read_b128 v[180:183], v145
	ds_read_b128 v[184:187], v145 offset:1024
	ds_read_b128 v[188:191], v145 offset:2048
	ds_read_b128 v[192:195], v145 offset:3072
	ds_read_b128 v[204:207], v145 offset:4096
	ds_read_b128 v[208:211], v145 offset:5120
	ds_read_b128 v[212:215], v145 offset:6144
	ds_read_b128 v[216:219], v145 offset:7168
	global_load_lds_dwordx4 v[140:141], off
	v_lshl_add_u64 v[140:141], s[58:59], 0, v[134:135]
	s_add_i32 m0, s75, 0xe000
	s_nop 0
	global_load_lds_dwordx4 v[140:141], off
	s_waitcnt vmcnt(8)
	s_waitcnt lgkmcnt(0)
	s_barrier
	s_setprio 1
	s_waitcnt lgkmcnt(0)
	v_mfma_f32_16x16x32_bf16 v[128:131], v[136:139], v[180:183], v[128:131]
	v_mfma_f32_16x16x32_bf16 v[124:127], v[150:153], v[180:183], v[124:127]
	v_mfma_f32_16x16x32_bf16 v[112:115], v[136:139], v[188:191], v[112:115]
	v_mfma_f32_16x16x32_bf16 v[108:111], v[150:153], v[188:191], v[108:111]
	v_mfma_f32_16x16x32_bf16 v[96:99], v[136:139], v[204:207], v[96:99]
	v_mfma_f32_16x16x32_bf16 v[92:95], v[150:153], v[204:207], v[92:95]
	v_mfma_f32_16x16x32_bf16 v[80:83], v[136:139], v[212:215], v[80:83]
	v_mfma_f32_16x16x32_bf16 v[76:79], v[150:153], v[212:215], v[76:79]
	v_mfma_f32_16x16x32_bf16 v[128:131], v[146:149], v[184:187], v[128:131]
	v_mfma_f32_16x16x32_bf16 v[124:127], v[154:157], v[184:187], v[124:127]
	v_mfma_f32_16x16x32_bf16 v[112:115], v[146:149], v[192:195], v[112:115]
	v_mfma_f32_16x16x32_bf16 v[108:111], v[154:157], v[192:195], v[108:111]
	v_mfma_f32_16x16x32_bf16 v[96:99], v[146:149], v[208:211], v[96:99]
	v_mfma_f32_16x16x32_bf16 v[92:95], v[154:157], v[208:211], v[92:95]
	v_mfma_f32_16x16x32_bf16 v[80:83], v[146:149], v[216:219], v[80:83]
	v_mfma_f32_16x16x32_bf16 v[76:79], v[154:157], v[216:219], v[76:79]
	v_mfma_f32_16x16x32_bf16 v[120:123], v[164:167], v[180:183], v[120:123]
	v_mfma_f32_16x16x32_bf16 v[116:119], v[172:175], v[180:183], v[116:119]
	v_mfma_f32_16x16x32_bf16 v[104:107], v[164:167], v[188:191], v[104:107]
	v_mfma_f32_16x16x32_bf16 v[100:103], v[172:175], v[188:191], v[100:103]
	v_mfma_f32_16x16x32_bf16 v[88:91], v[164:167], v[204:207], v[88:91]
	v_mfma_f32_16x16x32_bf16 v[84:87], v[172:175], v[204:207], v[84:87]
	v_mfma_f32_16x16x32_bf16 v[72:75], v[164:167], v[212:215], v[72:75]
	v_mfma_f32_16x16x32_bf16 v[68:71], v[172:175], v[212:215], v[68:71]
	v_mfma_f32_16x16x32_bf16 v[120:123], v[168:171], v[184:187], v[120:123]
	v_mfma_f32_16x16x32_bf16 v[116:119], v[176:179], v[184:187], v[116:119]
	v_mfma_f32_16x16x32_bf16 v[104:107], v[168:171], v[192:195], v[104:107]
	v_mfma_f32_16x16x32_bf16 v[100:103], v[176:179], v[192:195], v[100:103]
	v_mfma_f32_16x16x32_bf16 v[88:91], v[168:171], v[208:211], v[88:91]
	v_mfma_f32_16x16x32_bf16 v[84:87], v[176:179], v[208:211], v[84:87]
	v_mfma_f32_16x16x32_bf16 v[72:75], v[168:171], v[216:219], v[72:75]
	v_mfma_f32_16x16x32_bf16 v[68:71], v[176:179], v[216:219], v[68:71]
	s_setprio 0
	s_barrier
	s_add_i32 s31, s31, s67
	v_lshl_add_u64 v[140:141], s[62:63], 0, v[2:3]
	s_mov_b32 m0, s31
	ds_read_b128 v[180:183], v145 offset:16384
	ds_read_b128 v[184:187], v145 offset:17408
	ds_read_b128 v[188:191], v145 offset:18432
	ds_read_b128 v[192:195], v145 offset:19456
	ds_read_b128 v[204:207], v145 offset:20480
	ds_read_b128 v[208:211], v145 offset:21504
	ds_read_b128 v[212:215], v145 offset:22528
	ds_read_b128 v[216:219], v145 offset:23552
	global_load_lds_dwordx4 v[140:141], off
	s_add_i32 m0, s31, 0x2000
	s_add_u32 s58, s62, 0x80000
	v_lshl_add_u64 v[160:161], s[62:63], 0, v[0:1]
	s_addc_u32 s59, s63, 0
	s_add_i32 s31, s36, s67
	global_load_lds_dwordx4 v[160:161], off
	v_lshl_add_u64 v[162:163], s[58:59], 0, v[2:3]
	s_mov_b32 m0, s31
	v_lshl_add_u64 v[196:197], s[64:65], 0, v[0:1]
	global_load_lds_dwordx4 v[162:163], off
	v_lshl_add_u64 v[162:163], s[58:59], 0, v[0:1]
	s_add_i32 m0, s31, 0x2000
	s_nop 0
	global_load_lds_dwordx4 v[162:163], off
	v_lshl_add_u64 v[162:163], s[64:65], 0, v[2:3]
	s_mov_b32 m0, s75
	s_nop 0
	global_load_lds_dwordx4 v[162:163], off
	s_mov_b32 m0, s76
	s_nop 0
	global_load_lds_dwordx4 v[196:197], off
	s_waitcnt vmcnt(8)
	s_waitcnt lgkmcnt(0)
	s_barrier
; #define PG8_STAGE(bufoff, gbase, voff) do { _Pragma("unroll") for (int _i = 0; _i < 2; ++_i) \
;         __builtin_amdgcn_global_load_lds((const unsigned*)((const char*)(gbase) + (voff)[_i]), (LAS unsigned*)(lds + (bufoff) + ldsw + _i * 8192), 16, 0, 0); } while (0)
; #define PG8_LDA(dst, b, h) do { _Pragma("unroll") for (int m = 0; m < 4; ++m) _Pragma("unroll") for (int k = 0; k < 2; ++k) dst[m][k] = *(const LAS bf16x8*)(lds + PG8_SA(b, h) + aoff + m * 2048 + k * 1024); } while (0)
; #define PG8_LDB(dst, b, h) do { _Pragma("unroll") for (int n = 0; n < 2; ++n) _Pragma("unroll") for (int k = 0; k < 2; ++k) dst[n][k] = *(const LAS bf16x8*)(lds + PG8_SB(b, h) + boff + n * 2048 + k * 1024); } while (0)
; #define PG8_MMA(ai, bj, At, Bt) do { __builtin_amdgcn_s_setprio(1); _Pragma("unroll") for (int m = 0; m < 4; ++m) _Pragma("unroll") for (int n = 0; n < 2; ++n) _Pragma("unroll") for (int k = 0; k < 2; ++k) \
;         acc[ai][bj][m][n] = __builtin_amdgcn_mfma_f32_16x16x32_bf16(Bt[n][k], At[m][k], acc[ai][bj][m][n], 0, 0, 0); __builtin_amdgcn_s_setprio(0); } while (0)
; #define PG8_WAIT_V(n) asm volatile("s_waitcnt vmcnt(" #n ")" ::: "memory")
; #define PG8_WAIT_L(n) asm volatile("s_waitcnt lgkmcnt(" #n ")" ::: "memory")
; #define PG8_BAR __builtin_amdgcn_s_barrier()
; #define PG8_SCHED __builtin_amdgcn_sched_barrier(0)
; template <class Epi, class Sched, bool ALIGN_EPI = true>
; __device__ __forceinline__ void gemm_phase(LAS unsigned char* lds, const Gemm g, const Sched& S, const Epi& E) {
;     ...
;             PG8_WAIT_V(8); PG8_WAIT_L(0); PG8_BAR; PG8_MMA(1, 0, At, B0); PG8_MMA(1, 1, At, B1); PG8_BAR; PG8_SCHED;
;             PG8_LDB(B0, 1, 0); PG8_LDB(B1, 1, 1); PG8_SCHED; PG8_LDA(At, 1, 0); PG8_STAGE(PG8_SA(0, 1), a2 + hA, voffA);
;             PG8_WAIT_V(8); PG8_WAIT_L(0); PG8_BAR; PG8_MMA(0, 0, At, B0); PG8_MMA(0, 1, At, B1); PG8_BAR; PG8_SCHED;
;             PG8_LDA(At, 1, 1); PG8_STAGE(PG8_SB(1, 0), b3, voffB); PG8_STAGE(PG8_SB(1, 1), b3 + hB, voffB); PG8_STAGE(PG8_SA(1, 0), a3, voffA);
;             PG8_WAIT_V(8); PG8_WAIT_L(0); PG8_BAR; PG8_MMA(1, 0, At, B0); PG8_MMA(1, 1, At, B1); PG8_BAR; PG8_SCHED;
	s_setprio 1
	s_waitcnt lgkmcnt(0)
	v_mfma_f32_16x16x32_bf16 v[64:67], v[136:139], v[180:183], v[64:67]
	v_mfma_f32_16x16x32_bf16 v[60:63], v[150:153], v[180:183], v[60:63]
	v_mfma_f32_16x16x32_bf16 v[48:51], v[136:139], v[188:191], v[48:51]
	v_mfma_f32_16x16x32_bf16 v[44:47], v[150:153], v[188:191], v[44:47]
	v_mfma_f32_16x16x32_bf16 v[32:35], v[136:139], v[204:207], v[32:35]
	v_mfma_f32_16x16x32_bf16 v[28:31], v[150:153], v[204:207], v[28:31]
	v_mfma_f32_16x16x32_bf16 v[16:19], v[136:139], v[212:215], v[16:19]
	v_mfma_f32_16x16x32_bf16 v[12:15], v[150:153], v[212:215], v[12:15]
	v_mfma_f32_16x16x32_bf16 v[64:67], v[146:149], v[184:187], v[64:67]
	v_mfma_f32_16x16x32_bf16 v[60:63], v[154:157], v[184:187], v[60:63]
	v_mfma_f32_16x16x32_bf16 v[48:51], v[146:149], v[192:195], v[48:51]
	v_mfma_f32_16x16x32_bf16 v[44:47], v[154:157], v[192:195], v[44:47]
	v_mfma_f32_16x16x32_bf16 v[32:35], v[146:149], v[208:211], v[32:35]
	v_mfma_f32_16x16x32_bf16 v[28:31], v[154:157], v[208:211], v[28:31]
	v_mfma_f32_16x16x32_bf16 v[16:19], v[146:149], v[216:219], v[16:19]
	v_mfma_f32_16x16x32_bf16 v[12:15], v[154:157], v[216:219], v[12:15]
	v_mfma_f32_16x16x32_bf16 v[56:59], v[164:167], v[180:183], v[56:59]
	v_mfma_f32_16x16x32_bf16 v[52:55], v[172:175], v[180:183], v[52:55]
	v_mfma_f32_16x16x32_bf16 v[40:43], v[164:167], v[188:191], v[40:43]
	v_mfma_f32_16x16x32_bf16 v[36:39], v[172:175], v[188:191], v[36:39]
	v_mfma_f32_16x16x32_bf16 v[24:27], v[164:167], v[204:207], v[24:27]
	v_mfma_f32_16x16x32_bf16 v[20:23], v[172:175], v[204:207], v[20:23]
	v_mfma_f32_16x16x32_bf16 v[8:11], v[164:167], v[212:215], v[8:11]
	v_mfma_f32_16x16x32_bf16 v[4:7], v[172:175], v[212:215], v[4:7]
	v_mfma_f32_16x16x32_bf16 v[56:59], v[168:171], v[184:187], v[56:59]
	v_mfma_f32_16x16x32_bf16 v[52:55], v[176:179], v[184:187], v[52:55]
	v_mfma_f32_16x16x32_bf16 v[40:43], v[168:171], v[192:195], v[40:43]
	v_mfma_f32_16x16x32_bf16 v[36:39], v[176:179], v[192:195], v[36:39]
	v_mfma_f32_16x16x32_bf16 v[24:27], v[168:171], v[208:211], v[24:27]
	v_mfma_f32_16x16x32_bf16 v[20:23], v[176:179], v[208:211], v[20:23]
	v_mfma_f32_16x16x32_bf16 v[8:11], v[168:171], v[216:219], v[8:11]
	v_mfma_f32_16x16x32_bf16 v[4:7], v[176:179], v[216:219], v[4:7]
	s_setprio 0
	s_barrier
	s_add_i32 s31, 0, 0x18000
	s_add_i32 s36, 0, 0x1c000
	v_add_u32_e32 v154, s31, v143
	v_add_u32_e32 v158, s36, v143
	ds_read_b128 v[136:139], v154
	ds_read_b128 v[146:149], v154 offset:1024
	ds_read_b128 v[150:153], v154 offset:2048
	ds_read_b128 v[154:157], v154 offset:3072
	ds_read_b128 v[164:167], v158
	ds_read_b128 v[168:171], v158 offset:1024
	ds_read_b128 v[172:175], v158 offset:2048
	ds_read_b128 v[176:179], v158 offset:3072
	s_add_u32 s58, s64, 0x80000
	s_addc_u32 s59, s65, 0
	s_mov_b32 m0, s77
	v_lshl_add_u64 v[220:221], s[58:59], 0, v[2:3]
	ds_read_b128 v[180:183], v145 offset:32768
	ds_read_b128 v[184:187], v145 offset:33792
	ds_read_b128 v[188:191], v145 offset:34816
	ds_read_b128 v[192:195], v145 offset:35840
	ds_read_b128 v[204:207], v145 offset:36864
	ds_read_b128 v[208:211], v145 offset:37888
	ds_read_b128 v[212:215], v145 offset:38912
	ds_read_b128 v[216:219], v145 offset:39936
	global_load_lds_dwordx4 v[220:221], off
	v_lshl_add_u64 v[220:221], s[58:59], 0, v[0:1]
	s_mov_b32 m0, s78
	s_nop 0
	global_load_lds_dwordx4 v[220:221], off
	s_waitcnt vmcnt(8)
	s_waitcnt lgkmcnt(0)
	s_barrier
	s_setprio 1
	s_waitcnt lgkmcnt(0)
	v_mfma_f32_16x16x32_bf16 v[128:131], v[136:139], v[180:183], v[128:131]
	v_mfma_f32_16x16x32_bf16 v[124:127], v[150:153], v[180:183], v[124:127]
	v_mfma_f32_16x16x32_bf16 v[112:115], v[136:139], v[188:191], v[112:115]
	v_mfma_f32_16x16x32_bf16 v[108:111], v[150:153], v[188:191], v[108:111]
	v_mfma_f32_16x16x32_bf16 v[96:99], v[136:139], v[204:207], v[96:99]
	v_mfma_f32_16x16x32_bf16 v[92:95], v[150:153], v[204:207], v[92:95]
	v_mfma_f32_16x16x32_bf16 v[80:83], v[136:139], v[212:215], v[80:83]
	v_mfma_f32_16x16x32_bf16 v[76:79], v[150:153], v[212:215], v[76:79]
	v_mfma_f32_16x16x32_bf16 v[128:131], v[146:149], v[184:187], v[128:131]
	v_mfma_f32_16x16x32_bf16 v[124:127], v[154:157], v[184:187], v[124:127]
	v_mfma_f32_16x16x32_bf16 v[112:115], v[146:149], v[192:195], v[112:115]
	v_mfma_f32_16x16x32_bf16 v[108:111], v[154:157], v[192:195], v[108:111]
	v_mfma_f32_16x16x32_bf16 v[96:99], v[146:149], v[208:211], v[96:99]
	v_mfma_f32_16x16x32_bf16 v[92:95], v[154:157], v[208:211], v[92:95]
	v_mfma_f32_16x16x32_bf16 v[80:83], v[146:149], v[216:219], v[80:83]
	v_mfma_f32_16x16x32_bf16 v[76:79], v[154:157], v[216:219], v[76:79]
	v_mfma_f32_16x16x32_bf16 v[120:123], v[164:167], v[180:183], v[120:123]
	v_mfma_f32_16x16x32_bf16 v[116:119], v[172:175], v[180:183], v[116:119]
	v_mfma_f32_16x16x32_bf16 v[104:107], v[164:167], v[188:191], v[104:107]
	v_mfma_f32_16x16x32_bf16 v[100:103], v[172:175], v[188:191], v[100:103]
	v_mfma_f32_16x16x32_bf16 v[88:91], v[164:167], v[204:207], v[88:91]
	v_mfma_f32_16x16x32_bf16 v[84:87], v[172:175], v[204:207], v[84:87]
	v_mfma_f32_16x16x32_bf16 v[72:75], v[164:167], v[212:215], v[72:75]
	v_mfma_f32_16x16x32_bf16 v[68:71], v[172:175], v[212:215], v[68:71]
	v_mfma_f32_16x16x32_bf16 v[120:123], v[168:171], v[184:187], v[120:123]
	v_mfma_f32_16x16x32_bf16 v[116:119], v[176:179], v[184:187], v[116:119]
	v_mfma_f32_16x16x32_bf16 v[104:107], v[168:171], v[192:195], v[104:107]
	v_mfma_f32_16x16x32_bf16 v[100:103], v[176:179], v[192:195], v[100:103]
	v_mfma_f32_16x16x32_bf16 v[88:91], v[168:171], v[208:211], v[88:91]
	v_mfma_f32_16x16x32_bf16 v[84:87], v[176:179], v[208:211], v[84:87]
	v_mfma_f32_16x16x32_bf16 v[72:75], v[168:171], v[216:219], v[72:75]
	v_mfma_f32_16x16x32_bf16 v[68:71], v[176:179], v[216:219], v[68:71]
	s_setprio 0
	s_barrier
; #define PG8_STAGE(bufoff, gbase, voff) do { _Pragma("unroll") for (int _i = 0; _i < 2; ++_i) \
;         __builtin_amdgcn_global_load_lds((const unsigned*)((const char*)(gbase) + (voff)[_i]), (LAS unsigned*)(lds + (bufoff) + ldsw + _i * 8192), 16, 0, 0); } while (0)
; #define PG8_LDA(dst, b, h) do { _Pragma("unroll") for (int m = 0; m < 4; ++m) _Pragma("unroll") for (int k = 0; k < 2; ++k) dst[m][k] = *(const LAS bf16x8*)(lds + PG8_SA(b, h) + aoff + m * 2048 + k * 1024); } while (0)
; #define PG8_MMA(ai, bj, At, Bt) do { __builtin_amdgcn_s_setprio(1); _Pragma("unroll") for (int m = 0; m < 4; ++m) _Pragma("unroll") for (int n = 0; n < 2; ++n) _Pragma("unroll") for (int k = 0; k < 2; ++k) \
;         acc[ai][bj][m][n] = __builtin_amdgcn_mfma_f32_16x16x32_bf16(Bt[n][k], At[m][k], acc[ai][bj][m][n], 0, 0, 0); __builtin_amdgcn_s_setprio(0); } while (0)
; #define PG8_WAIT_V(n) asm volatile("s_waitcnt vmcnt(" #n ")" ::: "memory")
; #define PG8_WAIT_L(n) asm volatile("s_waitcnt lgkmcnt(" #n ")" ::: "memory")
; #define PG8_BAR __builtin_amdgcn_s_barrier()
; #define PG8_SCHED __builtin_amdgcn_sched_barrier(0)
; template <class Epi, class Sched, bool ALIGN_EPI = true>
; __device__ __forceinline__ void gemm_phase(LAS unsigned char* lds, const Gemm g, const Sched& S, const Epi& E) {
;     ...
;             PG8_LDA(At, 1, 1); PG8_STAGE(PG8_SB(1, 0), b3, voffB); PG8_STAGE(PG8_SB(1, 1), b3 + hB, voffB); PG8_STAGE(PG8_SA(1, 0), a3, voffA);
;             PG8_WAIT_V(8); PG8_WAIT_L(0); PG8_BAR; PG8_MMA(1, 0, At, B0); PG8_MMA(1, 1, At, B1); PG8_BAR; PG8_SCHED;
;         }
;         if constexpr (ALIGN_EPI) { if (wr == 0) PG8_BAR; }
	s_add_i32 s31, s31, s67
	v_lshl_add_u64 v[140:141], v[140:141], 0, s[86:87]
	s_mov_b32 m0, s31
	ds_read_b128 v[180:183], v145 offset:49152
	ds_read_b128 v[184:187], v145 offset:50176
	ds_read_b128 v[188:191], v145 offset:51200
	ds_read_b128 v[192:195], v145 offset:52224
	ds_read_b128 v[204:207], v145 offset:53248
	ds_read_b128 v[208:211], v145 offset:54272
	ds_read_b128 v[212:215], v145 offset:55296
	ds_read_b128 v[216:219], v145 offset:56320
	global_load_lds_dwordx4 v[140:141], off
	s_add_i32 m0, s31, 0x2000
	s_add_u32 s58, s62, 0x80080
	v_lshl_add_u64 v[140:141], v[160:161], 0, s[86:87]
	s_addc_u32 s59, s63, 0
	s_add_i32 s31, s36, s67
	global_load_lds_dwordx4 v[140:141], off
	v_lshl_add_u64 v[140:141], s[58:59], 0, v[2:3]
	s_mov_b32 m0, s31
	s_nop 0
	global_load_lds_dwordx4 v[140:141], off
	v_lshl_add_u64 v[140:141], s[58:59], 0, v[0:1]
	s_add_i32 m0, s31, 0x2000
	s_nop 0
	global_load_lds_dwordx4 v[140:141], off
	v_lshl_add_u64 v[140:141], v[162:163], 0, s[86:87]
	s_mov_b32 m0, s79
	s_nop 0
	global_load_lds_dwordx4 v[140:141], off
	v_lshl_add_u64 v[140:141], v[196:197], 0, s[86:87]
	s_mov_b32 m0, s80
	s_nop 0
	global_load_lds_dwordx4 v[140:141], off
	s_waitcnt vmcnt(8)
	s_waitcnt lgkmcnt(0)
	s_barrier
	s_setprio 1
	s_waitcnt lgkmcnt(0)
	v_mfma_f32_16x16x32_bf16 v[64:67], v[136:139], v[180:183], v[64:67]
	v_mfma_f32_16x16x32_bf16 v[60:63], v[150:153], v[180:183], v[60:63]
	v_mfma_f32_16x16x32_bf16 v[48:51], v[136:139], v[188:191], v[48:51]
	v_mfma_f32_16x16x32_bf16 v[44:47], v[150:153], v[188:191], v[44:47]
	v_mfma_f32_16x16x32_bf16 v[32:35], v[136:139], v[204:207], v[32:35]
	v_mfma_f32_16x16x32_bf16 v[28:31], v[150:153], v[204:207], v[28:31]
	v_mfma_f32_16x16x32_bf16 v[16:19], v[136:139], v[212:215], v[16:19]
	v_mfma_f32_16x16x32_bf16 v[12:15], v[150:153], v[212:215], v[12:15]
	v_mfma_f32_16x16x32_bf16 v[64:67], v[146:149], v[184:187], v[64:67]
	v_mfma_f32_16x16x32_bf16 v[60:63], v[154:157], v[184:187], v[60:63]
	v_mfma_f32_16x16x32_bf16 v[48:51], v[146:149], v[192:195], v[48:51]
	v_mfma_f32_16x16x32_bf16 v[44:47], v[154:157], v[192:195], v[44:47]
	v_mfma_f32_16x16x32_bf16 v[32:35], v[146:149], v[208:211], v[32:35]
	v_mfma_f32_16x16x32_bf16 v[28:31], v[154:157], v[208:211], v[28:31]
	v_mfma_f32_16x16x32_bf16 v[16:19], v[146:149], v[216:219], v[16:19]
	v_mfma_f32_16x16x32_bf16 v[12:15], v[154:157], v[216:219], v[12:15]
	v_mfma_f32_16x16x32_bf16 v[56:59], v[164:167], v[180:183], v[56:59]
	v_mfma_f32_16x16x32_bf16 v[52:55], v[172:175], v[180:183], v[52:55]
	v_mfma_f32_16x16x32_bf16 v[40:43], v[164:167], v[188:191], v[40:43]
	v_mfma_f32_16x16x32_bf16 v[36:39], v[172:175], v[188:191], v[36:39]
	v_mfma_f32_16x16x32_bf16 v[24:27], v[164:167], v[204:207], v[24:27]
	v_mfma_f32_16x16x32_bf16 v[20:23], v[172:175], v[204:207], v[20:23]
	v_mfma_f32_16x16x32_bf16 v[8:11], v[164:167], v[212:215], v[8:11]
	v_mfma_f32_16x16x32_bf16 v[4:7], v[172:175], v[212:215], v[4:7]
	v_mfma_f32_16x16x32_bf16 v[56:59], v[168:171], v[184:187], v[56:59]
	v_mfma_f32_16x16x32_bf16 v[52:55], v[176:179], v[184:187], v[52:55]
	v_mfma_f32_16x16x32_bf16 v[40:43], v[168:171], v[192:195], v[40:43]
	v_mfma_f32_16x16x32_bf16 v[36:39], v[176:179], v[192:195], v[36:39]
	v_mfma_f32_16x16x32_bf16 v[24:27], v[168:171], v[208:211], v[24:27]
	v_mfma_f32_16x16x32_bf16 v[20:23], v[176:179], v[208:211], v[20:23]
	v_mfma_f32_16x16x32_bf16 v[8:11], v[168:171], v[216:219], v[8:11]
	v_mfma_f32_16x16x32_bf16 v[4:7], v[176:179], v[216:219], v[4:7]
	s_setprio 0
	s_barrier
	s_add_i32 s30, s30, 2
	s_add_u32 s26, s26, 0x100
	s_addc_u32 s27, s27, 0
	s_cmp_gt_u32 s30, 29
	s_mov_b64 s[58:59], s[60:61]
	s_cbranch_scc0 .LBB0_544
	s_and_b64 vcc, exec, s[14:15]
	s_cbranch_vccz .LBB0_547
	s_barrier

;     __device__ bool next(int i, Unit& u) const { if (i >= 2) return false; const int x = c & 7, j = c >> 3; u.pm = 32 * i + 4 * x + (j & 3); u.pn = j >> 2; return true; }
; #define PG8_STAGE(bufoff, gbase, voff) do { _Pragma("unroll") for (int _i = 0; _i < 2; ++_i) \
;         __builtin_amdgcn_global_load_lds((const unsigned*)((const char*)(gbase) + (voff)[_i]), (LAS unsigned*)(lds + (bufoff) + ldsw + _i * 8192), 16, 0, 0); } while (0)
; #define PG8_LDA(dst, b, h) do { _Pragma("unroll") for (int m = 0; m < 4; ++m) _Pragma("unroll") for (int k = 0; k < 2; ++k) dst[m][k] = *(const LAS bf16x8*)(lds + PG8_SA(b, h) + aoff + m * 2048 + k * 1024); } while (0)
; #define PG8_LDB(dst, b, h) do { _Pragma("unroll") for (int n = 0; n < 2; ++n) _Pragma("unroll") for (int k = 0; k < 2; ++k) dst[n][k] = *(const LAS bf16x8*)(lds + PG8_SB(b, h) + boff + n * 2048 + k * 1024); } while (0)
; #define PG8_WAIT_V(n) asm volatile("s_waitcnt vmcnt(" #n ")" ::: "memory")
; #define PG8_WAIT_L(n) asm volatile("s_waitcnt lgkmcnt(" #n ")" ::: "memory")
; #define PG8_BAR __builtin_amdgcn_s_barrier()
; template <class Epi, class Sched, bool ALIGN_EPI = true>
; __device__ __forceinline__ void gemm_phase(LAS unsigned char* lds, const Gemm g, const Sched& S, const Epi& E) {
;     ...
;         const bool has_next = S.next(ui + 1, nxt);
;         const char* nA = has_next ? (const char*)g.A + ((size_t)nxt.pm * BM * g.lda + (size_t)nxt.pn * g.a_pn_off) * 2 : cA; const char* nB = has_next ? (const char*)g.Bt + (size_t)nxt.pn * BM * g.ldb * 2 : cB;
;         for (int t = 0; t < nt; t += 2) {
;             const bool last = (t == nt - 2);
;             const char* a1 = cA + (size_t)(t + 1) * kstep;
;             const char* a2 = last ? nA : cA + (size_t)(t + 2) * kstep; const char* b2 = last ? nB : cB + (size_t)(t + 2) * kstep;
;             const char* a3 = a2 + kstep; const char* b3 = b2 + kstep;
;             PG8_LDB(B0, 0, 0); PG8_LDB(B1, 0, 1); PG8_SCHED; PG8_LDA(At, 0, 0); PG8_STAGE(PG8_SA(1, 1), a1 + hA, voffA);
;             PG8_WAIT_V(8); PG8_WAIT_L(0); PG8_BAR; PG8_MMA(0, 0, At, B0); PG8_MMA(0, 1, At, B1); PG8_BAR; PG8_SCHED;
;             PG8_LDA(At, 0, 1); PG8_STAGE(PG8_SB(0, 0), b2, voffB); PG8_STAGE(PG8_SB(0, 1), b2 + hB, voffB); PG8_STAGE(PG8_SA(0, 0), a2, voffA);
;             PG8_WAIT_V(8); PG8_WAIT_L(0); PG8_BAR; PG8_MMA(1, 0, At, B0); PG8_MMA(1, 1, At, B1); PG8_BAR; PG8_SCHED;
.LBB0_666:
	s_mov_b32 s82, s81
	s_or_b32 s81, s17, s68
	s_mov_b64 s[10:11], s[12:13]
	s_lshl_b32 s12, s81, 20
	s_add_u32 s12, s28, s12
	s_addc_u32 s13, s29, 0
	s_and_b64 s[16:17], s[38:39], exec
	s_cselect_b32 s16, s13, s11
	s_cselect_b32 s17, s12, s10
	s_add_u32 s18, s10, 0x100
	s_addc_u32 s19, s11, 0
	s_add_u32 s10, s10, 0x80080
	s_addc_u32 s11, s11, 0
	v_lshl_add_u64 v[132:133], s[10:11], 0, v[166:167]
	v_lshl_add_u64 v[134:135], s[10:11], 0, v[168:169]
	s_mov_b32 s24, -2
	s_mov_b64 s[10:11], 0
	s_add_u32 vcc_lo, s10, 0x100
	s_addc_u32 vcc_hi, s11, 0
	s_add_u32 s25, s18, s10
	s_addc_u32 s26, s19, s11
	s_add_i32 s27, 0, 0x10000
	s_cmp_eq_u32 s24, 28
	s_cselect_b32 s65, s16, s26
	s_cselect_b32 s26, 0, vcc_lo
	s_cselect_b32 s64, s17, s25
	s_cselect_b32 s25, 0, vcc_hi
	s_add_u32 s62, s14, s26
	v_add_u32_e32 v160, s27, v186
	s_addc_u32 s63, s15, s25
	s_add_i32 s25, 0, 0x14000
	ds_read_b128 v[136:139], v160
	ds_read_b128 v[140:143], v160 offset:1024
	ds_read_b128 v[144:147], v160 offset:2048
	ds_read_b128 v[170:173], v160 offset:3072
	v_add_u32_e32 v160, s25, v186
	ds_read_b128 v[174:177], v160
	ds_read_b128 v[178:181], v160 offset:1024
	ds_read_b128 v[182:185], v160 offset:2048
	ds_read_b128 v[208:211], v160 offset:3072
	v_lshl_add_u64 v[244:245], v[132:133], 0, s[10:11]
	s_add_i32 m0, s53, 0xc000
	ds_read_b128 v[212:215], v197
	ds_read_b128 v[216:219], v197 offset:1024
	ds_read_b128 v[220:223], v197 offset:2048
	ds_read_b128 v[224:227], v197 offset:3072
	ds_read_b128 v[228:231], v197 offset:4096
	ds_read_b128 v[232:235], v197 offset:5120
	ds_read_b128 v[236:239], v197 offset:6144
	ds_read_b128 v[240:243], v197 offset:7168
	global_load_lds_dwordx4 v[244:245], off
	v_lshl_add_u64 v[244:245], v[134:135], 0, s[10:11]
	s_add_i32 m0, s53, 0xe000
	s_nop 0
	global_load_lds_dwordx4 v[244:245], off
	s_waitcnt vmcnt(8)
	s_waitcnt lgkmcnt(0)
	s_barrier
	s_setprio 1
	s_waitcnt lgkmcnt(0)
	v_mfma_f32_16x16x32_bf16 v[36:39], v[136:139], v[212:215], 0
	v_mfma_f32_16x16x32_bf16 v[36:39], v[140:143], v[216:219], v[36:39]
	v_mfma_f32_16x16x32_bf16 v[40:43], v[144:147], v[212:215], 0
	v_mfma_f32_16x16x32_bf16 v[40:43], v[170:173], v[216:219], v[40:43]
	v_mfma_f32_16x16x32_bf16 v[68:71], v[136:139], v[220:223], 0
	v_mfma_f32_16x16x32_bf16 v[68:71], v[140:143], v[224:227], v[68:71]
	v_mfma_f32_16x16x32_bf16 v[72:75], v[144:147], v[220:223], 0
	v_mfma_f32_16x16x32_bf16 v[72:75], v[170:173], v[224:227], v[72:75]
	v_mfma_f32_16x16x32_bf16 v[100:103], v[136:139], v[228:231], 0
	v_mfma_f32_16x16x32_bf16 v[100:103], v[140:143], v[232:235], v[100:103]
	v_mfma_f32_16x16x32_bf16 v[104:107], v[144:147], v[228:231], 0
	v_mfma_f32_16x16x32_bf16 v[104:107], v[170:173], v[232:235], v[104:107]
	v_mfma_f32_16x16x32_bf16 v[128:131], v[136:139], v[236:239], 0
	v_mfma_f32_16x16x32_bf16 v[128:131], v[140:143], v[240:243], v[128:131]
	v_mfma_f32_16x16x32_bf16 v[124:127], v[144:147], v[236:239], 0
	v_mfma_f32_16x16x32_bf16 v[124:127], v[170:173], v[240:243], v[124:127]
	v_mfma_f32_16x16x32_bf16 v[8:11], v[174:177], v[212:215], 0
	v_mfma_f32_16x16x32_bf16 v[8:11], v[178:181], v[216:219], v[8:11]
	v_mfma_f32_16x16x32_bf16 v[4:7], v[182:185], v[212:215], 0
	v_mfma_f32_16x16x32_bf16 v[4:7], v[208:211], v[216:219], v[4:7]
	v_mfma_f32_16x16x32_bf16 v[32:35], v[174:177], v[220:223], 0
	v_mfma_f32_16x16x32_bf16 v[32:35], v[178:181], v[224:227], v[32:35]
	v_mfma_f32_16x16x32_bf16 v[28:31], v[182:185], v[220:223], 0
	v_mfma_f32_16x16x32_bf16 v[28:31], v[208:211], v[224:227], v[28:31]
	v_mfma_f32_16x16x32_bf16 v[56:59], v[174:177], v[228:231], 0
	v_mfma_f32_16x16x32_bf16 v[56:59], v[178:181], v[232:235], v[56:59]
	v_mfma_f32_16x16x32_bf16 v[52:55], v[182:185], v[228:231], 0
	v_mfma_f32_16x16x32_bf16 v[52:55], v[208:211], v[232:235], v[52:55]
	v_mfma_f32_16x16x32_bf16 v[80:83], v[174:177], v[236:239], 0
	v_mfma_f32_16x16x32_bf16 v[80:83], v[178:181], v[240:243], v[80:83]
	s_setprio 2
	s_barrier
	v_mfma_f32_16x16x32_bf16 v[76:79], v[182:185], v[236:239], 0
	v_mfma_f32_16x16x32_bf16 v[76:79], v[208:211], v[240:243], v[76:79]
	s_setprio 0
	s_add_i32 s10, s27, s67
	v_lshl_add_u64 v[244:245], s[62:63], 0, v[2:3]
	s_mov_b32 m0, s10
	ds_read_b128 v[212:215], v197 offset:16384
	ds_read_b128 v[216:219], v197 offset:17408
	ds_read_b128 v[220:223], v197 offset:18432
	ds_read_b128 v[224:227], v197 offset:19456
	ds_read_b128 v[228:231], v197 offset:20480
	ds_read_b128 v[232:235], v197 offset:21504
	ds_read_b128 v[236:239], v197 offset:22528
	ds_read_b128 v[240:243], v197 offset:23552
	global_load_lds_dwordx4 v[244:245], off
	s_add_i32 m0, s10, 0x2000
	s_add_u32 s10, s62, 0x80000
	v_lshl_add_u64 v[246:247], s[62:63], 0, v[150:151]
	s_addc_u32 s11, s63, 0
	s_add_i32 s25, s25, s67
	global_load_lds_dwordx4 v[246:247], off
	v_lshl_add_u64 v[248:249], s[10:11], 0, v[2:3]
	s_mov_b32 m0, s25
	v_lshl_add_u64 v[160:161], s[64:65], 0, v[148:149]
	global_load_lds_dwordx4 v[248:249], off
	v_lshl_add_u64 v[248:249], s[10:11], 0, v[150:151]
	s_add_i32 m0, s25, 0x2000
	s_nop 0
	global_load_lds_dwordx4 v[248:249], off
	v_lshl_add_u64 v[248:249], s[64:65], 0, v[0:1]
	s_mov_b32 m0, s53
	s_nop 0
	global_load_lds_dwordx4 v[248:249], off
	s_mov_b32 m0, s66
	s_nop 0
	global_load_lds_dwordx4 v[160:161], off
	s_waitcnt vmcnt(8)
	s_waitcnt lgkmcnt(0)
	s_barrier
; #define PG8_STAGE(bufoff, gbase, voff) do { _Pragma("unroll") for (int _i = 0; _i < 2; ++_i) \
;         __builtin_amdgcn_global_load_lds((const unsigned*)((const char*)(gbase) + (voff)[_i]), (LAS unsigned*)(lds + (bufoff) + ldsw + _i * 8192), 16, 0, 0); } while (0)
; #define PG8_LDA(dst, b, h) do { _Pragma("unroll") for (int m = 0; m < 4; ++m) _Pragma("unroll") for (int k = 0; k < 2; ++k) dst[m][k] = *(const LAS bf16x8*)(lds + PG8_SA(b, h) + aoff + m * 2048 + k * 1024); } while (0)
; #define PG8_LDB(dst, b, h) do { _Pragma("unroll") for (int n = 0; n < 2; ++n) _Pragma("unroll") for (int k = 0; k < 2; ++k) dst[n][k] = *(const LAS bf16x8*)(lds + PG8_SB(b, h) + boff + n * 2048 + k * 1024); } while (0)
; #define PG8_MMA(ai, bj, At, Bt) do { __builtin_amdgcn_s_setprio(1); _Pragma("unroll") for (int m = 0; m < 4; ++m) _Pragma("unroll") for (int n = 0; n < 2; ++n) _Pragma("unroll") for (int k = 0; k < 2; ++k) \
;         acc[ai][bj][m][n] = __builtin_amdgcn_mfma_f32_16x16x32_bf16(Bt[n][k], At[m][k], acc[ai][bj][m][n], 0, 0, 0); __builtin_amdgcn_s_setprio(0); } while (0)
; #define PG8_WAIT_V(n) asm volatile("s_waitcnt vmcnt(" #n ")" ::: "memory")
; #define PG8_WAIT_L(n) asm volatile("s_waitcnt lgkmcnt(" #n ")" ::: "memory")
; #define PG8_BAR __builtin_amdgcn_s_barrier()
; #define PG8_SCHED __builtin_amdgcn_sched_barrier(0)
; template <class Epi, class Sched, bool ALIGN_EPI = true>
; __device__ __forceinline__ void gemm_phase(LAS unsigned char* lds, const Gemm g, const Sched& S, const Epi& E) {
;     ...
;             PG8_WAIT_V(8); PG8_WAIT_L(0); PG8_BAR; PG8_MMA(1, 0, At, B0); PG8_MMA(1, 1, At, B1); PG8_BAR; PG8_SCHED;
;             PG8_LDB(B0, 1, 0); PG8_LDB(B1, 1, 1); PG8_SCHED; PG8_LDA(At, 1, 0); PG8_STAGE(PG8_SA(0, 1), a2 + hA, voffA);
;             PG8_WAIT_V(8); PG8_WAIT_L(0); PG8_BAR; PG8_MMA(0, 0, At, B0); PG8_MMA(0, 1, At, B1); PG8_BAR; PG8_SCHED;
	s_setprio 1
	s_waitcnt lgkmcnt(0)
	v_mfma_f32_16x16x32_bf16 v[120:123], v[136:139], v[212:215], 0
	v_mfma_f32_16x16x32_bf16 v[120:123], v[140:143], v[216:219], v[120:123]
	v_mfma_f32_16x16x32_bf16 v[116:119], v[144:147], v[212:215], 0
	v_mfma_f32_16x16x32_bf16 v[116:119], v[170:173], v[216:219], v[116:119]
	v_mfma_f32_16x16x32_bf16 v[96:99], v[136:139], v[220:223], 0
	v_mfma_f32_16x16x32_bf16 v[96:99], v[140:143], v[224:227], v[96:99]
	v_mfma_f32_16x16x32_bf16 v[92:95], v[144:147], v[220:223], 0
	v_mfma_f32_16x16x32_bf16 v[92:95], v[170:173], v[224:227], v[92:95]
	v_mfma_f32_16x16x32_bf16 v[64:67], v[136:139], v[228:231], 0
	v_mfma_f32_16x16x32_bf16 v[64:67], v[140:143], v[232:235], v[64:67]
	v_mfma_f32_16x16x32_bf16 v[60:63], v[144:147], v[228:231], 0
	v_mfma_f32_16x16x32_bf16 v[60:63], v[170:173], v[232:235], v[60:63]
	v_mfma_f32_16x16x32_bf16 v[24:27], v[136:139], v[236:239], 0
	v_mfma_f32_16x16x32_bf16 v[24:27], v[140:143], v[240:243], v[24:27]
	v_mfma_f32_16x16x32_bf16 v[20:23], v[144:147], v[236:239], 0
	v_mfma_f32_16x16x32_bf16 v[20:23], v[170:173], v[240:243], v[20:23]
	v_mfma_f32_16x16x32_bf16 v[112:115], v[174:177], v[212:215], 0
	v_mfma_f32_16x16x32_bf16 v[112:115], v[178:181], v[216:219], v[112:115]
	v_mfma_f32_16x16x32_bf16 v[108:111], v[182:185], v[212:215], 0
	v_mfma_f32_16x16x32_bf16 v[108:111], v[208:211], v[216:219], v[108:111]
	v_mfma_f32_16x16x32_bf16 v[88:91], v[174:177], v[220:223], 0
	v_mfma_f32_16x16x32_bf16 v[88:91], v[178:181], v[224:227], v[88:91]
	v_mfma_f32_16x16x32_bf16 v[84:87], v[182:185], v[220:223], 0
	v_mfma_f32_16x16x32_bf16 v[84:87], v[208:211], v[224:227], v[84:87]
	v_mfma_f32_16x16x32_bf16 v[48:51], v[174:177], v[228:231], 0
	v_mfma_f32_16x16x32_bf16 v[48:51], v[178:181], v[232:235], v[48:51]
	v_mfma_f32_16x16x32_bf16 v[44:47], v[182:185], v[228:231], 0
	v_mfma_f32_16x16x32_bf16 v[44:47], v[208:211], v[232:235], v[44:47]
	v_mfma_f32_16x16x32_bf16 v[16:19], v[174:177], v[236:239], 0
	v_mfma_f32_16x16x32_bf16 v[16:19], v[178:181], v[240:243], v[16:19]
	s_setprio 2
	s_barrier
	v_mfma_f32_16x16x32_bf16 v[12:15], v[182:185], v[236:239], 0
	v_mfma_f32_16x16x32_bf16 v[12:15], v[208:211], v[240:243], v[12:15]
	s_setprio 0
	s_add_i32 s25, 0, 0x18000
	v_add_u32_e32 v162, s25, v186
	s_add_i32 s26, 0, 0x1c000
	ds_read_b128 v[136:139], v162
	ds_read_b128 v[140:143], v162 offset:1024
	ds_read_b128 v[144:147], v162 offset:2048
	ds_read_b128 v[170:173], v162 offset:3072
	v_add_u32_e32 v162, s26, v186
	ds_read_b128 v[174:177], v162
	ds_read_b128 v[178:181], v162 offset:1024
	ds_read_b128 v[182:185], v162 offset:2048
	ds_read_b128 v[208:211], v162 offset:3072
	s_add_u32 s10, s64, 0x80000
	s_addc_u32 s11, s65, 0
	s_mov_b32 m0, s75
	v_lshl_add_u64 v[162:163], s[10:11], 0, v[0:1]
	ds_read_b128 v[212:215], v197 offset:32768
	ds_read_b128 v[216:219], v197 offset:33792
	ds_read_b128 v[220:223], v197 offset:34816
	ds_read_b128 v[224:227], v197 offset:35840
	ds_read_b128 v[228:231], v197 offset:36864
	ds_read_b128 v[232:235], v197 offset:37888
	ds_read_b128 v[236:239], v197 offset:38912
	ds_read_b128 v[240:243], v197 offset:39936
	global_load_lds_dwordx4 v[162:163], off
	v_lshl_add_u64 v[162:163], s[10:11], 0, v[148:149]
	s_mov_b32 m0, s76
	s_nop 0
	global_load_lds_dwordx4 v[162:163], off
	s_waitcnt vmcnt(8)
	s_waitcnt lgkmcnt(0)
	s_barrier
	s_setprio 1
	s_waitcnt lgkmcnt(0)
	v_mfma_f32_16x16x32_bf16 v[36:39], v[136:139], v[212:215], v[36:39]
	v_mfma_f32_16x16x32_bf16 v[36:39], v[140:143], v[216:219], v[36:39]
	v_mfma_f32_16x16x32_bf16 v[40:43], v[144:147], v[212:215], v[40:43]
	v_mfma_f32_16x16x32_bf16 v[40:43], v[170:173], v[216:219], v[40:43]
	v_mfma_f32_16x16x32_bf16 v[68:71], v[136:139], v[220:223], v[68:71]
	v_mfma_f32_16x16x32_bf16 v[68:71], v[140:143], v[224:227], v[68:71]
	v_mfma_f32_16x16x32_bf16 v[72:75], v[144:147], v[220:223], v[72:75]
	v_mfma_f32_16x16x32_bf16 v[72:75], v[170:173], v[224:227], v[72:75]
	v_mfma_f32_16x16x32_bf16 v[100:103], v[136:139], v[228:231], v[100:103]
	v_mfma_f32_16x16x32_bf16 v[100:103], v[140:143], v[232:235], v[100:103]
	v_mfma_f32_16x16x32_bf16 v[104:107], v[144:147], v[228:231], v[104:107]
	v_mfma_f32_16x16x32_bf16 v[104:107], v[170:173], v[232:235], v[104:107]
	v_mfma_f32_16x16x32_bf16 v[128:131], v[136:139], v[236:239], v[128:131]
	v_mfma_f32_16x16x32_bf16 v[128:131], v[140:143], v[240:243], v[128:131]
	v_mfma_f32_16x16x32_bf16 v[124:127], v[144:147], v[236:239], v[124:127]
	v_mfma_f32_16x16x32_bf16 v[124:127], v[170:173], v[240:243], v[124:127]
	v_mfma_f32_16x16x32_bf16 v[8:11], v[174:177], v[212:215], v[8:11]
	v_mfma_f32_16x16x32_bf16 v[8:11], v[178:181], v[216:219], v[8:11]
	v_mfma_f32_16x16x32_bf16 v[4:7], v[182:185], v[212:215], v[4:7]
	v_mfma_f32_16x16x32_bf16 v[4:7], v[208:211], v[216:219], v[4:7]
	v_mfma_f32_16x16x32_bf16 v[32:35], v[174:177], v[220:223], v[32:35]
	v_mfma_f32_16x16x32_bf16 v[32:35], v[178:181], v[224:227], v[32:35]
	v_mfma_f32_16x16x32_bf16 v[28:31], v[182:185], v[220:223], v[28:31]
	v_mfma_f32_16x16x32_bf16 v[28:31], v[208:211], v[224:227], v[28:31]
	v_mfma_f32_16x16x32_bf16 v[56:59], v[174:177], v[228:231], v[56:59]
	v_mfma_f32_16x16x32_bf16 v[56:59], v[178:181], v[232:235], v[56:59]
	v_mfma_f32_16x16x32_bf16 v[52:55], v[182:185], v[228:231], v[52:55]
	v_mfma_f32_16x16x32_bf16 v[52:55], v[208:211], v[232:235], v[52:55]
	v_mfma_f32_16x16x32_bf16 v[80:83], v[174:177], v[236:239], v[80:83]
	v_mfma_f32_16x16x32_bf16 v[80:83], v[178:181], v[240:243], v[80:83]
	s_setprio 2
	s_barrier
; #define PG8_STAGE(bufoff, gbase, voff) do { _Pragma("unroll") for (int _i = 0; _i < 2; ++_i) \
;         __builtin_amdgcn_global_load_lds((const unsigned*)((const char*)(gbase) + (voff)[_i]), (LAS unsigned*)(lds + (bufoff) + ldsw + _i * 8192), 16, 0, 0); } while (0)
; #define PG8_LDA(dst, b, h) do { _Pragma("unroll") for (int m = 0; m < 4; ++m) _Pragma("unroll") for (int k = 0; k < 2; ++k) dst[m][k] = *(const LAS bf16x8*)(lds + PG8_SA(b, h) + aoff + m * 2048 + k * 1024); } while (0)
; #define PG8_LDB(dst, b, h) do { _Pragma("unroll") for (int n = 0; n < 2; ++n) _Pragma("unroll") for (int k = 0; k < 2; ++k) dst[n][k] = *(const LAS bf16x8*)(lds + PG8_SB(b, h) + boff + n * 2048 + k * 1024); } while (0)
; #define PG8_MMA(ai, bj, At, Bt) do { __builtin_amdgcn_s_setprio(1); _Pragma("unroll") for (int m = 0; m < 4; ++m) _Pragma("unroll") for (int n = 0; n < 2; ++n) _Pragma("unroll") for (int k = 0; k < 2; ++k) \
;         acc[ai][bj][m][n] = __builtin_amdgcn_mfma_f32_16x16x32_bf16(Bt[n][k], At[m][k], acc[ai][bj][m][n], 0, 0, 0); __builtin_amdgcn_s_setprio(0); } while (0)
; #define PG8_WAIT_V(n) asm volatile("s_waitcnt vmcnt(" #n ")" ::: "memory")
; #define PG8_BAR __builtin_amdgcn_s_barrier()
; template <class Epi, class Sched, bool ALIGN_EPI = true>
; __device__ __forceinline__ void gemm_phase(LAS unsigned char* lds, const Gemm g, const Sched& S, const Epi& E) {
;     ...
;             PG8_LDB(B0, 0, 0); PG8_LDB(B1, 0, 1); PG8_SCHED; PG8_LDA(At, 0, 0); PG8_STAGE(PG8_SA(1, 1), a1 + hA, voffA);
;             PG8_WAIT_V(8); PG8_WAIT_L(0); PG8_BAR; PG8_MMA(0, 0, At, B0); PG8_MMA(0, 1, At, B1); PG8_BAR; PG8_SCHED;
;             PG8_LDA(At, 0, 1); PG8_STAGE(PG8_SB(0, 0), b2, voffB); PG8_STAGE(PG8_SB(0, 1), b2 + hB, voffB); PG8_STAGE(PG8_SA(0, 0), a2, voffA);
;             PG8_WAIT_V(8); PG8_WAIT_L(0); PG8_BAR; PG8_MMA(1, 0, At, B0); PG8_MMA(1, 1, At, B1); PG8_BAR; PG8_SCHED;
;             PG8_LDB(B0, 1, 0); PG8_LDB(B1, 1, 1); PG8_SCHED; PG8_LDA(At, 1, 0); PG8_STAGE(PG8_SA(0, 1), a2 + hA, voffA);
;             PG8_WAIT_V(8); PG8_WAIT_L(0); PG8_BAR; PG8_MMA(0, 0, At, B0); PG8_MMA(0, 1, At, B1); PG8_BAR; PG8_SCHED;
;             PG8_LDA(At, 1, 1); PG8_STAGE(PG8_SB(1, 0), b3, voffB); PG8_STAGE(PG8_SB(1, 1), b3 + hB, voffB); PG8_STAGE(PG8_SA(1, 0), a3, voffA);
;             PG8_WAIT_V(8); PG8_WAIT_L(0); PG8_BAR; PG8_MMA(1, 0, At, B0); PG8_MMA(1, 1, At, B1); PG8_BAR; PG8_SCHED;
	v_mfma_f32_16x16x32_bf16 v[76:79], v[182:185], v[236:239], v[76:79]
	v_mfma_f32_16x16x32_bf16 v[76:79], v[208:211], v[240:243], v[76:79]
	s_setprio 0
	s_add_i32 s10, s25, s67
	v_lshl_add_u64 v[162:163], v[244:245], 0, s[86:87]
	s_mov_b32 m0, s10
	ds_read_b128 v[212:215], v197 offset:49152
	ds_read_b128 v[216:219], v197 offset:50176
	ds_read_b128 v[220:223], v197 offset:51200
	ds_read_b128 v[224:227], v197 offset:52224
	ds_read_b128 v[228:231], v197 offset:53248
	ds_read_b128 v[232:235], v197 offset:54272
	ds_read_b128 v[236:239], v197 offset:55296
	ds_read_b128 v[240:243], v197 offset:56320
	global_load_lds_dwordx4 v[162:163], off
	s_add_i32 m0, s10, 0x2000
	s_add_u32 s10, s62, 0x80080
	v_lshl_add_u64 v[162:163], v[246:247], 0, s[86:87]
	s_addc_u32 s11, s63, 0
	s_add_i32 s25, s26, s67
	global_load_lds_dwordx4 v[162:163], off
	v_lshl_add_u64 v[162:163], s[10:11], 0, v[2:3]
	s_mov_b32 m0, s25
	v_lshl_add_u64 v[160:161], v[160:161], 0, s[86:87]
	global_load_lds_dwordx4 v[162:163], off
	v_lshl_add_u64 v[162:163], s[10:11], 0, v[150:151]
	s_add_i32 m0, s25, 0x2000
	s_nop 0
	global_load_lds_dwordx4 v[162:163], off
	v_lshl_add_u64 v[162:163], v[248:249], 0, s[86:87]
	s_mov_b32 m0, s79
	s_nop 0
	global_load_lds_dwordx4 v[162:163], off
	s_mov_b32 m0, s80
	s_nop 0
	global_load_lds_dwordx4 v[160:161], off
	s_waitcnt vmcnt(8)
	s_waitcnt lgkmcnt(0)
	s_barrier
	s_setprio 1
	s_waitcnt lgkmcnt(0)
	v_mfma_f32_16x16x32_bf16 v[120:123], v[136:139], v[212:215], v[120:123]
	v_mfma_f32_16x16x32_bf16 v[120:123], v[140:143], v[216:219], v[120:123]
	v_mfma_f32_16x16x32_bf16 v[116:119], v[144:147], v[212:215], v[116:119]
	v_mfma_f32_16x16x32_bf16 v[116:119], v[170:173], v[216:219], v[116:119]
	v_mfma_f32_16x16x32_bf16 v[96:99], v[136:139], v[220:223], v[96:99]
	v_mfma_f32_16x16x32_bf16 v[96:99], v[140:143], v[224:227], v[96:99]
	v_mfma_f32_16x16x32_bf16 v[92:95], v[144:147], v[220:223], v[92:95]
	v_mfma_f32_16x16x32_bf16 v[92:95], v[170:173], v[224:227], v[92:95]
	v_mfma_f32_16x16x32_bf16 v[64:67], v[136:139], v[228:231], v[64:67]
	v_mfma_f32_16x16x32_bf16 v[64:67], v[140:143], v[232:235], v[64:67]
	v_mfma_f32_16x16x32_bf16 v[60:63], v[144:147], v[228:231], v[60:63]
	v_mfma_f32_16x16x32_bf16 v[60:63], v[170:173], v[232:235], v[60:63]
	v_mfma_f32_16x16x32_bf16 v[24:27], v[136:139], v[236:239], v[24:27]
	v_mfma_f32_16x16x32_bf16 v[24:27], v[140:143], v[240:243], v[24:27]
	v_mfma_f32_16x16x32_bf16 v[20:23], v[144:147], v[236:239], v[20:23]
	v_mfma_f32_16x16x32_bf16 v[20:23], v[170:173], v[240:243], v[20:23]
	v_mfma_f32_16x16x32_bf16 v[112:115], v[174:177], v[212:215], v[112:115]
	v_mfma_f32_16x16x32_bf16 v[112:115], v[178:181], v[216:219], v[112:115]
	v_mfma_f32_16x16x32_bf16 v[108:111], v[182:185], v[212:215], v[108:111]
	v_mfma_f32_16x16x32_bf16 v[108:111], v[208:211], v[216:219], v[108:111]
	v_mfma_f32_16x16x32_bf16 v[88:91], v[174:177], v[220:223], v[88:91]
	v_mfma_f32_16x16x32_bf16 v[88:91], v[178:181], v[224:227], v[88:91]
	v_mfma_f32_16x16x32_bf16 v[84:87], v[182:185], v[220:223], v[84:87]
	v_mfma_f32_16x16x32_bf16 v[84:87], v[208:211], v[224:227], v[84:87]
	v_mfma_f32_16x16x32_bf16 v[48:51], v[174:177], v[228:231], v[48:51]
	v_mfma_f32_16x16x32_bf16 v[48:51], v[178:181], v[232:235], v[48:51]
	v_mfma_f32_16x16x32_bf16 v[44:47], v[182:185], v[228:231], v[44:47]
	v_mfma_f32_16x16x32_bf16 v[44:47], v[208:211], v[232:235], v[44:47]
	v_mfma_f32_16x16x32_bf16 v[16:19], v[174:177], v[236:239], v[16:19]
	v_mfma_f32_16x16x32_bf16 v[16:19], v[178:181], v[240:243], v[16:19]
	s_setprio 2
	s_barrier
	v_mfma_f32_16x16x32_bf16 v[12:15], v[182:185], v[236:239], v[12:15]
	v_mfma_f32_16x16x32_bf16 v[12:15], v[208:211], v[240:243], v[12:15]
	s_setprio 0
	s_add_i32 s24, s24, 2
	s_cmp_gt_u32 s24, 29
	s_mov_b64 s[10:11], vcc
	s_cbranch_scc1 .Lpeel_exit_667
.LBB0_667:
	s_add_u32 vcc_lo, s10, 0x100
	s_addc_u32 vcc_hi, s11, 0
	s_add_u32 s25, s18, s10
	s_addc_u32 s26, s19, s11
	s_add_i32 s27, 0, 0x10000
	s_cmp_eq_u32 s24, 28
	s_cselect_b32 s65, s16, s26
	s_cselect_b32 s26, 0, vcc_lo
	s_cselect_b32 s64, s17, s25
	s_cselect_b32 s25, 0, vcc_hi
	s_add_u32 s62, s14, s26
	v_add_u32_e32 v160, s27, v186
	s_addc_u32 s63, s15, s25
	s_add_i32 s25, 0, 0x14000
	ds_read_b128 v[136:139], v160
	ds_read_b128 v[140:143], v160 offset:1024
	ds_read_b128 v[144:147], v160 offset:2048
	ds_read_b128 v[170:173], v160 offset:3072
	v_add_u32_e32 v160, s25, v186
	ds_read_b128 v[174:177], v160
	ds_read_b128 v[178:181], v160 offset:1024
	ds_read_b128 v[182:185], v160 offset:2048
	ds_read_b128 v[208:211], v160 offset:3072
	v_lshl_add_u64 v[244:245], v[132:133], 0, s[10:11]
	s_add_i32 m0, s53, 0xc000
	ds_read_b128 v[212:215], v197
	ds_read_b128 v[216:219], v197 offset:1024
	ds_read_b128 v[220:223], v197 offset:2048
	ds_read_b128 v[224:227], v197 offset:3072
	ds_read_b128 v[228:231], v197 offset:4096
	ds_read_b128 v[232:235], v197 offset:5120
	ds_read_b128 v[236:239], v197 offset:6144
	ds_read_b128 v[240:243], v197 offset:7168
	global_load_lds_dwordx4 v[244:245], off
	v_lshl_add_u64 v[244:245], v[134:135], 0, s[10:11]
	s_add_i32 m0, s53, 0xe000
	s_nop 0
	global_load_lds_dwordx4 v[244:245], off
	s_waitcnt vmcnt(8)
	s_waitcnt lgkmcnt(0)
	s_barrier
; #define PG8_STAGE(bufoff, gbase, voff) do { _Pragma("unroll") for (int _i = 0; _i < 2; ++_i) \
;         __builtin_amdgcn_global_load_lds((const unsigned*)((const char*)(gbase) + (voff)[_i]), (LAS unsigned*)(lds + (bufoff) + ldsw + _i * 8192), 16, 0, 0); } while (0)
; #define PG8_LDA(dst, b, h) do { _Pragma("unroll") for (int m = 0; m < 4; ++m) _Pragma("unroll") for (int k = 0; k < 2; ++k) dst[m][k] = *(const LAS bf16x8*)(lds + PG8_SA(b, h) + aoff + m * 2048 + k * 1024); } while (0)
; #define PG8_MMA(ai, bj, At, Bt) do { __builtin_amdgcn_s_setprio(1); _Pragma("unroll") for (int m = 0; m < 4; ++m) _Pragma("unroll") for (int n = 0; n < 2; ++n) _Pragma("unroll") for (int k = 0; k < 2; ++k) \
;         acc[ai][bj][m][n] = __builtin_amdgcn_mfma_f32_16x16x32_bf16(Bt[n][k], At[m][k], acc[ai][bj][m][n], 0, 0, 0); __builtin_amdgcn_s_setprio(0); } while (0)
; #define PG8_WAIT_V(n) asm volatile("s_waitcnt vmcnt(" #n ")" ::: "memory")
; #define PG8_WAIT_L(n) asm volatile("s_waitcnt lgkmcnt(" #n ")" ::: "memory")
; #define PG8_BAR __builtin_amdgcn_s_barrier()
; #define PG8_SCHED __builtin_amdgcn_sched_barrier(0)
; template <class Epi, class Sched, bool ALIGN_EPI = true>
; __device__ __forceinline__ void gemm_phase(LAS unsigned char* lds, const Gemm g, const Sched& S, const Epi& E) {
;     ...
;             PG8_WAIT_V(8); PG8_WAIT_L(0); PG8_BAR; PG8_MMA(0, 0, At, B0); PG8_MMA(0, 1, At, B1); PG8_BAR; PG8_SCHED;
;             PG8_LDA(At, 0, 1); PG8_STAGE(PG8_SB(0, 0), b2, voffB); PG8_STAGE(PG8_SB(0, 1), b2 + hB, voffB); PG8_STAGE(PG8_SA(0, 0), a2, voffA);
;             PG8_WAIT_V(8); PG8_WAIT_L(0); PG8_BAR; PG8_MMA(1, 0, At, B0); PG8_MMA(1, 1, At, B1); PG8_BAR; PG8_SCHED;
	s_setprio 1
	s_waitcnt lgkmcnt(0)
	v_mfma_f32_16x16x32_bf16 v[36:39], v[136:139], v[212:215], v[36:39]
	v_mfma_f32_16x16x32_bf16 v[36:39], v[140:143], v[216:219], v[36:39]
	v_mfma_f32_16x16x32_bf16 v[40:43], v[144:147], v[212:215], v[40:43]
	v_mfma_f32_16x16x32_bf16 v[40:43], v[170:173], v[216:219], v[40:43]
	v_mfma_f32_16x16x32_bf16 v[68:71], v[136:139], v[220:223], v[68:71]
	v_mfma_f32_16x16x32_bf16 v[68:71], v[140:143], v[224:227], v[68:71]
	v_mfma_f32_16x16x32_bf16 v[72:75], v[144:147], v[220:223], v[72:75]
	v_mfma_f32_16x16x32_bf16 v[72:75], v[170:173], v[224:227], v[72:75]
	v_mfma_f32_16x16x32_bf16 v[100:103], v[136:139], v[228:231], v[100:103]
	v_mfma_f32_16x16x32_bf16 v[100:103], v[140:143], v[232:235], v[100:103]
	v_mfma_f32_16x16x32_bf16 v[104:107], v[144:147], v[228:231], v[104:107]
	v_mfma_f32_16x16x32_bf16 v[104:107], v[170:173], v[232:235], v[104:107]
	v_mfma_f32_16x16x32_bf16 v[128:131], v[136:139], v[236:239], v[128:131]
	v_mfma_f32_16x16x32_bf16 v[128:131], v[140:143], v[240:243], v[128:131]
	v_mfma_f32_16x16x32_bf16 v[124:127], v[144:147], v[236:239], v[124:127]
	v_mfma_f32_16x16x32_bf16 v[124:127], v[170:173], v[240:243], v[124:127]
	v_mfma_f32_16x16x32_bf16 v[8:11], v[174:177], v[212:215], v[8:11]
	v_mfma_f32_16x16x32_bf16 v[8:11], v[178:181], v[216:219], v[8:11]
	v_mfma_f32_16x16x32_bf16 v[4:7], v[182:185], v[212:215], v[4:7]
	v_mfma_f32_16x16x32_bf16 v[4:7], v[208:211], v[216:219], v[4:7]
	v_mfma_f32_16x16x32_bf16 v[32:35], v[174:177], v[220:223], v[32:35]
	v_mfma_f32_16x16x32_bf16 v[32:35], v[178:181], v[224:227], v[32:35]
	v_mfma_f32_16x16x32_bf16 v[28:31], v[182:185], v[220:223], v[28:31]
	v_mfma_f32_16x16x32_bf16 v[28:31], v[208:211], v[224:227], v[28:31]
	v_mfma_f32_16x16x32_bf16 v[56:59], v[174:177], v[228:231], v[56:59]
	v_mfma_f32_16x16x32_bf16 v[56:59], v[178:181], v[232:235], v[56:59]
	v_mfma_f32_16x16x32_bf16 v[52:55], v[182:185], v[228:231], v[52:55]
	v_mfma_f32_16x16x32_bf16 v[52:55], v[208:211], v[232:235], v[52:55]
	v_mfma_f32_16x16x32_bf16 v[80:83], v[174:177], v[236:239], v[80:83]
	v_mfma_f32_16x16x32_bf16 v[80:83], v[178:181], v[240:243], v[80:83]
	s_setprio 2
	s_barrier
	v_mfma_f32_16x16x32_bf16 v[76:79], v[182:185], v[236:239], v[76:79]
	v_mfma_f32_16x16x32_bf16 v[76:79], v[208:211], v[240:243], v[76:79]
	s_setprio 0
	s_add_i32 s10, s27, s67
	v_lshl_add_u64 v[244:245], s[62:63], 0, v[2:3]
	s_mov_b32 m0, s10
	ds_read_b128 v[212:215], v197 offset:16384
	ds_read_b128 v[216:219], v197 offset:17408
	ds_read_b128 v[220:223], v197 offset:18432
	ds_read_b128 v[224:227], v197 offset:19456
	ds_read_b128 v[228:231], v197 offset:20480
	ds_read_b128 v[232:235], v197 offset:21504
	ds_read_b128 v[236:239], v197 offset:22528
	ds_read_b128 v[240:243], v197 offset:23552
	global_load_lds_dwordx4 v[244:245], off
	s_add_i32 m0, s10, 0x2000
	s_add_u32 s10, s62, 0x80000
	v_lshl_add_u64 v[246:247], s[62:63], 0, v[150:151]
	s_addc_u32 s11, s63, 0
	s_add_i32 s25, s25, s67
	global_load_lds_dwordx4 v[246:247], off
	v_lshl_add_u64 v[248:249], s[10:11], 0, v[2:3]
	s_mov_b32 m0, s25
	v_lshl_add_u64 v[160:161], s[64:65], 0, v[148:149]
	global_load_lds_dwordx4 v[248:249], off
	v_lshl_add_u64 v[248:249], s[10:11], 0, v[150:151]
	s_add_i32 m0, s25, 0x2000
	s_nop 0
	global_load_lds_dwordx4 v[248:249], off
	v_lshl_add_u64 v[248:249], s[64:65], 0, v[0:1]
	s_mov_b32 m0, s53
	s_nop 0
	global_load_lds_dwordx4 v[248:249], off
	s_mov_b32 m0, s66
	s_nop 0
	global_load_lds_dwordx4 v[160:161], off
	s_waitcnt vmcnt(8)
	s_waitcnt lgkmcnt(0)
	s_barrier
	s_setprio 1
	s_waitcnt lgkmcnt(0)
	v_mfma_f32_16x16x32_bf16 v[120:123], v[136:139], v[212:215], v[120:123]
	v_mfma_f32_16x16x32_bf16 v[120:123], v[140:143], v[216:219], v[120:123]
	v_mfma_f32_16x16x32_bf16 v[116:119], v[144:147], v[212:215], v[116:119]
	v_mfma_f32_16x16x32_bf16 v[116:119], v[170:173], v[216:219], v[116:119]
	v_mfma_f32_16x16x32_bf16 v[96:99], v[136:139], v[220:223], v[96:99]
	v_mfma_f32_16x16x32_bf16 v[96:99], v[140:143], v[224:227], v[96:99]
	v_mfma_f32_16x16x32_bf16 v[92:95], v[144:147], v[220:223], v[92:95]
	v_mfma_f32_16x16x32_bf16 v[92:95], v[170:173], v[224:227], v[92:95]
	v_mfma_f32_16x16x32_bf16 v[64:67], v[136:139], v[228:231], v[64:67]
	v_mfma_f32_16x16x32_bf16 v[64:67], v[140:143], v[232:235], v[64:67]
	v_mfma_f32_16x16x32_bf16 v[60:63], v[144:147], v[228:231], v[60:63]
	v_mfma_f32_16x16x32_bf16 v[60:63], v[170:173], v[232:235], v[60:63]
	v_mfma_f32_16x16x32_bf16 v[24:27], v[136:139], v[236:239], v[24:27]
	v_mfma_f32_16x16x32_bf16 v[24:27], v[140:143], v[240:243], v[24:27]
	v_mfma_f32_16x16x32_bf16 v[20:23], v[144:147], v[236:239], v[20:23]
	v_mfma_f32_16x16x32_bf16 v[20:23], v[170:173], v[240:243], v[20:23]
	v_mfma_f32_16x16x32_bf16 v[112:115], v[174:177], v[212:215], v[112:115]
	v_mfma_f32_16x16x32_bf16 v[112:115], v[178:181], v[216:219], v[112:115]
	v_mfma_f32_16x16x32_bf16 v[108:111], v[182:185], v[212:215], v[108:111]
	v_mfma_f32_16x16x32_bf16 v[108:111], v[208:211], v[216:219], v[108:111]
	v_mfma_f32_16x16x32_bf16 v[88:91], v[174:177], v[220:223], v[88:91]
	v_mfma_f32_16x16x32_bf16 v[88:91], v[178:181], v[224:227], v[88:91]
	v_mfma_f32_16x16x32_bf16 v[84:87], v[182:185], v[220:223], v[84:87]
	v_mfma_f32_16x16x32_bf16 v[84:87], v[208:211], v[224:227], v[84:87]
	v_mfma_f32_16x16x32_bf16 v[48:51], v[174:177], v[228:231], v[48:51]
	v_mfma_f32_16x16x32_bf16 v[48:51], v[178:181], v[232:235], v[48:51]
	v_mfma_f32_16x16x32_bf16 v[44:47], v[182:185], v[228:231], v[44:47]
	v_mfma_f32_16x16x32_bf16 v[44:47], v[208:211], v[232:235], v[44:47]
	v_mfma_f32_16x16x32_bf16 v[16:19], v[174:177], v[236:239], v[16:19]
	v_mfma_f32_16x16x32_bf16 v[16:19], v[178:181], v[240:243], v[16:19]
	s_setprio 2
	s_barrier
; #define PG8_STAGE(bufoff, gbase, voff) do { _Pragma("unroll") for (int _i = 0; _i < 2; ++_i) \
;         __builtin_amdgcn_global_load_lds((const unsigned*)((const char*)(gbase) + (voff)[_i]), (LAS unsigned*)(lds + (bufoff) + ldsw + _i * 8192), 16, 0, 0); } while (0)
; #define PG8_LDA(dst, b, h) do { _Pragma("unroll") for (int m = 0; m < 4; ++m) _Pragma("unroll") for (int k = 0; k < 2; ++k) dst[m][k] = *(const LAS bf16x8*)(lds + PG8_SA(b, h) + aoff + m * 2048 + k * 1024); } while (0)
; #define PG8_LDB(dst, b, h) do { _Pragma("unroll") for (int n = 0; n < 2; ++n) _Pragma("unroll") for (int k = 0; k < 2; ++k) dst[n][k] = *(const LAS bf16x8*)(lds + PG8_SB(b, h) + boff + n * 2048 + k * 1024); } while (0)
; #define PG8_MMA(ai, bj, At, Bt) do { __builtin_amdgcn_s_setprio(1); _Pragma("unroll") for (int m = 0; m < 4; ++m) _Pragma("unroll") for (int n = 0; n < 2; ++n) _Pragma("unroll") for (int k = 0; k < 2; ++k) \
;         acc[ai][bj][m][n] = __builtin_amdgcn_mfma_f32_16x16x32_bf16(Bt[n][k], At[m][k], acc[ai][bj][m][n], 0, 0, 0); __builtin_amdgcn_s_setprio(0); } while (0)
; #define PG8_WAIT_V(n) asm volatile("s_waitcnt vmcnt(" #n ")" ::: "memory")
; #define PG8_WAIT_L(n) asm volatile("s_waitcnt lgkmcnt(" #n ")" ::: "memory")
; #define PG8_BAR __builtin_amdgcn_s_barrier()
; #define PG8_SCHED __builtin_amdgcn_sched_barrier(0)
; template <class Epi, class Sched, bool ALIGN_EPI = true>
; __device__ __forceinline__ void gemm_phase(LAS unsigned char* lds, const Gemm g, const Sched& S, const Epi& E) {
;     ...
;             PG8_WAIT_V(8); PG8_WAIT_L(0); PG8_BAR; PG8_MMA(1, 0, At, B0); PG8_MMA(1, 1, At, B1); PG8_BAR; PG8_SCHED;
;             PG8_LDB(B0, 1, 0); PG8_LDB(B1, 1, 1); PG8_SCHED; PG8_LDA(At, 1, 0); PG8_STAGE(PG8_SA(0, 1), a2 + hA, voffA);
;             PG8_WAIT_V(8); PG8_WAIT_L(0); PG8_BAR; PG8_MMA(0, 0, At, B0); PG8_MMA(0, 1, At, B1); PG8_BAR; PG8_SCHED;
	v_mfma_f32_16x16x32_bf16 v[12:15], v[182:185], v[236:239], v[12:15]
	v_mfma_f32_16x16x32_bf16 v[12:15], v[208:211], v[240:243], v[12:15]
	s_setprio 0
	s_add_i32 s25, 0, 0x18000
	v_add_u32_e32 v162, s25, v186
	s_add_i32 s26, 0, 0x1c000
	ds_read_b128 v[136:139], v162
	ds_read_b128 v[140:143], v162 offset:1024
	ds_read_b128 v[144:147], v162 offset:2048
	ds_read_b128 v[170:173], v162 offset:3072
	v_add_u32_e32 v162, s26, v186
	ds_read_b128 v[174:177], v162
	ds_read_b128 v[178:181], v162 offset:1024
	ds_read_b128 v[182:185], v162 offset:2048
	ds_read_b128 v[208:211], v162 offset:3072
	s_add_u32 s10, s64, 0x80000
	s_addc_u32 s11, s65, 0
	s_mov_b32 m0, s75
	v_lshl_add_u64 v[162:163], s[10:11], 0, v[0:1]
	ds_read_b128 v[212:215], v197 offset:32768
	ds_read_b128 v[216:219], v197 offset:33792
	ds_read_b128 v[220:223], v197 offset:34816
	ds_read_b128 v[224:227], v197 offset:35840
	ds_read_b128 v[228:231], v197 offset:36864
	ds_read_b128 v[232:235], v197 offset:37888
	ds_read_b128 v[236:239], v197 offset:38912
	ds_read_b128 v[240:243], v197 offset:39936
	global_load_lds_dwordx4 v[162:163], off
	v_lshl_add_u64 v[162:163], s[10:11], 0, v[148:149]
	s_mov_b32 m0, s76
	s_nop 0
	global_load_lds_dwordx4 v[162:163], off
	s_waitcnt vmcnt(8)
	s_waitcnt lgkmcnt(0)
	s_barrier
	s_setprio 1
	s_waitcnt lgkmcnt(0)
	v_mfma_f32_16x16x32_bf16 v[36:39], v[136:139], v[212:215], v[36:39]
	v_mfma_f32_16x16x32_bf16 v[36:39], v[140:143], v[216:219], v[36:39]
	v_mfma_f32_16x16x32_bf16 v[40:43], v[144:147], v[212:215], v[40:43]
	v_mfma_f32_16x16x32_bf16 v[40:43], v[170:173], v[216:219], v[40:43]
	v_mfma_f32_16x16x32_bf16 v[68:71], v[136:139], v[220:223], v[68:71]
	v_mfma_f32_16x16x32_bf16 v[68:71], v[140:143], v[224:227], v[68:71]
	v_mfma_f32_16x16x32_bf16 v[72:75], v[144:147], v[220:223], v[72:75]
	v_mfma_f32_16x16x32_bf16 v[72:75], v[170:173], v[224:227], v[72:75]
	v_mfma_f32_16x16x32_bf16 v[100:103], v[136:139], v[228:231], v[100:103]
	v_mfma_f32_16x16x32_bf16 v[100:103], v[140:143], v[232:235], v[100:103]
	v_mfma_f32_16x16x32_bf16 v[104:107], v[144:147], v[228:231], v[104:107]
	v_mfma_f32_16x16x32_bf16 v[104:107], v[170:173], v[232:235], v[104:107]
	v_mfma_f32_16x16x32_bf16 v[128:131], v[136:139], v[236:239], v[128:131]
	v_mfma_f32_16x16x32_bf16 v[128:131], v[140:143], v[240:243], v[128:131]
	v_mfma_f32_16x16x32_bf16 v[124:127], v[144:147], v[236:239], v[124:127]
	v_mfma_f32_16x16x32_bf16 v[124:127], v[170:173], v[240:243], v[124:127]
	v_mfma_f32_16x16x32_bf16 v[8:11], v[174:177], v[212:215], v[8:11]
	v_mfma_f32_16x16x32_bf16 v[8:11], v[178:181], v[216:219], v[8:11]
	v_mfma_f32_16x16x32_bf16 v[4:7], v[182:185], v[212:215], v[4:7]
	v_mfma_f32_16x16x32_bf16 v[4:7], v[208:211], v[216:219], v[4:7]
	v_mfma_f32_16x16x32_bf16 v[32:35], v[174:177], v[220:223], v[32:35]
	v_mfma_f32_16x16x32_bf16 v[32:35], v[178:181], v[224:227], v[32:35]
	v_mfma_f32_16x16x32_bf16 v[28:31], v[182:185], v[220:223], v[28:31]
	v_mfma_f32_16x16x32_bf16 v[28:31], v[208:211], v[224:227], v[28:31]
	v_mfma_f32_16x16x32_bf16 v[56:59], v[174:177], v[228:231], v[56:59]
	v_mfma_f32_16x16x32_bf16 v[56:59], v[178:181], v[232:235], v[56:59]
	v_mfma_f32_16x16x32_bf16 v[52:55], v[182:185], v[228:231], v[52:55]
	v_mfma_f32_16x16x32_bf16 v[52:55], v[208:211], v[232:235], v[52:55]
	v_mfma_f32_16x16x32_bf16 v[80:83], v[174:177], v[236:239], v[80:83]
	v_mfma_f32_16x16x32_bf16 v[80:83], v[178:181], v[240:243], v[80:83]
	s_setprio 2
	s_barrier
; #define PG8_STAGE(bufoff, gbase, voff) do { _Pragma("unroll") for (int _i = 0; _i < 2; ++_i) \
;         __builtin_amdgcn_global_load_lds((const unsigned*)((const char*)(gbase) + (voff)[_i]), (LAS unsigned*)(lds + (bufoff) + ldsw + _i * 8192), 16, 0, 0); } while (0)
; #define PG8_LDA(dst, b, h) do { _Pragma("unroll") for (int m = 0; m < 4; ++m) _Pragma("unroll") for (int k = 0; k < 2; ++k) dst[m][k] = *(const LAS bf16x8*)(lds + PG8_SA(b, h) + aoff + m * 2048 + k * 1024); } while (0)
; #define PG8_MMA(ai, bj, At, Bt) do { __builtin_amdgcn_s_setprio(1); _Pragma("unroll") for (int m = 0; m < 4; ++m) _Pragma("unroll") for (int n = 0; n < 2; ++n) _Pragma("unroll") for (int k = 0; k < 2; ++k) \
;         acc[ai][bj][m][n] = __builtin_amdgcn_mfma_f32_16x16x32_bf16(Bt[n][k], At[m][k], acc[ai][bj][m][n], 0, 0, 0); __builtin_amdgcn_s_setprio(0); } while (0)
; #define PG8_WAIT_V(n) asm volatile("s_waitcnt vmcnt(" #n ")" ::: "memory")
; #define PG8_WAIT_L(n) asm volatile("s_waitcnt lgkmcnt(" #n ")" ::: "memory")
; #define PG8_BAR __builtin_amdgcn_s_barrier()
; #define PG8_SCHED __builtin_amdgcn_sched_barrier(0)
; template <class Epi, class Sched, bool ALIGN_EPI = true>
; __device__ __forceinline__ void gemm_phase(LAS unsigned char* lds, const Gemm g, const Sched& S, const Epi& E) {
;     ...
;             PG8_WAIT_V(8); PG8_WAIT_L(0); PG8_BAR; PG8_MMA(0, 0, At, B0); PG8_MMA(0, 1, At, B1); PG8_BAR; PG8_SCHED;
;             PG8_LDA(At, 1, 1); PG8_STAGE(PG8_SB(1, 0), b3, voffB); PG8_STAGE(PG8_SB(1, 1), b3 + hB, voffB); PG8_STAGE(PG8_SA(1, 0), a3, voffA);
;             PG8_WAIT_V(8); PG8_WAIT_L(0); PG8_BAR; PG8_MMA(1, 0, At, B0); PG8_MMA(1, 1, At, B1); PG8_BAR; PG8_SCHED;
;         }
	v_mfma_f32_16x16x32_bf16 v[76:79], v[182:185], v[236:239], v[76:79]
	v_mfma_f32_16x16x32_bf16 v[76:79], v[208:211], v[240:243], v[76:79]
	s_setprio 0
	s_add_i32 s10, s25, s67
	v_lshl_add_u64 v[162:163], v[244:245], 0, s[86:87]
	s_mov_b32 m0, s10
	ds_read_b128 v[212:215], v197 offset:49152
	ds_read_b128 v[216:219], v197 offset:50176
	ds_read_b128 v[220:223], v197 offset:51200
	ds_read_b128 v[224:227], v197 offset:52224
	ds_read_b128 v[228:231], v197 offset:53248
	ds_read_b128 v[232:235], v197 offset:54272
	ds_read_b128 v[236:239], v197 offset:55296
	ds_read_b128 v[240:243], v197 offset:56320
	global_load_lds_dwordx4 v[162:163], off
	s_add_i32 m0, s10, 0x2000
	s_add_u32 s10, s62, 0x80080
	v_lshl_add_u64 v[162:163], v[246:247], 0, s[86:87]
	s_addc_u32 s11, s63, 0
	s_add_i32 s25, s26, s67
	global_load_lds_dwordx4 v[162:163], off
	v_lshl_add_u64 v[162:163], s[10:11], 0, v[2:3]
	s_mov_b32 m0, s25
	v_lshl_add_u64 v[160:161], v[160:161], 0, s[86:87]
	global_load_lds_dwordx4 v[162:163], off
	v_lshl_add_u64 v[162:163], s[10:11], 0, v[150:151]
	s_add_i32 m0, s25, 0x2000
	s_nop 0
	global_load_lds_dwordx4 v[162:163], off
	v_lshl_add_u64 v[162:163], v[248:249], 0, s[86:87]
	s_mov_b32 m0, s79
	s_nop 0
	global_load_lds_dwordx4 v[162:163], off
	s_mov_b32 m0, s80
	s_nop 0
	global_load_lds_dwordx4 v[160:161], off
	s_waitcnt vmcnt(8)
	s_waitcnt lgkmcnt(0)
	s_barrier
	s_setprio 1
	s_waitcnt lgkmcnt(0)
	v_mfma_f32_16x16x32_bf16 v[120:123], v[136:139], v[212:215], v[120:123]
	v_mfma_f32_16x16x32_bf16 v[120:123], v[140:143], v[216:219], v[120:123]
	v_mfma_f32_16x16x32_bf16 v[116:119], v[144:147], v[212:215], v[116:119]
	v_mfma_f32_16x16x32_bf16 v[116:119], v[170:173], v[216:219], v[116:119]
	v_mfma_f32_16x16x32_bf16 v[96:99], v[136:139], v[220:223], v[96:99]
	v_mfma_f32_16x16x32_bf16 v[96:99], v[140:143], v[224:227], v[96:99]
	v_mfma_f32_16x16x32_bf16 v[92:95], v[144:147], v[220:223], v[92:95]
	v_mfma_f32_16x16x32_bf16 v[92:95], v[170:173], v[224:227], v[92:95]
	v_mfma_f32_16x16x32_bf16 v[64:67], v[136:139], v[228:231], v[64:67]
	v_mfma_f32_16x16x32_bf16 v[64:67], v[140:143], v[232:235], v[64:67]
	v_mfma_f32_16x16x32_bf16 v[60:63], v[144:147], v[228:231], v[60:63]
	v_mfma_f32_16x16x32_bf16 v[60:63], v[170:173], v[232:235], v[60:63]
	v_mfma_f32_16x16x32_bf16 v[24:27], v[136:139], v[236:239], v[24:27]
	v_mfma_f32_16x16x32_bf16 v[24:27], v[140:143], v[240:243], v[24:27]
	v_mfma_f32_16x16x32_bf16 v[20:23], v[144:147], v[236:239], v[20:23]
	v_mfma_f32_16x16x32_bf16 v[20:23], v[170:173], v[240:243], v[20:23]
	v_mfma_f32_16x16x32_bf16 v[112:115], v[174:177], v[212:215], v[112:115]
	v_mfma_f32_16x16x32_bf16 v[112:115], v[178:181], v[216:219], v[112:115]
	v_mfma_f32_16x16x32_bf16 v[108:111], v[182:185], v[212:215], v[108:111]
	v_mfma_f32_16x16x32_bf16 v[108:111], v[208:211], v[216:219], v[108:111]
	v_mfma_f32_16x16x32_bf16 v[88:91], v[174:177], v[220:223], v[88:91]
	v_mfma_f32_16x16x32_bf16 v[88:91], v[178:181], v[224:227], v[88:91]
	v_mfma_f32_16x16x32_bf16 v[84:87], v[182:185], v[220:223], v[84:87]
	v_mfma_f32_16x16x32_bf16 v[84:87], v[208:211], v[224:227], v[84:87]
	v_mfma_f32_16x16x32_bf16 v[48:51], v[174:177], v[228:231], v[48:51]
	v_mfma_f32_16x16x32_bf16 v[48:51], v[178:181], v[232:235], v[48:51]
	v_mfma_f32_16x16x32_bf16 v[44:47], v[182:185], v[228:231], v[44:47]
	v_mfma_f32_16x16x32_bf16 v[44:47], v[208:211], v[232:235], v[44:47]
	v_mfma_f32_16x16x32_bf16 v[16:19], v[174:177], v[236:239], v[16:19]
	v_mfma_f32_16x16x32_bf16 v[16:19], v[178:181], v[240:243], v[16:19]
	s_setprio 2
	s_barrier
	v_mfma_f32_16x16x32_bf16 v[12:15], v[182:185], v[236:239], v[12:15]
	v_mfma_f32_16x16x32_bf16 v[12:15], v[208:211], v[240:243], v[12:15]
	s_setprio 0
	s_add_i32 s24, s24, 2
	s_cmp_gt_u32 s24, 29
	s_mov_b64 s[10:11], vcc
	s_cbranch_scc0 .LBB0_667

;     __device__ bool next(int i, Unit& u) const { if (i >= 2) return false; const int x = c & 7, j = c >> 3; u.pm = 32 * i + 4 * x + (j & 3); u.pn = j >> 2; return true; }
; #define PG8_STAGE(bufoff, gbase, voff) do { _Pragma("unroll") for (int _i = 0; _i < 2; ++_i) \
;         __builtin_amdgcn_global_load_lds((const unsigned*)((const char*)(gbase) + (voff)[_i]), (LAS unsigned*)(lds + (bufoff) + ldsw + _i * 8192), 16, 0, 0); } while (0)
; #define PG8_LDA(dst, b, h) do { _Pragma("unroll") for (int m = 0; m < 4; ++m) _Pragma("unroll") for (int k = 0; k < 2; ++k) dst[m][k] = *(const LAS bf16x8*)(lds + PG8_SA(b, h) + aoff + m * 2048 + k * 1024); } while (0)
; #define PG8_LDB(dst, b, h) do { _Pragma("unroll") for (int n = 0; n < 2; ++n) _Pragma("unroll") for (int k = 0; k < 2; ++k) dst[n][k] = *(const LAS bf16x8*)(lds + PG8_SB(b, h) + boff + n * 2048 + k * 1024); } while (0)
;     __device__ __forceinline__ void operator()(f32x4 (&acc)[2][2][4][2], const Unit& u, int wr, int wc, int fr_, int fq_, int wid, int lane_) const {
;     ...
;             const int t = wid * 64 + lane, kind = t >> 6, pr = t & 63, bj = kind >> 2, tap = kind & 3;
;             const float* src = (tap < 3) ? (cw + (size_t)tap * FF2 + bj * FF + u.pn * 128 + 2 * pr) : (cb + bj * FF + u.pn * 128 + 2 * pr);
;             const f32x2 wv = *(const f32x2*)src;
; template <class Epi, class Sched, bool ALIGN_EPI = true>
; __device__ __forceinline__ void gemm_phase(LAS unsigned char* lds, const Gemm g, const Sched& S, const Epi& E) {
;     ...
;         const bool has_next = S.next(ui + 1, nxt);
;         const char* nA = has_next ? (const char*)g.A + ((size_t)nxt.pm * BM * g.lda + (size_t)nxt.pn * g.a_pn_off) * 2 : cA; const char* nB = has_next ? (const char*)g.Bt + (size_t)nxt.pn * BM * g.ldb * 2 : cB;
;         for (int t = 0; t < nt; t += 2) {
;             const bool last = (t == nt - 2);
;             const char* a1 = cA + (size_t)(t + 1) * kstep;
;             const char* a2 = last ? nA : cA + (size_t)(t + 2) * kstep; const char* b2 = last ? nB : cB + (size_t)(t + 2) * kstep;
;             const char* a3 = a2 + kstep; const char* b3 = b2 + kstep;
;             PG8_LDB(B0, 0, 0); PG8_LDB(B1, 0, 1); PG8_SCHED; PG8_LDA(At, 0, 0); PG8_STAGE(PG8_SA(1, 1), a1 + hA, voffA);
;             PG8_WAIT_V(8); PG8_WAIT_L(0); PG8_BAR; PG8_MMA(0, 0, At, B0); PG8_MMA(0, 1, At, B1); PG8_BAR; PG8_SCHED;
.LBB0_827:
	s_ashr_i32 s39, s38, 31
	s_lshl_b64 s[16:17], s[38:39], 20
	s_add_u32 s40, s46, s16
	s_addc_u32 s41, s47, s17
	s_and_b64 s[16:17], s[4:5], exec
	s_cselect_b32 s16, s41, s7
	s_cselect_b32 s17, s40, s6
	s_ashr_i32 s15, s14, 31
	s_lshl_b64 s[18:19], s[14:15], 20
	s_add_u32 s42, s53, s18
	s_addc_u32 s43, s60, s19
	s_and_b64 s[18:19], s[4:5], exec
	s_cselect_b32 s15, s43, s45
	s_cselect_b32 s18, s42, s44
	s_add_u32 s6, s6, 0x80080
	s_addc_u32 s7, s7, 0
	s_add_u32 s19, s44, 0x100
	s_addc_u32 s24, s45, 0
	s_mov_b32 s25, -2
	v_add_u32_e32 v228, s77, v158
	v_ashrrev_i32_e32 v229, 6, v228
	v_and_b32_e32 v230, 3, v229
	v_lshrrev_b32_e32 v231, 8, v228
	v_mul_u32_u24_e32 v228, 0x2c00, v230
	v_lshlrev_b32_e32 v228, 2, v228
	v_mov_b32_e32 v229, 0
	v_lshl_add_u64 v[232:233], s[2:3], 0, v[228:229]
	v_mov_b32_e32 v228, s9
	v_cmp_eq_u32_e32 vcc, 3, v230
	v_mul_i32_i24_e32 v234, 0x1600, v231
	v_ashrrev_i32_e32 v235, 31, v234
	v_cndmask_b32_e32 v233, v233, v228, vcc
	v_mov_b32_e32 v228, s8
	v_cndmask_b32_e32 v232, v232, v228, vcc
	v_lshl_add_u64 v[232:233], v[234:235], 2, v[232:233]
	s_lshl_b32 s26, s82, 7
	s_ashr_i32 s27, s26, 31
	v_lshl_add_u64 v[232:233], s[26:27], 2, v[232:233]
	v_and_b32_e32 v228, 63, v158
	v_lshlrev_b32_e32 v228, 3, v228
	v_mov_b32_e32 v229, 0
	v_lshl_add_u64 v[232:233], v[232:233], 0, v[228:229]
	global_load_dwordx2 v[226:227], v[232:233], off
	s_add_u32 s26, s6, 0xfff80080
	s_addc_u32 s27, s7, -1
	s_add_i32 s30, 0, 0x10000
	s_cmp_eq_u32 s25, 28
	s_cselect_b32 s59, s16, s27
	s_cselect_b32 s58, s17, s26
	v_add_u32_e32 v2, s30, v204
	s_cselect_b32 s45, s15, s24
	s_cselect_b32 s44, s18, s19
	s_add_i32 s31, 0, 0x14000
	ds_read_b128 v[132:135], v2
	ds_read_b128 v[136:139], v2 offset:1024
	ds_read_b128 v[140:143], v2 offset:2048
	ds_read_b128 v[144:147], v2 offset:3072
	v_add_u32_e32 v2, s31, v204
	ds_read_b128 v[148:151], v2
	ds_read_b128 v[152:155], v2 offset:1024
	ds_read_b128 v[174:177], v2 offset:2048
	ds_read_b128 v[178:181], v2 offset:3072
	v_lshl_add_u64 v[156:157], s[6:7], 0, v[170:171]
	s_add_i32 m0, s62, 0xc000
	ds_read_b128 v[182:185], v205
	ds_read_b128 v[186:189], v205 offset:1024
	ds_read_b128 v[190:193], v205 offset:2048
	ds_read_b128 v[194:197], v205 offset:3072
	ds_read_b128 v[206:209], v205 offset:4096
	ds_read_b128 v[210:213], v205 offset:5120
	ds_read_b128 v[214:217], v205 offset:6144
	ds_read_b128 v[218:221], v205 offset:7168
	global_load_lds_dwordx4 v[156:157], off
	v_lshl_add_u64 v[156:157], s[6:7], 0, v[172:173]
	s_add_i32 m0, s62, 0xe000
	s_nop 0
	global_load_lds_dwordx4 v[156:157], off
	s_waitcnt vmcnt(8)
	s_waitcnt lgkmcnt(0)
	s_barrier
	s_setprio 1
	s_waitcnt lgkmcnt(0)
	v_mfma_f32_16x16x32_bf16 v[116:119], v[132:135], v[182:185], 0
	v_mfma_f32_16x16x32_bf16 v[116:119], v[136:139], v[186:189], v[116:119]
	v_mfma_f32_16x16x32_bf16 v[100:103], v[140:143], v[182:185], 0
	v_mfma_f32_16x16x32_bf16 v[100:103], v[144:147], v[186:189], v[100:103]
	v_mfma_f32_16x16x32_bf16 v[108:111], v[132:135], v[190:193], 0
	v_mfma_f32_16x16x32_bf16 v[108:111], v[136:139], v[194:197], v[108:111]
	v_mfma_f32_16x16x32_bf16 v[96:99], v[140:143], v[190:193], 0
	v_mfma_f32_16x16x32_bf16 v[96:99], v[144:147], v[194:197], v[96:99]
	v_mfma_f32_16x16x32_bf16 v[88:91], v[132:135], v[206:209], 0
	v_mfma_f32_16x16x32_bf16 v[88:91], v[136:139], v[210:213], v[88:91]
	v_mfma_f32_16x16x32_bf16 v[84:87], v[140:143], v[206:209], 0
	v_mfma_f32_16x16x32_bf16 v[84:87], v[144:147], v[210:213], v[84:87]
	v_mfma_f32_16x16x32_bf16 v[72:75], v[132:135], v[214:217], 0
	v_mfma_f32_16x16x32_bf16 v[72:75], v[136:139], v[218:221], v[72:75]
	v_mfma_f32_16x16x32_bf16 v[80:83], v[140:143], v[214:217], 0
	v_mfma_f32_16x16x32_bf16 v[80:83], v[144:147], v[218:221], v[80:83]
	v_mfma_f32_16x16x32_bf16 v[128:131], v[148:151], v[182:185], 0
	v_mfma_f32_16x16x32_bf16 v[128:131], v[152:155], v[186:189], v[128:131]
	v_mfma_f32_16x16x32_bf16 v[44:47], v[174:177], v[182:185], 0
	v_mfma_f32_16x16x32_bf16 v[44:47], v[178:181], v[186:189], v[44:47]
	v_mfma_f32_16x16x32_bf16 v[124:127], v[148:151], v[190:193], 0
	v_mfma_f32_16x16x32_bf16 v[124:127], v[152:155], v[194:197], v[124:127]
	v_mfma_f32_16x16x32_bf16 v[36:39], v[174:177], v[190:193], 0
	v_mfma_f32_16x16x32_bf16 v[36:39], v[178:181], v[194:197], v[36:39]
	v_mfma_f32_16x16x32_bf16 v[120:123], v[148:151], v[206:209], 0
	v_mfma_f32_16x16x32_bf16 v[120:123], v[152:155], v[210:213], v[120:123]
	v_mfma_f32_16x16x32_bf16 v[32:35], v[174:177], v[206:209], 0
	v_mfma_f32_16x16x32_bf16 v[32:35], v[178:181], v[210:213], v[32:35]
	v_mfma_f32_16x16x32_bf16 v[112:115], v[148:151], v[214:217], 0
	v_mfma_f32_16x16x32_bf16 v[112:115], v[152:155], v[218:221], v[112:115]
	s_setprio 2
	s_barrier
	v_mfma_f32_16x16x32_bf16 v[28:31], v[174:177], v[214:217], 0
	v_mfma_f32_16x16x32_bf16 v[28:31], v[178:181], v[218:221], v[28:31]
	s_setprio 0
	s_add_i32 s26, s30, s61
	v_lshl_add_u64 v[156:157], s[44:45], 0, v[166:167]
	s_mov_b32 m0, s26
	ds_read_b128 v[182:185], v205 offset:16384
	ds_read_b128 v[186:189], v205 offset:17408
	ds_read_b128 v[190:193], v205 offset:18432
	ds_read_b128 v[194:197], v205 offset:19456
	ds_read_b128 v[206:209], v205 offset:20480
	ds_read_b128 v[210:213], v205 offset:21504
	ds_read_b128 v[214:217], v205 offset:22528
	ds_read_b128 v[218:221], v205 offset:23552
	global_load_lds_dwordx4 v[156:157], off
	s_add_i32 m0, s26, 0x2000
	s_add_u32 s26, s44, 0x80000
	v_lshl_add_u64 v[160:161], s[44:45], 0, v[0:1]
	s_addc_u32 s27, s45, 0
	s_add_i32 s30, s31, s61
	global_load_lds_dwordx4 v[160:161], off
	v_lshl_add_u64 v[162:163], s[26:27], 0, v[166:167]
	s_mov_b32 m0, s30
	v_lshl_add_u64 v[222:223], s[58:59], 0, v[164:165]
	global_load_lds_dwordx4 v[162:163], off
	v_lshl_add_u64 v[162:163], s[26:27], 0, v[0:1]
	s_add_i32 m0, s30, 0x2000
	s_nop 0
	global_load_lds_dwordx4 v[162:163], off
	v_lshl_add_u64 v[162:163], s[58:59], 0, v[168:169]
	s_mov_b32 m0, s62
	s_nop 0
	global_load_lds_dwordx4 v[162:163], off
	s_mov_b32 m0, s63
	s_nop 0
	global_load_lds_dwordx4 v[222:223], off
	s_waitcnt vmcnt(8)
	s_waitcnt lgkmcnt(0)
	s_barrier
; #define PG8_STAGE(bufoff, gbase, voff) do { _Pragma("unroll") for (int _i = 0; _i < 2; ++_i) \
;         __builtin_amdgcn_global_load_lds((const unsigned*)((const char*)(gbase) + (voff)[_i]), (LAS unsigned*)(lds + (bufoff) + ldsw + _i * 8192), 16, 0, 0); } while (0)
; #define PG8_LDA(dst, b, h) do { _Pragma("unroll") for (int m = 0; m < 4; ++m) _Pragma("unroll") for (int k = 0; k < 2; ++k) dst[m][k] = *(const LAS bf16x8*)(lds + PG8_SA(b, h) + aoff + m * 2048 + k * 1024); } while (0)
; #define PG8_LDB(dst, b, h) do { _Pragma("unroll") for (int n = 0; n < 2; ++n) _Pragma("unroll") for (int k = 0; k < 2; ++k) dst[n][k] = *(const LAS bf16x8*)(lds + PG8_SB(b, h) + boff + n * 2048 + k * 1024); } while (0)
; #define PG8_MMA(ai, bj, At, Bt) do { __builtin_amdgcn_s_setprio(1); _Pragma("unroll") for (int m = 0; m < 4; ++m) _Pragma("unroll") for (int n = 0; n < 2; ++n) _Pragma("unroll") for (int k = 0; k < 2; ++k) \
;         acc[ai][bj][m][n] = __builtin_amdgcn_mfma_f32_16x16x32_bf16(Bt[n][k], At[m][k], acc[ai][bj][m][n], 0, 0, 0); __builtin_amdgcn_s_setprio(0); } while (0)
; #define PG8_WAIT_V(n) asm volatile("s_waitcnt vmcnt(" #n ")" ::: "memory")
; #define PG8_WAIT_L(n) asm volatile("s_waitcnt lgkmcnt(" #n ")" ::: "memory")
; #define PG8_BAR __builtin_amdgcn_s_barrier()
; #define PG8_SCHED __builtin_amdgcn_sched_barrier(0)
; template <class Epi, class Sched, bool ALIGN_EPI = true>
; __device__ __forceinline__ void gemm_phase(LAS unsigned char* lds, const Gemm g, const Sched& S, const Epi& E) {
;     ...
;             PG8_WAIT_V(8); PG8_WAIT_L(0); PG8_BAR; PG8_MMA(0, 0, At, B0); PG8_MMA(0, 1, At, B1); PG8_BAR; PG8_SCHED;
;             PG8_LDA(At, 0, 1); PG8_STAGE(PG8_SB(0, 0), b2, voffB); PG8_STAGE(PG8_SB(0, 1), b2 + hB, voffB); PG8_STAGE(PG8_SA(0, 0), a2, voffA);
;             PG8_WAIT_V(8); PG8_WAIT_L(0); PG8_BAR; PG8_MMA(1, 0, At, B0); PG8_MMA(1, 1, At, B1); PG8_BAR; PG8_SCHED;
;             PG8_LDB(B0, 1, 0); PG8_LDB(B1, 1, 1); PG8_SCHED; PG8_LDA(At, 1, 0); PG8_STAGE(PG8_SA(0, 1), a2 + hA, voffA);
;             PG8_WAIT_V(8); PG8_WAIT_L(0); PG8_BAR; PG8_MMA(0, 0, At, B0); PG8_MMA(0, 1, At, B1); PG8_BAR; PG8_SCHED;
	s_setprio 1
	s_waitcnt lgkmcnt(0)
	v_mfma_f32_16x16x32_bf16 v[60:63], v[132:135], v[182:185], 0
	v_mfma_f32_16x16x32_bf16 v[60:63], v[136:139], v[186:189], v[60:63]
	v_mfma_f32_16x16x32_bf16 v[68:71], v[140:143], v[182:185], 0
	v_mfma_f32_16x16x32_bf16 v[68:71], v[144:147], v[186:189], v[68:71]
	v_mfma_f32_16x16x32_bf16 v[40:43], v[132:135], v[190:193], 0
	v_mfma_f32_16x16x32_bf16 v[40:43], v[136:139], v[194:197], v[40:43]
	v_mfma_f32_16x16x32_bf16 v[64:67], v[140:143], v[190:193], 0
	v_mfma_f32_16x16x32_bf16 v[64:67], v[144:147], v[194:197], v[64:67]
	v_mfma_f32_16x16x32_bf16 v[24:27], v[132:135], v[206:209], 0
	v_mfma_f32_16x16x32_bf16 v[24:27], v[136:139], v[210:213], v[24:27]
	v_mfma_f32_16x16x32_bf16 v[56:59], v[140:143], v[206:209], 0
	v_mfma_f32_16x16x32_bf16 v[56:59], v[144:147], v[210:213], v[56:59]
	v_mfma_f32_16x16x32_bf16 v[12:15], v[132:135], v[214:217], 0
	v_mfma_f32_16x16x32_bf16 v[12:15], v[136:139], v[218:221], v[12:15]
	v_mfma_f32_16x16x32_bf16 v[48:51], v[140:143], v[214:217], 0
	v_mfma_f32_16x16x32_bf16 v[48:51], v[144:147], v[218:221], v[48:51]
	v_mfma_f32_16x16x32_bf16 v[104:107], v[148:151], v[182:185], 0
	v_mfma_f32_16x16x32_bf16 v[104:107], v[152:155], v[186:189], v[104:107]
	v_mfma_f32_16x16x32_bf16 v[20:23], v[174:177], v[182:185], 0
	v_mfma_f32_16x16x32_bf16 v[20:23], v[178:181], v[186:189], v[20:23]
	v_mfma_f32_16x16x32_bf16 v[92:95], v[148:151], v[190:193], 0
	v_mfma_f32_16x16x32_bf16 v[92:95], v[152:155], v[194:197], v[92:95]
	v_mfma_f32_16x16x32_bf16 v[16:19], v[174:177], v[190:193], 0
	v_mfma_f32_16x16x32_bf16 v[16:19], v[178:181], v[194:197], v[16:19]
	v_mfma_f32_16x16x32_bf16 v[76:79], v[148:151], v[206:209], 0
	v_mfma_f32_16x16x32_bf16 v[76:79], v[152:155], v[210:213], v[76:79]
	v_mfma_f32_16x16x32_bf16 v[8:11], v[174:177], v[206:209], 0
	v_mfma_f32_16x16x32_bf16 v[8:11], v[178:181], v[210:213], v[8:11]
	v_mfma_f32_16x16x32_bf16 v[52:55], v[148:151], v[214:217], 0
	v_mfma_f32_16x16x32_bf16 v[52:55], v[152:155], v[218:221], v[52:55]
	s_setprio 2
	s_barrier
	v_mfma_f32_16x16x32_bf16 v[4:7], v[174:177], v[214:217], 0
	v_mfma_f32_16x16x32_bf16 v[4:7], v[178:181], v[218:221], v[4:7]
	s_setprio 0
	s_add_i32 s30, 0, 0x18000
	v_add_u32_e32 v2, s30, v204
	s_add_i32 s31, 0, 0x1c000
	ds_read_b128 v[132:135], v2
	ds_read_b128 v[136:139], v2 offset:1024
	ds_read_b128 v[140:143], v2 offset:2048
	ds_read_b128 v[144:147], v2 offset:3072
	v_add_u32_e32 v2, s31, v204
	ds_read_b128 v[148:151], v2
	ds_read_b128 v[152:155], v2 offset:1024
	ds_read_b128 v[174:177], v2 offset:2048
	ds_read_b128 v[178:181], v2 offset:3072
	s_add_u32 s26, s58, 0x80000
	s_addc_u32 s27, s59, 0
	s_mov_b32 m0, s64
	v_lshl_add_u64 v[224:225], s[26:27], 0, v[168:169]
	ds_read_b128 v[182:185], v205 offset:32768
	ds_read_b128 v[186:189], v205 offset:33792
	ds_read_b128 v[190:193], v205 offset:34816
	ds_read_b128 v[194:197], v205 offset:35840
	ds_read_b128 v[206:209], v205 offset:36864
	ds_read_b128 v[210:213], v205 offset:37888
	ds_read_b128 v[214:217], v205 offset:38912
	ds_read_b128 v[218:221], v205 offset:39936
	global_load_lds_dwordx4 v[224:225], off
	v_lshl_add_u64 v[224:225], s[26:27], 0, v[164:165]
	s_mov_b32 m0, s65
	s_nop 0
	global_load_lds_dwordx4 v[224:225], off
	s_waitcnt vmcnt(8)
	s_waitcnt lgkmcnt(0)
	s_barrier
	s_setprio 1
	s_waitcnt lgkmcnt(0)
	v_mfma_f32_16x16x32_bf16 v[116:119], v[132:135], v[182:185], v[116:119]
	v_mfma_f32_16x16x32_bf16 v[116:119], v[136:139], v[186:189], v[116:119]
	v_mfma_f32_16x16x32_bf16 v[100:103], v[140:143], v[182:185], v[100:103]
	v_mfma_f32_16x16x32_bf16 v[100:103], v[144:147], v[186:189], v[100:103]
	v_mfma_f32_16x16x32_bf16 v[108:111], v[132:135], v[190:193], v[108:111]
	v_mfma_f32_16x16x32_bf16 v[108:111], v[136:139], v[194:197], v[108:111]
	v_mfma_f32_16x16x32_bf16 v[96:99], v[140:143], v[190:193], v[96:99]
	v_mfma_f32_16x16x32_bf16 v[96:99], v[144:147], v[194:197], v[96:99]
	v_mfma_f32_16x16x32_bf16 v[88:91], v[132:135], v[206:209], v[88:91]
	v_mfma_f32_16x16x32_bf16 v[88:91], v[136:139], v[210:213], v[88:91]
	v_mfma_f32_16x16x32_bf16 v[84:87], v[140:143], v[206:209], v[84:87]
	v_mfma_f32_16x16x32_bf16 v[84:87], v[144:147], v[210:213], v[84:87]
	v_mfma_f32_16x16x32_bf16 v[72:75], v[132:135], v[214:217], v[72:75]
	v_mfma_f32_16x16x32_bf16 v[72:75], v[136:139], v[218:221], v[72:75]
	v_mfma_f32_16x16x32_bf16 v[80:83], v[140:143], v[214:217], v[80:83]
	v_mfma_f32_16x16x32_bf16 v[80:83], v[144:147], v[218:221], v[80:83]
	v_mfma_f32_16x16x32_bf16 v[128:131], v[148:151], v[182:185], v[128:131]
	v_mfma_f32_16x16x32_bf16 v[128:131], v[152:155], v[186:189], v[128:131]
	v_mfma_f32_16x16x32_bf16 v[44:47], v[174:177], v[182:185], v[44:47]
	v_mfma_f32_16x16x32_bf16 v[44:47], v[178:181], v[186:189], v[44:47]
	v_mfma_f32_16x16x32_bf16 v[124:127], v[148:151], v[190:193], v[124:127]
	v_mfma_f32_16x16x32_bf16 v[124:127], v[152:155], v[194:197], v[124:127]
	v_mfma_f32_16x16x32_bf16 v[36:39], v[174:177], v[190:193], v[36:39]
	v_mfma_f32_16x16x32_bf16 v[36:39], v[178:181], v[194:197], v[36:39]
	v_mfma_f32_16x16x32_bf16 v[120:123], v[148:151], v[206:209], v[120:123]
	v_mfma_f32_16x16x32_bf16 v[120:123], v[152:155], v[210:213], v[120:123]
	v_mfma_f32_16x16x32_bf16 v[32:35], v[174:177], v[206:209], v[32:35]
	v_mfma_f32_16x16x32_bf16 v[32:35], v[178:181], v[210:213], v[32:35]
	v_mfma_f32_16x16x32_bf16 v[112:115], v[148:151], v[214:217], v[112:115]
	v_mfma_f32_16x16x32_bf16 v[112:115], v[152:155], v[218:221], v[112:115]
	s_setprio 2
	s_barrier
; #define PG8_STAGE(bufoff, gbase, voff) do { _Pragma("unroll") for (int _i = 0; _i < 2; ++_i) \
;         __builtin_amdgcn_global_load_lds((const unsigned*)((const char*)(gbase) + (voff)[_i]), (LAS unsigned*)(lds + (bufoff) + ldsw + _i * 8192), 16, 0, 0); } while (0)
; #define PG8_LDA(dst, b, h) do { _Pragma("unroll") for (int m = 0; m < 4; ++m) _Pragma("unroll") for (int k = 0; k < 2; ++k) dst[m][k] = *(const LAS bf16x8*)(lds + PG8_SA(b, h) + aoff + m * 2048 + k * 1024); } while (0)
; #define PG8_MMA(ai, bj, At, Bt) do { __builtin_amdgcn_s_setprio(1); _Pragma("unroll") for (int m = 0; m < 4; ++m) _Pragma("unroll") for (int n = 0; n < 2; ++n) _Pragma("unroll") for (int k = 0; k < 2; ++k) \
;         acc[ai][bj][m][n] = __builtin_amdgcn_mfma_f32_16x16x32_bf16(Bt[n][k], At[m][k], acc[ai][bj][m][n], 0, 0, 0); __builtin_amdgcn_s_setprio(0); } while (0)
; #define PG8_WAIT_V(n) asm volatile("s_waitcnt vmcnt(" #n ")" ::: "memory")
; #define PG8_WAIT_L(n) asm volatile("s_waitcnt lgkmcnt(" #n ")" ::: "memory")
; #define PG8_BAR __builtin_amdgcn_s_barrier()
; #define PG8_SCHED __builtin_amdgcn_sched_barrier(0)
; template <class Epi, class Sched, bool ALIGN_EPI = true>
; __device__ __forceinline__ void gemm_phase(LAS unsigned char* lds, const Gemm g, const Sched& S, const Epi& E) {
;     ...
;             PG8_WAIT_V(8); PG8_WAIT_L(0); PG8_BAR; PG8_MMA(0, 0, At, B0); PG8_MMA(0, 1, At, B1); PG8_BAR; PG8_SCHED;
;             PG8_LDA(At, 1, 1); PG8_STAGE(PG8_SB(1, 0), b3, voffB); PG8_STAGE(PG8_SB(1, 1), b3 + hB, voffB); PG8_STAGE(PG8_SA(1, 0), a3, voffA);
;             PG8_WAIT_V(8); PG8_WAIT_L(0); PG8_BAR; PG8_MMA(1, 0, At, B0); PG8_MMA(1, 1, At, B1); PG8_BAR; PG8_SCHED;
	v_mfma_f32_16x16x32_bf16 v[28:31], v[174:177], v[214:217], v[28:31]
	v_mfma_f32_16x16x32_bf16 v[28:31], v[178:181], v[218:221], v[28:31]
	s_setprio 0
	s_add_i32 s26, s30, s61
	v_lshl_add_u64 v[156:157], v[156:157], 0, s[86:87]
	s_mov_b32 m0, s26
	ds_read_b128 v[182:185], v205 offset:49152
	ds_read_b128 v[186:189], v205 offset:50176
	ds_read_b128 v[190:193], v205 offset:51200
	ds_read_b128 v[194:197], v205 offset:52224
	ds_read_b128 v[206:209], v205 offset:53248
	ds_read_b128 v[210:213], v205 offset:54272
	ds_read_b128 v[214:217], v205 offset:55296
	ds_read_b128 v[218:221], v205 offset:56320
	global_load_lds_dwordx4 v[156:157], off
	s_add_i32 m0, s26, 0x2000
	s_add_u32 s26, s44, 0x80080
	v_lshl_add_u64 v[156:157], v[160:161], 0, s[86:87]
	s_addc_u32 s27, s45, 0
	s_add_i32 s30, s31, s61
	global_load_lds_dwordx4 v[156:157], off
	v_lshl_add_u64 v[156:157], s[26:27], 0, v[166:167]
	s_mov_b32 m0, s30
	s_nop 0
	global_load_lds_dwordx4 v[156:157], off
	v_lshl_add_u64 v[156:157], s[26:27], 0, v[0:1]
	s_add_i32 m0, s30, 0x2000
	s_nop 0
	global_load_lds_dwordx4 v[156:157], off
	v_lshl_add_u64 v[156:157], v[162:163], 0, s[86:87]
	s_mov_b32 m0, s75
	s_nop 0
	global_load_lds_dwordx4 v[156:157], off
	v_lshl_add_u64 v[156:157], v[222:223], 0, s[86:87]
	s_mov_b32 m0, s76
	s_nop 0
	global_load_lds_dwordx4 v[156:157], off
	s_waitcnt vmcnt(8)
	s_waitcnt lgkmcnt(0)
	s_barrier
	s_setprio 1
	s_waitcnt lgkmcnt(0)
	v_mfma_f32_16x16x32_bf16 v[60:63], v[132:135], v[182:185], v[60:63]
	v_mfma_f32_16x16x32_bf16 v[60:63], v[136:139], v[186:189], v[60:63]
	s_add_i32 s25, s25, 2
	s_add_u32 s6, s6, 0x100
	v_mfma_f32_16x16x32_bf16 v[68:71], v[140:143], v[182:185], v[68:71]
	v_mfma_f32_16x16x32_bf16 v[68:71], v[144:147], v[186:189], v[68:71]
	s_addc_u32 s7, s7, 0
	s_add_u32 s19, s19, 0x100
	v_mfma_f32_16x16x32_bf16 v[40:43], v[132:135], v[190:193], v[40:43]
	v_mfma_f32_16x16x32_bf16 v[40:43], v[136:139], v[194:197], v[40:43]
	s_addc_u32 s24, s24, 0
	s_add_u32 s26, s6, 0xfff80080
	v_mfma_f32_16x16x32_bf16 v[64:67], v[140:143], v[190:193], v[64:67]
	v_mfma_f32_16x16x32_bf16 v[64:67], v[144:147], v[194:197], v[64:67]
	s_addc_u32 s27, s7, -1
	s_add_i32 s30, 0, 0x10000
	v_mfma_f32_16x16x32_bf16 v[24:27], v[132:135], v[206:209], v[24:27]
	v_mfma_f32_16x16x32_bf16 v[24:27], v[136:139], v[210:213], v[24:27]
	s_cmp_eq_u32 s25, 28
	s_cselect_b32 s59, s16, s27
	v_mfma_f32_16x16x32_bf16 v[56:59], v[140:143], v[206:209], v[56:59]
	v_mfma_f32_16x16x32_bf16 v[56:59], v[144:147], v[210:213], v[56:59]
	s_cselect_b32 s58, s17, s26
	s_cselect_b32 s45, s15, s24
	v_mfma_f32_16x16x32_bf16 v[12:15], v[132:135], v[214:217], v[12:15]
	v_mfma_f32_16x16x32_bf16 v[12:15], v[136:139], v[218:221], v[12:15]
	s_cselect_b32 s44, s18, s19
	s_add_i32 s31, 0, 0x14000
	v_mfma_f32_16x16x32_bf16 v[48:51], v[140:143], v[214:217], v[48:51]
	v_mfma_f32_16x16x32_bf16 v[48:51], v[144:147], v[218:221], v[48:51]
	v_mfma_f32_16x16x32_bf16 v[104:107], v[148:151], v[182:185], v[104:107]
	v_mfma_f32_16x16x32_bf16 v[104:107], v[152:155], v[186:189], v[104:107]
	v_mfma_f32_16x16x32_bf16 v[20:23], v[174:177], v[182:185], v[20:23]
	v_mfma_f32_16x16x32_bf16 v[20:23], v[178:181], v[186:189], v[20:23]
	v_mfma_f32_16x16x32_bf16 v[92:95], v[148:151], v[190:193], v[92:95]
	v_mfma_f32_16x16x32_bf16 v[92:95], v[152:155], v[194:197], v[92:95]
	v_mfma_f32_16x16x32_bf16 v[16:19], v[174:177], v[190:193], v[16:19]
	v_mfma_f32_16x16x32_bf16 v[16:19], v[178:181], v[194:197], v[16:19]
	v_mfma_f32_16x16x32_bf16 v[76:79], v[148:151], v[206:209], v[76:79]
	v_mfma_f32_16x16x32_bf16 v[76:79], v[152:155], v[210:213], v[76:79]
	v_mfma_f32_16x16x32_bf16 v[8:11], v[174:177], v[206:209], v[8:11]
	v_mfma_f32_16x16x32_bf16 v[8:11], v[178:181], v[210:213], v[8:11]
	v_mfma_f32_16x16x32_bf16 v[52:55], v[148:151], v[214:217], v[52:55]
	v_mfma_f32_16x16x32_bf16 v[52:55], v[152:155], v[218:221], v[52:55]
	s_setprio 2
	s_barrier
	v_mfma_f32_16x16x32_bf16 v[4:7], v[174:177], v[214:217], v[4:7]
	v_mfma_f32_16x16x32_bf16 v[4:7], v[178:181], v[218:221], v[4:7]
	s_setprio 0
	s_cmp_gt_u32 s25, 29
	s_cbranch_scc1 .Lpeel_exit_828
.LBB0_828:
	v_add_u32_e32 v2, s30, v204
	ds_read_b128 v[132:135], v2
	ds_read_b128 v[136:139], v2 offset:1024
	ds_read_b128 v[140:143], v2 offset:2048
	ds_read_b128 v[144:147], v2 offset:3072
	v_add_u32_e32 v2, s31, v204
	ds_read_b128 v[148:151], v2
	ds_read_b128 v[152:155], v2 offset:1024
	ds_read_b128 v[174:177], v2 offset:2048
	ds_read_b128 v[178:181], v2 offset:3072
	v_lshl_add_u64 v[156:157], s[6:7], 0, v[170:171]
	s_add_i32 m0, s62, 0xc000
	ds_read_b128 v[182:185], v205
	ds_read_b128 v[186:189], v205 offset:1024
	ds_read_b128 v[190:193], v205 offset:2048
	ds_read_b128 v[194:197], v205 offset:3072
	ds_read_b128 v[206:209], v205 offset:4096
	ds_read_b128 v[210:213], v205 offset:5120
	ds_read_b128 v[214:217], v205 offset:6144
	ds_read_b128 v[218:221], v205 offset:7168
	global_load_lds_dwordx4 v[156:157], off
	v_lshl_add_u64 v[156:157], s[6:7], 0, v[172:173]
	s_add_i32 m0, s62, 0xe000
	s_nop 0
	global_load_lds_dwordx4 v[156:157], off
	s_waitcnt vmcnt(8)
	s_waitcnt lgkmcnt(0)
	s_barrier
; #define PG8_STAGE(bufoff, gbase, voff) do { _Pragma("unroll") for (int _i = 0; _i < 2; ++_i) \
;         __builtin_amdgcn_global_load_lds((const unsigned*)((const char*)(gbase) + (voff)[_i]), (LAS unsigned*)(lds + (bufoff) + ldsw + _i * 8192), 16, 0, 0); } while (0)
; #define PG8_LDA(dst, b, h) do { _Pragma("unroll") for (int m = 0; m < 4; ++m) _Pragma("unroll") for (int k = 0; k < 2; ++k) dst[m][k] = *(const LAS bf16x8*)(lds + PG8_SA(b, h) + aoff + m * 2048 + k * 1024); } while (0)
; #define PG8_LDB(dst, b, h) do { _Pragma("unroll") for (int n = 0; n < 2; ++n) _Pragma("unroll") for (int k = 0; k < 2; ++k) dst[n][k] = *(const LAS bf16x8*)(lds + PG8_SB(b, h) + boff + n * 2048 + k * 1024); } while (0)
; #define PG8_MMA(ai, bj, At, Bt) do { __builtin_amdgcn_s_setprio(1); _Pragma("unroll") for (int m = 0; m < 4; ++m) _Pragma("unroll") for (int n = 0; n < 2; ++n) _Pragma("unroll") for (int k = 0; k < 2; ++k) \
;         acc[ai][bj][m][n] = __builtin_amdgcn_mfma_f32_16x16x32_bf16(Bt[n][k], At[m][k], acc[ai][bj][m][n], 0, 0, 0); __builtin_amdgcn_s_setprio(0); } while (0)
; #define PG8_WAIT_V(n) asm volatile("s_waitcnt vmcnt(" #n ")" ::: "memory")
; #define PG8_WAIT_L(n) asm volatile("s_waitcnt lgkmcnt(" #n ")" ::: "memory")
; #define PG8_BAR __builtin_amdgcn_s_barrier()
; #define PG8_SCHED __builtin_amdgcn_sched_barrier(0)
; template <class Epi, class Sched, bool ALIGN_EPI = true>
; __device__ __forceinline__ void gemm_phase(LAS unsigned char* lds, const Gemm g, const Sched& S, const Epi& E) {
;     ...
;             PG8_WAIT_V(8); PG8_WAIT_L(0); PG8_BAR; PG8_MMA(0, 0, At, B0); PG8_MMA(0, 1, At, B1); PG8_BAR; PG8_SCHED;
;             PG8_LDA(At, 0, 1); PG8_STAGE(PG8_SB(0, 0), b2, voffB); PG8_STAGE(PG8_SB(0, 1), b2 + hB, voffB); PG8_STAGE(PG8_SA(0, 0), a2, voffA);
;             PG8_WAIT_V(8); PG8_WAIT_L(0); PG8_BAR; PG8_MMA(1, 0, At, B0); PG8_MMA(1, 1, At, B1); PG8_BAR; PG8_SCHED;
;             PG8_LDB(B0, 1, 0); PG8_LDB(B1, 1, 1); PG8_SCHED; PG8_LDA(At, 1, 0); PG8_STAGE(PG8_SA(0, 1), a2 + hA, voffA);
;             PG8_WAIT_V(8); PG8_WAIT_L(0); PG8_BAR; PG8_MMA(0, 0, At, B0); PG8_MMA(0, 1, At, B1); PG8_BAR; PG8_SCHED;
	s_setprio 1
	s_waitcnt lgkmcnt(0)
	v_mfma_f32_16x16x32_bf16 v[116:119], v[132:135], v[182:185], v[116:119]
	v_mfma_f32_16x16x32_bf16 v[116:119], v[136:139], v[186:189], v[116:119]
	v_mfma_f32_16x16x32_bf16 v[100:103], v[140:143], v[182:185], v[100:103]
	v_mfma_f32_16x16x32_bf16 v[100:103], v[144:147], v[186:189], v[100:103]
	v_mfma_f32_16x16x32_bf16 v[108:111], v[132:135], v[190:193], v[108:111]
	v_mfma_f32_16x16x32_bf16 v[108:111], v[136:139], v[194:197], v[108:111]
	v_mfma_f32_16x16x32_bf16 v[96:99], v[140:143], v[190:193], v[96:99]
	v_mfma_f32_16x16x32_bf16 v[96:99], v[144:147], v[194:197], v[96:99]
	v_mfma_f32_16x16x32_bf16 v[88:91], v[132:135], v[206:209], v[88:91]
	v_mfma_f32_16x16x32_bf16 v[88:91], v[136:139], v[210:213], v[88:91]
	v_mfma_f32_16x16x32_bf16 v[84:87], v[140:143], v[206:209], v[84:87]
	v_mfma_f32_16x16x32_bf16 v[84:87], v[144:147], v[210:213], v[84:87]
	v_mfma_f32_16x16x32_bf16 v[72:75], v[132:135], v[214:217], v[72:75]
	v_mfma_f32_16x16x32_bf16 v[72:75], v[136:139], v[218:221], v[72:75]
	v_mfma_f32_16x16x32_bf16 v[80:83], v[140:143], v[214:217], v[80:83]
	v_mfma_f32_16x16x32_bf16 v[80:83], v[144:147], v[218:221], v[80:83]
	v_mfma_f32_16x16x32_bf16 v[128:131], v[148:151], v[182:185], v[128:131]
	v_mfma_f32_16x16x32_bf16 v[128:131], v[152:155], v[186:189], v[128:131]
	v_mfma_f32_16x16x32_bf16 v[44:47], v[174:177], v[182:185], v[44:47]
	v_mfma_f32_16x16x32_bf16 v[44:47], v[178:181], v[186:189], v[44:47]
	v_mfma_f32_16x16x32_bf16 v[124:127], v[148:151], v[190:193], v[124:127]
	v_mfma_f32_16x16x32_bf16 v[124:127], v[152:155], v[194:197], v[124:127]
	v_mfma_f32_16x16x32_bf16 v[36:39], v[174:177], v[190:193], v[36:39]
	v_mfma_f32_16x16x32_bf16 v[36:39], v[178:181], v[194:197], v[36:39]
	v_mfma_f32_16x16x32_bf16 v[120:123], v[148:151], v[206:209], v[120:123]
	v_mfma_f32_16x16x32_bf16 v[120:123], v[152:155], v[210:213], v[120:123]
	v_mfma_f32_16x16x32_bf16 v[32:35], v[174:177], v[206:209], v[32:35]
	v_mfma_f32_16x16x32_bf16 v[32:35], v[178:181], v[210:213], v[32:35]
	v_mfma_f32_16x16x32_bf16 v[112:115], v[148:151], v[214:217], v[112:115]
	v_mfma_f32_16x16x32_bf16 v[112:115], v[152:155], v[218:221], v[112:115]
	s_setprio 2
	s_barrier
	v_mfma_f32_16x16x32_bf16 v[28:31], v[174:177], v[214:217], v[28:31]
	v_mfma_f32_16x16x32_bf16 v[28:31], v[178:181], v[218:221], v[28:31]
	s_setprio 0
	s_add_i32 s26, s30, s61
	v_lshl_add_u64 v[156:157], s[44:45], 0, v[166:167]
	s_mov_b32 m0, s26
	ds_read_b128 v[182:185], v205 offset:16384
	ds_read_b128 v[186:189], v205 offset:17408
	ds_read_b128 v[190:193], v205 offset:18432
	ds_read_b128 v[194:197], v205 offset:19456
	ds_read_b128 v[206:209], v205 offset:20480
	ds_read_b128 v[210:213], v205 offset:21504
	ds_read_b128 v[214:217], v205 offset:22528
	ds_read_b128 v[218:221], v205 offset:23552
	global_load_lds_dwordx4 v[156:157], off
	s_add_i32 m0, s26, 0x2000
	s_add_u32 s26, s44, 0x80000
	v_lshl_add_u64 v[160:161], s[44:45], 0, v[0:1]
	s_addc_u32 s27, s45, 0
	s_add_i32 s30, s31, s61
	global_load_lds_dwordx4 v[160:161], off
	v_lshl_add_u64 v[162:163], s[26:27], 0, v[166:167]
	s_mov_b32 m0, s30
	v_lshl_add_u64 v[222:223], s[58:59], 0, v[164:165]
	global_load_lds_dwordx4 v[162:163], off
	v_lshl_add_u64 v[162:163], s[26:27], 0, v[0:1]
	s_add_i32 m0, s30, 0x2000
	s_nop 0
	global_load_lds_dwordx4 v[162:163], off
	v_lshl_add_u64 v[162:163], s[58:59], 0, v[168:169]
	s_mov_b32 m0, s62
	s_nop 0
	global_load_lds_dwordx4 v[162:163], off
	s_mov_b32 m0, s63
	s_nop 0
	global_load_lds_dwordx4 v[222:223], off
	s_waitcnt vmcnt(8)
	s_waitcnt lgkmcnt(0)
	s_barrier
	s_setprio 1
	s_waitcnt lgkmcnt(0)
	v_mfma_f32_16x16x32_bf16 v[60:63], v[132:135], v[182:185], v[60:63]
	v_mfma_f32_16x16x32_bf16 v[60:63], v[136:139], v[186:189], v[60:63]
	v_mfma_f32_16x16x32_bf16 v[68:71], v[140:143], v[182:185], v[68:71]
	v_mfma_f32_16x16x32_bf16 v[68:71], v[144:147], v[186:189], v[68:71]
	v_mfma_f32_16x16x32_bf16 v[40:43], v[132:135], v[190:193], v[40:43]
	v_mfma_f32_16x16x32_bf16 v[40:43], v[136:139], v[194:197], v[40:43]
	v_mfma_f32_16x16x32_bf16 v[64:67], v[140:143], v[190:193], v[64:67]
	v_mfma_f32_16x16x32_bf16 v[64:67], v[144:147], v[194:197], v[64:67]
	v_mfma_f32_16x16x32_bf16 v[24:27], v[132:135], v[206:209], v[24:27]
	v_mfma_f32_16x16x32_bf16 v[24:27], v[136:139], v[210:213], v[24:27]
	v_mfma_f32_16x16x32_bf16 v[56:59], v[140:143], v[206:209], v[56:59]
	v_mfma_f32_16x16x32_bf16 v[56:59], v[144:147], v[210:213], v[56:59]
	v_mfma_f32_16x16x32_bf16 v[12:15], v[132:135], v[214:217], v[12:15]
	v_mfma_f32_16x16x32_bf16 v[12:15], v[136:139], v[218:221], v[12:15]
	v_mfma_f32_16x16x32_bf16 v[48:51], v[140:143], v[214:217], v[48:51]
	v_mfma_f32_16x16x32_bf16 v[48:51], v[144:147], v[218:221], v[48:51]
	v_mfma_f32_16x16x32_bf16 v[104:107], v[148:151], v[182:185], v[104:107]
	v_mfma_f32_16x16x32_bf16 v[104:107], v[152:155], v[186:189], v[104:107]
	v_mfma_f32_16x16x32_bf16 v[20:23], v[174:177], v[182:185], v[20:23]
	v_mfma_f32_16x16x32_bf16 v[20:23], v[178:181], v[186:189], v[20:23]
	v_mfma_f32_16x16x32_bf16 v[92:95], v[148:151], v[190:193], v[92:95]
	v_mfma_f32_16x16x32_bf16 v[92:95], v[152:155], v[194:197], v[92:95]
	v_mfma_f32_16x16x32_bf16 v[16:19], v[174:177], v[190:193], v[16:19]
	v_mfma_f32_16x16x32_bf16 v[16:19], v[178:181], v[194:197], v[16:19]
	v_mfma_f32_16x16x32_bf16 v[76:79], v[148:151], v[206:209], v[76:79]
	v_mfma_f32_16x16x32_bf16 v[76:79], v[152:155], v[210:213], v[76:79]
	v_mfma_f32_16x16x32_bf16 v[8:11], v[174:177], v[206:209], v[8:11]
	v_mfma_f32_16x16x32_bf16 v[8:11], v[178:181], v[210:213], v[8:11]
	v_mfma_f32_16x16x32_bf16 v[52:55], v[148:151], v[214:217], v[52:55]
	v_mfma_f32_16x16x32_bf16 v[52:55], v[152:155], v[218:221], v[52:55]
	s_setprio 2
	s_barrier
; #define PG8_STAGE(bufoff, gbase, voff) do { _Pragma("unroll") for (int _i = 0; _i < 2; ++_i) \
;         __builtin_amdgcn_global_load_lds((const unsigned*)((const char*)(gbase) + (voff)[_i]), (LAS unsigned*)(lds + (bufoff) + ldsw + _i * 8192), 16, 0, 0); } while (0)
; #define PG8_LDA(dst, b, h) do { _Pragma("unroll") for (int m = 0; m < 4; ++m) _Pragma("unroll") for (int k = 0; k < 2; ++k) dst[m][k] = *(const LAS bf16x8*)(lds + PG8_SA(b, h) + aoff + m * 2048 + k * 1024); } while (0)
; #define PG8_LDB(dst, b, h) do { _Pragma("unroll") for (int n = 0; n < 2; ++n) _Pragma("unroll") for (int k = 0; k < 2; ++k) dst[n][k] = *(const LAS bf16x8*)(lds + PG8_SB(b, h) + boff + n * 2048 + k * 1024); } while (0)
; #define PG8_MMA(ai, bj, At, Bt) do { __builtin_amdgcn_s_setprio(1); _Pragma("unroll") for (int m = 0; m < 4; ++m) _Pragma("unroll") for (int n = 0; n < 2; ++n) _Pragma("unroll") for (int k = 0; k < 2; ++k) \
;         acc[ai][bj][m][n] = __builtin_amdgcn_mfma_f32_16x16x32_bf16(Bt[n][k], At[m][k], acc[ai][bj][m][n], 0, 0, 0); __builtin_amdgcn_s_setprio(0); } while (0)
; #define PG8_WAIT_V(n) asm volatile("s_waitcnt vmcnt(" #n ")" ::: "memory")
; #define PG8_WAIT_L(n) asm volatile("s_waitcnt lgkmcnt(" #n ")" ::: "memory")
; #define PG8_BAR __builtin_amdgcn_s_barrier()
; #define PG8_SCHED __builtin_amdgcn_sched_barrier(0)
; template <class Epi, class Sched, bool ALIGN_EPI = true>
; __device__ __forceinline__ void gemm_phase(LAS unsigned char* lds, const Gemm g, const Sched& S, const Epi& E) {
;     ...
;             PG8_WAIT_V(8); PG8_WAIT_L(0); PG8_BAR; PG8_MMA(1, 0, At, B0); PG8_MMA(1, 1, At, B1); PG8_BAR; PG8_SCHED;
;             PG8_LDB(B0, 1, 0); PG8_LDB(B1, 1, 1); PG8_SCHED; PG8_LDA(At, 1, 0); PG8_STAGE(PG8_SA(0, 1), a2 + hA, voffA);
;             PG8_WAIT_V(8); PG8_WAIT_L(0); PG8_BAR; PG8_MMA(0, 0, At, B0); PG8_MMA(0, 1, At, B1); PG8_BAR; PG8_SCHED;
	v_mfma_f32_16x16x32_bf16 v[4:7], v[174:177], v[214:217], v[4:7]
	v_mfma_f32_16x16x32_bf16 v[4:7], v[178:181], v[218:221], v[4:7]
	s_setprio 0
	s_add_i32 s30, 0, 0x18000
	v_add_u32_e32 v2, s30, v204
	s_add_i32 s31, 0, 0x1c000
	ds_read_b128 v[132:135], v2
	ds_read_b128 v[136:139], v2 offset:1024
	ds_read_b128 v[140:143], v2 offset:2048
	ds_read_b128 v[144:147], v2 offset:3072
	v_add_u32_e32 v2, s31, v204
	ds_read_b128 v[148:151], v2
	ds_read_b128 v[152:155], v2 offset:1024
	ds_read_b128 v[174:177], v2 offset:2048
	ds_read_b128 v[178:181], v2 offset:3072
	s_add_u32 s26, s58, 0x80000
	s_addc_u32 s27, s59, 0
	s_mov_b32 m0, s64
	v_lshl_add_u64 v[224:225], s[26:27], 0, v[168:169]
	ds_read_b128 v[182:185], v205 offset:32768
	ds_read_b128 v[186:189], v205 offset:33792
	ds_read_b128 v[190:193], v205 offset:34816
	ds_read_b128 v[194:197], v205 offset:35840
	ds_read_b128 v[206:209], v205 offset:36864
	ds_read_b128 v[210:213], v205 offset:37888
	ds_read_b128 v[214:217], v205 offset:38912
	ds_read_b128 v[218:221], v205 offset:39936
	global_load_lds_dwordx4 v[224:225], off
	v_lshl_add_u64 v[224:225], s[26:27], 0, v[164:165]
	s_mov_b32 m0, s65
	s_nop 0
	global_load_lds_dwordx4 v[224:225], off
	s_waitcnt vmcnt(8)
	s_waitcnt lgkmcnt(0)
	s_barrier
	s_setprio 1
	s_waitcnt lgkmcnt(0)
	v_mfma_f32_16x16x32_bf16 v[116:119], v[132:135], v[182:185], v[116:119]
	v_mfma_f32_16x16x32_bf16 v[116:119], v[136:139], v[186:189], v[116:119]
	v_mfma_f32_16x16x32_bf16 v[100:103], v[140:143], v[182:185], v[100:103]
	v_mfma_f32_16x16x32_bf16 v[100:103], v[144:147], v[186:189], v[100:103]
	v_mfma_f32_16x16x32_bf16 v[108:111], v[132:135], v[190:193], v[108:111]
	v_mfma_f32_16x16x32_bf16 v[108:111], v[136:139], v[194:197], v[108:111]
	v_mfma_f32_16x16x32_bf16 v[96:99], v[140:143], v[190:193], v[96:99]
	v_mfma_f32_16x16x32_bf16 v[96:99], v[144:147], v[194:197], v[96:99]
	v_mfma_f32_16x16x32_bf16 v[88:91], v[132:135], v[206:209], v[88:91]
	v_mfma_f32_16x16x32_bf16 v[88:91], v[136:139], v[210:213], v[88:91]
	v_mfma_f32_16x16x32_bf16 v[84:87], v[140:143], v[206:209], v[84:87]
	v_mfma_f32_16x16x32_bf16 v[84:87], v[144:147], v[210:213], v[84:87]
	v_mfma_f32_16x16x32_bf16 v[72:75], v[132:135], v[214:217], v[72:75]
	v_mfma_f32_16x16x32_bf16 v[72:75], v[136:139], v[218:221], v[72:75]
	v_mfma_f32_16x16x32_bf16 v[80:83], v[140:143], v[214:217], v[80:83]
	v_mfma_f32_16x16x32_bf16 v[80:83], v[144:147], v[218:221], v[80:83]
	v_mfma_f32_16x16x32_bf16 v[128:131], v[148:151], v[182:185], v[128:131]
	v_mfma_f32_16x16x32_bf16 v[128:131], v[152:155], v[186:189], v[128:131]
	v_mfma_f32_16x16x32_bf16 v[44:47], v[174:177], v[182:185], v[44:47]
	v_mfma_f32_16x16x32_bf16 v[44:47], v[178:181], v[186:189], v[44:47]
	v_mfma_f32_16x16x32_bf16 v[124:127], v[148:151], v[190:193], v[124:127]
	v_mfma_f32_16x16x32_bf16 v[124:127], v[152:155], v[194:197], v[124:127]
	v_mfma_f32_16x16x32_bf16 v[36:39], v[174:177], v[190:193], v[36:39]
	v_mfma_f32_16x16x32_bf16 v[36:39], v[178:181], v[194:197], v[36:39]
	v_mfma_f32_16x16x32_bf16 v[120:123], v[148:151], v[206:209], v[120:123]
	v_mfma_f32_16x16x32_bf16 v[120:123], v[152:155], v[210:213], v[120:123]
	v_mfma_f32_16x16x32_bf16 v[32:35], v[174:177], v[206:209], v[32:35]
	v_mfma_f32_16x16x32_bf16 v[32:35], v[178:181], v[210:213], v[32:35]
	v_mfma_f32_16x16x32_bf16 v[112:115], v[148:151], v[214:217], v[112:115]
	v_mfma_f32_16x16x32_bf16 v[112:115], v[152:155], v[218:221], v[112:115]
	s_setprio 2
	s_barrier
; #define PG8_STAGE(bufoff, gbase, voff) do { _Pragma("unroll") for (int _i = 0; _i < 2; ++_i) \
;         __builtin_amdgcn_global_load_lds((const unsigned*)((const char*)(gbase) + (voff)[_i]), (LAS unsigned*)(lds + (bufoff) + ldsw + _i * 8192), 16, 0, 0); } while (0)
; #define PG8_LDA(dst, b, h) do { _Pragma("unroll") for (int m = 0; m < 4; ++m) _Pragma("unroll") for (int k = 0; k < 2; ++k) dst[m][k] = *(const LAS bf16x8*)(lds + PG8_SA(b, h) + aoff + m * 2048 + k * 1024); } while (0)
; #define PG8_MMA(ai, bj, At, Bt) do { __builtin_amdgcn_s_setprio(1); _Pragma("unroll") for (int m = 0; m < 4; ++m) _Pragma("unroll") for (int n = 0; n < 2; ++n) _Pragma("unroll") for (int k = 0; k < 2; ++k) \
;         acc[ai][bj][m][n] = __builtin_amdgcn_mfma_f32_16x16x32_bf16(Bt[n][k], At[m][k], acc[ai][bj][m][n], 0, 0, 0); __builtin_amdgcn_s_setprio(0); } while (0)
; #define PG8_WAIT_V(n) asm volatile("s_waitcnt vmcnt(" #n ")" ::: "memory")
; #define PG8_WAIT_L(n) asm volatile("s_waitcnt lgkmcnt(" #n ")" ::: "memory")
; #define PG8_BAR __builtin_amdgcn_s_barrier()
; #define PG8_SCHED __builtin_amdgcn_sched_barrier(0)
; template <class Epi, class Sched, bool ALIGN_EPI = true>
; __device__ __forceinline__ void gemm_phase(LAS unsigned char* lds, const Gemm g, const Sched& S, const Epi& E) {
;     ...
;             PG8_WAIT_V(8); PG8_WAIT_L(0); PG8_BAR; PG8_MMA(0, 0, At, B0); PG8_MMA(0, 1, At, B1); PG8_BAR; PG8_SCHED;
;             PG8_LDA(At, 1, 1); PG8_STAGE(PG8_SB(1, 0), b3, voffB); PG8_STAGE(PG8_SB(1, 1), b3 + hB, voffB); PG8_STAGE(PG8_SA(1, 0), a3, voffA);
;             PG8_WAIT_V(8); PG8_WAIT_L(0); PG8_BAR; PG8_MMA(1, 0, At, B0); PG8_MMA(1, 1, At, B1); PG8_BAR; PG8_SCHED;
;         }
	v_mfma_f32_16x16x32_bf16 v[28:31], v[174:177], v[214:217], v[28:31]
	v_mfma_f32_16x16x32_bf16 v[28:31], v[178:181], v[218:221], v[28:31]
	s_setprio 0
	s_add_i32 s26, s30, s61
	v_lshl_add_u64 v[156:157], v[156:157], 0, s[86:87]
	s_mov_b32 m0, s26
	ds_read_b128 v[182:185], v205 offset:49152
	ds_read_b128 v[186:189], v205 offset:50176
	ds_read_b128 v[190:193], v205 offset:51200
	ds_read_b128 v[194:197], v205 offset:52224
	ds_read_b128 v[206:209], v205 offset:53248
	ds_read_b128 v[210:213], v205 offset:54272
	ds_read_b128 v[214:217], v205 offset:55296
	ds_read_b128 v[218:221], v205 offset:56320
	global_load_lds_dwordx4 v[156:157], off
	s_add_i32 m0, s26, 0x2000
	s_add_u32 s26, s44, 0x80080
	v_lshl_add_u64 v[156:157], v[160:161], 0, s[86:87]
	s_addc_u32 s27, s45, 0
	s_add_i32 s30, s31, s61
	global_load_lds_dwordx4 v[156:157], off
	v_lshl_add_u64 v[156:157], s[26:27], 0, v[166:167]
	s_mov_b32 m0, s30
	s_nop 0
	global_load_lds_dwordx4 v[156:157], off
	v_lshl_add_u64 v[156:157], s[26:27], 0, v[0:1]
	s_add_i32 m0, s30, 0x2000
	s_nop 0
	global_load_lds_dwordx4 v[156:157], off
	v_lshl_add_u64 v[156:157], v[162:163], 0, s[86:87]
	s_mov_b32 m0, s75
	s_nop 0
	global_load_lds_dwordx4 v[156:157], off
	v_lshl_add_u64 v[156:157], v[222:223], 0, s[86:87]
	s_mov_b32 m0, s76
	s_nop 0
	global_load_lds_dwordx4 v[156:157], off
	s_waitcnt vmcnt(8)
	s_waitcnt lgkmcnt(0)
	s_barrier
	s_setprio 1
	s_waitcnt lgkmcnt(0)
	v_mfma_f32_16x16x32_bf16 v[60:63], v[132:135], v[182:185], v[60:63]
	v_mfma_f32_16x16x32_bf16 v[60:63], v[136:139], v[186:189], v[60:63]
	s_add_i32 s25, s25, 2
	s_add_u32 s6, s6, 0x100
	v_mfma_f32_16x16x32_bf16 v[68:71], v[140:143], v[182:185], v[68:71]
	v_mfma_f32_16x16x32_bf16 v[68:71], v[144:147], v[186:189], v[68:71]
	s_addc_u32 s7, s7, 0
	s_add_u32 s19, s19, 0x100
	v_mfma_f32_16x16x32_bf16 v[40:43], v[132:135], v[190:193], v[40:43]
	v_mfma_f32_16x16x32_bf16 v[40:43], v[136:139], v[194:197], v[40:43]
	s_addc_u32 s24, s24, 0
	s_add_u32 s26, s6, 0xfff80080
	v_mfma_f32_16x16x32_bf16 v[64:67], v[140:143], v[190:193], v[64:67]
	v_mfma_f32_16x16x32_bf16 v[64:67], v[144:147], v[194:197], v[64:67]
	s_addc_u32 s27, s7, -1
	s_add_i32 s30, 0, 0x10000
	v_mfma_f32_16x16x32_bf16 v[24:27], v[132:135], v[206:209], v[24:27]
	v_mfma_f32_16x16x32_bf16 v[24:27], v[136:139], v[210:213], v[24:27]
	s_cmp_eq_u32 s25, 28
	s_cselect_b32 s59, s16, s27
	v_mfma_f32_16x16x32_bf16 v[56:59], v[140:143], v[206:209], v[56:59]
	v_mfma_f32_16x16x32_bf16 v[56:59], v[144:147], v[210:213], v[56:59]
	s_cselect_b32 s58, s17, s26
	s_cselect_b32 s45, s15, s24
	v_mfma_f32_16x16x32_bf16 v[12:15], v[132:135], v[214:217], v[12:15]
	v_mfma_f32_16x16x32_bf16 v[12:15], v[136:139], v[218:221], v[12:15]
	s_cselect_b32 s44, s18, s19
	s_add_i32 s31, 0, 0x14000
	v_mfma_f32_16x16x32_bf16 v[48:51], v[140:143], v[214:217], v[48:51]
	v_mfma_f32_16x16x32_bf16 v[48:51], v[144:147], v[218:221], v[48:51]
	v_mfma_f32_16x16x32_bf16 v[104:107], v[148:151], v[182:185], v[104:107]
	v_mfma_f32_16x16x32_bf16 v[104:107], v[152:155], v[186:189], v[104:107]
	v_mfma_f32_16x16x32_bf16 v[20:23], v[174:177], v[182:185], v[20:23]
	v_mfma_f32_16x16x32_bf16 v[20:23], v[178:181], v[186:189], v[20:23]
	v_mfma_f32_16x16x32_bf16 v[92:95], v[148:151], v[190:193], v[92:95]
	v_mfma_f32_16x16x32_bf16 v[92:95], v[152:155], v[194:197], v[92:95]
	v_mfma_f32_16x16x32_bf16 v[16:19], v[174:177], v[190:193], v[16:19]
	v_mfma_f32_16x16x32_bf16 v[16:19], v[178:181], v[194:197], v[16:19]
	v_mfma_f32_16x16x32_bf16 v[76:79], v[148:151], v[206:209], v[76:79]
	v_mfma_f32_16x16x32_bf16 v[76:79], v[152:155], v[210:213], v[76:79]
	v_mfma_f32_16x16x32_bf16 v[8:11], v[174:177], v[206:209], v[8:11]
	v_mfma_f32_16x16x32_bf16 v[8:11], v[178:181], v[210:213], v[8:11]
	v_mfma_f32_16x16x32_bf16 v[52:55], v[148:151], v[214:217], v[52:55]
	v_mfma_f32_16x16x32_bf16 v[52:55], v[152:155], v[218:221], v[52:55]
	s_setprio 2
	s_barrier
	v_mfma_f32_16x16x32_bf16 v[4:7], v[174:177], v[214:217], v[4:7]
	v_mfma_f32_16x16x32_bf16 v[4:7], v[178:181], v[218:221], v[4:7]
	s_setprio 0
	s_cmp_gt_u32 s25, 29
	s_cbranch_scc0 .LBB0_828

; #define PG8_STAGE(bufoff, gbase, voff) do { _Pragma("unroll") for (int _i = 0; _i < 2; ++_i) \
;         __builtin_amdgcn_global_load_lds((const unsigned*)((const char*)(gbase) + (voff)[_i]), (LAS unsigned*)(lds + (bufoff) + ldsw + _i * 8192), 16, 0, 0); } while (0)
; #define PG8_LDA(dst, b, h) do { _Pragma("unroll") for (int m = 0; m < 4; ++m) _Pragma("unroll") for (int k = 0; k < 2; ++k) dst[m][k] = *(const LAS bf16x8*)(lds + PG8_SA(b, h) + aoff + m * 2048 + k * 1024); } while (0)
; #define PG8_LDB(dst, b, h) do { _Pragma("unroll") for (int n = 0; n < 2; ++n) _Pragma("unroll") for (int k = 0; k < 2; ++k) dst[n][k] = *(const LAS bf16x8*)(lds + PG8_SB(b, h) + boff + n * 2048 + k * 1024); } while (0)
; #define PG8_MMA(ai, bj, At, Bt) do { __builtin_amdgcn_s_setprio(1); _Pragma("unroll") for (int m = 0; m < 4; ++m) _Pragma("unroll") for (int n = 0; n < 2; ++n) _Pragma("unroll") for (int k = 0; k < 2; ++k) \
;         acc[ai][bj][m][n] = __builtin_amdgcn_mfma_f32_16x16x32_bf16(Bt[n][k], At[m][k], acc[ai][bj][m][n], 0, 0, 0); __builtin_amdgcn_s_setprio(0); } while (0)
; #define PG8_WAIT_V(n) asm volatile("s_waitcnt vmcnt(" #n ")" ::: "memory")
; #define PG8_WAIT_L(n) asm volatile("s_waitcnt lgkmcnt(" #n ")" ::: "memory")
; #define PG8_BAR __builtin_amdgcn_s_barrier()
; #define PG8_SCHED __builtin_amdgcn_sched_barrier(0)
; template <class Epi, class Sched, bool ALIGN_EPI = true>
; __device__ __forceinline__ void gemm_phase(LAS unsigned char* lds, const Gemm g, const Sched& S, const Epi& E) {
;     ...
;         for (int t = 0; t < nt; t += 2) {
;             const bool last = (t == nt - 2);
;             const char* a1 = cA + (size_t)(t + 1) * kstep;
;             const char* a2 = last ? nA : cA + (size_t)(t + 2) * kstep; const char* b2 = last ? nB : cB + (size_t)(t + 2) * kstep;
;             const char* a3 = a2 + kstep; const char* b3 = b2 + kstep;
;             PG8_LDB(B0, 0, 0); PG8_LDB(B1, 0, 1); PG8_SCHED; PG8_LDA(At, 0, 0); PG8_STAGE(PG8_SA(1, 1), a1 + hA, voffA);
;             PG8_WAIT_V(8); PG8_WAIT_L(0); PG8_BAR; PG8_MMA(0, 0, At, B0); PG8_MMA(0, 1, At, B1); PG8_BAR; PG8_SCHED;
;             PG8_LDA(At, 0, 1); PG8_STAGE(PG8_SB(0, 0), b2, voffB); PG8_STAGE(PG8_SB(0, 1), b2 + hB, voffB); PG8_STAGE(PG8_SA(0, 0), a2, voffA);
;             PG8_WAIT_V(8); PG8_WAIT_L(0); PG8_BAR; PG8_MMA(1, 0, At, B0); PG8_MMA(1, 1, At, B1); PG8_BAR; PG8_SCHED;
.LBB0_986:
	s_add_u32 s38, s14, 0x100
	s_addc_u32 s39, s15, 0
	s_add_i32 s25, 0, 0x10000
	s_cmpk_eq_i32 s24, 0x54
	s_cselect_b32 s43, s7, s39
	s_cselect_b32 s42, s6, s38
	v_add_u32_e32 v140, s25, v143
	s_cselect_b32 s41, s13, s19
	s_cselect_b32 s40, s12, s18
	s_add_i32 s26, 0, 0x14000
	ds_read_b128 v[136:139], v140
	ds_read_b128 v[146:149], v140 offset:1024
	ds_read_b128 v[150:153], v140 offset:2048
	ds_read_b128 v[154:157], v140 offset:3072
	v_add_u32_e32 v140, s26, v143
	ds_read_b128 v[164:167], v140
	ds_read_b128 v[168:171], v140 offset:1024
	ds_read_b128 v[172:175], v140 offset:2048
	ds_read_b128 v[176:179], v140 offset:3072
	v_lshl_add_u64 v[140:141], s[14:15], 0, v[132:133]
	s_add_i32 m0, s61, 0xc000
	ds_read_b128 v[180:183], v145
	ds_read_b128 v[184:187], v145 offset:1024
	ds_read_b128 v[188:191], v145 offset:2048
	ds_read_b128 v[192:195], v145 offset:3072
	ds_read_b128 v[204:207], v145 offset:4096
	ds_read_b128 v[208:211], v145 offset:5120
	ds_read_b128 v[212:215], v145 offset:6144
	ds_read_b128 v[216:219], v145 offset:7168
	global_load_lds_dwordx4 v[140:141], off
	v_lshl_add_u64 v[140:141], s[14:15], 0, v[134:135]
	s_add_i32 m0, s61, 0xe000
	s_nop 0
	global_load_lds_dwordx4 v[140:141], off
	s_waitcnt vmcnt(8)
	s_waitcnt lgkmcnt(0)
	s_barrier
	s_setprio 1
	s_waitcnt lgkmcnt(0)
	v_mfma_f32_16x16x32_bf16 v[128:131], v[136:139], v[180:183], v[128:131]
	v_mfma_f32_16x16x32_bf16 v[124:127], v[150:153], v[180:183], v[124:127]
	v_mfma_f32_16x16x32_bf16 v[112:115], v[136:139], v[188:191], v[112:115]
	v_mfma_f32_16x16x32_bf16 v[108:111], v[150:153], v[188:191], v[108:111]
	v_mfma_f32_16x16x32_bf16 v[96:99], v[136:139], v[204:207], v[96:99]
	v_mfma_f32_16x16x32_bf16 v[92:95], v[150:153], v[204:207], v[92:95]
	v_mfma_f32_16x16x32_bf16 v[80:83], v[136:139], v[212:215], v[80:83]
	v_mfma_f32_16x16x32_bf16 v[76:79], v[150:153], v[212:215], v[76:79]
	v_mfma_f32_16x16x32_bf16 v[128:131], v[146:149], v[184:187], v[128:131]
	v_mfma_f32_16x16x32_bf16 v[124:127], v[154:157], v[184:187], v[124:127]
	v_mfma_f32_16x16x32_bf16 v[112:115], v[146:149], v[192:195], v[112:115]
	v_mfma_f32_16x16x32_bf16 v[108:111], v[154:157], v[192:195], v[108:111]
	v_mfma_f32_16x16x32_bf16 v[96:99], v[146:149], v[208:211], v[96:99]
	v_mfma_f32_16x16x32_bf16 v[92:95], v[154:157], v[208:211], v[92:95]
	v_mfma_f32_16x16x32_bf16 v[80:83], v[146:149], v[216:219], v[80:83]
	v_mfma_f32_16x16x32_bf16 v[76:79], v[154:157], v[216:219], v[76:79]
	v_mfma_f32_16x16x32_bf16 v[120:123], v[164:167], v[180:183], v[120:123]
	v_mfma_f32_16x16x32_bf16 v[116:119], v[172:175], v[180:183], v[116:119]
	v_mfma_f32_16x16x32_bf16 v[104:107], v[164:167], v[188:191], v[104:107]
	v_mfma_f32_16x16x32_bf16 v[100:103], v[172:175], v[188:191], v[100:103]
	v_mfma_f32_16x16x32_bf16 v[88:91], v[164:167], v[204:207], v[88:91]
	v_mfma_f32_16x16x32_bf16 v[84:87], v[172:175], v[204:207], v[84:87]
	v_mfma_f32_16x16x32_bf16 v[72:75], v[164:167], v[212:215], v[72:75]
	v_mfma_f32_16x16x32_bf16 v[68:71], v[172:175], v[212:215], v[68:71]
	v_mfma_f32_16x16x32_bf16 v[120:123], v[168:171], v[184:187], v[120:123]
	v_mfma_f32_16x16x32_bf16 v[116:119], v[176:179], v[184:187], v[116:119]
	v_mfma_f32_16x16x32_bf16 v[104:107], v[168:171], v[192:195], v[104:107]
	v_mfma_f32_16x16x32_bf16 v[100:103], v[176:179], v[192:195], v[100:103]
	v_mfma_f32_16x16x32_bf16 v[88:91], v[168:171], v[208:211], v[88:91]
	v_mfma_f32_16x16x32_bf16 v[84:87], v[176:179], v[208:211], v[84:87]
	v_mfma_f32_16x16x32_bf16 v[72:75], v[168:171], v[216:219], v[72:75]
	v_mfma_f32_16x16x32_bf16 v[68:71], v[176:179], v[216:219], v[68:71]
	s_setprio 0
	s_barrier
	s_add_i32 s14, s25, s60
	v_lshl_add_u64 v[140:141], s[40:41], 0, v[2:3]
	s_mov_b32 m0, s14
	ds_read_b128 v[180:183], v145 offset:16384
	ds_read_b128 v[184:187], v145 offset:17408
	ds_read_b128 v[188:191], v145 offset:18432
	ds_read_b128 v[192:195], v145 offset:19456
	ds_read_b128 v[204:207], v145 offset:20480
	ds_read_b128 v[208:211], v145 offset:21504
	ds_read_b128 v[212:215], v145 offset:22528
	ds_read_b128 v[216:219], v145 offset:23552
	global_load_lds_dwordx4 v[140:141], off
	s_add_i32 m0, s14, 0x2000
	s_add_u32 s14, s40, 0x160000
	v_lshl_add_u64 v[160:161], s[40:41], 0, v[0:1]
	s_addc_u32 s15, s41, 0
	s_add_i32 s25, s26, s60
	global_load_lds_dwordx4 v[160:161], off
	v_lshl_add_u64 v[162:163], s[14:15], 0, v[2:3]
	s_mov_b32 m0, s25
	v_lshl_add_u64 v[196:197], s[42:43], 0, v[0:1]
	global_load_lds_dwordx4 v[162:163], off
	v_lshl_add_u64 v[162:163], s[14:15], 0, v[0:1]
	s_add_i32 m0, s25, 0x2000
	s_nop 0
	global_load_lds_dwordx4 v[162:163], off
	v_lshl_add_u64 v[162:163], s[42:43], 0, v[2:3]
	s_mov_b32 m0, s61
	s_nop 0
	global_load_lds_dwordx4 v[162:163], off
	s_mov_b32 m0, s62
	s_nop 0
	global_load_lds_dwordx4 v[196:197], off
	s_waitcnt vmcnt(8)
	s_waitcnt lgkmcnt(0)
	s_barrier
; #define PG8_STAGE(bufoff, gbase, voff) do { _Pragma("unroll") for (int _i = 0; _i < 2; ++_i) \
;         __builtin_amdgcn_global_load_lds((const unsigned*)((const char*)(gbase) + (voff)[_i]), (LAS unsigned*)(lds + (bufoff) + ldsw + _i * 8192), 16, 0, 0); } while (0)
; #define PG8_LDA(dst, b, h) do { _Pragma("unroll") for (int m = 0; m < 4; ++m) _Pragma("unroll") for (int k = 0; k < 2; ++k) dst[m][k] = *(const LAS bf16x8*)(lds + PG8_SA(b, h) + aoff + m * 2048 + k * 1024); } while (0)
; #define PG8_LDB(dst, b, h) do { _Pragma("unroll") for (int n = 0; n < 2; ++n) _Pragma("unroll") for (int k = 0; k < 2; ++k) dst[n][k] = *(const LAS bf16x8*)(lds + PG8_SB(b, h) + boff + n * 2048 + k * 1024); } while (0)
; #define PG8_MMA(ai, bj, At, Bt) do { __builtin_amdgcn_s_setprio(1); _Pragma("unroll") for (int m = 0; m < 4; ++m) _Pragma("unroll") for (int n = 0; n < 2; ++n) _Pragma("unroll") for (int k = 0; k < 2; ++k) \
;         acc[ai][bj][m][n] = __builtin_amdgcn_mfma_f32_16x16x32_bf16(Bt[n][k], At[m][k], acc[ai][bj][m][n], 0, 0, 0); __builtin_amdgcn_s_setprio(0); } while (0)
; #define PG8_WAIT_V(n) asm volatile("s_waitcnt vmcnt(" #n ")" ::: "memory")
; #define PG8_WAIT_L(n) asm volatile("s_waitcnt lgkmcnt(" #n ")" ::: "memory")
; #define PG8_BAR __builtin_amdgcn_s_barrier()
; #define PG8_SCHED __builtin_amdgcn_sched_barrier(0)
; template <class Epi, class Sched, bool ALIGN_EPI = true>
; __device__ __forceinline__ void gemm_phase(LAS unsigned char* lds, const Gemm g, const Sched& S, const Epi& E) {
;     ...
;             PG8_WAIT_V(8); PG8_WAIT_L(0); PG8_BAR; PG8_MMA(1, 0, At, B0); PG8_MMA(1, 1, At, B1); PG8_BAR; PG8_SCHED;
;             PG8_LDB(B0, 1, 0); PG8_LDB(B1, 1, 1); PG8_SCHED; PG8_LDA(At, 1, 0); PG8_STAGE(PG8_SA(0, 1), a2 + hA, voffA);
;             PG8_WAIT_V(8); PG8_WAIT_L(0); PG8_BAR; PG8_MMA(0, 0, At, B0); PG8_MMA(0, 1, At, B1); PG8_BAR; PG8_SCHED;
	s_setprio 1
	s_waitcnt lgkmcnt(0)
	v_mfma_f32_16x16x32_bf16 v[64:67], v[136:139], v[180:183], v[64:67]
	v_mfma_f32_16x16x32_bf16 v[60:63], v[150:153], v[180:183], v[60:63]
	v_mfma_f32_16x16x32_bf16 v[48:51], v[136:139], v[188:191], v[48:51]
	v_mfma_f32_16x16x32_bf16 v[44:47], v[150:153], v[188:191], v[44:47]
	v_mfma_f32_16x16x32_bf16 v[32:35], v[136:139], v[204:207], v[32:35]
	v_mfma_f32_16x16x32_bf16 v[28:31], v[150:153], v[204:207], v[28:31]
	v_mfma_f32_16x16x32_bf16 v[16:19], v[136:139], v[212:215], v[16:19]
	v_mfma_f32_16x16x32_bf16 v[12:15], v[150:153], v[212:215], v[12:15]
	v_mfma_f32_16x16x32_bf16 v[64:67], v[146:149], v[184:187], v[64:67]
	v_mfma_f32_16x16x32_bf16 v[60:63], v[154:157], v[184:187], v[60:63]
	v_mfma_f32_16x16x32_bf16 v[48:51], v[146:149], v[192:195], v[48:51]
	v_mfma_f32_16x16x32_bf16 v[44:47], v[154:157], v[192:195], v[44:47]
	v_mfma_f32_16x16x32_bf16 v[32:35], v[146:149], v[208:211], v[32:35]
	v_mfma_f32_16x16x32_bf16 v[28:31], v[154:157], v[208:211], v[28:31]
	v_mfma_f32_16x16x32_bf16 v[16:19], v[146:149], v[216:219], v[16:19]
	v_mfma_f32_16x16x32_bf16 v[12:15], v[154:157], v[216:219], v[12:15]
	v_mfma_f32_16x16x32_bf16 v[56:59], v[164:167], v[180:183], v[56:59]
	v_mfma_f32_16x16x32_bf16 v[52:55], v[172:175], v[180:183], v[52:55]
	v_mfma_f32_16x16x32_bf16 v[40:43], v[164:167], v[188:191], v[40:43]
	v_mfma_f32_16x16x32_bf16 v[36:39], v[172:175], v[188:191], v[36:39]
	v_mfma_f32_16x16x32_bf16 v[24:27], v[164:167], v[204:207], v[24:27]
	v_mfma_f32_16x16x32_bf16 v[20:23], v[172:175], v[204:207], v[20:23]
	v_mfma_f32_16x16x32_bf16 v[8:11], v[164:167], v[212:215], v[8:11]
	v_mfma_f32_16x16x32_bf16 v[4:7], v[172:175], v[212:215], v[4:7]
	v_mfma_f32_16x16x32_bf16 v[56:59], v[168:171], v[184:187], v[56:59]
	v_mfma_f32_16x16x32_bf16 v[52:55], v[176:179], v[184:187], v[52:55]
	v_mfma_f32_16x16x32_bf16 v[40:43], v[168:171], v[192:195], v[40:43]
	v_mfma_f32_16x16x32_bf16 v[36:39], v[176:179], v[192:195], v[36:39]
	v_mfma_f32_16x16x32_bf16 v[24:27], v[168:171], v[208:211], v[24:27]
	v_mfma_f32_16x16x32_bf16 v[20:23], v[176:179], v[208:211], v[20:23]
	v_mfma_f32_16x16x32_bf16 v[8:11], v[168:171], v[216:219], v[8:11]
	v_mfma_f32_16x16x32_bf16 v[4:7], v[176:179], v[216:219], v[4:7]
	s_setprio 0
	s_barrier
	s_add_i32 s25, 0, 0x18000
	s_add_i32 s26, 0, 0x1c000
	v_add_u32_e32 v154, s25, v143
	v_add_u32_e32 v158, s26, v143
	ds_read_b128 v[136:139], v154
	ds_read_b128 v[146:149], v154 offset:1024
	ds_read_b128 v[150:153], v154 offset:2048
	ds_read_b128 v[154:157], v154 offset:3072
	ds_read_b128 v[164:167], v158
	ds_read_b128 v[168:171], v158 offset:1024
	ds_read_b128 v[172:175], v158 offset:2048
	ds_read_b128 v[176:179], v158 offset:3072
	s_add_u32 s14, s42, 0x160000
	s_addc_u32 s15, s43, 0
	s_mov_b32 m0, s63
	v_lshl_add_u64 v[220:221], s[14:15], 0, v[2:3]
	ds_read_b128 v[180:183], v145 offset:32768
	ds_read_b128 v[184:187], v145 offset:33792
	ds_read_b128 v[188:191], v145 offset:34816
	ds_read_b128 v[192:195], v145 offset:35840
	ds_read_b128 v[204:207], v145 offset:36864
	ds_read_b128 v[208:211], v145 offset:37888
	ds_read_b128 v[212:215], v145 offset:38912
	ds_read_b128 v[216:219], v145 offset:39936
	global_load_lds_dwordx4 v[220:221], off
	v_lshl_add_u64 v[220:221], s[14:15], 0, v[0:1]
	s_mov_b32 m0, s64
	s_nop 0
	global_load_lds_dwordx4 v[220:221], off
	s_waitcnt vmcnt(8)
	s_waitcnt lgkmcnt(0)
	s_barrier
	s_setprio 1
	s_waitcnt lgkmcnt(0)
	v_mfma_f32_16x16x32_bf16 v[128:131], v[136:139], v[180:183], v[128:131]
	v_mfma_f32_16x16x32_bf16 v[124:127], v[150:153], v[180:183], v[124:127]
	v_mfma_f32_16x16x32_bf16 v[112:115], v[136:139], v[188:191], v[112:115]
	v_mfma_f32_16x16x32_bf16 v[108:111], v[150:153], v[188:191], v[108:111]
	v_mfma_f32_16x16x32_bf16 v[96:99], v[136:139], v[204:207], v[96:99]
	v_mfma_f32_16x16x32_bf16 v[92:95], v[150:153], v[204:207], v[92:95]
	v_mfma_f32_16x16x32_bf16 v[80:83], v[136:139], v[212:215], v[80:83]
	v_mfma_f32_16x16x32_bf16 v[76:79], v[150:153], v[212:215], v[76:79]
	v_mfma_f32_16x16x32_bf16 v[128:131], v[146:149], v[184:187], v[128:131]
	v_mfma_f32_16x16x32_bf16 v[124:127], v[154:157], v[184:187], v[124:127]
	v_mfma_f32_16x16x32_bf16 v[112:115], v[146:149], v[192:195], v[112:115]
	v_mfma_f32_16x16x32_bf16 v[108:111], v[154:157], v[192:195], v[108:111]
	v_mfma_f32_16x16x32_bf16 v[96:99], v[146:149], v[208:211], v[96:99]
	v_mfma_f32_16x16x32_bf16 v[92:95], v[154:157], v[208:211], v[92:95]
	v_mfma_f32_16x16x32_bf16 v[80:83], v[146:149], v[216:219], v[80:83]
	v_mfma_f32_16x16x32_bf16 v[76:79], v[154:157], v[216:219], v[76:79]
	v_mfma_f32_16x16x32_bf16 v[120:123], v[164:167], v[180:183], v[120:123]
	v_mfma_f32_16x16x32_bf16 v[116:119], v[172:175], v[180:183], v[116:119]
	v_mfma_f32_16x16x32_bf16 v[104:107], v[164:167], v[188:191], v[104:107]
	v_mfma_f32_16x16x32_bf16 v[100:103], v[172:175], v[188:191], v[100:103]
	v_mfma_f32_16x16x32_bf16 v[88:91], v[164:167], v[204:207], v[88:91]
	v_mfma_f32_16x16x32_bf16 v[84:87], v[172:175], v[204:207], v[84:87]
	v_mfma_f32_16x16x32_bf16 v[72:75], v[164:167], v[212:215], v[72:75]
	v_mfma_f32_16x16x32_bf16 v[68:71], v[172:175], v[212:215], v[68:71]
	v_mfma_f32_16x16x32_bf16 v[120:123], v[168:171], v[184:187], v[120:123]
	v_mfma_f32_16x16x32_bf16 v[116:119], v[176:179], v[184:187], v[116:119]
	v_mfma_f32_16x16x32_bf16 v[104:107], v[168:171], v[192:195], v[104:107]
	v_mfma_f32_16x16x32_bf16 v[100:103], v[176:179], v[192:195], v[100:103]
	v_mfma_f32_16x16x32_bf16 v[88:91], v[168:171], v[208:211], v[88:91]
	v_mfma_f32_16x16x32_bf16 v[84:87], v[176:179], v[208:211], v[84:87]
	v_mfma_f32_16x16x32_bf16 v[72:75], v[168:171], v[216:219], v[72:75]
	v_mfma_f32_16x16x32_bf16 v[68:71], v[176:179], v[216:219], v[68:71]
	s_setprio 0
	s_barrier
; #define PG8_STAGE(bufoff, gbase, voff) do { _Pragma("unroll") for (int _i = 0; _i < 2; ++_i) \
;         __builtin_amdgcn_global_load_lds((const unsigned*)((const char*)(gbase) + (voff)[_i]), (LAS unsigned*)(lds + (bufoff) + ldsw + _i * 8192), 16, 0, 0); } while (0)
; #define PG8_LDA(dst, b, h) do { _Pragma("unroll") for (int m = 0; m < 4; ++m) _Pragma("unroll") for (int k = 0; k < 2; ++k) dst[m][k] = *(const LAS bf16x8*)(lds + PG8_SA(b, h) + aoff + m * 2048 + k * 1024); } while (0)
; #define PG8_MMA(ai, bj, At, Bt) do { __builtin_amdgcn_s_setprio(1); _Pragma("unroll") for (int m = 0; m < 4; ++m) _Pragma("unroll") for (int n = 0; n < 2; ++n) _Pragma("unroll") for (int k = 0; k < 2; ++k) \
;         acc[ai][bj][m][n] = __builtin_amdgcn_mfma_f32_16x16x32_bf16(Bt[n][k], At[m][k], acc[ai][bj][m][n], 0, 0, 0); __builtin_amdgcn_s_setprio(0); } while (0)
; #define PG8_WAIT_V(n) asm volatile("s_waitcnt vmcnt(" #n ")" ::: "memory")
; #define PG8_WAIT_L(n) asm volatile("s_waitcnt lgkmcnt(" #n ")" ::: "memory")
; #define PG8_BAR __builtin_amdgcn_s_barrier()
; #define PG8_SCHED __builtin_amdgcn_sched_barrier(0)
; template <class Epi, class Sched, bool ALIGN_EPI = true>
; __device__ __forceinline__ void gemm_phase(LAS unsigned char* lds, const Gemm g, const Sched& S, const Epi& E) {
;     ...
;             PG8_LDA(At, 1, 1); PG8_STAGE(PG8_SB(1, 0), b3, voffB); PG8_STAGE(PG8_SB(1, 1), b3 + hB, voffB); PG8_STAGE(PG8_SA(1, 0), a3, voffA);
;             PG8_WAIT_V(8); PG8_WAIT_L(0); PG8_BAR; PG8_MMA(1, 0, At, B0); PG8_MMA(1, 1, At, B1); PG8_BAR; PG8_SCHED;
;         }
;         if constexpr (ALIGN_EPI) { if (wr == 0) PG8_BAR; }
	s_add_i32 s14, s25, s60
	v_lshl_add_u64 v[140:141], v[140:141], 0, s[86:87]
	s_mov_b32 m0, s14
	ds_read_b128 v[180:183], v145 offset:49152
	ds_read_b128 v[184:187], v145 offset:50176
	ds_read_b128 v[188:191], v145 offset:51200
	ds_read_b128 v[192:195], v145 offset:52224
	ds_read_b128 v[204:207], v145 offset:53248
	ds_read_b128 v[208:211], v145 offset:54272
	ds_read_b128 v[212:215], v145 offset:55296
	ds_read_b128 v[216:219], v145 offset:56320
	global_load_lds_dwordx4 v[140:141], off
	s_add_i32 m0, s14, 0x2000
	s_add_u32 s14, s40, 0x160080
	v_lshl_add_u64 v[140:141], v[160:161], 0, s[86:87]
	s_addc_u32 s15, s41, 0
	s_add_i32 s25, s26, s60
	global_load_lds_dwordx4 v[140:141], off
	v_lshl_add_u64 v[140:141], s[14:15], 0, v[2:3]
	s_mov_b32 m0, s25
	s_nop 0
	global_load_lds_dwordx4 v[140:141], off
	v_lshl_add_u64 v[140:141], s[14:15], 0, v[0:1]
	s_add_i32 m0, s25, 0x2000
	s_nop 0
	global_load_lds_dwordx4 v[140:141], off
	v_lshl_add_u64 v[140:141], v[162:163], 0, s[86:87]
	s_mov_b32 m0, s65
	s_nop 0
	global_load_lds_dwordx4 v[140:141], off
	v_lshl_add_u64 v[140:141], v[196:197], 0, s[86:87]
	s_mov_b32 m0, s66
	s_nop 0
	global_load_lds_dwordx4 v[140:141], off
	s_waitcnt vmcnt(8)
	s_waitcnt lgkmcnt(0)
	s_barrier
	s_setprio 1
	s_waitcnt lgkmcnt(0)
	v_mfma_f32_16x16x32_bf16 v[64:67], v[136:139], v[180:183], v[64:67]
	v_mfma_f32_16x16x32_bf16 v[60:63], v[150:153], v[180:183], v[60:63]
	v_mfma_f32_16x16x32_bf16 v[48:51], v[136:139], v[188:191], v[48:51]
	v_mfma_f32_16x16x32_bf16 v[44:47], v[150:153], v[188:191], v[44:47]
	v_mfma_f32_16x16x32_bf16 v[32:35], v[136:139], v[204:207], v[32:35]
	v_mfma_f32_16x16x32_bf16 v[28:31], v[150:153], v[204:207], v[28:31]
	v_mfma_f32_16x16x32_bf16 v[16:19], v[136:139], v[212:215], v[16:19]
	v_mfma_f32_16x16x32_bf16 v[12:15], v[150:153], v[212:215], v[12:15]
	v_mfma_f32_16x16x32_bf16 v[64:67], v[146:149], v[184:187], v[64:67]
	v_mfma_f32_16x16x32_bf16 v[60:63], v[154:157], v[184:187], v[60:63]
	v_mfma_f32_16x16x32_bf16 v[48:51], v[146:149], v[192:195], v[48:51]
	v_mfma_f32_16x16x32_bf16 v[44:47], v[154:157], v[192:195], v[44:47]
	v_mfma_f32_16x16x32_bf16 v[32:35], v[146:149], v[208:211], v[32:35]
	v_mfma_f32_16x16x32_bf16 v[28:31], v[154:157], v[208:211], v[28:31]
	v_mfma_f32_16x16x32_bf16 v[16:19], v[146:149], v[216:219], v[16:19]
	v_mfma_f32_16x16x32_bf16 v[12:15], v[154:157], v[216:219], v[12:15]
	v_mfma_f32_16x16x32_bf16 v[56:59], v[164:167], v[180:183], v[56:59]
	v_mfma_f32_16x16x32_bf16 v[52:55], v[172:175], v[180:183], v[52:55]
	v_mfma_f32_16x16x32_bf16 v[40:43], v[164:167], v[188:191], v[40:43]
	v_mfma_f32_16x16x32_bf16 v[36:39], v[172:175], v[188:191], v[36:39]
	v_mfma_f32_16x16x32_bf16 v[24:27], v[164:167], v[204:207], v[24:27]
	v_mfma_f32_16x16x32_bf16 v[20:23], v[172:175], v[204:207], v[20:23]
	v_mfma_f32_16x16x32_bf16 v[8:11], v[164:167], v[212:215], v[8:11]
	v_mfma_f32_16x16x32_bf16 v[4:7], v[172:175], v[212:215], v[4:7]
	v_mfma_f32_16x16x32_bf16 v[56:59], v[168:171], v[184:187], v[56:59]
	v_mfma_f32_16x16x32_bf16 v[52:55], v[176:179], v[184:187], v[52:55]
	v_mfma_f32_16x16x32_bf16 v[40:43], v[168:171], v[192:195], v[40:43]
	v_mfma_f32_16x16x32_bf16 v[36:39], v[176:179], v[192:195], v[36:39]
	v_mfma_f32_16x16x32_bf16 v[24:27], v[168:171], v[208:211], v[24:27]
	v_mfma_f32_16x16x32_bf16 v[20:23], v[176:179], v[208:211], v[20:23]
	v_mfma_f32_16x16x32_bf16 v[8:11], v[168:171], v[216:219], v[8:11]
	v_mfma_f32_16x16x32_bf16 v[4:7], v[176:179], v[216:219], v[4:7]
	s_setprio 0
	s_barrier
	s_add_i32 s24, s24, 2
	s_add_u32 s18, s18, 0x100
	s_addc_u32 s19, s19, 0
	s_cmpk_gt_u32 s24, 0x55
	s_mov_b64 s[14:15], s[38:39]
	s_cbranch_scc0 .LBB0_986
	s_and_b64 vcc, exec, s[8:9]
	s_cbranch_vccz .LBB0_989
	s_barrier

;     __device__ bool next(int i, Unit& u) const { if (i >= 2) return false; const int x = c & 7, j = c >> 3; u.pm = 32 * i + 4 * x + (j & 3); u.pn = j >> 2; return true; }
; #define PG8_STAGE(bufoff, gbase, voff) do { _Pragma("unroll") for (int _i = 0; _i < 2; ++_i) \
;         __builtin_amdgcn_global_load_lds((const unsigned*)((const char*)(gbase) + (voff)[_i]), (LAS unsigned*)(lds + (bufoff) + ldsw + _i * 8192), 16, 0, 0); } while (0)
; #define PG8_LDA(dst, b, h) do { _Pragma("unroll") for (int m = 0; m < 4; ++m) _Pragma("unroll") for (int k = 0; k < 2; ++k) dst[m][k] = *(const LAS bf16x8*)(lds + PG8_SA(b, h) + aoff + m * 2048 + k * 1024); } while (0)
; #define PG8_LDB(dst, b, h) do { _Pragma("unroll") for (int n = 0; n < 2; ++n) _Pragma("unroll") for (int k = 0; k < 2; ++k) dst[n][k] = *(const LAS bf16x8*)(lds + PG8_SB(b, h) + boff + n * 2048 + k * 1024); } while (0)
; #define PG8_WAIT_V(n) asm volatile("s_waitcnt vmcnt(" #n ")" ::: "memory")
; #define PG8_WAIT_L(n) asm volatile("s_waitcnt lgkmcnt(" #n ")" ::: "memory")
; #define PG8_BAR __builtin_amdgcn_s_barrier()
; template <class Epi, class Sched, bool ALIGN_EPI = true>
; __device__ __forceinline__ void gemm_phase(LAS unsigned char* lds, const Gemm g, const Sched& S, const Epi& E) {
;     ...
;         const bool has_next = S.next(ui + 1, nxt);
;         const char* nA = has_next ? (const char*)g.A + ((size_t)nxt.pm * BM * g.lda + (size_t)nxt.pn * g.a_pn_off) * 2 : cA; const char* nB = has_next ? (const char*)g.Bt + (size_t)nxt.pn * BM * g.ldb * 2 : cB;
;         for (int t = 0; t < nt; t += 2) {
;             const bool last = (t == nt - 2);
;             const char* a1 = cA + (size_t)(t + 1) * kstep;
;             const char* a2 = last ? nA : cA + (size_t)(t + 2) * kstep; const char* b2 = last ? nB : cB + (size_t)(t + 2) * kstep;
;             const char* a3 = a2 + kstep; const char* b3 = b2 + kstep;
;             PG8_LDB(B0, 0, 0); PG8_LDB(B1, 0, 1); PG8_SCHED; PG8_LDA(At, 0, 0); PG8_STAGE(PG8_SA(1, 1), a1 + hA, voffA);
;             PG8_WAIT_V(8); PG8_WAIT_L(0); PG8_BAR; PG8_MMA(0, 0, At, B0); PG8_MMA(0, 1, At, B1); PG8_BAR; PG8_SCHED;
;             PG8_LDA(At, 0, 1); PG8_STAGE(PG8_SB(0, 0), b2, voffB); PG8_STAGE(PG8_SB(0, 1), b2 + hB, voffB); PG8_STAGE(PG8_SA(0, 0), a2, voffA);
;             PG8_WAIT_V(8); PG8_WAIT_L(0); PG8_BAR; PG8_MMA(1, 0, At, B0); PG8_MMA(1, 1, At, B1); PG8_BAR; PG8_SCHED;
.LBB0_1110:
	s_add_u32 s16, s10, 0x100
	s_addc_u32 s17, s11, 0
	s_add_u32 s10, s10, 0x160080
	s_addc_u32 s11, s11, 0
	v_lshl_add_u64 v[132:133], s[10:11], 0, v[168:169]
	v_lshl_add_u64 v[134:135], s[10:11], 0, v[170:171]
	s_mov_b32 s18, -2
	s_mov_b64 s[10:11], 0
	s_add_u32 vcc_lo, s10, 0x100
	s_addc_u32 vcc_hi, s11, 0
	s_add_u32 s19, s16, s10
	s_addc_u32 s24, s17, s11
	s_add_i32 s25, 0, 0x10000
	s_cmpk_eq_i32 s18, 0x54
	s_cselect_b32 s65, s61, s24
	s_cselect_b32 s24, 0, vcc_lo
	s_cselect_b32 s64, s60, s19
	s_cselect_b32 s19, 0, vcc_hi
	s_add_u32 s62, s2, s24
	v_add_u32_e32 v160, s25, v188
	s_addc_u32 s63, s3, s19
	s_add_i32 s19, 0, 0x14000
	ds_read_b128 v[136:139], v160
	ds_read_b128 v[140:143], v160 offset:1024
	ds_read_b128 v[144:147], v160 offset:2048
	ds_read_b128 v[172:175], v160 offset:3072
	v_add_u32_e32 v160, s19, v188
	ds_read_b128 v[176:179], v160
	ds_read_b128 v[180:183], v160 offset:1024
	ds_read_b128 v[184:187], v160 offset:2048
	ds_read_b128 v[208:211], v160 offset:3072
	v_lshl_add_u64 v[160:161], v[132:133], 0, s[10:11]
	s_add_i32 m0, s67, 0xc000
	ds_read_b128 v[212:215], v197
	ds_read_b128 v[216:219], v197 offset:1024
	ds_read_b128 v[220:223], v197 offset:2048
	ds_read_b128 v[224:227], v197 offset:3072
	ds_read_b128 v[228:231], v197 offset:4096
	ds_read_b128 v[232:235], v197 offset:5120
	ds_read_b128 v[236:239], v197 offset:6144
	ds_read_b128 v[240:243], v197 offset:7168
	global_load_lds_dwordx4 v[160:161], off
	v_lshl_add_u64 v[160:161], v[134:135], 0, s[10:11]
	s_add_i32 m0, s67, 0xe000
	s_nop 0
	global_load_lds_dwordx4 v[160:161], off
	s_waitcnt vmcnt(8)
	s_waitcnt lgkmcnt(0)
	s_barrier
	s_setprio 1
	s_waitcnt lgkmcnt(0)
	v_mfma_f32_16x16x32_bf16 v[16:19], v[136:139], v[212:215], 0
	v_mfma_f32_16x16x32_bf16 v[16:19], v[140:143], v[216:219], v[16:19]
	v_mfma_f32_16x16x32_bf16 v[12:15], v[144:147], v[212:215], 0
	v_mfma_f32_16x16x32_bf16 v[12:15], v[172:175], v[216:219], v[12:15]
	v_mfma_f32_16x16x32_bf16 v[56:59], v[136:139], v[220:223], 0
	v_mfma_f32_16x16x32_bf16 v[56:59], v[140:143], v[224:227], v[56:59]
	v_mfma_f32_16x16x32_bf16 v[52:55], v[144:147], v[220:223], 0
	v_mfma_f32_16x16x32_bf16 v[52:55], v[172:175], v[224:227], v[52:55]
	v_mfma_f32_16x16x32_bf16 v[88:91], v[136:139], v[228:231], 0
	v_mfma_f32_16x16x32_bf16 v[88:91], v[140:143], v[232:235], v[88:91]
	v_mfma_f32_16x16x32_bf16 v[76:79], v[144:147], v[228:231], 0
	v_mfma_f32_16x16x32_bf16 v[76:79], v[172:175], v[232:235], v[76:79]
	v_mfma_f32_16x16x32_bf16 v[112:115], v[136:139], v[236:239], 0
	v_mfma_f32_16x16x32_bf16 v[112:115], v[140:143], v[240:243], v[112:115]
	v_mfma_f32_16x16x32_bf16 v[108:111], v[144:147], v[236:239], 0
	v_mfma_f32_16x16x32_bf16 v[108:111], v[172:175], v[240:243], v[108:111]
	v_mfma_f32_16x16x32_bf16 v[8:11], v[176:179], v[212:215], 0
	v_mfma_f32_16x16x32_bf16 v[8:11], v[180:183], v[216:219], v[8:11]
	v_mfma_f32_16x16x32_bf16 v[4:7], v[184:187], v[212:215], 0
	v_mfma_f32_16x16x32_bf16 v[4:7], v[208:211], v[216:219], v[4:7]
	v_mfma_f32_16x16x32_bf16 v[40:43], v[176:179], v[220:223], 0
	v_mfma_f32_16x16x32_bf16 v[40:43], v[180:183], v[224:227], v[40:43]
	v_mfma_f32_16x16x32_bf16 v[36:39], v[184:187], v[220:223], 0
	v_mfma_f32_16x16x32_bf16 v[36:39], v[208:211], v[224:227], v[36:39]
	v_mfma_f32_16x16x32_bf16 v[64:67], v[176:179], v[228:231], 0
	v_mfma_f32_16x16x32_bf16 v[64:67], v[180:183], v[232:235], v[64:67]
	v_mfma_f32_16x16x32_bf16 v[60:63], v[184:187], v[228:231], 0
	v_mfma_f32_16x16x32_bf16 v[60:63], v[208:211], v[232:235], v[60:63]
	v_mfma_f32_16x16x32_bf16 v[96:99], v[176:179], v[236:239], 0
	v_mfma_f32_16x16x32_bf16 v[96:99], v[180:183], v[240:243], v[96:99]
	s_setprio 2
	s_barrier
	v_mfma_f32_16x16x32_bf16 v[92:95], v[184:187], v[236:239], 0
	v_mfma_f32_16x16x32_bf16 v[92:95], v[208:211], v[240:243], v[92:95]
	s_setprio 0
	s_add_i32 s10, s25, s66
	v_lshl_add_u64 v[160:161], s[62:63], 0, v[2:3]
	s_mov_b32 m0, s10
	ds_read_b128 v[212:215], v197 offset:16384
	ds_read_b128 v[216:219], v197 offset:17408
	ds_read_b128 v[220:223], v197 offset:18432
	ds_read_b128 v[224:227], v197 offset:19456
	ds_read_b128 v[228:231], v197 offset:20480
	ds_read_b128 v[232:235], v197 offset:21504
	ds_read_b128 v[236:239], v197 offset:22528
	ds_read_b128 v[240:243], v197 offset:23552
	global_load_lds_dwordx4 v[160:161], off
	s_add_i32 m0, s10, 0x2000
	s_add_u32 s10, s62, 0x160000
	v_lshl_add_u64 v[162:163], s[62:63], 0, v[150:151]
	s_addc_u32 s11, s63, 0
	s_add_i32 s19, s19, s66
	global_load_lds_dwordx4 v[162:163], off
	v_lshl_add_u64 v[244:245], s[10:11], 0, v[2:3]
	s_mov_b32 m0, s19
	v_lshl_add_u64 v[246:247], s[64:65], 0, v[148:149]
	global_load_lds_dwordx4 v[244:245], off
	v_lshl_add_u64 v[244:245], s[10:11], 0, v[150:151]
	s_add_i32 m0, s19, 0x2000
	s_nop 0
	global_load_lds_dwordx4 v[244:245], off
	v_lshl_add_u64 v[244:245], s[64:65], 0, v[0:1]
	s_mov_b32 m0, s67
	s_nop 0
	global_load_lds_dwordx4 v[244:245], off
	s_mov_b32 m0, s75
	s_nop 0
	global_load_lds_dwordx4 v[246:247], off
	s_waitcnt vmcnt(8)
	s_waitcnt lgkmcnt(0)
	s_barrier
; #define PG8_STAGE(bufoff, gbase, voff) do { _Pragma("unroll") for (int _i = 0; _i < 2; ++_i) \
;         __builtin_amdgcn_global_load_lds((const unsigned*)((const char*)(gbase) + (voff)[_i]), (LAS unsigned*)(lds + (bufoff) + ldsw + _i * 8192), 16, 0, 0); } while (0)
; #define PG8_LDA(dst, b, h) do { _Pragma("unroll") for (int m = 0; m < 4; ++m) _Pragma("unroll") for (int k = 0; k < 2; ++k) dst[m][k] = *(const LAS bf16x8*)(lds + PG8_SA(b, h) + aoff + m * 2048 + k * 1024); } while (0)
; #define PG8_LDB(dst, b, h) do { _Pragma("unroll") for (int n = 0; n < 2; ++n) _Pragma("unroll") for (int k = 0; k < 2; ++k) dst[n][k] = *(const LAS bf16x8*)(lds + PG8_SB(b, h) + boff + n * 2048 + k * 1024); } while (0)
; #define PG8_MMA(ai, bj, At, Bt) do { __builtin_amdgcn_s_setprio(1); _Pragma("unroll") for (int m = 0; m < 4; ++m) _Pragma("unroll") for (int n = 0; n < 2; ++n) _Pragma("unroll") for (int k = 0; k < 2; ++k) \
;         acc[ai][bj][m][n] = __builtin_amdgcn_mfma_f32_16x16x32_bf16(Bt[n][k], At[m][k], acc[ai][bj][m][n], 0, 0, 0); __builtin_amdgcn_s_setprio(0); } while (0)
; #define PG8_WAIT_V(n) asm volatile("s_waitcnt vmcnt(" #n ")" ::: "memory")
; #define PG8_WAIT_L(n) asm volatile("s_waitcnt lgkmcnt(" #n ")" ::: "memory")
; #define PG8_BAR __builtin_amdgcn_s_barrier()
; #define PG8_SCHED __builtin_amdgcn_sched_barrier(0)
; template <class Epi, class Sched, bool ALIGN_EPI = true>
; __device__ __forceinline__ void gemm_phase(LAS unsigned char* lds, const Gemm g, const Sched& S, const Epi& E) {
;     ...
;             PG8_WAIT_V(8); PG8_WAIT_L(0); PG8_BAR; PG8_MMA(1, 0, At, B0); PG8_MMA(1, 1, At, B1); PG8_BAR; PG8_SCHED;
;             PG8_LDB(B0, 1, 0); PG8_LDB(B1, 1, 1); PG8_SCHED; PG8_LDA(At, 1, 0); PG8_STAGE(PG8_SA(0, 1), a2 + hA, voffA);
;             PG8_WAIT_V(8); PG8_WAIT_L(0); PG8_BAR; PG8_MMA(0, 0, At, B0); PG8_MMA(0, 1, At, B1); PG8_BAR; PG8_SCHED;
	s_setprio 1
	s_waitcnt lgkmcnt(0)
	v_mfma_f32_16x16x32_bf16 v[128:131], v[136:139], v[212:215], 0
	v_mfma_f32_16x16x32_bf16 v[128:131], v[140:143], v[216:219], v[128:131]
	v_mfma_f32_16x16x32_bf16 v[124:127], v[144:147], v[212:215], 0
	v_mfma_f32_16x16x32_bf16 v[124:127], v[172:175], v[216:219], v[124:127]
	v_mfma_f32_16x16x32_bf16 v[104:107], v[136:139], v[220:223], 0
	v_mfma_f32_16x16x32_bf16 v[104:107], v[140:143], v[224:227], v[104:107]
	v_mfma_f32_16x16x32_bf16 v[100:103], v[144:147], v[220:223], 0
	v_mfma_f32_16x16x32_bf16 v[100:103], v[172:175], v[224:227], v[100:103]
	v_mfma_f32_16x16x32_bf16 v[72:75], v[136:139], v[228:231], 0
	v_mfma_f32_16x16x32_bf16 v[72:75], v[140:143], v[232:235], v[72:75]
	v_mfma_f32_16x16x32_bf16 v[68:71], v[144:147], v[228:231], 0
	v_mfma_f32_16x16x32_bf16 v[68:71], v[172:175], v[232:235], v[68:71]
	v_mfma_f32_16x16x32_bf16 v[32:35], v[136:139], v[236:239], 0
	v_mfma_f32_16x16x32_bf16 v[32:35], v[140:143], v[240:243], v[32:35]
	v_mfma_f32_16x16x32_bf16 v[28:31], v[144:147], v[236:239], 0
	v_mfma_f32_16x16x32_bf16 v[28:31], v[172:175], v[240:243], v[28:31]
	v_mfma_f32_16x16x32_bf16 v[120:123], v[176:179], v[212:215], 0
	v_mfma_f32_16x16x32_bf16 v[120:123], v[180:183], v[216:219], v[120:123]
	v_mfma_f32_16x16x32_bf16 v[116:119], v[184:187], v[212:215], 0
	v_mfma_f32_16x16x32_bf16 v[116:119], v[208:211], v[216:219], v[116:119]
	v_mfma_f32_16x16x32_bf16 v[84:87], v[176:179], v[220:223], 0
	v_mfma_f32_16x16x32_bf16 v[84:87], v[180:183], v[224:227], v[84:87]
	v_mfma_f32_16x16x32_bf16 v[80:83], v[184:187], v[220:223], 0
	v_mfma_f32_16x16x32_bf16 v[80:83], v[208:211], v[224:227], v[80:83]
	v_mfma_f32_16x16x32_bf16 v[48:51], v[176:179], v[228:231], 0
	v_mfma_f32_16x16x32_bf16 v[48:51], v[180:183], v[232:235], v[48:51]
	v_mfma_f32_16x16x32_bf16 v[44:47], v[184:187], v[228:231], 0
	v_mfma_f32_16x16x32_bf16 v[44:47], v[208:211], v[232:235], v[44:47]
	v_mfma_f32_16x16x32_bf16 v[24:27], v[176:179], v[236:239], 0
	v_mfma_f32_16x16x32_bf16 v[24:27], v[180:183], v[240:243], v[24:27]
	s_setprio 2
	s_barrier
	v_mfma_f32_16x16x32_bf16 v[20:23], v[184:187], v[236:239], 0
	v_mfma_f32_16x16x32_bf16 v[20:23], v[208:211], v[240:243], v[20:23]
	s_setprio 0
	s_add_i32 s19, 0, 0x18000
	s_add_i32 s24, 0, 0x1c000
	v_add_u32_e32 v172, s19, v188
	v_add_u32_e32 v207, s24, v188
	ds_read_b128 v[136:139], v172
	ds_read_b128 v[140:143], v172 offset:1024
	ds_read_b128 v[144:147], v172 offset:2048
	ds_read_b128 v[172:175], v172 offset:3072
	ds_read_b128 v[176:179], v207
	ds_read_b128 v[180:183], v207 offset:1024
	ds_read_b128 v[184:187], v207 offset:2048
	ds_read_b128 v[208:211], v207 offset:3072
	s_add_u32 s10, s64, 0x160000
	s_addc_u32 s11, s65, 0
	s_mov_b32 m0, s76
	v_lshl_add_u64 v[248:249], s[10:11], 0, v[0:1]
	ds_read_b128 v[212:215], v197 offset:32768
	ds_read_b128 v[216:219], v197 offset:33792
	ds_read_b128 v[220:223], v197 offset:34816
	ds_read_b128 v[224:227], v197 offset:35840
	ds_read_b128 v[228:231], v197 offset:36864
	ds_read_b128 v[232:235], v197 offset:37888
	ds_read_b128 v[236:239], v197 offset:38912
	ds_read_b128 v[240:243], v197 offset:39936
	global_load_lds_dwordx4 v[248:249], off
	v_lshl_add_u64 v[248:249], s[10:11], 0, v[148:149]
	s_mov_b32 m0, s77
	s_nop 0
	global_load_lds_dwordx4 v[248:249], off
	s_waitcnt vmcnt(8)
	s_waitcnt lgkmcnt(0)
	s_barrier
	s_setprio 1
	s_waitcnt lgkmcnt(0)
	v_mfma_f32_16x16x32_bf16 v[16:19], v[136:139], v[212:215], v[16:19]
	v_mfma_f32_16x16x32_bf16 v[16:19], v[140:143], v[216:219], v[16:19]
	v_mfma_f32_16x16x32_bf16 v[12:15], v[144:147], v[212:215], v[12:15]
	v_mfma_f32_16x16x32_bf16 v[12:15], v[172:175], v[216:219], v[12:15]
	v_mfma_f32_16x16x32_bf16 v[56:59], v[136:139], v[220:223], v[56:59]
	v_mfma_f32_16x16x32_bf16 v[56:59], v[140:143], v[224:227], v[56:59]
	v_mfma_f32_16x16x32_bf16 v[52:55], v[144:147], v[220:223], v[52:55]
	v_mfma_f32_16x16x32_bf16 v[52:55], v[172:175], v[224:227], v[52:55]
	v_mfma_f32_16x16x32_bf16 v[88:91], v[136:139], v[228:231], v[88:91]
	v_mfma_f32_16x16x32_bf16 v[88:91], v[140:143], v[232:235], v[88:91]
	v_mfma_f32_16x16x32_bf16 v[76:79], v[144:147], v[228:231], v[76:79]
	v_mfma_f32_16x16x32_bf16 v[76:79], v[172:175], v[232:235], v[76:79]
	v_mfma_f32_16x16x32_bf16 v[112:115], v[136:139], v[236:239], v[112:115]
	v_mfma_f32_16x16x32_bf16 v[112:115], v[140:143], v[240:243], v[112:115]
	v_mfma_f32_16x16x32_bf16 v[108:111], v[144:147], v[236:239], v[108:111]
	v_mfma_f32_16x16x32_bf16 v[108:111], v[172:175], v[240:243], v[108:111]
	v_mfma_f32_16x16x32_bf16 v[8:11], v[176:179], v[212:215], v[8:11]
	v_mfma_f32_16x16x32_bf16 v[8:11], v[180:183], v[216:219], v[8:11]
	v_mfma_f32_16x16x32_bf16 v[4:7], v[184:187], v[212:215], v[4:7]
	v_mfma_f32_16x16x32_bf16 v[4:7], v[208:211], v[216:219], v[4:7]
	v_mfma_f32_16x16x32_bf16 v[40:43], v[176:179], v[220:223], v[40:43]
	v_mfma_f32_16x16x32_bf16 v[40:43], v[180:183], v[224:227], v[40:43]
	v_mfma_f32_16x16x32_bf16 v[36:39], v[184:187], v[220:223], v[36:39]
	v_mfma_f32_16x16x32_bf16 v[36:39], v[208:211], v[224:227], v[36:39]
	v_mfma_f32_16x16x32_bf16 v[64:67], v[176:179], v[228:231], v[64:67]
	v_mfma_f32_16x16x32_bf16 v[64:67], v[180:183], v[232:235], v[64:67]
	v_mfma_f32_16x16x32_bf16 v[60:63], v[184:187], v[228:231], v[60:63]
	v_mfma_f32_16x16x32_bf16 v[60:63], v[208:211], v[232:235], v[60:63]
	v_mfma_f32_16x16x32_bf16 v[96:99], v[176:179], v[236:239], v[96:99]
	v_mfma_f32_16x16x32_bf16 v[96:99], v[180:183], v[240:243], v[96:99]
	s_setprio 2
	s_barrier
; #define PG8_STAGE(bufoff, gbase, voff) do { _Pragma("unroll") for (int _i = 0; _i < 2; ++_i) \
;         __builtin_amdgcn_global_load_lds((const unsigned*)((const char*)(gbase) + (voff)[_i]), (LAS unsigned*)(lds + (bufoff) + ldsw + _i * 8192), 16, 0, 0); } while (0)
; #define PG8_LDA(dst, b, h) do { _Pragma("unroll") for (int m = 0; m < 4; ++m) _Pragma("unroll") for (int k = 0; k < 2; ++k) dst[m][k] = *(const LAS bf16x8*)(lds + PG8_SA(b, h) + aoff + m * 2048 + k * 1024); } while (0)
; #define PG8_MMA(ai, bj, At, Bt) do { __builtin_amdgcn_s_setprio(1); _Pragma("unroll") for (int m = 0; m < 4; ++m) _Pragma("unroll") for (int n = 0; n < 2; ++n) _Pragma("unroll") for (int k = 0; k < 2; ++k) \
;         acc[ai][bj][m][n] = __builtin_amdgcn_mfma_f32_16x16x32_bf16(Bt[n][k], At[m][k], acc[ai][bj][m][n], 0, 0, 0); __builtin_amdgcn_s_setprio(0); } while (0)
; #define PG8_WAIT_V(n) asm volatile("s_waitcnt vmcnt(" #n ")" ::: "memory")
; #define PG8_WAIT_L(n) asm volatile("s_waitcnt lgkmcnt(" #n ")" ::: "memory")
; #define PG8_BAR __builtin_amdgcn_s_barrier()
; #define PG8_SCHED __builtin_amdgcn_sched_barrier(0)
; template <class Epi, class Sched, bool ALIGN_EPI = true>
; __device__ __forceinline__ void gemm_phase(LAS unsigned char* lds, const Gemm g, const Sched& S, const Epi& E) {
;     ...
;             PG8_WAIT_V(8); PG8_WAIT_L(0); PG8_BAR; PG8_MMA(0, 0, At, B0); PG8_MMA(0, 1, At, B1); PG8_BAR; PG8_SCHED;
;             PG8_LDA(At, 1, 1); PG8_STAGE(PG8_SB(1, 0), b3, voffB); PG8_STAGE(PG8_SB(1, 1), b3 + hB, voffB); PG8_STAGE(PG8_SA(1, 0), a3, voffA);
;             PG8_WAIT_V(8); PG8_WAIT_L(0); PG8_BAR; PG8_MMA(1, 0, At, B0); PG8_MMA(1, 1, At, B1); PG8_BAR; PG8_SCHED;
	v_mfma_f32_16x16x32_bf16 v[92:95], v[184:187], v[236:239], v[92:95]
	v_mfma_f32_16x16x32_bf16 v[92:95], v[208:211], v[240:243], v[92:95]
	s_setprio 0
	s_add_i32 s10, s19, s66
	v_lshl_add_u64 v[160:161], v[160:161], 0, s[86:87]
	s_mov_b32 m0, s10
	ds_read_b128 v[212:215], v197 offset:49152
	ds_read_b128 v[216:219], v197 offset:50176
	ds_read_b128 v[220:223], v197 offset:51200
	ds_read_b128 v[224:227], v197 offset:52224
	ds_read_b128 v[228:231], v197 offset:53248
	ds_read_b128 v[232:235], v197 offset:54272
	ds_read_b128 v[236:239], v197 offset:55296
	ds_read_b128 v[240:243], v197 offset:56320
	global_load_lds_dwordx4 v[160:161], off
	s_add_i32 m0, s10, 0x2000
	s_add_u32 s10, s62, 0x160080
	v_lshl_add_u64 v[160:161], v[162:163], 0, s[86:87]
	s_addc_u32 s11, s63, 0
	s_add_i32 s19, s24, s66
	global_load_lds_dwordx4 v[160:161], off
	v_lshl_add_u64 v[160:161], s[10:11], 0, v[2:3]
	s_mov_b32 m0, s19
	s_nop 0
	global_load_lds_dwordx4 v[160:161], off
	v_lshl_add_u64 v[160:161], s[10:11], 0, v[150:151]
	s_add_i32 m0, s19, 0x2000
	s_nop 0
	global_load_lds_dwordx4 v[160:161], off
	v_lshl_add_u64 v[160:161], v[244:245], 0, s[86:87]
	s_mov_b32 m0, s80
	s_nop 0
	global_load_lds_dwordx4 v[160:161], off
	v_lshl_add_u64 v[160:161], v[246:247], 0, s[86:87]
	s_mov_b32 m0, s81
	s_nop 0
	global_load_lds_dwordx4 v[160:161], off
	s_waitcnt vmcnt(8)
	s_waitcnt lgkmcnt(0)
	s_barrier
	s_setprio 1
	s_waitcnt lgkmcnt(0)
	v_mfma_f32_16x16x32_bf16 v[128:131], v[136:139], v[212:215], v[128:131]
	v_mfma_f32_16x16x32_bf16 v[128:131], v[140:143], v[216:219], v[128:131]
	v_mfma_f32_16x16x32_bf16 v[124:127], v[144:147], v[212:215], v[124:127]
	v_mfma_f32_16x16x32_bf16 v[124:127], v[172:175], v[216:219], v[124:127]
	v_mfma_f32_16x16x32_bf16 v[104:107], v[136:139], v[220:223], v[104:107]
	v_mfma_f32_16x16x32_bf16 v[104:107], v[140:143], v[224:227], v[104:107]
	v_mfma_f32_16x16x32_bf16 v[100:103], v[144:147], v[220:223], v[100:103]
	v_mfma_f32_16x16x32_bf16 v[100:103], v[172:175], v[224:227], v[100:103]
	v_mfma_f32_16x16x32_bf16 v[72:75], v[136:139], v[228:231], v[72:75]
	v_mfma_f32_16x16x32_bf16 v[72:75], v[140:143], v[232:235], v[72:75]
	v_mfma_f32_16x16x32_bf16 v[68:71], v[144:147], v[228:231], v[68:71]
	v_mfma_f32_16x16x32_bf16 v[68:71], v[172:175], v[232:235], v[68:71]
	v_mfma_f32_16x16x32_bf16 v[32:35], v[136:139], v[236:239], v[32:35]
	v_mfma_f32_16x16x32_bf16 v[32:35], v[140:143], v[240:243], v[32:35]
	v_mfma_f32_16x16x32_bf16 v[28:31], v[144:147], v[236:239], v[28:31]
	v_mfma_f32_16x16x32_bf16 v[28:31], v[172:175], v[240:243], v[28:31]
	v_mfma_f32_16x16x32_bf16 v[120:123], v[176:179], v[212:215], v[120:123]
	v_mfma_f32_16x16x32_bf16 v[120:123], v[180:183], v[216:219], v[120:123]
	v_mfma_f32_16x16x32_bf16 v[116:119], v[184:187], v[212:215], v[116:119]
	v_mfma_f32_16x16x32_bf16 v[116:119], v[208:211], v[216:219], v[116:119]
	v_mfma_f32_16x16x32_bf16 v[84:87], v[176:179], v[220:223], v[84:87]
	v_mfma_f32_16x16x32_bf16 v[84:87], v[180:183], v[224:227], v[84:87]
	v_mfma_f32_16x16x32_bf16 v[80:83], v[184:187], v[220:223], v[80:83]
	v_mfma_f32_16x16x32_bf16 v[80:83], v[208:211], v[224:227], v[80:83]
	v_mfma_f32_16x16x32_bf16 v[48:51], v[176:179], v[228:231], v[48:51]
	v_mfma_f32_16x16x32_bf16 v[48:51], v[180:183], v[232:235], v[48:51]
	v_mfma_f32_16x16x32_bf16 v[44:47], v[184:187], v[228:231], v[44:47]
	v_mfma_f32_16x16x32_bf16 v[44:47], v[208:211], v[232:235], v[44:47]
	v_mfma_f32_16x16x32_bf16 v[24:27], v[176:179], v[236:239], v[24:27]
	v_mfma_f32_16x16x32_bf16 v[24:27], v[180:183], v[240:243], v[24:27]
	s_setprio 2
	s_barrier
	v_mfma_f32_16x16x32_bf16 v[20:23], v[184:187], v[236:239], v[20:23]
	v_mfma_f32_16x16x32_bf16 v[20:23], v[208:211], v[240:243], v[20:23]
	s_setprio 0
	s_add_i32 s18, s18, 2
	s_cmpk_gt_u32 s18, 0x55
	s_mov_b64 s[10:11], vcc
	s_cbranch_scc1 .Lpeel_exit_1111
.LBB0_1111:
	s_add_u32 vcc_lo, s10, 0x100
	s_addc_u32 vcc_hi, s11, 0
	s_add_u32 s19, s16, s10
	s_addc_u32 s24, s17, s11
	s_add_i32 s25, 0, 0x10000
	s_cmpk_eq_i32 s18, 0x54
	s_cselect_b32 s65, s61, s24
	s_cselect_b32 s24, 0, vcc_lo
	s_cselect_b32 s64, s60, s19
	s_cselect_b32 s19, 0, vcc_hi
	s_add_u32 s62, s2, s24
	v_add_u32_e32 v160, s25, v188
	s_addc_u32 s63, s3, s19
	s_add_i32 s19, 0, 0x14000
	ds_read_b128 v[136:139], v160
	ds_read_b128 v[140:143], v160 offset:1024
	ds_read_b128 v[144:147], v160 offset:2048
	ds_read_b128 v[172:175], v160 offset:3072
	v_add_u32_e32 v160, s19, v188
	ds_read_b128 v[176:179], v160
	ds_read_b128 v[180:183], v160 offset:1024
	ds_read_b128 v[184:187], v160 offset:2048
	ds_read_b128 v[208:211], v160 offset:3072
	v_lshl_add_u64 v[160:161], v[132:133], 0, s[10:11]
	s_add_i32 m0, s67, 0xc000
	ds_read_b128 v[212:215], v197
	ds_read_b128 v[216:219], v197 offset:1024
	ds_read_b128 v[220:223], v197 offset:2048
	ds_read_b128 v[224:227], v197 offset:3072
	ds_read_b128 v[228:231], v197 offset:4096
	ds_read_b128 v[232:235], v197 offset:5120
	ds_read_b128 v[236:239], v197 offset:6144
	ds_read_b128 v[240:243], v197 offset:7168
	global_load_lds_dwordx4 v[160:161], off
	v_lshl_add_u64 v[160:161], v[134:135], 0, s[10:11]
	s_add_i32 m0, s67, 0xe000
	s_nop 0
	global_load_lds_dwordx4 v[160:161], off
	s_waitcnt vmcnt(8)
	s_waitcnt lgkmcnt(0)
	s_barrier
; #define PG8_STAGE(bufoff, gbase, voff) do { _Pragma("unroll") for (int _i = 0; _i < 2; ++_i) \
;         __builtin_amdgcn_global_load_lds((const unsigned*)((const char*)(gbase) + (voff)[_i]), (LAS unsigned*)(lds + (bufoff) + ldsw + _i * 8192), 16, 0, 0); } while (0)
; #define PG8_LDA(dst, b, h) do { _Pragma("unroll") for (int m = 0; m < 4; ++m) _Pragma("unroll") for (int k = 0; k < 2; ++k) dst[m][k] = *(const LAS bf16x8*)(lds + PG8_SA(b, h) + aoff + m * 2048 + k * 1024); } while (0)
; #define PG8_MMA(ai, bj, At, Bt) do { __builtin_amdgcn_s_setprio(1); _Pragma("unroll") for (int m = 0; m < 4; ++m) _Pragma("unroll") for (int n = 0; n < 2; ++n) _Pragma("unroll") for (int k = 0; k < 2; ++k) \
;         acc[ai][bj][m][n] = __builtin_amdgcn_mfma_f32_16x16x32_bf16(Bt[n][k], At[m][k], acc[ai][bj][m][n], 0, 0, 0); __builtin_amdgcn_s_setprio(0); } while (0)
; #define PG8_WAIT_V(n) asm volatile("s_waitcnt vmcnt(" #n ")" ::: "memory")
; #define PG8_WAIT_L(n) asm volatile("s_waitcnt lgkmcnt(" #n ")" ::: "memory")
; #define PG8_BAR __builtin_amdgcn_s_barrier()
; #define PG8_SCHED __builtin_amdgcn_sched_barrier(0)
; template <class Epi, class Sched, bool ALIGN_EPI = true>
; __device__ __forceinline__ void gemm_phase(LAS unsigned char* lds, const Gemm g, const Sched& S, const Epi& E) {
;     ...
;             PG8_WAIT_V(8); PG8_WAIT_L(0); PG8_BAR; PG8_MMA(0, 0, At, B0); PG8_MMA(0, 1, At, B1); PG8_BAR; PG8_SCHED;
;             PG8_LDA(At, 0, 1); PG8_STAGE(PG8_SB(0, 0), b2, voffB); PG8_STAGE(PG8_SB(0, 1), b2 + hB, voffB); PG8_STAGE(PG8_SA(0, 0), a2, voffA);
;             PG8_WAIT_V(8); PG8_WAIT_L(0); PG8_BAR; PG8_MMA(1, 0, At, B0); PG8_MMA(1, 1, At, B1); PG8_BAR; PG8_SCHED;
	s_setprio 1
	s_waitcnt lgkmcnt(0)
	v_mfma_f32_16x16x32_bf16 v[16:19], v[136:139], v[212:215], v[16:19]
	v_mfma_f32_16x16x32_bf16 v[16:19], v[140:143], v[216:219], v[16:19]
	v_mfma_f32_16x16x32_bf16 v[12:15], v[144:147], v[212:215], v[12:15]
	v_mfma_f32_16x16x32_bf16 v[12:15], v[172:175], v[216:219], v[12:15]
	v_mfma_f32_16x16x32_bf16 v[56:59], v[136:139], v[220:223], v[56:59]
	v_mfma_f32_16x16x32_bf16 v[56:59], v[140:143], v[224:227], v[56:59]
	v_mfma_f32_16x16x32_bf16 v[52:55], v[144:147], v[220:223], v[52:55]
	v_mfma_f32_16x16x32_bf16 v[52:55], v[172:175], v[224:227], v[52:55]
	v_mfma_f32_16x16x32_bf16 v[88:91], v[136:139], v[228:231], v[88:91]
	v_mfma_f32_16x16x32_bf16 v[88:91], v[140:143], v[232:235], v[88:91]
	v_mfma_f32_16x16x32_bf16 v[76:79], v[144:147], v[228:231], v[76:79]
	v_mfma_f32_16x16x32_bf16 v[76:79], v[172:175], v[232:235], v[76:79]
	v_mfma_f32_16x16x32_bf16 v[112:115], v[136:139], v[236:239], v[112:115]
	v_mfma_f32_16x16x32_bf16 v[112:115], v[140:143], v[240:243], v[112:115]
	v_mfma_f32_16x16x32_bf16 v[108:111], v[144:147], v[236:239], v[108:111]
	v_mfma_f32_16x16x32_bf16 v[108:111], v[172:175], v[240:243], v[108:111]
	v_mfma_f32_16x16x32_bf16 v[8:11], v[176:179], v[212:215], v[8:11]
	v_mfma_f32_16x16x32_bf16 v[8:11], v[180:183], v[216:219], v[8:11]
	v_mfma_f32_16x16x32_bf16 v[4:7], v[184:187], v[212:215], v[4:7]
	v_mfma_f32_16x16x32_bf16 v[4:7], v[208:211], v[216:219], v[4:7]
	v_mfma_f32_16x16x32_bf16 v[40:43], v[176:179], v[220:223], v[40:43]
	v_mfma_f32_16x16x32_bf16 v[40:43], v[180:183], v[224:227], v[40:43]
	v_mfma_f32_16x16x32_bf16 v[36:39], v[184:187], v[220:223], v[36:39]
	v_mfma_f32_16x16x32_bf16 v[36:39], v[208:211], v[224:227], v[36:39]
	v_mfma_f32_16x16x32_bf16 v[64:67], v[176:179], v[228:231], v[64:67]
	v_mfma_f32_16x16x32_bf16 v[64:67], v[180:183], v[232:235], v[64:67]
	v_mfma_f32_16x16x32_bf16 v[60:63], v[184:187], v[228:231], v[60:63]
	v_mfma_f32_16x16x32_bf16 v[60:63], v[208:211], v[232:235], v[60:63]
	v_mfma_f32_16x16x32_bf16 v[96:99], v[176:179], v[236:239], v[96:99]
	v_mfma_f32_16x16x32_bf16 v[96:99], v[180:183], v[240:243], v[96:99]
	s_setprio 2
	s_barrier
	v_mfma_f32_16x16x32_bf16 v[92:95], v[184:187], v[236:239], v[92:95]
	v_mfma_f32_16x16x32_bf16 v[92:95], v[208:211], v[240:243], v[92:95]
	s_setprio 0
	s_add_i32 s10, s25, s66
	v_lshl_add_u64 v[160:161], s[62:63], 0, v[2:3]
	s_mov_b32 m0, s10
	ds_read_b128 v[212:215], v197 offset:16384
	ds_read_b128 v[216:219], v197 offset:17408
	ds_read_b128 v[220:223], v197 offset:18432
	ds_read_b128 v[224:227], v197 offset:19456
	ds_read_b128 v[228:231], v197 offset:20480
	ds_read_b128 v[232:235], v197 offset:21504
	ds_read_b128 v[236:239], v197 offset:22528
	ds_read_b128 v[240:243], v197 offset:23552
	global_load_lds_dwordx4 v[160:161], off
	s_add_i32 m0, s10, 0x2000
	s_add_u32 s10, s62, 0x160000
	v_lshl_add_u64 v[162:163], s[62:63], 0, v[150:151]
	s_addc_u32 s11, s63, 0
	s_add_i32 s19, s19, s66
	global_load_lds_dwordx4 v[162:163], off
	v_lshl_add_u64 v[244:245], s[10:11], 0, v[2:3]
	s_mov_b32 m0, s19
	v_lshl_add_u64 v[246:247], s[64:65], 0, v[148:149]
	global_load_lds_dwordx4 v[244:245], off
	v_lshl_add_u64 v[244:245], s[10:11], 0, v[150:151]
	s_add_i32 m0, s19, 0x2000
	s_nop 0
	global_load_lds_dwordx4 v[244:245], off
	v_lshl_add_u64 v[244:245], s[64:65], 0, v[0:1]
	s_mov_b32 m0, s67
	s_nop 0
	global_load_lds_dwordx4 v[244:245], off
	s_mov_b32 m0, s75
	s_nop 0
	global_load_lds_dwordx4 v[246:247], off
	s_waitcnt vmcnt(8)
	s_waitcnt lgkmcnt(0)
	s_barrier
	s_setprio 1
	s_waitcnt lgkmcnt(0)
	v_mfma_f32_16x16x32_bf16 v[128:131], v[136:139], v[212:215], v[128:131]
	v_mfma_f32_16x16x32_bf16 v[128:131], v[140:143], v[216:219], v[128:131]
	v_mfma_f32_16x16x32_bf16 v[124:127], v[144:147], v[212:215], v[124:127]
	v_mfma_f32_16x16x32_bf16 v[124:127], v[172:175], v[216:219], v[124:127]
	v_mfma_f32_16x16x32_bf16 v[104:107], v[136:139], v[220:223], v[104:107]
	v_mfma_f32_16x16x32_bf16 v[104:107], v[140:143], v[224:227], v[104:107]
	v_mfma_f32_16x16x32_bf16 v[100:103], v[144:147], v[220:223], v[100:103]
	v_mfma_f32_16x16x32_bf16 v[100:103], v[172:175], v[224:227], v[100:103]
	v_mfma_f32_16x16x32_bf16 v[72:75], v[136:139], v[228:231], v[72:75]
	v_mfma_f32_16x16x32_bf16 v[72:75], v[140:143], v[232:235], v[72:75]
	v_mfma_f32_16x16x32_bf16 v[68:71], v[144:147], v[228:231], v[68:71]
	v_mfma_f32_16x16x32_bf16 v[68:71], v[172:175], v[232:235], v[68:71]
	v_mfma_f32_16x16x32_bf16 v[32:35], v[136:139], v[236:239], v[32:35]
	v_mfma_f32_16x16x32_bf16 v[32:35], v[140:143], v[240:243], v[32:35]
	v_mfma_f32_16x16x32_bf16 v[28:31], v[144:147], v[236:239], v[28:31]
	v_mfma_f32_16x16x32_bf16 v[28:31], v[172:175], v[240:243], v[28:31]
	v_mfma_f32_16x16x32_bf16 v[120:123], v[176:179], v[212:215], v[120:123]
	v_mfma_f32_16x16x32_bf16 v[120:123], v[180:183], v[216:219], v[120:123]
	v_mfma_f32_16x16x32_bf16 v[116:119], v[184:187], v[212:215], v[116:119]
	v_mfma_f32_16x16x32_bf16 v[116:119], v[208:211], v[216:219], v[116:119]
	v_mfma_f32_16x16x32_bf16 v[84:87], v[176:179], v[220:223], v[84:87]
	v_mfma_f32_16x16x32_bf16 v[84:87], v[180:183], v[224:227], v[84:87]
	v_mfma_f32_16x16x32_bf16 v[80:83], v[184:187], v[220:223], v[80:83]
	v_mfma_f32_16x16x32_bf16 v[80:83], v[208:211], v[224:227], v[80:83]
	v_mfma_f32_16x16x32_bf16 v[48:51], v[176:179], v[228:231], v[48:51]
	v_mfma_f32_16x16x32_bf16 v[48:51], v[180:183], v[232:235], v[48:51]
	v_mfma_f32_16x16x32_bf16 v[44:47], v[184:187], v[228:231], v[44:47]
	v_mfma_f32_16x16x32_bf16 v[44:47], v[208:211], v[232:235], v[44:47]
	v_mfma_f32_16x16x32_bf16 v[24:27], v[176:179], v[236:239], v[24:27]
	v_mfma_f32_16x16x32_bf16 v[24:27], v[180:183], v[240:243], v[24:27]
	s_setprio 2
	s_barrier
; #define PG8_STAGE(bufoff, gbase, voff) do { _Pragma("unroll") for (int _i = 0; _i < 2; ++_i) \
;         __builtin_amdgcn_global_load_lds((const unsigned*)((const char*)(gbase) + (voff)[_i]), (LAS unsigned*)(lds + (bufoff) + ldsw + _i * 8192), 16, 0, 0); } while (0)
; #define PG8_LDA(dst, b, h) do { _Pragma("unroll") for (int m = 0; m < 4; ++m) _Pragma("unroll") for (int k = 0; k < 2; ++k) dst[m][k] = *(const LAS bf16x8*)(lds + PG8_SA(b, h) + aoff + m * 2048 + k * 1024); } while (0)
; #define PG8_LDB(dst, b, h) do { _Pragma("unroll") for (int n = 0; n < 2; ++n) _Pragma("unroll") for (int k = 0; k < 2; ++k) dst[n][k] = *(const LAS bf16x8*)(lds + PG8_SB(b, h) + boff + n * 2048 + k * 1024); } while (0)
; #define PG8_MMA(ai, bj, At, Bt) do { __builtin_amdgcn_s_setprio(1); _Pragma("unroll") for (int m = 0; m < 4; ++m) _Pragma("unroll") for (int n = 0; n < 2; ++n) _Pragma("unroll") for (int k = 0; k < 2; ++k) \
;         acc[ai][bj][m][n] = __builtin_amdgcn_mfma_f32_16x16x32_bf16(Bt[n][k], At[m][k], acc[ai][bj][m][n], 0, 0, 0); __builtin_amdgcn_s_setprio(0); } while (0)
; #define PG8_WAIT_V(n) asm volatile("s_waitcnt vmcnt(" #n ")" ::: "memory")
; #define PG8_WAIT_L(n) asm volatile("s_waitcnt lgkmcnt(" #n ")" ::: "memory")
; #define PG8_BAR __builtin_amdgcn_s_barrier()
; #define PG8_SCHED __builtin_amdgcn_sched_barrier(0)
; template <class Epi, class Sched, bool ALIGN_EPI = true>
; __device__ __forceinline__ void gemm_phase(LAS unsigned char* lds, const Gemm g, const Sched& S, const Epi& E) {
;     ...
;             PG8_WAIT_V(8); PG8_WAIT_L(0); PG8_BAR; PG8_MMA(1, 0, At, B0); PG8_MMA(1, 1, At, B1); PG8_BAR; PG8_SCHED;
;             PG8_LDB(B0, 1, 0); PG8_LDB(B1, 1, 1); PG8_SCHED; PG8_LDA(At, 1, 0); PG8_STAGE(PG8_SA(0, 1), a2 + hA, voffA);
;             PG8_WAIT_V(8); PG8_WAIT_L(0); PG8_BAR; PG8_MMA(0, 0, At, B0); PG8_MMA(0, 1, At, B1); PG8_BAR; PG8_SCHED;
	v_mfma_f32_16x16x32_bf16 v[20:23], v[184:187], v[236:239], v[20:23]
	v_mfma_f32_16x16x32_bf16 v[20:23], v[208:211], v[240:243], v[20:23]
	s_setprio 0
	s_add_i32 s19, 0, 0x18000
	s_add_i32 s24, 0, 0x1c000
	v_add_u32_e32 v172, s19, v188
	v_add_u32_e32 v207, s24, v188
	ds_read_b128 v[136:139], v172
	ds_read_b128 v[140:143], v172 offset:1024
	ds_read_b128 v[144:147], v172 offset:2048
	ds_read_b128 v[172:175], v172 offset:3072
	ds_read_b128 v[176:179], v207
	ds_read_b128 v[180:183], v207 offset:1024
	ds_read_b128 v[184:187], v207 offset:2048
	ds_read_b128 v[208:211], v207 offset:3072
	s_add_u32 s10, s64, 0x160000
	s_addc_u32 s11, s65, 0
	s_mov_b32 m0, s76
	v_lshl_add_u64 v[248:249], s[10:11], 0, v[0:1]
	ds_read_b128 v[212:215], v197 offset:32768
	ds_read_b128 v[216:219], v197 offset:33792
	ds_read_b128 v[220:223], v197 offset:34816
	ds_read_b128 v[224:227], v197 offset:35840
	ds_read_b128 v[228:231], v197 offset:36864
	ds_read_b128 v[232:235], v197 offset:37888
	ds_read_b128 v[236:239], v197 offset:38912
	ds_read_b128 v[240:243], v197 offset:39936
	global_load_lds_dwordx4 v[248:249], off
	v_lshl_add_u64 v[248:249], s[10:11], 0, v[148:149]
	s_mov_b32 m0, s77
	s_nop 0
	global_load_lds_dwordx4 v[248:249], off
	s_waitcnt vmcnt(8)
	s_waitcnt lgkmcnt(0)
	s_barrier
	s_setprio 1
	s_waitcnt lgkmcnt(0)
	v_mfma_f32_16x16x32_bf16 v[16:19], v[136:139], v[212:215], v[16:19]
	v_mfma_f32_16x16x32_bf16 v[16:19], v[140:143], v[216:219], v[16:19]
	v_mfma_f32_16x16x32_bf16 v[12:15], v[144:147], v[212:215], v[12:15]
	v_mfma_f32_16x16x32_bf16 v[12:15], v[172:175], v[216:219], v[12:15]
	v_mfma_f32_16x16x32_bf16 v[56:59], v[136:139], v[220:223], v[56:59]
	v_mfma_f32_16x16x32_bf16 v[56:59], v[140:143], v[224:227], v[56:59]
	v_mfma_f32_16x16x32_bf16 v[52:55], v[144:147], v[220:223], v[52:55]
	v_mfma_f32_16x16x32_bf16 v[52:55], v[172:175], v[224:227], v[52:55]
	v_mfma_f32_16x16x32_bf16 v[88:91], v[136:139], v[228:231], v[88:91]
	v_mfma_f32_16x16x32_bf16 v[88:91], v[140:143], v[232:235], v[88:91]
	v_mfma_f32_16x16x32_bf16 v[76:79], v[144:147], v[228:231], v[76:79]
	v_mfma_f32_16x16x32_bf16 v[76:79], v[172:175], v[232:235], v[76:79]
	v_mfma_f32_16x16x32_bf16 v[112:115], v[136:139], v[236:239], v[112:115]
	v_mfma_f32_16x16x32_bf16 v[112:115], v[140:143], v[240:243], v[112:115]
	v_mfma_f32_16x16x32_bf16 v[108:111], v[144:147], v[236:239], v[108:111]
	v_mfma_f32_16x16x32_bf16 v[108:111], v[172:175], v[240:243], v[108:111]
	v_mfma_f32_16x16x32_bf16 v[8:11], v[176:179], v[212:215], v[8:11]
	v_mfma_f32_16x16x32_bf16 v[8:11], v[180:183], v[216:219], v[8:11]
	v_mfma_f32_16x16x32_bf16 v[4:7], v[184:187], v[212:215], v[4:7]
	v_mfma_f32_16x16x32_bf16 v[4:7], v[208:211], v[216:219], v[4:7]
	v_mfma_f32_16x16x32_bf16 v[40:43], v[176:179], v[220:223], v[40:43]
	v_mfma_f32_16x16x32_bf16 v[40:43], v[180:183], v[224:227], v[40:43]
	v_mfma_f32_16x16x32_bf16 v[36:39], v[184:187], v[220:223], v[36:39]
	v_mfma_f32_16x16x32_bf16 v[36:39], v[208:211], v[224:227], v[36:39]
	v_mfma_f32_16x16x32_bf16 v[64:67], v[176:179], v[228:231], v[64:67]
	v_mfma_f32_16x16x32_bf16 v[64:67], v[180:183], v[232:235], v[64:67]
	v_mfma_f32_16x16x32_bf16 v[60:63], v[184:187], v[228:231], v[60:63]
	v_mfma_f32_16x16x32_bf16 v[60:63], v[208:211], v[232:235], v[60:63]
	v_mfma_f32_16x16x32_bf16 v[96:99], v[176:179], v[236:239], v[96:99]
	v_mfma_f32_16x16x32_bf16 v[96:99], v[180:183], v[240:243], v[96:99]
	s_setprio 2
	s_barrier
; #define PG8_STAGE(bufoff, gbase, voff) do { _Pragma("unroll") for (int _i = 0; _i < 2; ++_i) \
;         __builtin_amdgcn_global_load_lds((const unsigned*)((const char*)(gbase) + (voff)[_i]), (LAS unsigned*)(lds + (bufoff) + ldsw + _i * 8192), 16, 0, 0); } while (0)
; #define PG8_LDA(dst, b, h) do { _Pragma("unroll") for (int m = 0; m < 4; ++m) _Pragma("unroll") for (int k = 0; k < 2; ++k) dst[m][k] = *(const LAS bf16x8*)(lds + PG8_SA(b, h) + aoff + m * 2048 + k * 1024); } while (0)
; #define PG8_MMA(ai, bj, At, Bt) do { __builtin_amdgcn_s_setprio(1); _Pragma("unroll") for (int m = 0; m < 4; ++m) _Pragma("unroll") for (int n = 0; n < 2; ++n) _Pragma("unroll") for (int k = 0; k < 2; ++k) \
;         acc[ai][bj][m][n] = __builtin_amdgcn_mfma_f32_16x16x32_bf16(Bt[n][k], At[m][k], acc[ai][bj][m][n], 0, 0, 0); __builtin_amdgcn_s_setprio(0); } while (0)
; #define PG8_WAIT_V(n) asm volatile("s_waitcnt vmcnt(" #n ")" ::: "memory")
; #define PG8_WAIT_L(n) asm volatile("s_waitcnt lgkmcnt(" #n ")" ::: "memory")
; #define PG8_BAR __builtin_amdgcn_s_barrier()
; #define PG8_SCHED __builtin_amdgcn_sched_barrier(0)
; template <class Epi, class Sched, bool ALIGN_EPI = true>
; __device__ __forceinline__ void gemm_phase(LAS unsigned char* lds, const Gemm g, const Sched& S, const Epi& E) {
;     ...
;             PG8_WAIT_V(8); PG8_WAIT_L(0); PG8_BAR; PG8_MMA(0, 0, At, B0); PG8_MMA(0, 1, At, B1); PG8_BAR; PG8_SCHED;
;             PG8_LDA(At, 1, 1); PG8_STAGE(PG8_SB(1, 0), b3, voffB); PG8_STAGE(PG8_SB(1, 1), b3 + hB, voffB); PG8_STAGE(PG8_SA(1, 0), a3, voffA);
;             PG8_WAIT_V(8); PG8_WAIT_L(0); PG8_BAR; PG8_MMA(1, 0, At, B0); PG8_MMA(1, 1, At, B1); PG8_BAR; PG8_SCHED;
;         }
	v_mfma_f32_16x16x32_bf16 v[92:95], v[184:187], v[236:239], v[92:95]
	v_mfma_f32_16x16x32_bf16 v[92:95], v[208:211], v[240:243], v[92:95]
	s_setprio 0
	s_add_i32 s10, s19, s66
	v_lshl_add_u64 v[160:161], v[160:161], 0, s[86:87]
	s_mov_b32 m0, s10
	ds_read_b128 v[212:215], v197 offset:49152
	ds_read_b128 v[216:219], v197 offset:50176
	ds_read_b128 v[220:223], v197 offset:51200
	ds_read_b128 v[224:227], v197 offset:52224
	ds_read_b128 v[228:231], v197 offset:53248
	ds_read_b128 v[232:235], v197 offset:54272
	ds_read_b128 v[236:239], v197 offset:55296
	ds_read_b128 v[240:243], v197 offset:56320
	global_load_lds_dwordx4 v[160:161], off
	s_add_i32 m0, s10, 0x2000
	s_add_u32 s10, s62, 0x160080
	v_lshl_add_u64 v[160:161], v[162:163], 0, s[86:87]
	s_addc_u32 s11, s63, 0
	s_add_i32 s19, s24, s66
	global_load_lds_dwordx4 v[160:161], off
	v_lshl_add_u64 v[160:161], s[10:11], 0, v[2:3]
	s_mov_b32 m0, s19
	s_nop 0
	global_load_lds_dwordx4 v[160:161], off
	v_lshl_add_u64 v[160:161], s[10:11], 0, v[150:151]
	s_add_i32 m0, s19, 0x2000
	s_nop 0
	global_load_lds_dwordx4 v[160:161], off
	v_lshl_add_u64 v[160:161], v[244:245], 0, s[86:87]
	s_mov_b32 m0, s80
	s_nop 0
	global_load_lds_dwordx4 v[160:161], off
	v_lshl_add_u64 v[160:161], v[246:247], 0, s[86:87]
	s_mov_b32 m0, s81
	s_nop 0
	global_load_lds_dwordx4 v[160:161], off
	s_waitcnt vmcnt(8)
	s_waitcnt lgkmcnt(0)
	s_barrier
	s_setprio 1
	s_waitcnt lgkmcnt(0)
	v_mfma_f32_16x16x32_bf16 v[128:131], v[136:139], v[212:215], v[128:131]
	v_mfma_f32_16x16x32_bf16 v[128:131], v[140:143], v[216:219], v[128:131]
	v_mfma_f32_16x16x32_bf16 v[124:127], v[144:147], v[212:215], v[124:127]
	v_mfma_f32_16x16x32_bf16 v[124:127], v[172:175], v[216:219], v[124:127]
	v_mfma_f32_16x16x32_bf16 v[104:107], v[136:139], v[220:223], v[104:107]
	v_mfma_f32_16x16x32_bf16 v[104:107], v[140:143], v[224:227], v[104:107]
	v_mfma_f32_16x16x32_bf16 v[100:103], v[144:147], v[220:223], v[100:103]
	v_mfma_f32_16x16x32_bf16 v[100:103], v[172:175], v[224:227], v[100:103]
	v_mfma_f32_16x16x32_bf16 v[72:75], v[136:139], v[228:231], v[72:75]
	v_mfma_f32_16x16x32_bf16 v[72:75], v[140:143], v[232:235], v[72:75]
	v_mfma_f32_16x16x32_bf16 v[68:71], v[144:147], v[228:231], v[68:71]
	v_mfma_f32_16x16x32_bf16 v[68:71], v[172:175], v[232:235], v[68:71]
	v_mfma_f32_16x16x32_bf16 v[32:35], v[136:139], v[236:239], v[32:35]
	v_mfma_f32_16x16x32_bf16 v[32:35], v[140:143], v[240:243], v[32:35]
	v_mfma_f32_16x16x32_bf16 v[28:31], v[144:147], v[236:239], v[28:31]
	v_mfma_f32_16x16x32_bf16 v[28:31], v[172:175], v[240:243], v[28:31]
	v_mfma_f32_16x16x32_bf16 v[120:123], v[176:179], v[212:215], v[120:123]
	v_mfma_f32_16x16x32_bf16 v[120:123], v[180:183], v[216:219], v[120:123]
	v_mfma_f32_16x16x32_bf16 v[116:119], v[184:187], v[212:215], v[116:119]
	v_mfma_f32_16x16x32_bf16 v[116:119], v[208:211], v[216:219], v[116:119]
	v_mfma_f32_16x16x32_bf16 v[84:87], v[176:179], v[220:223], v[84:87]
	v_mfma_f32_16x16x32_bf16 v[84:87], v[180:183], v[224:227], v[84:87]
	v_mfma_f32_16x16x32_bf16 v[80:83], v[184:187], v[220:223], v[80:83]
	v_mfma_f32_16x16x32_bf16 v[80:83], v[208:211], v[224:227], v[80:83]
	v_mfma_f32_16x16x32_bf16 v[48:51], v[176:179], v[228:231], v[48:51]
	v_mfma_f32_16x16x32_bf16 v[48:51], v[180:183], v[232:235], v[48:51]
	v_mfma_f32_16x16x32_bf16 v[44:47], v[184:187], v[228:231], v[44:47]
	v_mfma_f32_16x16x32_bf16 v[44:47], v[208:211], v[232:235], v[44:47]
	v_mfma_f32_16x16x32_bf16 v[24:27], v[176:179], v[236:239], v[24:27]
	v_mfma_f32_16x16x32_bf16 v[24:27], v[180:183], v[240:243], v[24:27]
	s_setprio 2
	s_barrier
	v_mfma_f32_16x16x32_bf16 v[20:23], v[184:187], v[236:239], v[20:23]
	v_mfma_f32_16x16x32_bf16 v[20:23], v[208:211], v[240:243], v[20:23]
	s_setprio 0
	s_add_i32 s18, s18, 2
	s_cmpk_gt_u32 s18, 0x55
	s_mov_b64 s[10:11], vcc
	s_cbranch_scc0 .LBB0_1111
